# stack2
# baseline (speedup 1.0000x reference)
;   #define LDA(dst,b,h) for(int m=0;m<4;++m)for(int k=0;k<2;++k) \
;     dst[m][k]=*reinterpret_cast<const bf16x8*>((char*)SA(b,h)+lds_byte(wr*64+m*16+fr,k*32+fq*8))
;   #define LDB(dst,b,h) for(int n=0;n<2;++n)for(int k=0;k<2;++k) \
;     dst[n][k]=*reinterpret_cast<const bf16x8*>((char*)SB(b,h)+lds_byte(wc*32+n*16+fr,k*32+fq*8))
;   #define MMA(ai,bj,At,Bt_) do{__builtin_amdgcn_s_setprio(1); \
;     for(int m=0;m<4;++m)for(int n=0;n<2;++n)for(int k=0;k<2;++k) \
;       acc[ai][bj][m][n]=__builtin_amdgcn_mfma_f32_16x16x32_bf16(Bt_[n][k],At[m][k],acc[ai][bj][m][n],0,0,0); \
;     __builtin_amdgcn_s_setprio(0);}while(0)
;   #define WAIT_V(n) asm volatile("s_waitcnt vmcnt(" #n ")":::"memory")
;   #define WAIT_L(n) asm volatile("s_waitcnt lgkmcnt(" #n ")":::"memory")
;   #define BAR __builtin_amdgcn_s_barrier()
;   #define SCHED __builtin_amdgcn_sched_barrier(0)
; template <bool TWO, class MID> ...
;     ...
;   for(int t=0;t<nt-2;t+=2){
;     if (TWO && t == nt1) mid();
;     LDB(B0,0,0); SCHED; LDA(At,0,0); STAGE_A(SA(1,1),1,t+1);
;     WAIT_L(8); BAR; WAIT_L(0); MMA(0,0,At,B0); BAR; SCHED;
;     LDB(B1,0,1); STAGE_B(SB(0,0),0,t+2);
;     BAR; WAIT_L(0); MMA(0,1,At,B1); BAR;
;     LDA(At,0,1); STAGE_A(SA(0,0),0,t+2);
;     BAR; WAIT_L(0); MMA(1,0,At,B0); BAR; SCHED;
;     STAGE_B(SB(0,1),1,t+2);
;     WAIT_V(6); BAR; MMA(1,1,At,B1); BAR;
.LBB0_169:
	ds_read_b128 v[170:173], v143
	ds_read_b128 v[174:177], v143 offset:1024
	ds_read_b128 v[178:181], v143 offset:2048
	ds_read_b128 v[182:185], v143 offset:3072
	ds_read_b128 v[186:189], v168
	ds_read_b128 v[190:193], v168 offset:1024
	ds_read_b128 v[196:199], v167
	ds_read_b128 v[200:203], v167 offset:1024
	ds_read_b128 v[204:207], v166
	ds_read_b128 v[208:211], v166 offset:1024
	ds_read_b128 v[212:215], v147
	ds_read_b128 v[216:219], v147 offset:1024
	s_add_u32 s17, s0, s12
	s_addc_u32 s18, s1, s13
	s_add_u32 s20, s17, 0x8080080
	s_addc_u32 s21, s18, 0
	v_lshl_add_u64 v[220:221], s[20:21], 0, v[132:133]
	v_readfirstlane_b32 s19, v148
	s_mov_b32 m0, s19
	global_load_lds_dwordx4 v[220:221], off
	v_lshl_add_u64 v[220:221], s[20:21], 0, v[130:131]
	v_readfirstlane_b32 s19, v156
	s_mov_b32 m0, s19
	global_load_lds_dwordx4 v[220:221], off
	s_waitcnt lgkmcnt(8)
	s_barrier
	s_waitcnt lgkmcnt(0)
	s_setprio 1
	s_waitcnt lgkmcnt(7)
	v_mfma_f32_16x16x32_bf16 v[126:129], v[170:173], v[186:189], v[126:129]
	v_mfma_f32_16x16x32_bf16 v[122:125], v[178:181], v[186:189], v[122:125]
	s_waitcnt lgkmcnt(5)
	v_mfma_f32_16x16x32_bf16 v[118:121], v[170:173], v[196:199], v[118:121]
	v_mfma_f32_16x16x32_bf16 v[114:117], v[178:181], v[196:199], v[114:117]
	s_waitcnt lgkmcnt(3)
	v_mfma_f32_16x16x32_bf16 v[110:113], v[170:173], v[204:207], v[110:113]
	v_mfma_f32_16x16x32_bf16 v[106:109], v[178:181], v[204:207], v[106:109]
	s_waitcnt lgkmcnt(1)
	v_mfma_f32_16x16x32_bf16 v[102:105], v[170:173], v[212:215], v[102:105]
	v_mfma_f32_16x16x32_bf16 v[98:101], v[178:181], v[212:215], v[98:101]
	v_mfma_f32_16x16x32_bf16 v[126:129], v[174:177], v[190:193], v[126:129]
	v_mfma_f32_16x16x32_bf16 v[122:125], v[182:185], v[190:193], v[122:125]
	v_mfma_f32_16x16x32_bf16 v[118:121], v[174:177], v[200:203], v[118:121]
	v_mfma_f32_16x16x32_bf16 v[114:117], v[182:185], v[200:203], v[114:117]
	v_mfma_f32_16x16x32_bf16 v[110:113], v[174:177], v[208:211], v[110:113]
	v_mfma_f32_16x16x32_bf16 v[106:109], v[182:185], v[208:211], v[106:109]
	s_waitcnt lgkmcnt(0)
	v_mfma_f32_16x16x32_bf16 v[102:105], v[174:177], v[216:219], v[102:105]
	v_mfma_f32_16x16x32_bf16 v[98:101], v[182:185], v[216:219], v[98:101]
	s_setprio 0
	s_barrier
	s_add_u32 s19, s0, s14
	ds_read_b128 v[220:223], v141
	ds_read_b128 v[224:227], v141 offset:1024
	ds_read_b128 v[228:231], v141 offset:2048
	ds_read_b128 v[232:235], v141 offset:3072
	s_addc_u32 s20, s1, s15
	s_add_u32 s26, s19, 0x100
	s_addc_u32 s27, s20, 0
	v_lshl_add_u64 v[236:237], s[26:27], 0, v[132:133]
	v_readfirstlane_b32 s21, v150
	s_mov_b32 m0, s21
	global_load_lds_dwordx4 v[236:237], off
	v_lshl_add_u64 v[236:237], s[26:27], 0, v[130:131]
	v_readfirstlane_b32 s21, v158
	s_mov_b32 m0, s21
	global_load_lds_dwordx4 v[236:237], off
	s_barrier
	s_waitcnt lgkmcnt(0)
	s_setprio 1
	s_waitcnt lgkmcnt(3)
	v_mfma_f32_16x16x32_bf16 v[94:97], v[220:223], v[186:189], v[94:97]
	s_waitcnt lgkmcnt(1)
	v_mfma_f32_16x16x32_bf16 v[90:93], v[228:231], v[186:189], v[90:93]
	v_mfma_f32_16x16x32_bf16 v[86:89], v[220:223], v[196:199], v[86:89]
	v_mfma_f32_16x16x32_bf16 v[82:85], v[228:231], v[196:199], v[82:85]
	v_mfma_f32_16x16x32_bf16 v[78:81], v[220:223], v[204:207], v[78:81]
	v_mfma_f32_16x16x32_bf16 v[74:77], v[228:231], v[204:207], v[74:77]
	v_mfma_f32_16x16x32_bf16 v[70:73], v[220:223], v[212:215], v[70:73]
	v_mfma_f32_16x16x32_bf16 v[66:69], v[228:231], v[212:215], v[66:69]
	v_mfma_f32_16x16x32_bf16 v[94:97], v[224:227], v[190:193], v[94:97]
	s_waitcnt lgkmcnt(0)
	v_mfma_f32_16x16x32_bf16 v[90:93], v[232:235], v[190:193], v[90:93]
	v_mfma_f32_16x16x32_bf16 v[86:89], v[224:227], v[200:203], v[86:89]
	v_mfma_f32_16x16x32_bf16 v[82:85], v[232:235], v[200:203], v[82:85]
	v_mfma_f32_16x16x32_bf16 v[78:81], v[224:227], v[208:211], v[78:81]
	v_mfma_f32_16x16x32_bf16 v[74:77], v[232:235], v[208:211], v[74:77]
	v_mfma_f32_16x16x32_bf16 v[70:73], v[224:227], v[216:219], v[70:73]
	v_mfma_f32_16x16x32_bf16 v[66:69], v[232:235], v[216:219], v[66:69]
	s_setprio 0
	s_barrier
	ds_read_b128 v[186:189], v168 offset:16384
	ds_read_b128 v[190:193], v168 offset:17408
	ds_read_b128 v[196:199], v167 offset:16384
	ds_read_b128 v[200:203], v167 offset:17408
	ds_read_b128 v[204:207], v166 offset:16384
	ds_read_b128 v[208:211], v166 offset:17408
	ds_read_b128 v[212:215], v147 offset:16384
	ds_read_b128 v[216:219], v147 offset:17408
	s_add_u32 s26, s17, 0x8000100
	s_addc_u32 s27, s18, 0
	v_lshl_add_u64 v[236:237], s[26:27], 0, v[132:133]
	v_readfirstlane_b32 s21, v138
	s_mov_b32 m0, s21
	global_load_lds_dwordx4 v[236:237], off
	v_lshl_add_u64 v[236:237], s[26:27], 0, v[130:131]
	v_readfirstlane_b32 s21, v160
	s_mov_b32 m0, s21
	global_load_lds_dwordx4 v[236:237], off
	s_barrier
	s_waitcnt lgkmcnt(0)
	s_setprio 1
	s_waitcnt lgkmcnt(7)
	v_mfma_f32_16x16x32_bf16 v[62:65], v[170:173], v[186:189], v[62:65]
	v_mfma_f32_16x16x32_bf16 v[58:61], v[178:181], v[186:189], v[58:61]
	s_waitcnt lgkmcnt(5)
	v_mfma_f32_16x16x32_bf16 v[54:57], v[170:173], v[196:199], v[54:57]
	v_mfma_f32_16x16x32_bf16 v[50:53], v[178:181], v[196:199], v[50:53]
	s_waitcnt lgkmcnt(3)
	v_mfma_f32_16x16x32_bf16 v[46:49], v[170:173], v[204:207], v[46:49]
	v_mfma_f32_16x16x32_bf16 v[42:45], v[178:181], v[204:207], v[42:45]
	s_waitcnt lgkmcnt(1)
	v_mfma_f32_16x16x32_bf16 v[38:41], v[170:173], v[212:215], v[38:41]
	v_mfma_f32_16x16x32_bf16 v[34:37], v[178:181], v[212:215], v[34:37]
	v_mfma_f32_16x16x32_bf16 v[62:65], v[174:177], v[190:193], v[62:65]
	v_mfma_f32_16x16x32_bf16 v[58:61], v[182:185], v[190:193], v[58:61]
	v_mfma_f32_16x16x32_bf16 v[54:57], v[174:177], v[200:203], v[54:57]
	v_mfma_f32_16x16x32_bf16 v[50:53], v[182:185], v[200:203], v[50:53]
	v_mfma_f32_16x16x32_bf16 v[46:49], v[174:177], v[208:211], v[46:49]
	v_mfma_f32_16x16x32_bf16 v[42:45], v[182:185], v[208:211], v[42:45]
	s_waitcnt lgkmcnt(0)
	v_mfma_f32_16x16x32_bf16 v[38:41], v[174:177], v[216:219], v[38:41]
	v_mfma_f32_16x16x32_bf16 v[34:37], v[182:185], v[216:219], v[34:37]
	s_setprio 0
	s_barrier
;   #define LDA(dst,b,h) for(int m=0;m<4;++m)for(int k=0;k<2;++k) \
;     dst[m][k]=*reinterpret_cast<const bf16x8*>((char*)SA(b,h)+lds_byte(wr*64+m*16+fr,k*32+fq*8))
;   #define LDB(dst,b,h) for(int n=0;n<2;++n)for(int k=0;k<2;++k) \
;     dst[n][k]=*reinterpret_cast<const bf16x8*>((char*)SB(b,h)+lds_byte(wc*32+n*16+fr,k*32+fq*8))
;   #define MMA(ai,bj,At,Bt_) do{__builtin_amdgcn_s_setprio(1); \
;     for(int m=0;m<4;++m)for(int n=0;n<2;++n)for(int k=0;k<2;++k) \
;       acc[ai][bj][m][n]=__builtin_amdgcn_mfma_f32_16x16x32_bf16(Bt_[n][k],At[m][k],acc[ai][bj][m][n],0,0,0); \
;     __builtin_amdgcn_s_setprio(0);}while(0)
;   #define WAIT_V(n) asm volatile("s_waitcnt vmcnt(" #n ")":::"memory")
;   #define WAIT_L(n) asm volatile("s_waitcnt lgkmcnt(" #n ")":::"memory")
;   #define BAR __builtin_amdgcn_s_barrier()
;   #define SCHED __builtin_amdgcn_sched_barrier(0)
; template <bool TWO, class MID> ...
;     ...
;     WAIT_V(6); BAR; MMA(1,1,At,B1); BAR;
;     LDB(B0,1,0); SCHED; LDA(At,1,0); STAGE_A(SA(0,1),1,t+2);
;     WAIT_L(8); BAR; WAIT_L(0); MMA(0,0,At,B0); BAR; SCHED;
;     LDB(B1,1,1); STAGE_B(SB(1,0),0,t+3);
;     BAR; WAIT_L(0); MMA(0,1,At,B1); BAR;
;     LDA(At,1,1); STAGE_A(SA(1,0),0,t+3);
;     BAR; WAIT_L(0); MMA(1,0,At,B0); BAR; SCHED;
	s_add_u32 s26, s19, 0x80100
	s_addc_u32 s27, s20, 0
	v_lshl_add_u64 v[170:171], s[26:27], 0, v[132:133]
	v_readfirstlane_b32 s21, v152
	s_mov_b32 m0, s21
	global_load_lds_dwordx4 v[170:171], off
	v_lshl_add_u64 v[170:171], s[26:27], 0, v[130:131]
	v_readfirstlane_b32 s21, v162
	s_mov_b32 m0, s21
	global_load_lds_dwordx4 v[170:171], off
	s_waitcnt vmcnt(6)
	s_barrier
	s_setprio 1
	v_mfma_f32_16x16x32_bf16 v[30:33], v[220:223], v[186:189], v[30:33]
	v_mfma_f32_16x16x32_bf16 v[26:29], v[228:231], v[186:189], v[26:29]
	v_mfma_f32_16x16x32_bf16 v[22:25], v[220:223], v[196:199], v[22:25]
	v_mfma_f32_16x16x32_bf16 v[18:21], v[228:231], v[196:199], v[18:21]
	v_mfma_f32_16x16x32_bf16 v[14:17], v[220:223], v[204:207], v[14:17]
	v_mfma_f32_16x16x32_bf16 v[10:13], v[228:231], v[204:207], v[10:13]
	v_mfma_f32_16x16x32_bf16 v[6:9], v[220:223], v[212:215], v[6:9]
	v_mfma_f32_16x16x32_bf16 v[2:5], v[228:231], v[212:215], v[2:5]
	v_mfma_f32_16x16x32_bf16 v[30:33], v[224:227], v[190:193], v[30:33]
	v_mfma_f32_16x16x32_bf16 v[26:29], v[232:235], v[190:193], v[26:29]
	v_mfma_f32_16x16x32_bf16 v[22:25], v[224:227], v[200:203], v[22:25]
	v_mfma_f32_16x16x32_bf16 v[18:21], v[232:235], v[200:203], v[18:21]
	v_mfma_f32_16x16x32_bf16 v[14:17], v[224:227], v[208:211], v[14:17]
	v_mfma_f32_16x16x32_bf16 v[10:13], v[232:235], v[208:211], v[10:13]
	v_mfma_f32_16x16x32_bf16 v[6:9], v[224:227], v[216:219], v[6:9]
	v_mfma_f32_16x16x32_bf16 v[2:5], v[232:235], v[216:219], v[2:5]
	s_setprio 0
	s_barrier
	ds_read_b128 v[170:173], v137
	ds_read_b128 v[174:177], v137 offset:1024
	ds_read_b128 v[178:181], v137 offset:2048
	ds_read_b128 v[182:185], v137 offset:3072
	ds_read_b128 v[186:189], v168 offset:32768
	ds_read_b128 v[190:193], v168 offset:33792
	ds_read_b128 v[196:199], v167 offset:32768
	ds_read_b128 v[200:203], v167 offset:33792
	ds_read_b128 v[204:207], v166 offset:32768
	ds_read_b128 v[208:211], v166 offset:33792
	ds_read_b128 v[212:215], v147 offset:32768
	ds_read_b128 v[216:219], v147 offset:33792
	s_add_u32 s26, s17, 0x8080100
	s_addc_u32 s27, s18, 0
	v_lshl_add_u64 v[220:221], s[26:27], 0, v[132:133]
	v_readfirstlane_b32 s21, v154
	s_mov_b32 m0, s21
	global_load_lds_dwordx4 v[220:221], off
	v_lshl_add_u64 v[220:221], s[26:27], 0, v[130:131]
	v_readfirstlane_b32 s21, v164
	s_mov_b32 m0, s21
	global_load_lds_dwordx4 v[220:221], off
	s_waitcnt lgkmcnt(8)
	s_barrier
	s_waitcnt lgkmcnt(0)
	s_setprio 1
	s_waitcnt lgkmcnt(7)
	v_mfma_f32_16x16x32_bf16 v[126:129], v[170:173], v[186:189], v[126:129]
	v_mfma_f32_16x16x32_bf16 v[122:125], v[178:181], v[186:189], v[122:125]
	s_waitcnt lgkmcnt(5)
	v_mfma_f32_16x16x32_bf16 v[118:121], v[170:173], v[196:199], v[118:121]
	v_mfma_f32_16x16x32_bf16 v[114:117], v[178:181], v[196:199], v[114:117]
	s_waitcnt lgkmcnt(3)
	v_mfma_f32_16x16x32_bf16 v[110:113], v[170:173], v[204:207], v[110:113]
	v_mfma_f32_16x16x32_bf16 v[106:109], v[178:181], v[204:207], v[106:109]
	s_waitcnt lgkmcnt(1)
	v_mfma_f32_16x16x32_bf16 v[102:105], v[170:173], v[212:215], v[102:105]
	v_mfma_f32_16x16x32_bf16 v[98:101], v[178:181], v[212:215], v[98:101]
	v_mfma_f32_16x16x32_bf16 v[126:129], v[174:177], v[190:193], v[126:129]
	v_mfma_f32_16x16x32_bf16 v[122:125], v[182:185], v[190:193], v[122:125]
	v_mfma_f32_16x16x32_bf16 v[118:121], v[174:177], v[200:203], v[118:121]
	v_mfma_f32_16x16x32_bf16 v[114:117], v[182:185], v[200:203], v[114:117]
	v_mfma_f32_16x16x32_bf16 v[110:113], v[174:177], v[208:211], v[110:113]
	v_mfma_f32_16x16x32_bf16 v[106:109], v[182:185], v[208:211], v[106:109]
	s_waitcnt lgkmcnt(0)
	v_mfma_f32_16x16x32_bf16 v[102:105], v[174:177], v[216:219], v[102:105]
	v_mfma_f32_16x16x32_bf16 v[98:101], v[182:185], v[216:219], v[98:101]
	s_setprio 0
	s_barrier
	ds_read_b128 v[220:223], v135
	ds_read_b128 v[224:227], v135 offset:1024
	ds_read_b128 v[228:231], v135 offset:2048
	ds_read_b128 v[232:235], v135 offset:3072
	s_add_u32 s26, s19, 0x180
	s_addc_u32 s27, s20, 0
	v_lshl_add_u64 v[236:237], s[26:27], 0, v[132:133]
	v_readfirstlane_b32 s21, v134
	s_mov_b32 m0, s21
	global_load_lds_dwordx4 v[236:237], off
	v_lshl_add_u64 v[236:237], s[26:27], 0, v[130:131]
	v_readfirstlane_b32 s21, v136
	s_mov_b32 m0, s21
	global_load_lds_dwordx4 v[236:237], off
	s_barrier
	s_waitcnt lgkmcnt(0)
	s_setprio 1
	s_waitcnt lgkmcnt(3)
	v_mfma_f32_16x16x32_bf16 v[94:97], v[220:223], v[186:189], v[94:97]
	s_waitcnt lgkmcnt(1)
	v_mfma_f32_16x16x32_bf16 v[90:93], v[228:231], v[186:189], v[90:93]
	v_mfma_f32_16x16x32_bf16 v[86:89], v[220:223], v[196:199], v[86:89]
	v_mfma_f32_16x16x32_bf16 v[82:85], v[228:231], v[196:199], v[82:85]
	v_mfma_f32_16x16x32_bf16 v[78:81], v[220:223], v[204:207], v[78:81]
	v_mfma_f32_16x16x32_bf16 v[74:77], v[228:231], v[204:207], v[74:77]
	v_mfma_f32_16x16x32_bf16 v[70:73], v[220:223], v[212:215], v[70:73]
	v_mfma_f32_16x16x32_bf16 v[66:69], v[228:231], v[212:215], v[66:69]
	v_mfma_f32_16x16x32_bf16 v[94:97], v[224:227], v[190:193], v[94:97]
	s_waitcnt lgkmcnt(0)
	v_mfma_f32_16x16x32_bf16 v[90:93], v[232:235], v[190:193], v[90:93]
	v_mfma_f32_16x16x32_bf16 v[86:89], v[224:227], v[200:203], v[86:89]
	v_mfma_f32_16x16x32_bf16 v[82:85], v[232:235], v[200:203], v[82:85]
	v_mfma_f32_16x16x32_bf16 v[78:81], v[224:227], v[208:211], v[78:81]
	v_mfma_f32_16x16x32_bf16 v[74:77], v[232:235], v[208:211], v[74:77]
	v_mfma_f32_16x16x32_bf16 v[70:73], v[224:227], v[216:219], v[70:73]
	v_mfma_f32_16x16x32_bf16 v[66:69], v[232:235], v[216:219], v[66:69]
	s_setprio 0
	s_barrier
;   #define LDA(dst,b,h) for(int m=0;m<4;++m)for(int k=0;k<2;++k) \
;     dst[m][k]=*reinterpret_cast<const bf16x8*>((char*)SA(b,h)+lds_byte(wr*64+m*16+fr,k*32+fq*8))
;   #define LDB(dst,b,h) for(int n=0;n<2;++n)for(int k=0;k<2;++k) \
;     dst[n][k]=*reinterpret_cast<const bf16x8*>((char*)SB(b,h)+lds_byte(wc*32+n*16+fr,k*32+fq*8))
;   #define MMA(ai,bj,At,Bt_) do{__builtin_amdgcn_s_setprio(1); \
;     for(int m=0;m<4;++m)for(int n=0;n<2;++n)for(int k=0;k<2;++k) \
;       acc[ai][bj][m][n]=__builtin_amdgcn_mfma_f32_16x16x32_bf16(Bt_[n][k],At[m][k],acc[ai][bj][m][n],0,0,0); \
;     __builtin_amdgcn_s_setprio(0);}while(0)
;   #define WAIT_V(n) asm volatile("s_waitcnt vmcnt(" #n ")":::"memory")
;   #define WAIT_L(n) asm volatile("s_waitcnt lgkmcnt(" #n ")":::"memory")
;   #define BAR __builtin_amdgcn_s_barrier()
;   #define SCHED __builtin_amdgcn_sched_barrier(0)
; template <bool TWO, class MID> ...
;     ...
;     BAR; WAIT_L(0); MMA(1,0,At,B0); BAR; SCHED;
;     STAGE_B(SB(1,1),1,t+3);
;     WAIT_V(6); BAR; MMA(1,1,At,B1); BAR;
;   }
;   { LDB(B0,0,0); LDA(At,0,0); STAGE_A(SA(1,1),1,nt-1);
;     BAR; WAIT_L(0); MMA(0,0,At,B0); BAR;
	ds_read_b128 v[186:189], v168 offset:49152
	ds_read_b128 v[190:193], v168 offset:50176
	ds_read_b128 v[196:199], v167 offset:49152
	ds_read_b128 v[200:203], v167 offset:50176
	ds_read_b128 v[204:207], v166 offset:49152
	ds_read_b128 v[208:211], v166 offset:50176
	ds_read_b128 v[212:215], v147 offset:49152
	ds_read_b128 v[216:219], v147 offset:50176
	s_add_u32 s26, s17, 0x8000180
	s_addc_u32 s27, s18, 0
	v_lshl_add_u64 v[236:237], s[26:27], 0, v[132:133]
	v_readfirstlane_b32 s17, v140
	s_mov_b32 m0, s17
	global_load_lds_dwordx4 v[236:237], off
	v_lshl_add_u64 v[236:237], s[26:27], 0, v[130:131]
	v_readfirstlane_b32 s17, v142
	s_mov_b32 m0, s17
	global_load_lds_dwordx4 v[236:237], off
	s_barrier
	s_waitcnt lgkmcnt(0)
	s_setprio 1
	s_waitcnt lgkmcnt(7)
	v_mfma_f32_16x16x32_bf16 v[62:65], v[170:173], v[186:189], v[62:65]
	v_mfma_f32_16x16x32_bf16 v[58:61], v[178:181], v[186:189], v[58:61]
	s_waitcnt lgkmcnt(5)
	v_mfma_f32_16x16x32_bf16 v[54:57], v[170:173], v[196:199], v[54:57]
	v_mfma_f32_16x16x32_bf16 v[50:53], v[178:181], v[196:199], v[50:53]
	s_waitcnt lgkmcnt(3)
	v_mfma_f32_16x16x32_bf16 v[46:49], v[170:173], v[204:207], v[46:49]
	v_mfma_f32_16x16x32_bf16 v[42:45], v[178:181], v[204:207], v[42:45]
	s_waitcnt lgkmcnt(1)
	v_mfma_f32_16x16x32_bf16 v[38:41], v[170:173], v[212:215], v[38:41]
	v_mfma_f32_16x16x32_bf16 v[34:37], v[178:181], v[212:215], v[34:37]
	v_mfma_f32_16x16x32_bf16 v[62:65], v[174:177], v[190:193], v[62:65]
	v_mfma_f32_16x16x32_bf16 v[58:61], v[182:185], v[190:193], v[58:61]
	v_mfma_f32_16x16x32_bf16 v[54:57], v[174:177], v[200:203], v[54:57]
	v_mfma_f32_16x16x32_bf16 v[50:53], v[182:185], v[200:203], v[50:53]
	v_mfma_f32_16x16x32_bf16 v[46:49], v[174:177], v[208:211], v[46:49]
	v_mfma_f32_16x16x32_bf16 v[42:45], v[182:185], v[208:211], v[42:45]
	s_waitcnt lgkmcnt(0)
	v_mfma_f32_16x16x32_bf16 v[38:41], v[174:177], v[216:219], v[38:41]
	v_mfma_f32_16x16x32_bf16 v[34:37], v[182:185], v[216:219], v[34:37]
	s_setprio 0
	s_barrier
	s_add_u32 s18, s19, 0x80180
	s_addc_u32 s19, s20, 0
	v_lshl_add_u64 v[170:171], s[18:19], 0, v[132:133]
	v_readfirstlane_b32 s17, v144
	s_mov_b32 m0, s17
	global_load_lds_dwordx4 v[170:171], off
	v_lshl_add_u64 v[170:171], s[18:19], 0, v[130:131]
	v_readfirstlane_b32 s17, v146
	s_mov_b32 m0, s17
	global_load_lds_dwordx4 v[170:171], off
	s_waitcnt vmcnt(6)
	s_barrier
	s_setprio 1
	v_mfma_f32_16x16x32_bf16 v[30:33], v[220:223], v[186:189], v[30:33]
	v_mfma_f32_16x16x32_bf16 v[26:29], v[228:231], v[186:189], v[26:29]
	v_mfma_f32_16x16x32_bf16 v[22:25], v[220:223], v[196:199], v[22:25]
	v_mfma_f32_16x16x32_bf16 v[18:21], v[228:231], v[196:199], v[18:21]
	v_mfma_f32_16x16x32_bf16 v[14:17], v[220:223], v[204:207], v[14:17]
	v_mfma_f32_16x16x32_bf16 v[10:13], v[228:231], v[204:207], v[10:13]
	v_mfma_f32_16x16x32_bf16 v[6:9], v[220:223], v[212:215], v[6:9]
	v_mfma_f32_16x16x32_bf16 v[2:5], v[228:231], v[212:215], v[2:5]
	v_mfma_f32_16x16x32_bf16 v[30:33], v[224:227], v[190:193], v[30:33]
	v_mfma_f32_16x16x32_bf16 v[26:29], v[232:235], v[190:193], v[26:29]
	v_mfma_f32_16x16x32_bf16 v[22:25], v[224:227], v[200:203], v[22:25]
	v_mfma_f32_16x16x32_bf16 v[18:21], v[232:235], v[200:203], v[18:21]
	v_mfma_f32_16x16x32_bf16 v[14:17], v[224:227], v[208:211], v[14:17]
	v_mfma_f32_16x16x32_bf16 v[10:13], v[232:235], v[208:211], v[10:13]
	v_mfma_f32_16x16x32_bf16 v[6:9], v[224:227], v[216:219], v[6:9]
	v_mfma_f32_16x16x32_bf16 v[2:5], v[232:235], v[216:219], v[2:5]
	s_setprio 0
	s_add_i32 s9, s9, 2
	s_add_u32 s0, s0, 0x100
	s_addc_u32 s1, s1, 0
	s_cmp_lt_u32 s9, 28
	s_barrier
	s_cbranch_scc1 .LBB0_169
	ds_read_b128 v[150:153], v143
	ds_read_b128 v[158:161], v143 offset:1024
	ds_read_b128 v[162:165], v143 offset:2048
	ds_read_b128 v[142:145], v143 offset:3072
	ds_read_b128 v[170:173], v168
	ds_read_b128 v[174:177], v168 offset:1024
	ds_read_b128 v[178:181], v167
	ds_read_b128 v[182:185], v167 offset:1024
	ds_read_b128 v[186:189], v166
	ds_read_b128 v[190:193], v166 offset:1024
	ds_read_b128 v[196:199], v147
	ds_read_b128 v[200:203], v147 offset:1024
	s_add_u32 s0, s11, 0x80f80
	s_addc_u32 s1, s16, 0
	v_lshl_add_u64 v[132:133], s[0:1], 0, v[132:133]
	v_readfirstlane_b32 s9, v148
	s_mov_b32 m0, s9
	global_load_lds_dwordx4 v[132:133], off
	v_lshl_add_u64 v[130:131], s[0:1], 0, v[130:131]
	v_readfirstlane_b32 s0, v156
	s_mov_b32 m0, s0
	global_load_lds_dwordx4 v[130:131], off
	s_barrier
	s_waitcnt lgkmcnt(0)
	s_setprio 1
	s_waitcnt lgkmcnt(7)
	v_mfma_f32_16x16x32_bf16 v[126:129], v[150:153], v[170:173], v[126:129]
	v_mfma_f32_16x16x32_bf16 v[122:125], v[162:165], v[170:173], v[122:125]
	s_waitcnt lgkmcnt(5)
	v_mfma_f32_16x16x32_bf16 v[114:117], v[162:165], v[178:181], v[114:117]
	s_waitcnt lgkmcnt(3)
	v_mfma_f32_16x16x32_bf16 v[106:109], v[162:165], v[186:189], v[106:109]
	s_waitcnt lgkmcnt(1)
	v_mfma_f32_16x16x32_bf16 v[98:101], v[162:165], v[196:199], v[98:101]
	v_mfma_f32_16x16x32_bf16 v[126:129], v[158:161], v[174:177], v[126:129]
	v_mfma_f32_16x16x32_bf16 v[122:125], v[142:145], v[174:177], v[122:125]
	v_mfma_f32_16x16x32_bf16 v[118:121], v[150:153], v[178:181], v[118:121]
	v_mfma_f32_16x16x32_bf16 v[114:117], v[142:145], v[182:185], v[114:117]
	v_mfma_f32_16x16x32_bf16 v[110:113], v[150:153], v[186:189], v[110:113]
	v_mfma_f32_16x16x32_bf16 v[106:109], v[142:145], v[190:193], v[106:109]
	v_mfma_f32_16x16x32_bf16 v[102:105], v[150:153], v[196:199], v[102:105]
	s_waitcnt lgkmcnt(0)
	v_mfma_f32_16x16x32_bf16 v[130:133], v[142:145], v[200:203], v[98:101]
	v_mfma_f32_16x16x32_bf16 v[118:121], v[158:161], v[182:185], v[118:121]
	v_mfma_f32_16x16x32_bf16 v[110:113], v[158:161], v[190:193], v[110:113]
	v_mfma_f32_16x16x32_bf16 v[102:105], v[158:161], v[200:203], v[102:105]
	s_setprio 0
	s_barrier
;   #define LDA(dst,b,h) for(int m=0;m<4;++m)for(int k=0;k<2;++k) \
;     dst[m][k]=*reinterpret_cast<const bf16x8*>((char*)SA(b,h)+lds_byte(wr*64+m*16+fr,k*32+fq*8))
;   #define LDB(dst,b,h) for(int n=0;n<2;++n)for(int k=0;k<2;++k) \
;     dst[n][k]=*reinterpret_cast<const bf16x8*>((char*)SB(b,h)+lds_byte(wc*32+n*16+fr,k*32+fq*8))
;   #define MMA(ai,bj,At,Bt_) do{__builtin_amdgcn_s_setprio(1); \
;     for(int m=0;m<4;++m)for(int n=0;n<2;++n)for(int k=0;k<2;++k) \
;       acc[ai][bj][m][n]=__builtin_amdgcn_mfma_f32_16x16x32_bf16(Bt_[n][k],At[m][k],acc[ai][bj][m][n],0,0,0); \
;     __builtin_amdgcn_s_setprio(0);}while(0)
;   #define WAIT_V(n) asm volatile("s_waitcnt vmcnt(" #n ")":::"memory")
;   #define WAIT_L(n) asm volatile("s_waitcnt lgkmcnt(" #n ")":::"memory")
;   #define BAR __builtin_amdgcn_s_barrier()
; template <bool TWO, class MID> ...
;     ...
;     LDB(B1,0,1); BAR; WAIT_L(0); MMA(0,1,At,B1); BAR;
;     LDA(At,0,1); WAIT_V(4); BAR; WAIT_L(0); MMA(1,0,At,B0); MMA(1,1,At,B1); BAR; }
;   { LDB(B0,1,0); LDA(At,1,0); WAIT_V(2); BAR; WAIT_L(0); MMA(0,0,At,B0); BAR;
	ds_read_b128 v[98:101], v141
	ds_read_b128 v[154:157], v141 offset:1024
	ds_read_b128 v[204:207], v141 offset:2048
	ds_read_b128 v[138:141], v141 offset:3072
	s_barrier
	s_waitcnt lgkmcnt(0)
	s_setprio 1
	s_waitcnt lgkmcnt(3)
	v_mfma_f32_16x16x32_bf16 v[86:89], v[98:101], v[178:181], v[86:89]
	s_waitcnt lgkmcnt(1)
	v_mfma_f32_16x16x32_bf16 v[82:85], v[204:207], v[178:181], v[82:85]
	v_mfma_f32_16x16x32_bf16 v[70:73], v[98:101], v[196:199], v[70:73]
	v_mfma_f32_16x16x32_bf16 v[66:69], v[204:207], v[196:199], v[66:69]
	v_mfma_f32_16x16x32_bf16 v[94:97], v[98:101], v[170:173], v[94:97]
	v_mfma_f32_16x16x32_bf16 v[90:93], v[204:207], v[170:173], v[90:93]
	v_mfma_f32_16x16x32_bf16 v[86:89], v[154:157], v[182:185], v[86:89]
	s_waitcnt lgkmcnt(0)
	v_mfma_f32_16x16x32_bf16 v[82:85], v[138:141], v[182:185], v[82:85]
	v_mfma_f32_16x16x32_bf16 v[78:81], v[98:101], v[186:189], v[78:81]
	v_mfma_f32_16x16x32_bf16 v[74:77], v[204:207], v[186:189], v[74:77]
	v_mfma_f32_16x16x32_bf16 v[70:73], v[154:157], v[200:203], v[70:73]
	v_mfma_f32_16x16x32_bf16 v[66:69], v[138:141], v[200:203], v[66:69]
	v_mfma_f32_16x16x32_bf16 v[94:97], v[154:157], v[174:177], v[94:97]
	v_mfma_f32_16x16x32_bf16 v[170:173], v[138:141], v[174:177], v[90:93]
	v_mfma_f32_16x16x32_bf16 v[174:177], v[154:157], v[190:193], v[78:81]
	v_mfma_f32_16x16x32_bf16 v[178:181], v[138:141], v[190:193], v[74:77]
	s_setprio 0
	s_barrier
	s_nop 0
	ds_read_b128 v[74:77], v168 offset:16384
	ds_read_b128 v[78:81], v168 offset:17408
	ds_read_b128 v[90:93], v167 offset:16384
	ds_read_b128 v[182:185], v167 offset:17408
	ds_read_b128 v[186:189], v166 offset:16384
	ds_read_b128 v[190:193], v166 offset:17408
	ds_read_b128 v[196:199], v147 offset:16384
	ds_read_b128 v[200:203], v147 offset:17408
	s_waitcnt vmcnt(4)
	s_barrier
	s_waitcnt lgkmcnt(0)
	s_setprio 1
	s_waitcnt lgkmcnt(7)
	v_mfma_f32_16x16x32_bf16 v[62:65], v[150:153], v[74:77], v[62:65]
	v_mfma_f32_16x16x32_bf16 v[58:61], v[162:165], v[74:77], v[58:61]
	s_waitcnt lgkmcnt(5)
	v_mfma_f32_16x16x32_bf16 v[54:57], v[150:153], v[90:93], v[54:57]
	v_mfma_f32_16x16x32_bf16 v[50:53], v[162:165], v[90:93], v[50:53]
	s_waitcnt lgkmcnt(1)
	v_mfma_f32_16x16x32_bf16 v[38:41], v[150:153], v[196:199], v[38:41]
	v_mfma_f32_16x16x32_bf16 v[34:37], v[162:165], v[196:199], v[34:37]
	v_mfma_f32_16x16x32_bf16 v[62:65], v[158:161], v[78:81], v[62:65]
	v_mfma_f32_16x16x32_bf16 v[58:61], v[142:145], v[78:81], v[58:61]
	v_mfma_f32_16x16x32_bf16 v[54:57], v[158:161], v[182:185], v[54:57]
	v_mfma_f32_16x16x32_bf16 v[50:53], v[142:145], v[182:185], v[50:53]
	v_mfma_f32_16x16x32_bf16 v[46:49], v[150:153], v[186:189], v[46:49]
	v_mfma_f32_16x16x32_bf16 v[42:45], v[162:165], v[186:189], v[42:45]
	s_waitcnt lgkmcnt(0)
	v_mfma_f32_16x16x32_bf16 v[38:41], v[158:161], v[200:203], v[38:41]
	v_mfma_f32_16x16x32_bf16 v[34:37], v[142:145], v[200:203], v[34:37]
	v_mfma_f32_16x16x32_bf16 v[208:211], v[158:161], v[190:193], v[46:49]
	v_mfma_f32_16x16x32_bf16 v[212:215], v[142:145], v[190:193], v[42:45]
	s_setprio 0
	s_setprio 1
	v_mfma_f32_16x16x32_bf16 v[22:25], v[98:101], v[90:93], v[22:25]
	v_mfma_f32_16x16x32_bf16 v[18:21], v[204:207], v[90:93], v[18:21]
	v_mfma_f32_16x16x32_bf16 v[6:9], v[98:101], v[196:199], v[6:9]
	v_mfma_f32_16x16x32_bf16 v[2:5], v[204:207], v[196:199], v[2:5]
	v_mfma_f32_16x16x32_bf16 v[30:33], v[98:101], v[74:77], v[30:33]
	v_mfma_f32_16x16x32_bf16 v[26:29], v[204:207], v[74:77], v[26:29]
	v_mfma_f32_16x16x32_bf16 v[22:25], v[154:157], v[182:185], v[22:25]
	v_mfma_f32_16x16x32_bf16 v[18:21], v[138:141], v[182:185], v[18:21]
	v_mfma_f32_16x16x32_bf16 v[14:17], v[98:101], v[186:189], v[14:17]
	v_mfma_f32_16x16x32_bf16 v[10:13], v[204:207], v[186:189], v[10:13]
	v_mfma_f32_16x16x32_bf16 v[6:9], v[154:157], v[200:203], v[6:9]
	v_mfma_f32_16x16x32_bf16 v[2:5], v[138:141], v[200:203], v[2:5]
	v_mfma_f32_16x16x32_bf16 v[148:151], v[154:157], v[78:81], v[30:33]
	v_mfma_f32_16x16x32_bf16 v[158:161], v[138:141], v[78:81], v[26:29]
	v_mfma_f32_16x16x32_bf16 v[162:165], v[154:157], v[190:193], v[14:17]
	v_mfma_f32_16x16x32_bf16 v[182:185], v[138:141], v[190:193], v[10:13]
	s_setprio 0
	s_barrier
	s_nop 0
	ds_read_b128 v[10:13], v137
	ds_read_b128 v[14:17], v137 offset:1024
	ds_read_b128 v[152:155], v137 offset:2048
	ds_read_b128 v[186:189], v137 offset:3072
	ds_read_b128 v[26:29], v168 offset:32768
	ds_read_b128 v[30:33], v168 offset:33792
	ds_read_b128 v[42:45], v167 offset:32768
	ds_read_b128 v[46:49], v167 offset:33792
	ds_read_b128 v[190:193], v166 offset:32768
	ds_read_b128 v[196:199], v166 offset:33792
	ds_read_b128 v[200:203], v147 offset:32768
	ds_read_b128 v[204:207], v147 offset:33792
	s_waitcnt vmcnt(2)
	s_barrier
;   #define LDA(dst,b,h) for(int m=0;m<4;++m)for(int k=0;k<2;++k) \
;     dst[m][k]=*reinterpret_cast<const bf16x8*>((char*)SA(b,h)+lds_byte(wr*64+m*16+fr,k*32+fq*8))
;   #define LDB(dst,b,h) for(int n=0;n<2;++n)for(int k=0;k<2;++k) \
;     dst[n][k]=*reinterpret_cast<const bf16x8*>((char*)SB(b,h)+lds_byte(wc*32+n*16+fr,k*32+fq*8))
;   #define MMA(ai,bj,At,Bt_) do{__builtin_amdgcn_s_setprio(1); \
;     for(int m=0;m<4;++m)for(int n=0;n<2;++n)for(int k=0;k<2;++k) \
;       acc[ai][bj][m][n]=__builtin_amdgcn_mfma_f32_16x16x32_bf16(Bt_[n][k],At[m][k],acc[ai][bj][m][n],0,0,0); \
;     __builtin_amdgcn_s_setprio(0);}while(0)
;   #define WAIT_V(n) asm volatile("s_waitcnt vmcnt(" #n ")":::"memory")
;   #define WAIT_L(n) asm volatile("s_waitcnt lgkmcnt(" #n ")":::"memory")
;   #define BAR __builtin_amdgcn_s_barrier()
; template <bool TWO, class MID> ...
;     ...
;   { LDB(B0,1,0); LDA(At,1,0); WAIT_V(2); BAR; WAIT_L(0); MMA(0,0,At,B0); BAR;
;     LDB(B1,1,1); WAIT_V(0); BAR; WAIT_L(0); MMA(0,1,At,B1); BAR;
;     LDA(At,1,1); BAR; WAIT_L(0); MMA(1,0,At,B0); MMA(1,1,At,B1); BAR; }
;   if(wr==0)BAR;
	s_waitcnt lgkmcnt(0)
	s_setprio 1
	s_waitcnt lgkmcnt(7)
	v_mfma_f32_16x16x32_bf16 v[74:77], v[10:13], v[26:29], v[126:129]
	s_waitcnt lgkmcnt(6)
	v_mfma_f32_16x16x32_bf16 v[142:145], v[14:17], v[30:33], v[74:77]
	v_mfma_f32_16x16x32_bf16 v[74:77], v[152:155], v[26:29], v[122:125]
	v_mfma_f32_16x16x32_bf16 v[138:141], v[186:189], v[30:33], v[74:77]
	s_waitcnt lgkmcnt(5)
	v_mfma_f32_16x16x32_bf16 v[74:77], v[10:13], v[42:45], v[118:121]
	s_waitcnt lgkmcnt(4)
	v_mfma_f32_16x16x32_bf16 v[126:129], v[14:17], v[46:49], v[74:77]
	v_mfma_f32_16x16x32_bf16 v[74:77], v[152:155], v[42:45], v[114:117]
	v_mfma_f32_16x16x32_bf16 v[122:125], v[186:189], v[46:49], v[74:77]
	s_waitcnt lgkmcnt(3)
	v_mfma_f32_16x16x32_bf16 v[74:77], v[10:13], v[190:193], v[110:113]
	s_waitcnt lgkmcnt(2)
	v_mfma_f32_16x16x32_bf16 v[98:101], v[14:17], v[196:199], v[74:77]
	v_mfma_f32_16x16x32_bf16 v[74:77], v[152:155], v[190:193], v[106:109]
	v_mfma_f32_16x16x32_bf16 v[90:93], v[186:189], v[196:199], v[74:77]
	s_waitcnt lgkmcnt(1)
	v_mfma_f32_16x16x32_bf16 v[74:77], v[10:13], v[200:203], v[102:105]
	s_waitcnt lgkmcnt(0)
	v_mfma_f32_16x16x32_bf16 v[78:81], v[14:17], v[204:207], v[74:77]
	v_mfma_f32_16x16x32_bf16 v[74:77], v[152:155], v[200:203], v[130:133]
	v_mfma_f32_16x16x32_bf16 v[74:77], v[186:189], v[204:207], v[74:77]
	s_setprio 0
	s_barrier
	ds_read_b128 v[102:105], v135
	ds_read_b128 v[110:113], v135 offset:1024
	ds_read_b128 v[118:121], v135 offset:2048
	ds_read_b128 v[216:219], v135 offset:3072
	s_waitcnt vmcnt(0)
	s_barrier
	s_waitcnt lgkmcnt(0)
	s_setprio 1
	s_waitcnt lgkmcnt(3)
	v_mfma_f32_16x16x32_bf16 v[94:97], v[102:105], v[26:29], v[94:97]
	s_waitcnt lgkmcnt(1)
	v_mfma_f32_16x16x32_bf16 v[26:29], v[118:121], v[26:29], v[170:173]
	s_waitcnt lgkmcnt(0)
	v_mfma_f32_16x16x32_bf16 v[130:133], v[216:219], v[30:33], v[26:29]
	v_mfma_f32_16x16x32_bf16 v[26:29], v[102:105], v[42:45], v[86:89]
	v_mfma_f32_16x16x32_bf16 v[114:117], v[110:113], v[46:49], v[26:29]
	v_mfma_f32_16x16x32_bf16 v[26:29], v[118:121], v[42:45], v[82:85]
	v_mfma_f32_16x16x32_bf16 v[106:109], v[216:219], v[46:49], v[26:29]
	v_mfma_f32_16x16x32_bf16 v[26:29], v[102:105], v[190:193], v[174:177]
	v_mfma_f32_16x16x32_bf16 v[86:89], v[110:113], v[196:199], v[26:29]
	v_mfma_f32_16x16x32_bf16 v[26:29], v[118:121], v[190:193], v[178:181]
	v_mfma_f32_16x16x32_bf16 v[82:85], v[216:219], v[196:199], v[26:29]
	v_mfma_f32_16x16x32_bf16 v[26:29], v[102:105], v[200:203], v[70:73]
	v_mfma_f32_16x16x32_bf16 v[70:73], v[110:113], v[204:207], v[26:29]
	v_mfma_f32_16x16x32_bf16 v[26:29], v[118:121], v[200:203], v[66:69]
	v_mfma_f32_16x16x32_bf16 v[134:137], v[110:113], v[30:33], v[94:97]
	v_mfma_f32_16x16x32_bf16 v[66:69], v[216:219], v[204:207], v[26:29]
	s_setprio 0
	s_barrier
	ds_read_b128 v[94:97], v168 offset:49152
	ds_read_b128 v[168:171], v168 offset:50176
	ds_read_b128 v[172:175], v167 offset:49152
	ds_read_b128 v[176:179], v167 offset:50176
	ds_read_b128 v[190:193], v166 offset:49152
	ds_read_b128 v[196:199], v166 offset:50176
	ds_read_b128 v[200:203], v147 offset:49152
	ds_read_b128 v[204:207], v147 offset:50176
	s_barrier
	s_waitcnt lgkmcnt(0)
	s_setprio 1
	s_waitcnt lgkmcnt(7)
	v_mfma_f32_16x16x32_bf16 v[26:29], v[10:13], v[94:97], v[62:65]
	s_waitcnt lgkmcnt(6)
	v_mfma_f32_16x16x32_bf16 v[62:65], v[14:17], v[168:171], v[26:29]
	v_mfma_f32_16x16x32_bf16 v[26:29], v[152:155], v[94:97], v[58:61]
	v_mfma_f32_16x16x32_bf16 v[58:61], v[186:189], v[168:171], v[26:29]
	s_waitcnt lgkmcnt(5)
	v_mfma_f32_16x16x32_bf16 v[26:29], v[10:13], v[172:175], v[54:57]
	s_waitcnt lgkmcnt(4)
	v_mfma_f32_16x16x32_bf16 v[46:49], v[14:17], v[176:179], v[26:29]
	v_mfma_f32_16x16x32_bf16 v[26:29], v[152:155], v[172:175], v[50:53]
	v_mfma_f32_16x16x32_bf16 v[42:45], v[186:189], v[176:179], v[26:29]
	s_waitcnt lgkmcnt(3)
	v_mfma_f32_16x16x32_bf16 v[26:29], v[10:13], v[190:193], v[208:211]
	s_waitcnt lgkmcnt(1)
	v_mfma_f32_16x16x32_bf16 v[10:13], v[10:13], v[200:203], v[38:41]
	v_mfma_f32_16x16x32_bf16 v[30:33], v[14:17], v[196:199], v[26:29]
	v_mfma_f32_16x16x32_bf16 v[26:29], v[152:155], v[190:193], v[212:215]
	s_waitcnt lgkmcnt(0)
	v_mfma_f32_16x16x32_bf16 v[14:17], v[14:17], v[204:207], v[10:13]
	v_mfma_f32_16x16x32_bf16 v[10:13], v[152:155], v[200:203], v[34:37]
	v_mfma_f32_16x16x32_bf16 v[26:29], v[186:189], v[196:199], v[26:29]
	v_mfma_f32_16x16x32_bf16 v[10:13], v[186:189], v[204:207], v[10:13]
	s_setprio 0
	s_setprio 1
	v_mfma_f32_16x16x32_bf16 v[34:37], v[102:105], v[94:97], v[148:151]
	v_mfma_f32_16x16x32_bf16 v[54:57], v[110:113], v[168:171], v[34:37]
	v_mfma_f32_16x16x32_bf16 v[34:37], v[118:121], v[94:97], v[158:161]
	v_mfma_f32_16x16x32_bf16 v[18:21], v[118:121], v[172:175], v[18:21]
	v_mfma_f32_16x16x32_bf16 v[50:53], v[216:219], v[168:171], v[34:37]
	v_mfma_f32_16x16x32_bf16 v[22:25], v[102:105], v[172:175], v[22:25]
	v_mfma_f32_16x16x32_bf16 v[34:37], v[216:219], v[176:179], v[18:21]
	v_mfma_f32_16x16x32_bf16 v[18:21], v[102:105], v[190:193], v[162:165]
	v_mfma_f32_16x16x32_bf16 v[38:41], v[110:113], v[176:179], v[22:25]
	v_mfma_f32_16x16x32_bf16 v[22:25], v[110:113], v[196:199], v[18:21]
	v_mfma_f32_16x16x32_bf16 v[18:21], v[118:121], v[190:193], v[182:185]
	v_mfma_f32_16x16x32_bf16 v[6:9], v[102:105], v[200:203], v[6:9]
	v_mfma_f32_16x16x32_bf16 v[2:5], v[118:121], v[200:203], v[2:5]
	v_mfma_f32_16x16x32_bf16 v[18:21], v[216:219], v[196:199], v[18:21]
	v_mfma_f32_16x16x32_bf16 v[6:9], v[110:113], v[204:207], v[6:9]
	v_mfma_f32_16x16x32_bf16 v[2:5], v[216:219], v[204:207], v[2:5]
	s_setprio 0
	v_cmp_gt_u32_e32 vcc, s30, v1
	s_barrier
	s_and_saveexec_b64 s[0:1], vcc
	s_cbranch_execz .LBB0_172
	s_barrier

; #define LDS_BARRIER() do { asm volatile("s_waitcnt lgkmcnt(0)" ::: "memory"); __builtin_amdgcn_s_barrier(); asm volatile("" ::: "memory"); } while (0)
; __device__ __forceinline__ void st16_asm(void* ptr, u32x4 v) { asm volatile("global_store_dwordx4 %0, %1, off\n\ts_nop 7" :: "v"(ptr), "v"(v) : "memory"); }
; __device__ __forceinline__ char* stg_ptr(bf16* shm, int bj, int row, int chunk8) {
;   return (char*)shm + (bj ? 98304 : 32768) + row * 256 + ((chunk8 ^ ((row & 15) << 1)) << 3);
; }
; __device__ __forceinline__ void stg_flush(bf16* shm, int tid, bf16* dst, size_t pitch, bool first, bool tail_barrier = true) {
;   LDS_BARRIER();
;   if (first) asm volatile("s_waitcnt vmcnt(0)" ::: "memory");
;   _Pragma("unroll") for (int i = 0; i < 8; ++i) {
;     const int idx = tid + 512 * i, bjr = idx >> 11, row = (idx >> 4) & 127, c16 = idx & 15;
;     const u32x4 d = *(const u32x4*)stg_ptr(shm, bjr, row, 2 * c16);
;     st16_asm(dst + (size_t)row * pitch + bjr * HALF + c16 * 8, d); }
; template <int EPI>
; __device__ void gemm_phase(const bf16* A, int lda, const bf16* Bt, int K, int N, const Params& p, bool last, bf16* dstb, bf16* shm, unsigned long long* SSQ, int wv, const float* gbias = nullptr) {
;     ...
;       if (!gate_tile) {
;         _Pragma("unroll") for (int ai = 0; ai < 2; ++ai) {
;           _Pragma("unroll") for (int m = 0; m < 4; ++m) {
;             const int rl = wr * 64 + m * 16 + fr; const float rs = rsv[ai][m];
;             _Pragma("unroll") for (int bj = 0; bj < 2; ++bj) _Pragma("unroll") for (int n = 0; n < 2; ++n) {
;               f32x4 v = acc[ai][bj][m][n] * rs; u32x2 o = {pk2(v[0], v[1]), pk2(v[2], v[3])};
;               *(u32x2*)stg_ptr(shm, bj, rl, wc * 8 + n * 4 + fq) = o; }
;           }
;           stg_flush(shm, tid, dst + (size_t)(brow + ai * HALF) * pitch + c0, pitch, ai == 0, ai == 0);
.LBB0_187:
	v_lshrrev_b32_e32 v157, 4, v1
	v_cmp_gt_u32_e32 vcc, s85, v1
	v_xor_b32_e32 v157, v157, v1
	v_bfe_u32 v159, v1, 4, 7
	v_cndmask_b32_e32 v161, v244, v245, vcc
	v_lshlrev_b32_e32 v157, 4, v157
	v_add_u32_e32 v161, 0, v161
	v_lshlrev_b32_e32 v162, 8, v159
	v_and_b32_e32 v157, 0xf0, v157
	v_add3_u32 v157, v161, v162, v157
	v_mul_u32_u24_e32 v186, s12, v159
	v_ashrrev_i32_e32 v159, 4, v1
	v_add_u32_e32 v161, 0x200, v1
	v_and_b32_e32 v162, 0xffffff80, v159
	v_lshrrev_b32_e32 v159, 4, v161
	v_cmp_gt_u32_e32 vcc, s85, v161
	v_xor_b32_e32 v159, v159, v1
	v_bfe_u32 v164, v161, 4, 7
	v_cndmask_b32_e32 v165, v244, v245, vcc
	v_lshlrev_b32_e32 v159, 4, v159
	v_add_u32_e32 v165, 0, v165
	v_lshlrev_b32_e32 v166, 8, v164
	v_and_b32_e32 v159, 0xf0, v159
	v_add3_u32 v159, v165, v166, v159
	v_ashrrev_i32_e32 v161, 4, v161
	v_add_u32_e32 v166, 0x400, v1
	v_mul_u32_u24_e32 v190, s12, v164
	v_and_b32_e32 v164, 0xffffff80, v161
	v_lshrrev_b32_e32 v161, 4, v166
	v_cmp_gt_u32_e32 vcc, s85, v166
	v_xor_b32_e32 v161, v161, v1
	v_bfe_u32 v167, v166, 4, 7
	v_cndmask_b32_e32 v168, v244, v245, vcc
	v_lshlrev_b32_e32 v161, 4, v161
	v_add_u32_e32 v168, 0, v168
	v_lshlrev_b32_e32 v169, 8, v167
	v_and_b32_e32 v161, 0xf0, v161
	v_add3_u32 v161, v168, v169, v161
	v_add_u32_e32 v168, 0x600, v1
	v_lshrrev_b32_e32 v169, 4, v168
	v_cmp_gt_u32_e32 vcc, s85, v168
	v_xor_b32_e32 v169, v169, v1
	v_bfe_u32 v170, v168, 4, 7
	v_cndmask_b32_e32 v171, v244, v245, vcc
	v_lshlrev_b32_e32 v169, 4, v169
	v_add_u32_e32 v171, 0, v171
	v_lshlrev_b32_e32 v172, 8, v170
	v_and_b32_e32 v169, 0xf0, v169
	v_mul_u32_u24_e32 v198, s12, v170
	v_add_u32_e32 v170, 0x800, v1
	v_add3_u32 v178, v171, v172, v169
	v_lshrrev_b32_e32 v171, 4, v170
	v_cmp_lt_u32_e32 vcc, s35, v1
	v_xor_b32_e32 v171, v171, v1
	v_bfe_u32 v172, v170, 4, 7
	v_cndmask_b32_e32 v173, v244, v245, vcc
	v_lshlrev_b32_e32 v171, 4, v171
	v_add_u32_e32 v173, 0, v173
	v_lshlrev_b32_e32 v174, 8, v172
	v_and_b32_e32 v171, 0xf0, v171
	v_mul_u32_u24_e32 v199, s12, v172
	v_add_u32_e32 v172, 0xa00, v1
	v_add3_u32 v206, v173, v174, v171
	v_lshrrev_b32_e32 v173, 4, v172
	v_cmp_gt_u32_e32 vcc, s85, v172
	v_xor_b32_e32 v173, v173, v1
	v_bfe_u32 v174, v172, 4, 7
	v_cndmask_b32_e32 v175, v244, v245, vcc
	v_lshlrev_b32_e32 v173, 4, v173
	v_add_u32_e32 v175, 0, v175
	v_lshlrev_b32_e32 v176, 8, v174
	v_and_b32_e32 v173, 0xf0, v173
	v_mul_u32_u24_e32 v200, s12, v174
	v_add_u32_e32 v174, 0xc00, v1
	v_add3_u32 v207, v175, v176, v173
	v_lshrrev_b32_e32 v175, 4, v174
	v_cmp_gt_u32_e32 vcc, s85, v174
	v_xor_b32_e32 v175, v175, v1
	v_bfe_u32 v176, v174, 4, 7
	v_cndmask_b32_e32 v177, v244, v245, vcc
	v_lshlrev_b32_e32 v175, 4, v175
	v_add_u32_e32 v177, 0, v177
	v_lshlrev_b32_e32 v180, 8, v176
	v_and_b32_e32 v175, 0xf0, v175
	v_mul_u32_u24_e32 v202, s12, v176
	v_add_u32_e32 v176, 0xe00, v1
	v_add3_u32 v208, v177, v180, v175
	v_lshrrev_b32_e32 v177, 4, v176
	v_cmp_gt_u32_e32 vcc, s85, v176
	v_xor_b32_e32 v177, v177, v1
	v_bfe_u32 v180, v176, 4, 7
	v_cndmask_b32_e32 v181, v244, v245, vcc
	v_lshlrev_b32_e32 v177, 4, v177
	v_lshlrev_b32_e32 v179, 4, v153
	v_add_u32_e32 v181, 0, v181
	v_lshlrev_b32_e32 v182, 8, v180
	v_and_b32_e32 v177, 0xf0, v177
	v_lshlrev_b32_e32 v151, 14, v151
	v_lshlrev_b32_e32 v153, 8, v153
	v_lshlrev_b32_e32 v147, 6, v147
	v_lshlrev_b32_e32 v149, 3, v149
	v_add3_u32 v209, v181, v182, v177
	v_mul_u32_u24_e32 v204, s12, v180
	v_add3_u32 v151, 0, v151, v153
	v_pk_mul_f32 v[180:181], v[144:145], v[160:161] op_sel_hi:[1,0]
	v_pk_mul_f32 v[182:183], v[142:143], v[160:161] op_sel_hi:[1,0]
	v_or_b32_e32 v153, v147, v149
	v_bitop3_b32 v147, v147, v179, v149 bitop3:0x36
	v_cvt_pk_bf16_f32 v182, v182, v183
	v_cvt_pk_bf16_f32 v183, v180, v181
	v_add_u32_e32 v149, v151, v147
	ds_write_b64 v149, v[182:183] offset:32768
	v_pk_mul_f32 v[180:181], v[140:141], v[160:161] op_sel_hi:[1,0]
	v_pk_mul_f32 v[182:183], v[138:139], v[160:161] op_sel_hi:[1,0]
	v_add_u32_e32 v187, 0x18000, v151
	v_cvt_pk_bf16_f32 v182, v182, v183
	v_cvt_pk_bf16_f32 v183, v180, v181
	v_pk_mul_f32 v[180:181], v[136:137], v[160:161] op_sel_hi:[1,0]
	v_pk_mul_f32 v[184:185], v[134:135], v[160:161] op_sel_hi:[1,0]
	v_add_u32_e32 v210, v187, v147
	v_cvt_pk_bf16_f32 v184, v184, v185
	v_cvt_pk_bf16_f32 v185, v180, v181
	v_bitop3_b32 v153, v153, v179, 32 bitop3:0x36
	ds_write_b64 v210, v[184:185]
	v_pk_mul_f32 v[180:181], v[132:133], v[160:161] op_sel_hi:[1,0]
	v_pk_mul_f32 v[184:185], v[130:131], v[160:161] op_sel_hi:[1,0]
	v_add_u32_e32 v211, v187, v153
	v_cvt_pk_bf16_f32 v184, v184, v185
	v_cvt_pk_bf16_f32 v185, v180, v181
	ds_write_b64 v211, v[184:185]
	v_pk_mul_f32 v[180:181], v[128:129], v[158:159] op_sel_hi:[1,0]
	v_pk_mul_f32 v[184:185], v[126:127], v[158:159] op_sel_hi:[1,0]
	v_add_u32_e32 v179, v151, v153
	v_cvt_pk_bf16_f32 v184, v184, v185
	v_cvt_pk_bf16_f32 v185, v180, v181
	ds_write_b64 v149, v[184:185] offset:36864
	v_pk_mul_f32 v[180:181], v[124:125], v[158:159] op_sel_hi:[1,0]
	v_pk_mul_f32 v[184:185], v[122:123], v[158:159] op_sel_hi:[1,0]
	v_add_u32_e32 v187, 0x1a000, v151
	v_cvt_pk_bf16_f32 v184, v184, v185
	v_cvt_pk_bf16_f32 v185, v180, v181
	ds_write2st64_b64 v179, v[182:183], v[184:185] offset0:64 offset1:72
	v_add_u32_e32 v184, 0x19000, v151
	v_pk_mul_f32 v[180:181], v[116:117], v[158:159] op_sel_hi:[1,0]
	v_pk_mul_f32 v[182:183], v[114:115], v[158:159] op_sel_hi:[1,0]
	v_add_u32_e32 v212, v184, v147
	v_cvt_pk_bf16_f32 v182, v182, v183
	v_cvt_pk_bf16_f32 v183, v180, v181
	ds_write_b64 v212, v[182:183]
	v_pk_mul_f32 v[180:181], v[108:109], v[158:159] op_sel_hi:[1,0]
	v_pk_mul_f32 v[182:183], v[106:107], v[158:159] op_sel_hi:[1,0]
	v_add_u32_e32 v213, v184, v153
; #define LDS_BARRIER() do { asm volatile("s_waitcnt lgkmcnt(0)" ::: "memory"); __builtin_amdgcn_s_barrier(); asm volatile("" ::: "memory"); } while (0)
; __device__ __forceinline__ void st16_asm(void* ptr, u32x4 v) { asm volatile("global_store_dwordx4 %0, %1, off\n\ts_nop 7" :: "v"(ptr), "v"(v) : "memory"); }
; __device__ __forceinline__ void stg_flush(bf16* shm, int tid, bf16* dst, size_t pitch, bool first, bool tail_barrier = true) {
;   LDS_BARRIER();
;   if (first) asm volatile("s_waitcnt vmcnt(0)" ::: "memory");
;   _Pragma("unroll") for (int i = 0; i < 8; ++i) {
;     const int idx = tid + 512 * i, bjr = idx >> 11, row = (idx >> 4) & 127, c16 = idx & 15;
;     const u32x4 d = *(const u32x4*)stg_ptr(shm, bjr, row, 2 * c16);
;     st16_asm(dst + (size_t)row * pitch + bjr * HALF + c16 * 8, d); }
;   if (tail_barrier) LDS_BARRIER();
; template <int EPI>
; __device__ void gemm_phase(const bf16* A, int lda, const bf16* Bt, int K, int N, const Params& p, bool last, bf16* dstb, bf16* shm, unsigned long long* SSQ, int wv, const float* gbias = nullptr) {
;     ...
;         _Pragma("unroll") for (int ai = 0; ai < 2; ++ai) {
;           _Pragma("unroll") for (int m = 0; m < 4; ++m) {
;             const int rl = wr * 64 + m * 16 + fr; const float rs = rsv[ai][m];
;             _Pragma("unroll") for (int bj = 0; bj < 2; ++bj) _Pragma("unroll") for (int n = 0; n < 2; ++n) {
;               f32x4 v = acc[ai][bj][m][n] * rs; u32x2 o = {pk2(v[0], v[1]), pk2(v[2], v[3])};
;               *(u32x2*)stg_ptr(shm, bj, rl, wc * 8 + n * 4 + fq) = o; }
;           }
;           stg_flush(shm, tid, dst + (size_t)(brow + ai * HALF) * pitch + c0, pitch, ai == 0, ai == 0);
	v_cvt_pk_bf16_f32 v182, v182, v183
	v_cvt_pk_bf16_f32 v183, v180, v181
	ds_write_b64 v213, v[182:183]
	v_pk_mul_f32 v[180:181], v[100:101], v[156:157] op_sel_hi:[1,0]
	v_pk_mul_f32 v[182:183], v[98:99], v[156:157] op_sel_hi:[1,0]
	v_pk_mul_f32 v[184:185], v[86:87], v[156:157] op_sel_hi:[1,0]
	v_cvt_pk_bf16_f32 v182, v182, v183
	v_cvt_pk_bf16_f32 v183, v180, v181
	ds_write_b64 v149, v[182:183] offset:40960
	v_pk_mul_f32 v[180:181], v[92:93], v[156:157] op_sel_hi:[1,0]
	v_pk_mul_f32 v[182:183], v[90:91], v[156:157] op_sel_hi:[1,0]
	v_cvt_pk_bf16_f32 v184, v184, v185
	v_cvt_pk_bf16_f32 v182, v182, v183
	v_cvt_pk_bf16_f32 v183, v180, v181
	v_pk_mul_f32 v[180:181], v[88:89], v[156:157] op_sel_hi:[1,0]
	v_add_u32_e32 v214, v187, v147
	v_cvt_pk_bf16_f32 v185, v180, v181
	ds_write_b64 v214, v[184:185]
	v_pk_mul_f32 v[180:181], v[84:85], v[156:157] op_sel_hi:[1,0]
	v_pk_mul_f32 v[184:185], v[82:83], v[156:157] op_sel_hi:[1,0]
	v_add_u32_e32 v215, v187, v153
	v_cvt_pk_bf16_f32 v184, v184, v185
	v_cvt_pk_bf16_f32 v185, v180, v181
	ds_write_b64 v215, v[184:185]
	v_pk_mul_f32 v[180:181], v[80:81], v[154:155] op_sel_hi:[1,0]
	v_pk_mul_f32 v[184:185], v[78:79], v[154:155] op_sel_hi:[1,0]
	s_ashr_i32 s9, s8, 31
	v_cvt_pk_bf16_f32 v184, v184, v185
	v_cvt_pk_bf16_f32 v185, v180, v181
	s_lshl_b64 s[16:17], s[8:9], 1
	ds_write_b64 v149, v[184:185] offset:45056
	v_pk_mul_f32 v[180:181], v[76:77], v[154:155] op_sel_hi:[1,0]
	v_pk_mul_f32 v[184:185], v[74:75], v[154:155] op_sel_hi:[1,0]
	s_add_u32 s9, s14, s16
	v_cvt_pk_bf16_f32 v184, v184, v185
	v_cvt_pk_bf16_f32 v185, v180, v181
	s_addc_u32 s7, s15, s17
	ds_write2st64_b64 v179, v[182:183], v[184:185] offset0:80 offset1:88
	v_add_u32_e32 v151, 0x1b000, v151
	v_pk_mul_f32 v[180:181], v[72:73], v[154:155] op_sel_hi:[1,0]
	v_pk_mul_f32 v[182:183], v[70:71], v[154:155] op_sel_hi:[1,0]
	s_mul_hi_i32 s15, s12, s10
	s_mul_i32 s14, s12, s10
	v_cvt_pk_bf16_f32 v182, v182, v183
	v_cvt_pk_bf16_f32 v183, v180, v181
	v_add_u32_e32 v147, v151, v147
	s_lshl_b64 s[14:15], s[14:15], 1
	ds_write_b64 v147, v[182:183]
	v_pk_mul_f32 v[180:181], v[68:69], v[154:155] op_sel_hi:[1,0]
	v_pk_mul_f32 v[182:183], v[66:67], v[154:155] op_sel_hi:[1,0]
	s_add_u32 s14, s9, s14
	v_ashrrev_i32_e32 v163, 31, v162
	v_cvt_pk_bf16_f32 v182, v182, v183
	v_cvt_pk_bf16_f32 v183, v180, v181
	v_add_u32_e32 v151, v151, v153
	s_addc_u32 s15, s7, s15
	v_lshlrev_b32_e32 v184, 1, v186
	v_mov_b32_e32 v185, v0
	ds_write_b64 v151, v[182:183]
	v_lshl_add_u64 v[186:187], s[14:15], 0, v[184:185]
	v_lshlrev_b64 v[188:189], 1, v[162:163]
	s_waitcnt lgkmcnt(0)
	s_barrier
	v_lshl_add_u64 v[186:187], v[186:187], 0, v[188:189]
	v_and_b32_e32 v162, 0xf0, v155
	v_mov_b32_e32 v163, v0
	s_waitcnt vmcnt(0)
	v_lshl_add_u64 v[186:187], v[186:187], 0, v[162:163]
	v_ashrrev_i32_e32 v165, 31, v164
	ds_read_b128 v[180:183], v157
	s_waitcnt lgkmcnt(0)
	global_store_dwordx4 v[186:187], v[180:183], off sc1
	s_nop 7
	v_lshlrev_b32_e32 v186, 1, v190
	v_mov_b32_e32 v187, v0
	v_ashrrev_i32_e32 v166, 4, v166
	v_lshl_add_u64 v[190:191], s[14:15], 0, v[186:187]
	v_lshlrev_b64 v[192:193], 1, v[164:165]
	v_mul_u32_u24_e32 v196, s12, v167
	v_and_b32_e32 v166, 0xffffff80, v166
	v_lshl_add_u64 v[164:165], v[190:191], 0, v[192:193]
	v_ashrrev_i32_e32 v167, 31, v166
	v_lshl_add_u64 v[164:165], v[164:165], 0, v[162:163]
	v_lshlrev_b32_e32 v190, 1, v196
	v_mov_b32_e32 v191, v0
	v_ashrrev_i32_e32 v168, 4, v168
	ds_read_b128 v[180:183], v159
	s_waitcnt lgkmcnt(0)
	global_store_dwordx4 v[164:165], v[180:183], off sc1
	s_nop 7
	v_lshl_add_u64 v[164:165], s[14:15], 0, v[190:191]
	v_lshlrev_b64 v[196:197], 1, v[166:167]
	v_and_b32_e32 v168, 0xffffff80, v168
	ds_read_b128 v[180:183], v161
	v_lshl_add_u64 v[164:165], v[164:165], 0, v[196:197]
	v_ashrrev_i32_e32 v169, 31, v168
	v_lshl_add_u64 v[164:165], v[164:165], 0, v[162:163]
	s_waitcnt lgkmcnt(0)
	global_store_dwordx4 v[164:165], v[180:183], off sc1
	s_nop 7
	v_lshlrev_b32_e32 v180, 1, v198
	v_mov_b32_e32 v181, v0
	v_lshl_add_u64 v[182:183], s[14:15], 0, v[180:181]
	v_lshlrev_b64 v[168:169], 1, v[168:169]
	v_ashrrev_i32_e32 v170, 4, v170
	v_lshl_add_u64 v[182:183], v[182:183], 0, v[168:169]
	v_and_b32_e32 v170, 0xffffff80, v170
	v_lshl_add_u64 v[182:183], v[182:183], 0, v[162:163]
	v_ashrrev_i32_e32 v171, 31, v170
	ds_read_b128 v[164:167], v178
	s_waitcnt lgkmcnt(0)
	global_store_dwordx4 v[182:183], v[164:167], off sc1
	s_nop 7
	v_lshlrev_b32_e32 v182, 1, v199
	v_mov_b32_e32 v183, v0
	v_lshl_add_u64 v[198:199], s[14:15], 0, v[182:183]
	v_lshlrev_b64 v[170:171], 1, v[170:171]
	v_ashrrev_i32_e32 v172, 4, v172
	v_lshl_add_u64 v[198:199], v[198:199], 0, v[170:171]
	v_and_b32_e32 v172, 0xffffff80, v172
	v_lshl_add_u64 v[198:199], v[198:199], 0, v[162:163]
	v_ashrrev_i32_e32 v173, 31, v172
	ds_read_b128 v[164:167], v206
	s_waitcnt lgkmcnt(0)
	global_store_dwordx4 v[198:199], v[164:167], off sc1
	s_nop 7
	v_lshlrev_b32_e32 v198, 1, v200
	v_mov_b32_e32 v199, v0
	v_lshl_add_u64 v[200:201], s[14:15], 0, v[198:199]
	v_lshlrev_b64 v[172:173], 1, v[172:173]
	v_ashrrev_i32_e32 v174, 4, v174
	v_lshl_add_u64 v[200:201], v[200:201], 0, v[172:173]
	v_and_b32_e32 v174, 0xffffff80, v174
	v_lshl_add_u64 v[200:201], v[200:201], 0, v[162:163]
	v_ashrrev_i32_e32 v175, 31, v174
	ds_read_b128 v[164:167], v207
	s_waitcnt lgkmcnt(0)
	global_store_dwordx4 v[200:201], v[164:167], off sc1
	s_nop 7
	v_lshlrev_b32_e32 v200, 1, v202
	v_mov_b32_e32 v201, v0
	v_lshl_add_u64 v[202:203], s[14:15], 0, v[200:201]
	v_lshlrev_b64 v[174:175], 1, v[174:175]
	v_ashrrev_i32_e32 v176, 4, v176
	v_lshl_add_u64 v[202:203], v[202:203], 0, v[174:175]
	v_and_b32_e32 v176, 0xffffff80, v176
	v_lshl_add_u64 v[202:203], v[202:203], 0, v[162:163]
	v_ashrrev_i32_e32 v177, 31, v176
	ds_read_b128 v[164:167], v208
	s_waitcnt lgkmcnt(0)
	global_store_dwordx4 v[202:203], v[164:167], off sc1
	s_nop 7
	v_lshlrev_b32_e32 v202, 1, v204
	v_mov_b32_e32 v203, v0
	v_lshl_add_u64 v[204:205], s[14:15], 0, v[202:203]
	v_lshlrev_b64 v[176:177], 1, v[176:177]
	ds_read_b128 v[164:167], v209
	v_lshl_add_u64 v[204:205], v[204:205], 0, v[176:177]
	v_lshl_add_u64 v[204:205], v[204:205], 0, v[162:163]
	s_waitcnt lgkmcnt(0)
	global_store_dwordx4 v[204:205], v[164:167], off sc1
	s_nop 7
	v_pk_mul_f32 v[164:165], v[64:65], v[152:153] op_sel_hi:[1,0]
	v_pk_mul_f32 v[166:167], v[62:63], v[152:153] op_sel_hi:[1,0]
	s_waitcnt lgkmcnt(0)
	s_barrier
; #define LDS_BARRIER() do { asm volatile("s_waitcnt lgkmcnt(0)" ::: "memory"); __builtin_amdgcn_s_barrier(); asm volatile("" ::: "memory"); } while (0)
; __device__ __forceinline__ void st16_asm(void* ptr, u32x4 v) { asm volatile("global_store_dwordx4 %0, %1, off\n\ts_nop 7" :: "v"(ptr), "v"(v) : "memory"); }
; __device__ __forceinline__ void stg_flush(bf16* shm, int tid, bf16* dst, size_t pitch, bool first, bool tail_barrier = true) {
;   LDS_BARRIER();
;   if (first) asm volatile("s_waitcnt vmcnt(0)" ::: "memory");
;   _Pragma("unroll") for (int i = 0; i < 8; ++i) {
;     const int idx = tid + 512 * i, bjr = idx >> 11, row = (idx >> 4) & 127, c16 = idx & 15;
;     const u32x4 d = *(const u32x4*)stg_ptr(shm, bjr, row, 2 * c16);
;     st16_asm(dst + (size_t)row * pitch + bjr * HALF + c16 * 8, d); }
;   if (tail_barrier) LDS_BARRIER();
; template <int EPI>
; __device__ void gemm_phase(const bf16* A, int lda, const bf16* Bt, int K, int N, const Params& p, bool last, bf16* dstb, bf16* shm, unsigned long long* SSQ, int wv, const float* gbias = nullptr) {
;     ...
;         _Pragma("unroll") for (int ai = 0; ai < 2; ++ai) {
;           _Pragma("unroll") for (int m = 0; m < 4; ++m) {
;             const int rl = wr * 64 + m * 16 + fr; const float rs = rsv[ai][m];
;             _Pragma("unroll") for (int bj = 0; bj < 2; ++bj) _Pragma("unroll") for (int n = 0; n < 2; ++n) {
;               f32x4 v = acc[ai][bj][m][n] * rs; u32x2 o = {pk2(v[0], v[1]), pk2(v[2], v[3])};
;               *(u32x2*)stg_ptr(shm, bj, rl, wc * 8 + n * 4 + fq) = o; }
;           }
;           stg_flush(shm, tid, dst + (size_t)(brow + ai * HALF) * pitch + c0, pitch, ai == 0, ai == 0);
	v_cvt_pk_bf16_f32 v166, v166, v167
	v_cvt_pk_bf16_f32 v167, v164, v165
	ds_write_b64 v149, v[166:167] offset:32768
	v_pk_mul_f32 v[164:165], v[60:61], v[152:153] op_sel_hi:[1,0]
	v_pk_mul_f32 v[166:167], v[58:59], v[152:153] op_sel_hi:[1,0]
	v_pk_mul_f32 v[204:205], v[54:55], v[152:153] op_sel_hi:[1,0]
	v_cvt_pk_bf16_f32 v166, v166, v167
	v_cvt_pk_bf16_f32 v167, v164, v165
	v_pk_mul_f32 v[164:165], v[56:57], v[152:153] op_sel_hi:[1,0]
	v_cvt_pk_bf16_f32 v204, v204, v205
	v_cvt_pk_bf16_f32 v205, v164, v165
	ds_write_b64 v210, v[204:205]
	v_pk_mul_f32 v[164:165], v[52:53], v[152:153] op_sel_hi:[1,0]
	v_pk_mul_f32 v[204:205], v[50:51], v[152:153] op_sel_hi:[1,0]
	s_bitset1_b32 s10, 7
	v_cvt_pk_bf16_f32 v204, v204, v205
	v_cvt_pk_bf16_f32 v205, v164, v165
	ds_write_b64 v211, v[204:205]
	v_pk_mul_f32 v[164:165], v[48:49], v[150:151] op_sel_hi:[1,0]
	v_pk_mul_f32 v[204:205], v[46:47], v[150:151] op_sel_hi:[1,0]
	s_mul_hi_i32 s13, s12, s10
	v_cvt_pk_bf16_f32 v204, v204, v205
	v_cvt_pk_bf16_f32 v205, v164, v165
	ds_write_b64 v149, v[204:205] offset:36864
	v_pk_mul_f32 v[164:165], v[44:45], v[150:151] op_sel_hi:[1,0]
	v_pk_mul_f32 v[204:205], v[42:43], v[150:151] op_sel_hi:[1,0]
	s_mul_i32 s12, s12, s10
	v_cvt_pk_bf16_f32 v204, v204, v205
	v_cvt_pk_bf16_f32 v205, v164, v165
	ds_write2st64_b64 v179, v[166:167], v[204:205] offset0:64 offset1:72
	v_pk_mul_f32 v[164:165], v[40:41], v[150:151] op_sel_hi:[1,0]
	v_pk_mul_f32 v[166:167], v[38:39], v[150:151] op_sel_hi:[1,0]
	v_pk_mul_f32 v[204:205], v[22:23], v[148:149] op_sel_hi:[1,0]
	v_cvt_pk_bf16_f32 v166, v166, v167
	v_cvt_pk_bf16_f32 v167, v164, v165
	ds_write_b64 v212, v[166:167]
	v_pk_mul_f32 v[164:165], v[36:37], v[150:151] op_sel_hi:[1,0]
	v_pk_mul_f32 v[166:167], v[34:35], v[150:151] op_sel_hi:[1,0]
	v_cvt_pk_bf16_f32 v204, v204, v205
	v_cvt_pk_bf16_f32 v166, v166, v167
	v_cvt_pk_bf16_f32 v167, v164, v165
	ds_write_b64 v213, v[166:167]
	v_pk_mul_f32 v[164:165], v[32:33], v[148:149] op_sel_hi:[1,0]
	v_pk_mul_f32 v[166:167], v[30:31], v[148:149] op_sel_hi:[1,0]
	s_lshl_b64 s[12:13], s[12:13], 1
	v_cvt_pk_bf16_f32 v166, v166, v167
	v_cvt_pk_bf16_f32 v167, v164, v165
	ds_write_b64 v149, v[166:167] offset:40960
	v_pk_mul_f32 v[164:165], v[28:29], v[148:149] op_sel_hi:[1,0]
	v_pk_mul_f32 v[166:167], v[26:27], v[148:149] op_sel_hi:[1,0]
	s_add_u32 s12, s9, s12
	v_cvt_pk_bf16_f32 v166, v166, v167
	v_cvt_pk_bf16_f32 v167, v164, v165
	v_pk_mul_f32 v[164:165], v[24:25], v[148:149] op_sel_hi:[1,0]
	s_addc_u32 s13, s7, s13
	v_cvt_pk_bf16_f32 v205, v164, v165
	ds_write_b64 v214, v[204:205]
	v_pk_mul_f32 v[164:165], v[20:21], v[148:149] op_sel_hi:[1,0]
	v_pk_mul_f32 v[204:205], v[18:19], v[148:149] op_sel_hi:[1,0]
	v_lshl_add_u64 v[184:185], s[12:13], 0, v[184:185]
	v_cvt_pk_bf16_f32 v204, v204, v205
	v_cvt_pk_bf16_f32 v205, v164, v165
	ds_write_b64 v215, v[204:205]
	v_pk_mul_f32 v[164:165], v[16:17], v[146:147] op_sel_hi:[1,0]
	v_pk_mul_f32 v[204:205], v[14:15], v[146:147] op_sel_hi:[1,0]
	v_lshl_add_u64 v[184:185], v[184:185], 0, v[188:189]
	v_cvt_pk_bf16_f32 v204, v204, v205
	v_cvt_pk_bf16_f32 v205, v164, v165
	ds_write_b64 v149, v[204:205] offset:45056
	v_pk_mul_f32 v[164:165], v[12:13], v[146:147] op_sel_hi:[1,0]
	v_pk_mul_f32 v[204:205], v[10:11], v[146:147] op_sel_hi:[1,0]
	v_lshl_add_u64 v[184:185], v[184:185], 0, v[162:163]
	v_cvt_pk_bf16_f32 v204, v204, v205
	v_cvt_pk_bf16_f32 v205, v164, v165
	ds_write2st64_b64 v179, v[166:167], v[204:205] offset0:80 offset1:88
	v_pk_mul_f32 v[164:165], v[8:9], v[146:147] op_sel_hi:[1,0]
	v_pk_mul_f32 v[166:167], v[6:7], v[146:147] op_sel_hi:[1,0]
	s_nop 0
	v_cvt_pk_bf16_f32 v166, v166, v167
	v_cvt_pk_bf16_f32 v167, v164, v165
	ds_write_b64 v147, v[166:167]
	v_pk_mul_f32 v[164:165], v[4:5], v[146:147] op_sel_hi:[1,0]
	v_pk_mul_f32 v[166:167], v[2:3], v[146:147] op_sel_hi:[1,0]
	s_nop 0
	v_cvt_pk_bf16_f32 v166, v166, v167
	v_cvt_pk_bf16_f32 v167, v164, v165
	ds_write_b64 v151, v[166:167]
	s_waitcnt lgkmcnt(0)
	s_barrier
	ds_read_b128 v[164:167], v157
	s_waitcnt lgkmcnt(0)
	global_store_dwordx4 v[184:185], v[164:167], off sc1
	s_nop 7
	v_lshl_add_u64 v[184:185], s[12:13], 0, v[186:187]
	v_lshl_add_u64 v[184:185], v[184:185], 0, v[192:193]
	v_lshl_add_u64 v[184:185], v[184:185], 0, v[162:163]
	ds_read_b128 v[164:167], v159
	s_waitcnt lgkmcnt(0)
	global_store_dwordx4 v[184:185], v[164:167], off sc1
	s_nop 7
	v_lshl_add_u64 v[184:185], s[12:13], 0, v[190:191]
	v_lshl_add_u64 v[184:185], v[184:185], 0, v[196:197]
	ds_read_b128 v[164:167], v161
	v_lshl_add_u64 v[184:185], v[184:185], 0, v[162:163]
	s_waitcnt lgkmcnt(0)
	global_store_dwordx4 v[184:185], v[164:167], off sc1
	s_nop 7
	ds_read_b128 v[164:167], v178
	v_lshl_add_u64 v[178:179], s[12:13], 0, v[180:181]
	v_lshl_add_u64 v[168:169], v[178:179], 0, v[168:169]
	v_lshl_add_u64 v[168:169], v[168:169], 0, v[162:163]
	s_waitcnt lgkmcnt(0)
	global_store_dwordx4 v[168:169], v[164:167], off sc1
	s_nop 7
	v_lshl_add_u64 v[168:169], s[12:13], 0, v[182:183]
	v_lshl_add_u64 v[168:169], v[168:169], 0, v[170:171]
	v_lshl_add_u64 v[168:169], v[168:169], 0, v[162:163]
	ds_read_b128 v[164:167], v206
	s_waitcnt lgkmcnt(0)
	global_store_dwordx4 v[168:169], v[164:167], off sc1
	s_nop 7
	v_lshl_add_u64 v[168:169], s[12:13], 0, v[198:199]
	v_lshl_add_u64 v[168:169], v[168:169], 0, v[172:173]
	v_lshl_add_u64 v[168:169], v[168:169], 0, v[162:163]
	ds_read_b128 v[164:167], v207
	s_waitcnt lgkmcnt(0)
	global_store_dwordx4 v[168:169], v[164:167], off sc1
	s_nop 7
	v_lshl_add_u64 v[168:169], s[12:13], 0, v[200:201]
	v_lshl_add_u64 v[168:169], v[168:169], 0, v[174:175]
	v_lshl_add_u64 v[168:169], v[168:169], 0, v[162:163]
	ds_read_b128 v[164:167], v208
	s_waitcnt lgkmcnt(0)
	global_store_dwordx4 v[168:169], v[164:167], off sc1
	s_nop 7
	v_lshl_add_u64 v[168:169], s[12:13], 0, v[202:203]
	v_lshl_add_u64 v[168:169], v[168:169], 0, v[176:177]
	ds_read_b128 v[164:167], v209
	v_lshl_add_u64 v[162:163], v[168:169], 0, v[162:163]
	s_waitcnt lgkmcnt(0)
	global_store_dwordx4 v[162:163], v[164:167], off sc1
	s_nop 7
	s_cbranch_execnz .LBB0_161

; template <bool DIL> __device__ __forceinline__ AttnDesc attn_decode(const Params& p, int idx) {
;     ...
;   if constexpr (DIL) {
;     ...
;     d.r = (d.g == 0) ? 1 : (d.g == 1) ? 4 : 16; int nbk = 64 / d.r; d.c = cn / nbk; d.nb = cn % nbk;
;     ...
;     d.korg = (d.nb - 1) * 128; d.kt0 = (d.nb == 0) ? 2 : 0; d.ntile = 4 - d.kt0; d.step = 1;
;   } else {
;     d.b = idx >> 9; int h = (idx >> 6) & 7; d.nb = idx & 63; d.r = 1; d.c = 0;
;     d.base = (bf16*)(p.ws + OFF_QKVS); d.pitch = PS; d.qcol = h * 128; d.kcol = SBW + d.qcol; d.vcol = 2 * SBW + d.qcol;
;     d.korg = 0; d.kt0 = 2 * d.nb + 1; d.ntile = 2 * d.nb + 2; d.step = -1;
;   }
;   d.tok0 = (size_t)d.b * SEQ;
;   return d;
; }
; __device__ __forceinline__ void attn_prefetch(const AttnDesc& d, int ktile, int tid, AttnPre& R) {
;   const int sr = tid >> 4, sc = tid & 15;
;   _Pragma("unroll") for (int h = 0; h < 2; ++h) {
;     const int ktok = (d.korg + ktile * 64 + sr + 32 * h) * d.r + d.c;
;     const bf16* rp = d.base + (d.tok0 + (size_t)ktok) * d.pitch;
;     R.k[h] = *(const u32x4*)(rp + d.kcol + sc * 8); R.v[h] = *(const u32x4*)(rp + d.vcol + sc * 8);
;   }
; }
; __device__ __forceinline__ void attn_prefetch_tab(const Params& p, const AttnDesc& d, int ktile, int tid, AttnTab& Tb) {
;   const int sr = tid >> 4, sc = tid & 15;
;   const float* ct = (const float*)(p.ws + OFF_ROPE); const float* st = ct + SEQ * 64;
;   _Pragma("unroll") for (int h = 0; h < 2; ++h) {
;     const int ktok = (d.korg + ktile * 64 + sr + 32 * h) * d.r + d.c;
;     const float* cp = ct + (size_t)ktok * 64 + (sc & 7) * 8; const float* sp = st + (size_t)ktok * 64 + (sc & 7) * 8;
;     Tb.c[h][0] = *(const f32x4*)cp; Tb.c[h][1] = *(const f32x4*)(cp + 4); Tb.s[h][0] = *(const f32x4*)sp; Tb.s[h][1] = *(const f32x4*)(sp + 4);
;   }
; }
.LBB0_273:
	v_readlane_b32 s4, v253, 27
	s_add_i32 s5, s27, s4
	s_ashr_i32 s10, s5, 10
	s_bfe_u32 s28, s5, 0x20006
	s_and_b32 s4, s27, 63
	s_cmp_eq_u32 s10, 1
	s_cselect_b32 s6, 2, 4
	s_cmpk_gt_u32 s5, 0x3ff
	s_cselect_b32 s29, s6, 0
	s_lshr_b32 s6, 64, s29
	s_xor_b32 s7, s29, 6
	s_add_i32 s6, s6, -1
	s_lshr_b32 s30, s4, s7
	s_and_b32 s31, s6, s4
	s_lshl_b32 s4, s10, 9
	s_lshl_b32 s6, s28, 7
	s_or_b32 s4, s6, s4
	s_add_i32 s12, s4, 0x600
	s_add_i32 s14, s4, 0xc00
	s_lshl_b32 s8, s31, 7
	s_cmp_eq_u32 s31, 0
	v_mbcnt_lo_u32_b32 v1, -1, 0
	v_mbcnt_hi_u32_b32 v1, -1, v1
	s_cselect_b32 s34, 2, 0
	s_waitcnt vmcnt(8)
	v_or_b32_e32 v2, s91, v1
	s_lshl_b32 s5, s5, 5
	v_lshlrev_b32_e32 v3, 4, v2
	v_lshlrev_b32_e32 v68, 5, v2
	s_and_b32 s62, s5, 0x6000
	v_ashrrev_i32_e32 v161, 4, v2
	s_mov_b64 s[6:7], -1
	s_andn2_b64 vcc, exec, s[0:1]
	v_and_b32_e32 v148, 0xf0, v3
	v_and_b32_e32 v150, 0xe0, v68
	s_cbranch_vccz .LBB0_275
	s_lshl_b32 s35, s34, 6
	s_add_i32 s9, s8, 0xffffff80
	v_add_u32_e32 v3, s35, v161
	v_add_u32_e32 v68, s9, v3
	v_lshlrev_b32_e32 v68, s29, v68
	v_add_u32_e32 v68, s30, v68
	v_ashrrev_i32_e32 v69, 31, v68
	v_lshl_add_u64 v[70:71], v[68:69], 0, s[62:63]
	v_mov_b64_e32 v[72:73], s[86:87]
	v_mad_u64_u32 v[74:75], s[0:1], v70, s81, v[72:73]
	s_ashr_i32 s5, s4, 31
	v_mad_i32_i24 v75, v71, s81, v75
	s_lshl_b64 s[0:1], s[4:5], 1
	v_lshl_add_u64 v[70:71], v[74:75], 0, s[0:1]
	v_mov_b32_e32 v149, v0
	v_lshl_add_u64 v[70:71], v[70:71], 0, v[148:149]
	s_movk_i32 s13, 0x1000
	v_add_co_u32_e32 v74, vcc, s13, v70
	s_add_i32 s11, s8, 0xffffffa0
	s_nop 0
	v_addc_co_u32_e32 v75, vcc, 0, v71, vcc
	global_load_dwordx4 v[84:87], v[70:71], off offset:3072
	global_load_dwordx4 v[88:91], v[74:75], off offset:2048
	v_add_u32_e32 v70, s11, v3
	v_lshlrev_b32_e32 v70, s29, v70
	v_add_u32_e32 v70, s30, v70
	v_ashrrev_i32_e32 v71, 31, v70
	v_lshl_add_u64 v[74:75], v[70:71], 0, s[62:63]
	v_mad_u64_u32 v[76:77], s[6:7], v74, s81, v[72:73]
	v_mad_i32_i24 v77, v75, s81, v77
	v_lshl_add_u64 v[74:75], v[76:77], 0, s[0:1]
	v_lshl_add_u64 v[74:75], v[74:75], 0, v[148:149]
	v_add_co_u32_e32 v76, vcc, s13, v74
	v_mov_b32_e32 v151, v0
	s_nop 0
	v_addc_co_u32_e32 v77, vcc, 0, v75, vcc
	global_load_dwordx4 v[100:103], v[74:75], off offset:3072
	global_load_dwordx4 v[104:107], v[76:77], off offset:2048
	v_lshl_add_u64 v[74:75], s[50:51], 0, v[150:151]
	v_lshl_add_u64 v[76:77], s[44:45], 0, v[150:151]
	v_lshlrev_b64 v[68:69], 8, v[68:69]
	v_lshl_add_u64 v[78:79], v[74:75], 0, v[68:69]
	v_lshl_add_u64 v[68:69], v[76:77], 0, v[68:69]
	global_load_dwordx4 v[92:95], v[78:79], off offset:16
	global_load_dwordx4 v[96:99], v[78:79], off
	global_load_dwordx4 v[108:111], v[68:69], off offset:16
	global_load_dwordx4 v[112:115], v[68:69], off
	v_lshlrev_b64 v[68:69], 8, v[70:71]
	v_lshl_add_u64 v[70:71], v[74:75], 0, v[68:69]
	v_lshl_add_u64 v[68:69], v[76:77], 0, v[68:69]
	v_add_u32_e32 v3, 64, v3
	global_load_dwordx4 v[116:119], v[70:71], off offset:16
	global_load_dwordx4 v[120:123], v[70:71], off
	global_load_dwordx4 v[124:127], v[68:69], off offset:16
	global_load_dwordx4 v[128:131], v[68:69], off
	v_add_u32_e32 v68, s9, v3
	v_lshlrev_b32_e32 v68, s29, v68
	v_add_u32_e32 v68, s30, v68
	v_ashrrev_i32_e32 v69, 31, v68
	v_lshl_add_u64 v[68:69], v[68:69], 0, s[62:63]
	v_mad_u64_u32 v[70:71], s[6:7], v68, s81, v[72:73]
	v_mad_i32_i24 v71, v69, s81, v71
	v_lshl_add_u64 v[68:69], v[70:71], 0, s[0:1]
	v_lshl_add_u64 v[68:69], v[68:69], 0, v[148:149]
	v_add_u32_e32 v3, s11, v3
	v_add_co_u32_e32 v70, vcc, s13, v68
	v_lshlrev_b32_e32 v3, s29, v3
	s_nop 0
	v_addc_co_u32_e32 v71, vcc, 0, v69, vcc
	global_load_dwordx4 v[132:135], v[68:69], off offset:3072
	global_load_dwordx4 v[136:139], v[70:71], off offset:2048
	v_add_u32_e32 v68, s30, v3
	v_ashrrev_i32_e32 v69, 31, v68
	v_lshl_add_u64 v[68:69], v[68:69], 0, s[62:63]
	v_mad_u64_u32 v[70:71], s[6:7], v68, s81, v[72:73]
	v_mad_i32_i24 v71, v69, s81, v71
	v_lshl_add_u64 v[68:69], v[70:71], 0, s[0:1]
	v_lshl_add_u64 v[68:69], v[68:69], 0, v[148:149]
	v_add_co_u32_e32 v70, vcc, 0x1000, v68
	s_ashr_i32 s13, s12, 31
	s_nop 0
	v_addc_co_u32_e32 v71, vcc, 0, v69, vcc
	global_load_dwordx4 v[140:143], v[68:69], off offset:3072
	global_load_dwordx4 v[144:147], v[70:71], off offset:2048
	s_ashr_i32 s15, s14, 31
	s_mov_b64 s[6:7], 0
	s_waitcnt vmcnt(0)
.LBB0_275:
	s_andn2_b64 vcc, exec, s[6:7]
	s_cbranch_vccnz .LBB0_277
	s_waitcnt vmcnt(12)
	v_mov_b64_e32 v[106:107], v[26:27]
	s_waitcnt vmcnt(8)
	v_mov_b64_e32 v[90:91], v[10:11]
	v_mov_b64_e32 v[102:103], v[22:23]
	v_mov_b64_e32 v[86:87], v[6:7]
	v_mov_b64_e32 v[146:147], v[58:59]
	v_mov_b64_e32 v[138:139], v[42:43]
	v_mov_b64_e32 v[142:143], v[54:55]
	v_mov_b64_e32 v[134:135], v[38:39]
	v_mov_b64_e32 v[126:127], v[62:63]
	v_mov_b64_e32 v[130:131], v[66:67]
	v_mov_b64_e32 v[110:111], v[30:31]
	v_mov_b64_e32 v[114:115], v[34:35]
	v_mov_b64_e32 v[118:119], v[46:47]
	v_mov_b64_e32 v[122:123], v[50:51]
	v_mov_b64_e32 v[94:95], v[14:15]
	v_mov_b64_e32 v[98:99], v[18:19]
	s_ashr_i32 s13, s12, 31
	s_ashr_i32 s15, s14, 31
	s_ashr_i32 s5, s4, 31
	s_lshl_b32 s35, s34, 6
	v_mov_b64_e32 v[104:105], v[24:25]
	v_mov_b64_e32 v[88:89], v[8:9]
	v_mov_b64_e32 v[100:101], v[20:21]
	v_mov_b64_e32 v[84:85], v[4:5]
	v_mov_b64_e32 v[144:145], v[56:57]
	v_mov_b64_e32 v[136:137], v[40:41]
	v_mov_b64_e32 v[140:141], v[52:53]
	v_mov_b64_e32 v[132:133], v[36:37]
	v_mov_b64_e32 v[124:125], v[60:61]
	v_mov_b64_e32 v[128:129], v[64:65]
	v_mov_b64_e32 v[108:109], v[28:29]
	v_mov_b64_e32 v[112:113], v[32:33]
	v_mov_b64_e32 v[116:117], v[44:45]
	v_mov_b64_e32 v[120:121], v[48:49]
	v_mov_b64_e32 v[92:93], v[12:13]
	v_mov_b64_e32 v[96:97], v[16:17]
; __device__ __forceinline__ float bflo(unsigned u) { return __uint_as_float(u << 16); }
; __device__ __forceinline__ float bfhi(unsigned u) { return __uint_as_float(u & 0xffff0000u); }
; #define shx(v, m) shxt<m>(v)
; template <bool DIL>
; __device__ void attn_item(const Params& p, int layer, int idx, char* shm, int wv, AttnPre& R0, AttnPre& R1, AttnTab& Tb, bool have_pre, int next_idx) {
;     ...
;   const int qsub = nb * 128 + 16 * w + n, qtok = qsub * r + c;
;   bf16* qrow = base + (tok0 + qtok) * pitch + qcol;
;   bf16x8 qf[4];
;   {
;     u32x4 raw[4];
;     for (int ks = 0; ks < 4; ++ks) raw[ks] = *(const u32x4*)(qrow + 32 * ks + 8 * q4);
;     if constexpr (DIL) {
;       float xv[4][8]; float ss = 0.f;
;       for (int ks = 0; ks < 4; ++ks) for (int j = 0; j < 4; ++j) { xv[ks][2 * j] = bflo(raw[ks][j]); xv[ks][2 * j + 1] = bfhi(raw[ks][j]); }
;       for (int ks = 0; ks < 4; ++ks) for (int j = 0; j < 8; ++j) ss += xv[ks][j] * xv[ks][j];
;       ss += shx(ss, 16); ss += shx(ss, 32);
;       const float rs = rsqrtf(ss * (1.f / HD) + EPS);
.LBB0_277:
	v_ashrrev_i32_e32 v4, 2, v2
	v_and_b32_e32 v149, -16, v4
	v_and_b32_e32 v3, 15, v1
	v_add_u32_e32 v5, s8, v149
	v_or_b32_e32 v5, v5, v3
	v_lshlrev_b32_e32 v5, s29, v5
	v_add_u32_e32 v154, s30, v5
	v_ashrrev_i32_e32 v155, 31, v154
	s_waitcnt vmcnt(8)
	v_lshl_add_u64 v[6:7], v[154:155], 0, s[62:63]
	v_mov_b64_e32 v[8:9], s[86:87]
	v_mad_u64_u32 v[8:9], s[0:1], v6, s81, v[8:9]
	v_mad_i32_i24 v9, v7, s81, v9
	v_lshl_add_u64 v[152:153], s[4:5], 1, v[8:9]
	v_and_b32_e32 v156, 48, v1
	v_mov_b32_e32 v157, v0
	v_lshl_add_u64 v[18:19], v[152:153], 0, v[156:157]
	global_load_dwordx4 v[6:9], v[18:19], off offset:64
	global_load_dwordx4 v[10:13], v[18:19], off offset:192
	global_load_dwordx4 v[14:17], v[18:19], off
	s_nop 0
	global_load_dwordx4 v[18:21], v[18:19], off offset:128
	s_sub_i32 s36, 4, s34
	s_ashr_i32 s11, s10, 31
	s_add_u32 s0, s10, s26
	s_addc_u32 s1, s11, 0
	v_readlane_b32 s64, v253, 11
	s_lshl_b64 s[0:1], s[0:1], 9
	v_readlane_b32 s70, v253, 17
	v_bfe_u32 v157, v1, 4, 2
	v_readlane_b32 s71, v253, 18
	s_add_u32 s4, s70, s0
	v_lshlrev_b32_e32 v54, 5, v157
	s_addc_u32 s5, s71, s1
	global_load_dwordx4 v[22:25], v54, s[4:5] offset:144
	global_load_dwordx4 v[26:29], v54, s[4:5] offset:128
	global_load_dwordx4 v[30:33], v54, s[4:5] offset:400
	global_load_dwordx4 v[34:37], v54, s[4:5] offset:384
	global_load_dwordx4 v[38:41], v54, s[4:5] offset:16
	global_load_dwordx4 v[42:45], v54, s[4:5]
	global_load_dwordx4 v[46:49], v54, s[4:5] offset:272
	global_load_dwordx4 v[50:53], v54, s[4:5] offset:256
	v_lshlrev_b64 v[56:57], 8, v[154:155]
	v_mov_b32_e32 v55, v0
	v_lshl_add_u64 v[58:59], s[50:51], 0, v[56:57]
	v_lshl_add_u64 v[56:57], s[44:45], 0, v[56:57]
	v_lshl_add_u64 v[74:75], v[58:59], 0, v[54:55]
	v_lshl_add_u64 v[82:83], v[56:57], 0, v[54:55]
	global_load_dwordx4 v[54:57], v[74:75], off offset:144
	global_load_dwordx4 v[58:61], v[74:75], off offset:128
	global_load_dwordx4 v[62:65], v[82:83], off offset:144
	global_load_dwordx4 v[66:69], v[82:83], off offset:128
	global_load_dwordx4 v[70:73], v[74:75], off offset:16
	s_nop 0
	global_load_dwordx4 v[74:77], v[74:75], off
	s_nop 0
	global_load_dwordx4 v[78:81], v[82:83], off offset:16
	global_load_dwordx4 v[162:165], v[82:83], off
	v_readlane_b32 s72, v253, 19
	v_readlane_b32 s73, v253, 20
	s_add_u32 s0, s72, s0
	s_addc_u32 s1, s73, s1
	s_mov_b32 s4, 0x3ffff8
	s_cmp_lg_u32 s31, 0
	s_cselect_b64 s[16:17], -1, 0
	v_readlane_b32 s66, v253, 13
	v_readlane_b32 s67, v253, 14
	v_readlane_b32 s68, v253, 15
	v_readlane_b32 s69, v253, 16
	v_readlane_b32 s76, v253, 23
	v_readlane_b32 s77, v253, 24
	v_readlane_b32 s78, v253, 25
	v_readlane_b32 s79, v253, 26
	v_readlane_b32 s74, v253, 21
	v_readlane_b32 s76, v252, 17
	v_readlane_b32 s54, v252, 21
	v_readlane_b32 s66, v253, 47
	v_readlane_b32 s68, v254, 10
	s_mov_b32 s39, 0
	v_mov_b32_e32 v214, 0
	v_mov_b32_e32 v215, 0xff800000
	v_readlane_b32 s77, v252, 18
	v_readlane_b32 s78, v252, 19
	v_readlane_b32 s79, v252, 20
	v_readlane_b32 s55, v252, 22
	v_readlane_b32 s67, v253, 48
	v_readlane_b32 s69, v254, 11
	v_readlane_b32 s74, v254, 23
	v_readlane_b32 s65, v253, 12
	v_readlane_b32 s75, v253, 22
	s_waitcnt vmcnt(19)
	v_lshlrev_b32_e32 v82, 16, v9
	v_and_b32_e32 v83, 0xffff0000, v9
	s_waitcnt vmcnt(17)
	v_lshlrev_b32_e32 v208, 16, v14
	v_and_b32_e32 v209, 0xffff0000, v14
	v_lshlrev_b32_e32 v158, 16, v13
	v_and_b32_e32 v159, 0xffff0000, v13
	v_lshlrev_b32_e32 v168, 16, v8
	v_and_b32_e32 v169, 0xffff0000, v8
	v_lshlrev_b32_e32 v8, 16, v12
	v_and_b32_e32 v9, 0xffff0000, v12
	v_lshlrev_b32_e32 v12, 16, v7
	v_and_b32_e32 v13, 0xffff0000, v7
	v_lshlrev_b32_e32 v170, 16, v11
	v_and_b32_e32 v171, 0xffff0000, v11
	v_lshlrev_b32_e32 v172, 16, v6
	v_and_b32_e32 v173, 0xffff0000, v6
	v_lshlrev_b32_e32 v6, 16, v10
	v_and_b32_e32 v7, 0xffff0000, v10
	v_lshlrev_b32_e32 v10, 16, v17
	v_and_b32_e32 v11, 0xffff0000, v17
	s_waitcnt vmcnt(16)
	v_lshlrev_b32_e32 v174, 16, v21
	v_and_b32_e32 v175, 0xffff0000, v21
	v_lshlrev_b32_e32 v176, 16, v16
	v_and_b32_e32 v177, 0xffff0000, v16
	v_lshlrev_b32_e32 v16, 16, v20
	v_and_b32_e32 v17, 0xffff0000, v20
	v_lshlrev_b32_e32 v20, 16, v15
	v_and_b32_e32 v21, 0xffff0000, v15
	v_lshlrev_b32_e32 v178, 16, v19
	v_and_b32_e32 v179, 0xffff0000, v19
	v_lshlrev_b32_e32 v14, 16, v18
	v_and_b32_e32 v15, 0xffff0000, v18
	v_pk_mul_f32 v[18:19], v[208:209], v[208:209]
	v_pk_mul_f32 v[204:205], v[20:21], v[20:21]
	v_add_f32_e32 v5, v18, v19
	v_add_f32_e32 v5, v204, v5
	v_pk_mul_f32 v[200:201], v[176:177], v[176:177]
	v_add_f32_e32 v5, v205, v5
	v_add_f32_e32 v5, v200, v5
	v_pk_mul_f32 v[196:197], v[10:11], v[10:11]
	v_add_f32_e32 v5, v201, v5
	v_add_f32_e32 v5, v196, v5
	v_pk_mul_f32 v[190:191], v[172:173], v[172:173]
	v_add_f32_e32 v5, v197, v5
	v_add_f32_e32 v5, v190, v5
	v_pk_mul_f32 v[186:187], v[12:13], v[12:13]
	v_add_f32_e32 v5, v191, v5
	v_add_f32_e32 v5, v186, v5
	v_pk_mul_f32 v[182:183], v[168:169], v[168:169]
	v_add_f32_e32 v5, v187, v5
	v_add_f32_e32 v5, v182, v5
	v_pk_mul_f32 v[166:167], v[82:83], v[82:83]
	v_add_f32_e32 v5, v183, v5
	v_add_f32_e32 v5, v166, v5
	v_pk_mul_f32 v[210:211], v[14:15], v[14:15]
	v_add_f32_e32 v5, v167, v5
	v_add_f32_e32 v5, v210, v5
	v_pk_mul_f32 v[206:207], v[178:179], v[178:179]
	v_add_f32_e32 v5, v211, v5
	v_add_f32_e32 v5, v206, v5
	v_pk_mul_f32 v[202:203], v[16:17], v[16:17]
	v_add_f32_e32 v5, v207, v5
	v_add_f32_e32 v5, v202, v5
	v_pk_mul_f32 v[198:199], v[174:175], v[174:175]
	v_add_f32_e32 v5, v203, v5
	v_add_f32_e32 v5, v198, v5
	v_pk_mul_f32 v[192:193], v[6:7], v[6:7]
	v_add_f32_e32 v5, v199, v5
	v_add_f32_e32 v5, v192, v5
	v_pk_mul_f32 v[188:189], v[170:171], v[170:171]
	v_add_f32_e32 v5, v193, v5
	v_add_f32_e32 v5, v188, v5
	v_pk_mul_f32 v[184:185], v[8:9], v[8:9]
	v_add_f32_e32 v5, v189, v5
	v_add_f32_e32 v5, v184, v5
	v_pk_mul_f32 v[180:181], v[158:159], v[158:159]
	v_add_f32_e32 v5, v185, v5
	v_add_f32_e32 v5, v180, v5
	v_add_f32_e32 v5, v181, v5
	v_mov_b32_e32 v18, v5
	v_mov_b32_e32 v19, v5
	s_nop 1
	v_permlane16_swap_b32_e32 v18, v19
	v_xor_b32_e32 v18, v18, v19
	v_xor_b32_e32 v18, v18, v5
	v_add_f32_e32 v5, v5, v18
	v_mov_b32_e32 v18, v5
	v_mov_b32_e32 v19, v5
	s_nop 1
	v_permlane32_swap_b32_e32 v18, v19
	v_xor_b32_e32 v18, v19, v18
	v_xor_b32_e32 v18, v18, v5
	v_add_f32_e32 v5, v5, v18
	v_fmamk_f32 v5, v5, 0x3c000000, v194
	v_mul_f32_e32 v18, 0x4b800000, v5
	v_cmp_gt_f32_e32 vcc, s80, v5
	v_and_b32_e32 v166, 63, v1
	s_nop 0
	v_cndmask_b32_e32 v5, v5, v18, vcc
	v_rsq_f32_e32 v5, v5
	s_nop 0
	v_mul_f32_e32 v18, 0x45800000, v5
	v_cndmask_b32_e32 v18, v5, v18, vcc
	s_waitcnt vmcnt(14)
; __device__ __forceinline__ float bflo(unsigned u) { return __uint_as_float(u << 16); }
; __device__ __forceinline__ float bfhi(unsigned u) { return __uint_as_float(u & 0xffff0000u); }
; #define shx(v, m) shxt<m>(v)
; template <bool DIL>
; __device__ void attn_item(const Params& p, int layer, int idx, char* shm, int wv, AttnPre& R0, AttnPre& R1, AttnTab& Tb, bool have_pre, int next_idx) {
;     ...
;       u32x4 kv = R.k[h];
;       if constexpr (DIL) {
;         float xv[8]; for (int j = 0; j < 4; ++j) { xv[2 * j] = bflo(kv[j]); xv[2 * j + 1] = bfhi(kv[j]); }
;         float ss = 0.f; for (int j = 0; j < 8; ++j) ss += xv[j] * xv[j];
;         ss = rsum16(ss);
;         const float rs = rsqrtf(ss * (1.f / HD) + EPS);
;         const float* gk = p.k_norm_g + ((size_t)layer * 3 + g) * HD + sc * 8;
;         for (int j = 0; j < 8; ++j) xv[j] *= rs * gk[j];
;         float rv[8];
;         for (int j = 0; j < 8; ++j) { const float ov = shx(xv[j], 8); const float cs = Tb.c[h][j >> 2][j & 3], sn = Tb.s[h][j >> 2][j & 3];
;           rv[j] = (sc < 8) ? (xv[j] * cs - ov * sn) : (xv[j] * cs + ov * sn); }
;         kv = u32x4{pk2(rv[0], rv[1]), pk2(rv[2], rv[3]), pk2(rv[4], rv[5]), pk2(rv[6], rv[7])};
;     ...
;       const float* gq = p.q_norm_g + ((size_t)layer * 3 + g) * HD;
;       for (int ks = 0; ks < 4; ++ks) for (int j = 0; j < 8; ++j) xv[ks][j] *= rs * gq[32 * ks + 8 * q4 + j];
;       for (int ks = 0; ks < 2; ++ks) {
;         const float* cp = ct + (size_t)qtok * 64 + 32 * ks + 8 * q4; const float* sp = st + (size_t)qtok * 64 + 32 * ks + 8 * q4;
;         for (int j = 0; j < 8; ++j) { float cs = cp[j], sn = sp[j], x1 = xv[ks][j], x2 = xv[ks + 2][j];
;           xv[ks][j] = x1 * cs - x2 * sn; xv[ks + 2][j] = x2 * cs + x1 * sn; }
;       }
;       for (int ks = 0; ks < 4; ++ks) for (int j = 0; j < 4; ++j) raw[ks][j] = pk2(xv[ks][2 * j], xv[ks][2 * j + 1]);
	v_pk_mul_f32 v[28:29], v[28:29], v[18:19] op_sel_hi:[1,0]
	s_waitcnt vmcnt(11)
	v_pk_mul_f32 v[40:41], v[40:41], v[18:19] op_sel_hi:[1,0]
	v_pk_mul_f32 v[12:13], v[28:29], v[12:13]
	s_waitcnt vmcnt(8)
	v_pk_mul_f32 v[28:29], v[50:51], v[18:19] op_sel_hi:[1,0]
	v_pk_mul_f32 v[44:45], v[44:45], v[18:19] op_sel_hi:[1,0]
	v_pk_mul_f32 v[14:15], v[28:29], v[14:15]
	v_pk_mul_f32 v[28:29], v[52:53], v[18:19] op_sel_hi:[1,0]
	v_pk_mul_f32 v[10:11], v[40:41], v[10:11]
	v_pk_mul_f32 v[28:29], v[28:29], v[178:179]
	v_pk_mul_f32 v[40:41], v[46:47], v[18:19] op_sel_hi:[1,0]
	v_pk_mul_f32 v[34:35], v[34:35], v[18:19] op_sel_hi:[1,0]
	v_pk_mul_f32 v[42:43], v[42:43], v[18:19] op_sel_hi:[1,0]
	v_pk_mul_f32 v[20:21], v[44:45], v[20:21]
	v_pk_mul_f32 v[38:39], v[38:39], v[18:19] op_sel_hi:[1,0]
	v_pk_mul_f32 v[26:27], v[26:27], v[18:19] op_sel_hi:[1,0]
	v_pk_mul_f32 v[22:23], v[22:23], v[18:19] op_sel_hi:[1,0]
	v_pk_mul_f32 v[24:25], v[24:25], v[18:19] op_sel_hi:[1,0]
	v_pk_mul_f32 v[16:17], v[40:41], v[16:17]
	v_pk_mul_f32 v[40:41], v[48:49], v[18:19] op_sel_hi:[1,0]
	v_pk_mul_f32 v[6:7], v[34:35], v[6:7]
	v_pk_mul_f32 v[34:35], v[36:37], v[18:19] op_sel_hi:[1,0]
	v_pk_mul_f32 v[30:31], v[30:31], v[18:19] op_sel_hi:[1,0]
	v_pk_mul_f32 v[18:19], v[32:33], v[18:19] op_sel_hi:[1,0]
	s_waitcnt vmcnt(0)
	v_pk_mul_f32 v[32:33], v[164:165], v[28:29]
	v_pk_mul_f32 v[28:29], v[76:77], v[28:29]
	v_pk_mul_f32 v[38:39], v[38:39], v[176:177]
	v_pk_fma_f32 v[32:33], v[76:77], v[20:21], v[32:33] neg_lo:[0,0,1] neg_hi:[0,0,1]
	v_pk_fma_f32 v[20:21], v[164:165], v[20:21], v[28:29]
	v_pk_mul_f32 v[28:29], v[78:79], v[16:17]
	v_pk_mul_f32 v[16:17], v[70:71], v[16:17]
	v_pk_mul_f32 v[26:27], v[26:27], v[172:173]
	v_pk_fma_f32 v[28:29], v[70:71], v[38:39], v[28:29] neg_lo:[0,0,1] neg_hi:[0,0,1]
	v_pk_fma_f32 v[16:17], v[78:79], v[38:39], v[16:17]
	v_pk_mul_f32 v[38:39], v[6:7], v[66:67]
	v_pk_mul_f32 v[34:35], v[34:35], v[170:171]
	v_pk_fma_f32 v[38:39], v[26:27], v[58:59], v[38:39] neg_lo:[0,0,1] neg_hi:[0,0,1]
	v_pk_mul_f32 v[26:27], v[26:27], v[66:67]
	v_pk_mul_f32 v[40:41], v[40:41], v[174:175]
	v_pk_fma_f32 v[6:7], v[6:7], v[58:59], v[26:27]
	v_pk_mul_f32 v[26:27], v[34:35], v[68:69]
	v_pk_mul_f32 v[8:9], v[30:31], v[8:9]
	v_pk_mul_f32 v[36:37], v[40:41], v[80:81]
	v_pk_fma_f32 v[26:27], v[12:13], v[60:61], v[26:27] neg_lo:[0,0,1] neg_hi:[0,0,1]
	v_pk_mul_f32 v[12:13], v[12:13], v[68:69]
	v_pk_mul_f32 v[22:23], v[22:23], v[168:169]
	v_pk_fma_f32 v[36:37], v[10:11], v[72:73], v[36:37] neg_lo:[0,0,1] neg_hi:[0,0,1]
	v_pk_mul_f32 v[10:11], v[80:81], v[10:11]
	v_pk_fma_f32 v[12:13], v[34:35], v[60:61], v[12:13]
	v_pk_mul_f32 v[34:35], v[8:9], v[62:63]
	v_pk_fma_f32 v[10:11], v[72:73], v[40:41], v[10:11]
	v_pk_fma_f32 v[34:35], v[22:23], v[54:55], v[34:35] neg_lo:[0,0,1] neg_hi:[0,0,1]
	v_pk_mul_f32 v[22:23], v[22:23], v[62:63]
	v_cvt_pk_bf16_f32 v79, v10, v11
	v_pk_fma_f32 v[8:9], v[8:9], v[54:55], v[22:23]
	v_cvt_pk_bf16_f32 v80, v6, v7
	v_lshlrev_b32_e32 v5, 2, v1
	v_and_b32_e32 v6, 3, v1
	v_lshlrev_b32_e32 v10, 5, v3
	v_mov_b32_e32 v11, v0
	v_pk_mul_f32 v[24:25], v[24:25], v[82:83]
	v_pk_mul_f32 v[18:19], v[18:19], v[158:159]
	v_cvt_pk_bf16_f32 v81, v12, v13
	v_cvt_pk_bf16_f32 v82, v8, v9
	v_and_or_b32 v5, v5, 48, v6
	v_lshl_add_u64 v[158:159], s[0:1], 0, v[10:11]
	global_load_dwordx4 v[6:9], v10, s[0:1] offset:16
	s_nop 0
	global_load_dwordx4 v[10:13], v10, s[0:1]
	v_cvt_pk_bf16_f32 v70, v28, v29
	v_ashrrev_i32_e32 v28, 8, v2
	v_lshlrev_b32_e32 v29, 2, v28
	v_and_b32_e32 v29, 12, v29
	v_bfe_u32 v46, v2, 4, 2
	v_bitop3_b32 v29, v29, v3, v46 bitop3:0x36
	v_pk_mul_f32 v[22:23], v[18:19], v[64:65]
	v_lshl_add_u32 v2, v161, 8, 0
	v_lshlrev_b32_e32 v29, 4, v29
	v_and_b32_e32 v47, 12, v161
	v_pk_mul_f32 v[42:43], v[42:43], v[208:209]
	v_pk_mul_f32 v[30:31], v[162:163], v[14:15]
	v_pk_fma_f32 v[22:23], v[24:25], v[56:57], v[22:23] neg_lo:[0,0,1] neg_hi:[0,0,1]
	v_cvt_pk_bf16_f32 v73, v26, v27
	v_and_b32_e32 v27, 0xffff0000, v84
	v_add_u32_e32 v151, v2, v29
	v_add_u32_e32 v2, v47, v28
	v_and_b32_e32 v41, 0xffff0000, v100
	v_pk_fma_f32 v[30:31], v[74:75], v[42:43], v[30:31] neg_lo:[0,0,1] neg_hi:[0,0,1]
	v_pk_mul_f32 v[14:15], v[74:75], v[14:15]
	v_pk_mul_f32 v[24:25], v[24:25], v[64:65]
	v_cvt_pk_bf16_f32 v71, v36, v37
	v_cvt_pk_bf16_f32 v75, v22, v23
	v_lshlrev_b32_e32 v22, 16, v85
	v_and_b32_e32 v23, 0xffff0000, v85
	v_lshlrev_b32_e32 v26, 16, v84
	v_lshlrev_b32_e32 v28, 2, v2
	v_lshlrev_b32_e32 v36, 16, v101
	v_and_b32_e32 v37, 0xffff0000, v101
	v_lshlrev_b32_e32 v40, 16, v100
	v_mov_b32_e32 v44, v41
	v_mov_b32_e32 v45, v27
	v_pk_fma_f32 v[14:15], v[162:163], v[42:43], v[14:15]
	v_pk_fma_f32 v[18:19], v[18:19], v[56:57], v[24:25]
	v_cvt_pk_bf16_f32 v72, v38, v39
	v_pk_mul_f32 v[24:25], v[22:23], v[22:23]
	v_bfe_u32 v48, v1, 1, 3
	v_and_b32_e32 v28, 28, v28
	v_bfe_u32 v49, v3, 1, 2
	v_pk_mul_f32 v[38:39], v[36:37], v[36:37]
	v_mov_b32_e32 v42, v40
	v_mov_b32_e32 v43, v26
	v_pk_mul_f32 v[44:45], v[44:45], v[44:45]
	v_cvt_pk_bf16_f32 v69, v32, v33
	v_cvt_pk_bf16_f32 v83, v18, v19
	v_lshlrev_b32_e32 v18, 16, v86
	v_and_b32_e32 v19, 0xffff0000, v86
	v_and_or_b32 v2, v2, s4, v48
	v_bitop3_b32 v28, v28, v49, v46 bitop3:0x36
	v_lshlrev_b32_e32 v32, 16, v102
	v_and_b32_e32 v33, 0xffff0000, v102
	v_pk_fma_f32 v[42:43], v[42:43], v[42:43], v[44:45]
	v_mov_b32_e32 v44, v38
	v_mov_b32_e32 v45, v24
	v_cvt_pk_bf16_f32 v74, v34, v35
	v_cvt_pk_bf16_f32 v77, v20, v21
	v_pk_mul_f32 v[20:21], v[18:19], v[18:19]
	v_lshlrev_b32_e32 v2, 10, v2
	v_lshlrev_b32_e32 v28, 5, v28
	v_pk_mul_f32 v[34:35], v[32:33], v[32:33]
	v_pk_add_f32 v[42:43], v[44:45], v[42:43]
	v_mov_b32_e32 v24, v39
; __device__ __forceinline__ float bflo(unsigned u) { return __uint_as_float(u << 16); }
; __device__ __forceinline__ float bfhi(unsigned u) { return __uint_as_float(u & 0xffff0000u); }
; #define shx(v, m) shxt<m>(v)
; template <bool DIL>
; __device__ void attn_item(const Params& p, int layer, int idx, char* shm, int wv, AttnPre& R0, AttnPre& R1, AttnTab& Tb, bool have_pre, int next_idx) {
;     ...
;       u32x4 kv = R.k[h];
;       if constexpr (DIL) {
;         float xv[8]; for (int j = 0; j < 4; ++j) { xv[2 * j] = bflo(kv[j]); xv[2 * j + 1] = bfhi(kv[j]); }
;         float ss = 0.f; for (int j = 0; j < 8; ++j) ss += xv[j] * xv[j];
;         ss = rsum16(ss);
;         const float rs = rsqrtf(ss * (1.f / HD) + EPS);
;         const float* gk = p.k_norm_g + ((size_t)layer * 3 + g) * HD + sc * 8;
;         for (int j = 0; j < 8; ++j) xv[j] *= rs * gk[j];
;         float rv[8];
;         for (int j = 0; j < 8; ++j) { const float ov = shx(xv[j], 8); const float cs = Tb.c[h][j >> 2][j & 3], sn = Tb.s[h][j >> 2][j & 3];
;           rv[j] = (sc < 8) ? (xv[j] * cs - ov * sn) : (xv[j] * cs + ov * sn); }
;         kv = u32x4{pk2(rv[0], rv[1]), pk2(rv[2], rv[3]), pk2(rv[4], rv[5]), pk2(rv[6], rv[7])};
;       }
;       const int sw = ((row >> 4) & 3) * 4 + (row & 3);
;       *(u32x4*)(buf + row * 256 + ((sc ^ sw) << 4)) = kv;
;       const int rho = ((row >> 2) & 3) * 16 + (row >> 4) * 4 + (row & 3);
;       *(u32x4*)(buf + 16384 + ((rho >> 5) * 8 + (sc >> 1)) * 1024 + (((rho & 31) ^ ((sc >> 1) & 3)) * 32) + (sc & 1) * 16) = R.v[h];
	v_cvt_pk_bf16_f32 v76, v14, v15
	v_lshlrev_b32_e32 v14, 16, v87
	v_and_b32_e32 v15, 0xffff0000, v87
	v_add3_u32 v2, 0, v2, v28
	v_lshlrev_b32_e32 v28, 16, v103
	v_and_b32_e32 v29, 0xffff0000, v103
	v_pk_add_f32 v[24:25], v[24:25], v[42:43]
	v_mov_b32_e32 v38, v34
	v_mov_b32_e32 v39, v20
	v_cvt_pk_bf16_f32 v68, v30, v31
	v_cvt_pk_bf16_f32 v78, v16, v17
	v_pk_mul_f32 v[16:17], v[14:15], v[14:15]
	v_pk_mul_f32 v[30:31], v[28:29], v[28:29]
	v_pk_add_f32 v[24:25], v[38:39], v[24:25]
	v_mov_b32_e32 v20, v35
	v_pk_add_f32 v[20:21], v[20:21], v[24:25]
	v_mov_b32_e32 v24, v30
	v_mov_b32_e32 v25, v16
	v_pk_add_f32 v[20:21], v[24:25], v[20:21]
	v_mov_b32_e32 v16, v31
	v_pk_add_f32 v[16:17], v[16:17], v[20:21]
	v_cmp_gt_u32_e64 s[0:1], 8, v3
	v_bfi_b32 v171, -16, v4, v1
	v_mov_b32_dpp v21, v17 row_ror:8 row_mask:0xf bank_mask:0xf bound_ctrl:1
	v_mov_b32_dpp v20, v16 row_ror:8 row_mask:0xf bank_mask:0xf bound_ctrl:1
	v_pk_add_f32 v[16:17], v[16:17], v[20:21]
	v_or_b32_e32 v172, 15, v4
	v_lshl_add_u32 v5, v5, 8, 0
	v_mov_b32_dpp v21, v17 row_ror:4 row_mask:0xf bank_mask:0xf bound_ctrl:1
	v_mov_b32_dpp v20, v16 row_ror:4 row_mask:0xf bank_mask:0xf bound_ctrl:1
	v_pk_add_f32 v[16:17], v[16:17], v[20:21]
	v_mov_b64_e32 v[56:57], v[144:145]
	v_mov_b64_e32 v[52:53], v[140:141]
	v_mov_b32_dpp v21, v17 row_ror:2 row_mask:0xf bank_mask:0xf bound_ctrl:1
	v_mov_b32_dpp v20, v16 row_ror:2 row_mask:0xf bank_mask:0xf bound_ctrl:1
	v_pk_add_f32 v[16:17], v[16:17], v[20:21]
	v_mov_b64_e32 v[60:61], v[124:125]
	v_mov_b64_e32 v[64:65], v[128:129]
	v_mov_b32_dpp v21, v17 row_ror:1 row_mask:0xf bank_mask:0xf bound_ctrl:1
	v_mov_b32_dpp v20, v16 row_ror:1 row_mask:0xf bank_mask:0xf bound_ctrl:1
	v_pk_add_f32 v[16:17], v[16:17], v[20:21]
	v_add_u32_e32 v170, 0x8f, v149
	v_pk_fma_f32 v[20:21], v[16:17], s[84:85], v[194:195] op_sel_hi:[1,0,0]
	v_lshlrev_b32_e32 v17, 4, v1
	v_mul_f32_e32 v16, 0x4b800000, v21
	v_cmp_gt_f32_e32 vcc, s80, v21
	v_add_u32_e32 v173, 0x41, v149
	v_add_u32_e32 v174, 0x80, v171
	v_cndmask_b32_e32 v16, v21, v16, vcc
	v_rsq_f32_e32 v16, v16
	v_and_b32_e32 v21, 16, v17
	v_add_u32_e32 v167, v2, v21
	v_add_u32_e32 v209, s8, v161
	v_mul_f32_e32 v2, 0x45800000, v16
	v_cndmask_b32_e32 v2, v16, v2, vcc
	s_waitcnt vmcnt(0)
	v_pk_mul_f32 v[24:25], v[12:13], v[2:3] op_sel_hi:[1,0]
	v_pk_mul_f32 v[16:17], v[10:11], v[2:3] op_sel_hi:[1,0]
	v_pk_mul_f32 v[22:23], v[24:25], v[22:23]
	v_pk_mul_f32 v[24:25], v[6:7], v[2:3] op_sel_hi:[1,0]
	v_pk_mul_f32 v[16:17], v[16:17], v[26:27]
	v_pk_mul_f32 v[18:19], v[24:25], v[18:19]
	v_pk_mul_f32 v[24:25], v[8:9], v[2:3] op_sel_hi:[1,0]
	v_mul_f32_e32 v2, 0x4b800000, v20
	v_pk_mul_f32 v[14:15], v[24:25], v[14:15]
	v_mov_b32_dpp v24, v16 row_ror:8 row_mask:0xf bank_mask:0xf bound_ctrl:1
	v_mov_b32_dpp v25, v17 row_ror:8 row_mask:0xf bank_mask:0xf bound_ctrl:1
	v_pk_mul_f32 v[24:25], v[112:113], v[24:25]
	v_cmp_gt_f32_e32 vcc, s80, v20
	v_cndmask_b32_e64 v25, v25, -v25, s[0:1]
	v_cndmask_b32_e64 v24, v24, -v24, s[0:1]
	v_pk_fma_f32 v[16:17], v[96:97], v[16:17], v[24:25]
	v_mov_b32_dpp v25, v23 row_ror:8 row_mask:0xf bank_mask:0xf bound_ctrl:1
	v_mov_b32_dpp v24, v22 row_ror:8 row_mask:0xf bank_mask:0xf bound_ctrl:1
	v_pk_mul_f32 v[24:25], v[114:115], v[24:25]
	v_cndmask_b32_e32 v2, v20, v2, vcc
	v_cndmask_b32_e64 v25, v25, -v25, s[0:1]
	v_cndmask_b32_e64 v24, v24, -v24, s[0:1]
	v_pk_fma_f32 v[22:23], v[98:99], v[22:23], v[24:25]
	v_mov_b32_dpp v25, v19 row_ror:8 row_mask:0xf bank_mask:0xf bound_ctrl:1
	v_mov_b32_dpp v24, v18 row_ror:8 row_mask:0xf bank_mask:0xf bound_ctrl:1
	v_pk_mul_f32 v[24:25], v[108:109], v[24:25]
	v_rsq_f32_e32 v2, v2
	v_cndmask_b32_e64 v25, v25, -v25, s[0:1]
	v_cndmask_b32_e64 v24, v24, -v24, s[0:1]
	v_pk_fma_f32 v[18:19], v[92:93], v[18:19], v[24:25]
	v_mov_b32_dpp v25, v15 row_ror:8 row_mask:0xf bank_mask:0xf bound_ctrl:1
	v_mov_b32_dpp v24, v14 row_ror:8 row_mask:0xf bank_mask:0xf bound_ctrl:1
	v_pk_mul_f32 v[24:25], v[110:111], v[24:25]
	v_mov_b64_e32 v[58:59], v[146:147]
	v_cndmask_b32_e64 v25, v25, -v25, s[0:1]
	v_cndmask_b32_e64 v24, v24, -v24, s[0:1]
	v_pk_fma_f32 v[24:25], v[94:95], v[14:15], v[24:25]
	v_cvt_pk_bf16_f32 v14, v16, v17
	v_cvt_pk_bf16_f32 v15, v22, v23
	v_cvt_pk_bf16_f32 v16, v18, v19
	v_cvt_pk_bf16_f32 v17, v24, v25
	ds_write_b128 v151, v[14:17]
	ds_write_b128 v167, v[88:91] offset:16384
	v_mul_f32_e32 v14, 0x45800000, v2
	v_cndmask_b32_e32 v2, v2, v14, vcc
	v_pk_mul_f32 v[10:11], v[10:11], v[2:3] op_sel_hi:[1,0]
	v_pk_mul_f32 v[12:13], v[12:13], v[2:3] op_sel_hi:[1,0]
	v_pk_mul_f32 v[10:11], v[10:11], v[40:41]
	v_pk_mul_f32 v[12:13], v[12:13], v[36:37]
	v_pk_mul_f32 v[6:7], v[6:7], v[2:3] op_sel_hi:[1,0]
	v_mov_b32_dpp v14, v10 row_ror:8 row_mask:0xf bank_mask:0xf bound_ctrl:1
	v_mov_b32_dpp v15, v11 row_ror:8 row_mask:0xf bank_mask:0xf bound_ctrl:1
	v_pk_mul_f32 v[14:15], v[128:129], v[14:15]
	v_pk_mul_f32 v[6:7], v[6:7], v[32:33]
	v_cndmask_b32_e64 v15, v15, -v15, s[0:1]
	v_cndmask_b32_e64 v14, v14, -v14, s[0:1]
	v_pk_fma_f32 v[10:11], v[120:121], v[10:11], v[14:15]
	v_mov_b32_dpp v15, v13 row_ror:8 row_mask:0xf bank_mask:0xf bound_ctrl:1
	v_mov_b32_dpp v14, v12 row_ror:8 row_mask:0xf bank_mask:0xf bound_ctrl:1
	v_pk_mul_f32 v[14:15], v[130:131], v[14:15]
	v_pk_mul_f32 v[8:9], v[8:9], v[2:3] op_sel_hi:[1,0]
	v_cndmask_b32_e64 v15, v15, -v15, s[0:1]
; #define LDS_BARRIER() do { asm volatile("s_waitcnt lgkmcnt(0)" ::: "memory"); __builtin_amdgcn_s_barrier(); asm volatile("" ::: "memory"); } while (0)
; template <bool DIL>
; __device__ void attn_item(const Params& p, int layer, int idx, char* shm, int wv, AttnPre& R0, AttnPre& R1, AttnTab& Tb, bool have_pre, int next_idx) {
;     ...
;       const int sw = ((row >> 4) & 3) * 4 + (row & 3);
;       *(u32x4*)(buf + row * 256 + ((sc ^ sw) << 4)) = kv;
;       const int rho = ((row >> 2) & 3) * 16 + (row >> 4) * 4 + (row & 3);
;       *(u32x4*)(buf + 16384 + ((rho >> 5) * 8 + (sc >> 1)) * 1024 + (((rho & 31) ^ ((sc >> 1) & 3)) * 32) + (sc & 1) * 16) = R.v[h];
;     ...
;   f32x4 o[8]; for (int d = 0; d < 8; ++d) o[d] = f32x4{0.f, 0.f, 0.f, 0.f};
;   float carry = 0.f;
;   float mrun = -__builtin_inff(), lrun = 0.f;
;   const float scale = 0.08838834764831845f;
;   const int krow_m = (n >> 2) * 16 + (n & 3);
;   __attribute__((address_space(3))) int* flags = (__attribute__((address_space(3))) int*)(shm + 65536);
;   stage(shm, R0);
;   LDS_BARRIER();
	v_cndmask_b32_e64 v14, v14, -v14, s[0:1]
	v_pk_fma_f32 v[12:13], v[122:123], v[12:13], v[14:15]
	v_mov_b32_dpp v15, v7 row_ror:8 row_mask:0xf bank_mask:0xf bound_ctrl:1
	v_mov_b32_dpp v14, v6 row_ror:8 row_mask:0xf bank_mask:0xf bound_ctrl:1
	v_pk_mul_f32 v[14:15], v[124:125], v[14:15]
	v_pk_mul_f32 v[8:9], v[8:9], v[28:29]
	v_cndmask_b32_e64 v15, v15, -v15, s[0:1]
	v_cndmask_b32_e64 v14, v14, -v14, s[0:1]
	v_pk_fma_f32 v[14:15], v[116:117], v[6:7], v[14:15]
	v_mov_b32_dpp v6, v8 row_ror:8 row_mask:0xf bank_mask:0xf bound_ctrl:1
	v_mov_b32_dpp v7, v9 row_ror:8 row_mask:0xf bank_mask:0xf bound_ctrl:1
	v_pk_mul_f32 v[6:7], v[126:127], v[6:7]
	v_add_u32_e32 v2, 32, v161
	v_cndmask_b32_e64 v7, v7, -v7, s[0:1]
	v_cndmask_b32_e64 v6, v6, -v6, s[0:1]
	v_pk_fma_f32 v[16:17], v[118:119], v[8:9], v[6:7]
	v_cvt_pk_bf16_f32 v6, v10, v11
	v_ashrrev_i32_e32 v10, 4, v2
	v_lshlrev_b32_e32 v11, 2, v10
	v_and_b32_e32 v11, 12, v11
	v_bitop3_b32 v11, v11, v3, v46 bitop3:0x36
	v_lshl_add_u32 v2, v2, 8, 0
	v_lshlrev_b32_e32 v11, 4, v11
	v_cvt_pk_bf16_f32 v7, v12, v13
	v_cvt_pk_bf16_f32 v8, v14, v15
	v_cvt_pk_bf16_f32 v9, v16, v17
	v_add_u32_e32 v168, v2, v11
	v_add_u32_e32 v2, v10, v47
	ds_write_b128 v168, v[6:9]
	v_lshlrev_b32_e32 v6, 2, v2
	v_and_b32_e32 v6, 28, v6
	v_and_or_b32 v2, v2, s4, v48
	v_bitop3_b32 v6, v6, v49, v46 bitop3:0x36
	v_lshlrev_b32_e32 v2, 10, v2
	v_lshlrev_b32_e32 v6, 5, v6
	v_add3_u32 v2, 0, v2, v6
	v_bitop3_b32 v7, v157, v3, 4 bitop3:0x36
	v_bitop3_b32 v8, v157, v3, 8 bitop3:0x36
	v_bitop3_b32 v3, v157, v3, 12 bitop3:0x36
	s_add_i32 s4, 0, 0x4000
	v_add_u32_e32 v169, v2, v21
	v_lshlrev_b32_e32 v2, 3, v1
	v_lshlrev_b32_e32 v9, 4, v3
	v_lshlrev_b32_e32 v3, 7, v157
	s_cmp_lg_u32 s4, -1
	v_and_or_b32 v3, v2, 24, v3
	s_cselect_b32 s4, s4, 0
	v_add_u32_e32 v4, s4, v3
	s_movk_i32 s4, 0x60
	v_and_b32_e32 v160, 0x78, v2
	v_and_b32_e32 v10, 0x60, v2
	v_bitop3_b32 v11, v2, 32, v246 bitop3:0x6c
	v_bitop3_b32 v13, v2, 64, v246 bitop3:0x6c
	v_bitop3_b32 v2, v2, s4, v2 bitop3:0xc
	s_add_i32 s4, 0, 0xc000
	s_cmp_lg_u32 s4, -1
	s_cselect_b32 s4, s4, 0
	v_add_u32_e32 v3, s4, v3
	v_bitop3_b32 v6, v157, v1, 15 bitop3:0x78
	v_add_u32_e32 v175, v4, v10
	v_add_u32_e32 v12, v4, v11
	v_add_u32_e32 v14, v4, v13
	v_add_u32_e32 v4, v4, v2
	v_add_u32_e32 v2, v3, v2
	v_lshlrev_b32_e32 v1, 5, v1
	ds_write_b128 v169, v[104:107] offset:16384
	v_lshlrev_b32_e32 v6, 4, v6
	v_lshlrev_b32_e32 v7, 4, v7
	v_lshlrev_b32_e32 v8, 4, v8
	v_add_u32_e32 v181, 0xc00, v4
	v_add_u32_e32 v182, 0x2c00, v4
	v_add_u32_e32 v189, 0x1c00, v4
	v_add_u32_e32 v190, 0x3c00, v4
	v_add_u32_e32 v191, v3, v10
	v_add_u32_e32 v4, v3, v11
	v_add_u32_e32 v10, v3, v13
	v_add_u32_e32 v199, 0xc00, v2
	v_add_u32_e32 v200, 0x2c00, v2
	v_add_u32_e32 v207, 0x1c00, v2
	v_add_u32_e32 v208, 0x3c00, v2
	v_and_b32_e32 v2, 0xe0, v1
	v_mov_b32_e32 v3, v0
	s_waitcnt lgkmcnt(0)
	s_barrier
	v_add_u32_e32 v177, 0x400, v12
	v_add_u32_e32 v178, 0x2400, v12
	v_add_u32_e32 v179, 0x800, v14
	v_add_u32_e32 v180, 0x2800, v14
	v_add_u32_e32 v185, 0x1400, v12
	v_add_u32_e32 v186, 0x3400, v12
	v_add_u32_e32 v187, 0x1800, v14
	v_add_u32_e32 v188, 0x3800, v14
	v_add_u32_e32 v193, 0x400, v4
	v_add_u32_e32 v196, 0x2400, v4
	v_add_u32_e32 v197, 0x800, v10
	v_add_u32_e32 v198, 0x2800, v10
	v_add_u32_e32 v203, 0x1400, v4
	v_add_u32_e32 v204, 0x3400, v4
	v_add_u32_e32 v205, 0x1800, v10
	v_add_u32_e32 v206, 0x3800, v10
	v_lshl_add_u64 v[162:163], s[50:51], 0, v[2:3]
	v_lshl_add_u64 v[164:165], s[44:45], 0, v[2:3]
	v_mov_b32_e32 v2, v0
	v_add_u32_e32 v210, v5, v6
	v_add_u32_e32 v211, v5, v7
	v_add_u32_e32 v212, v5, v8
	v_add_u32_e32 v213, v5, v9
	v_mov_b64_e32 v[24:25], v[104:105]
	v_mov_b64_e32 v[8:9], v[88:89]
	v_mov_b64_e32 v[20:21], v[100:101]
	v_mov_b64_e32 v[4:5], v[84:85]
	v_mov_b64_e32 v[28:29], v[108:109]
	v_mov_b64_e32 v[32:33], v[112:113]
	v_mov_b64_e32 v[12:13], v[92:93]
	v_mov_b64_e32 v[16:17], v[96:97]
	v_mov_b32_e32 v1, v0
	v_mov_b64_e32 v[26:27], v[106:107]
	v_mov_b64_e32 v[10:11], v[90:91]
	v_mov_b64_e32 v[22:23], v[102:103]
	v_mov_b64_e32 v[6:7], v[86:87]
	v_mov_b64_e32 v[40:41], v[136:137]
	v_mov_b64_e32 v[36:37], v[132:133]
	v_mov_b64_e32 v[30:31], v[110:111]
	v_mov_b64_e32 v[34:35], v[114:115]
	v_mov_b64_e32 v[44:45], v[116:117]
	v_mov_b64_e32 v[48:49], v[120:121]
	v_mov_b64_e32 v[14:15], v[94:95]
	v_mov_b64_e32 v[18:19], v[98:99]
	v_mov_b64_e32 v[102:103], v[2:3]
	v_mov_b64_e32 v[106:107], v[2:3]
	v_mov_b64_e32 v[110:111], v[2:3]
	v_mov_b64_e32 v[114:115], v[2:3]
	v_mov_b64_e32 v[86:87], v[2:3]
	v_mov_b64_e32 v[90:91], v[2:3]
	v_mov_b64_e32 v[94:95], v[2:3]
	v_mov_b64_e32 v[98:99], v[2:3]
	v_add_u32_e32 v176, 0x2000, v175
	v_add_u32_e32 v183, 0x1000, v175
	v_add_u32_e32 v184, 0x3000, v175
	v_add_u32_e32 v192, 0x2000, v191
	v_add_u32_e32 v201, 0x1000, v191
	v_add_u32_e32 v202, 0x3000, v191
	v_mov_b64_e32 v[42:43], v[138:139]
	v_mov_b64_e32 v[54:55], v[142:143]
	v_mov_b64_e32 v[38:39], v[134:135]
	v_mov_b64_e32 v[62:63], v[126:127]
	v_mov_b64_e32 v[66:67], v[130:131]
	v_mov_b64_e32 v[46:47], v[118:119]
	v_mov_b64_e32 v[50:51], v[122:123]
	v_mov_b64_e32 v[100:101], v[0:1]
	v_mov_b64_e32 v[104:105], v[0:1]
	v_mov_b64_e32 v[108:109], v[0:1]
	v_mov_b64_e32 v[112:113], v[0:1]
	v_mov_b64_e32 v[84:85], v[0:1]
	v_mov_b64_e32 v[88:89], v[0:1]
	v_mov_b64_e32 v[92:93], v[0:1]
	v_mov_b64_e32 v[96:97], v[0:1]

; __device__ void mix_phase(const Params& p, int layer, bf16* shm, int wv) {
;     ...
;     unsigned w1a[2][4][2][2];
;     _Pragma("unroll") for (int ai = 0; ai < 2; ++ai) _Pragma("unroll") for (int m = 0; m < 4; ++m) _Pragma("unroll") for (int bj = 0; bj < 2; ++bj) _Pragma("unroll") for (int n = 0; n < 2; ++n)
;       w1a[ai][m][bj][n] = *(const unsigned*)(Gp + ((size_t)pm_ * 16 + 8 + pn_) * 65536 + (ai * 16 + m * 4 + bj * 2 + n) * 2048 + tid * 4);
;     asm volatile("s_waitcnt vmcnt(0)" ::: "memory");
;     _Pragma("unroll") for (int ai = 0; ai < 2; ++ai) {
;       unsigned (&w1)[4][2][2] = w1a[ai];
;       _Pragma("unroll") for (int m = 0; m < 4; ++m) _Pragma("unroll") for (int bj = 0; bj < 2; ++bj) _Pragma("unroll") for (int n = 0; n < 2; ++n) {
;         f32x4 g1 = gate_u8(w1[m][bj][n]); f32x4 v = acc[ai][bj][m][n];
;         for (int j = 0; j < 4; ++j) v[j] *= fmaxf(g1[j], 1.f / 510.f);
;         u32x2 o = {pk2(v[0], v[1]), pk2(v[2], v[3])};
;         *(u32x2*)stg_ptr(shm, bj, wr * 64 + m * 16 + fr, wc * 8 + n * 4 + fq) = o; }
.LBB0_396:
	s_or_b64 exec, exec, s[12:13]
	s_mov_b32 s1, 0xffffc0
	v_lshlrev_b32_e32 v130, 2, v249
	v_ashrrev_i32_e32 v131, 31, v130
	v_lshl_add_u64 v[130:131], s[10:11], 0, v[130:131]
	v_add_co_u32_e32 v134, vcc, 0x80000, v130
	s_mov_b64 s[10:11], 0x80000
	s_nop 0
	v_addc_co_u32_e32 v135, vcc, 0, v131, vcc
	v_add_co_u32_e32 v136, vcc, 0x81000, v130
	v_lshl_add_u64 v[132:133], v[130:131], 0, s[10:11]
	s_nop 0
	v_addc_co_u32_e32 v137, vcc, 0, v131, vcc
	v_add_co_u32_e32 v138, vcc, 0x82000, v130
	v_and_b32_e32 v1, 15, v249
	s_nop 0
	v_addc_co_u32_e32 v139, vcc, 0, v131, vcc
	v_add_co_u32_e32 v140, vcc, 0x83000, v130
	v_lshlrev_b32_e32 v196, 4, v1
	s_nop 0
	v_addc_co_u32_e32 v141, vcc, 0, v131, vcc
	global_load_dword v182, v[134:135], off
	global_load_dword v184, v[136:137], off
	global_load_dword v185, v[136:137], off offset:2048
	global_load_dword v186, v[138:139], off
	global_load_dword v187, v[138:139], off offset:2048
	global_load_dword v188, v[140:141], off
	global_load_dword v189, v[140:141], off offset:2048
	global_load_dword v190, v[132:133], off offset:2048
	v_add_co_u32_e32 v132, vcc, 0x84000, v130
	s_lshl_b64 s[8:9], s[8:9], 1
	s_nop 0
	v_addc_co_u32_e32 v133, vcc, 0, v131, vcc
	v_add_co_u32_e32 v134, vcc, 0x85000, v130
	v_bfe_u32 v172, v249, 4, 7
	s_nop 0
	v_addc_co_u32_e32 v135, vcc, 0, v131, vcc
	v_add_co_u32_e32 v136, vcc, 0x86000, v130
	s_add_u32 s5, s31, s8
	s_nop 0
	v_addc_co_u32_e32 v137, vcc, 0, v131, vcc
	v_add_co_u32_e32 v138, vcc, 0x87000, v130
	s_waitcnt vmcnt(7)
	v_cvt_f32_ubyte1_e32 v198, v182
	v_addc_co_u32_e32 v139, vcc, 0, v131, vcc
	global_load_dword v191, v[132:133], off
	global_load_dword v192, v[132:133], off offset:2048
	global_load_dword v193, v[134:135], off
	global_load_dword v180, v[134:135], off offset:2048
	global_load_dword v176, v[136:137], off
	global_load_dword v171, v[136:137], off offset:2048
	global_load_dword v170, v[138:139], off
	global_load_dword v169, v[138:139], off offset:2048
	v_add_co_u32_e32 v132, vcc, 0x88000, v130
	v_cvt_f32_ubyte2_e32 v199, v182
	s_nop 0
	v_addc_co_u32_e32 v133, vcc, 0, v131, vcc
	v_add_co_u32_e32 v134, vcc, 0x89000, v130
	v_cvt_f32_ubyte3_e32 v200, v182
	s_nop 0
	v_addc_co_u32_e32 v135, vcc, 0, v131, vcc
	v_add_co_u32_e32 v136, vcc, 0x8a000, v130
	s_nop 1
	v_addc_co_u32_e32 v137, vcc, 0, v131, vcc
	v_add_co_u32_e32 v138, vcc, 0x8b000, v130
	s_nop 1
	v_addc_co_u32_e32 v139, vcc, 0, v131, vcc
	global_load_dword v168, v[132:133], off
	global_load_dword v167, v[132:133], off offset:2048
	global_load_dword v166, v[134:135], off
	global_load_dword v165, v[134:135], off offset:2048
	global_load_dword v164, v[136:137], off
	global_load_dword v163, v[136:137], off offset:2048
	global_load_dword v162, v[138:139], off
	global_load_dword v160, v[138:139], off offset:2048
	v_add_co_u32_e32 v132, vcc, 0x8c000, v130
	s_nop 1
	v_addc_co_u32_e32 v133, vcc, 0, v131, vcc
	v_add_co_u32_e32 v134, vcc, 0x8d000, v130
	s_nop 1
	v_addc_co_u32_e32 v135, vcc, 0, v131, vcc
	v_add_co_u32_e32 v136, vcc, 0x8e000, v130
	s_nop 1
	v_addc_co_u32_e32 v137, vcc, 0, v131, vcc
	v_add_co_u32_e32 v130, vcc, 0x8f000, v130
	s_nop 1
	v_addc_co_u32_e32 v131, vcc, 0, v131, vcc
	global_load_dword v161, v[132:133], off
	global_load_dword v159, v[132:133], off offset:2048
	global_load_dword v158, v[134:135], off
	global_load_dword v157, v[134:135], off offset:2048
	global_load_dword v156, v[136:137], off
	global_load_dword v153, v[136:137], off offset:2048
	global_load_dword v150, v[130:131], off
	global_load_dword v147, v[130:131], off offset:2048
	v_add_u32_e32 v132, 0x200, v249
	v_lshrrev_b32_e32 v131, 2, v249
	v_cmp_gt_u32_e32 vcc, s85, v249
	v_lshrrev_b32_e32 v133, 4, v132
	v_and_or_b32 v183, v131, s1, v1
	v_cndmask_b32_e32 v1, v244, v245, vcc
	v_cmp_gt_u32_e32 vcc, s85, v132
	v_xor_b32_e32 v133, v133, v249
	v_bfe_u32 v173, v132, 4, 7
	v_cndmask_b32_e32 v134, v244, v245, vcc
	v_lshlrev_b32_e32 v133, 4, v133
	v_add_u32_e32 v134, 0, v134
	v_lshlrev_b32_e32 v135, 8, v173
	v_and_b32_e32 v133, 0xf0, v133
	v_add3_u32 v146, v134, v135, v133
	v_add_u32_e32 v134, 0x400, v249
	v_lshrrev_b32_e32 v135, 4, v134
	v_cmp_gt_u32_e32 vcc, s85, v134
	v_xor_b32_e32 v135, v135, v249
	v_bfe_u32 v174, v134, 4, 7
	v_cndmask_b32_e32 v136, v244, v245, vcc
	v_lshlrev_b32_e32 v135, 4, v135
	v_add_u32_e32 v136, 0, v136
	v_lshlrev_b32_e32 v137, 8, v174
	v_and_b32_e32 v135, 0xf0, v135
	v_add3_u32 v148, v136, v137, v135
	v_add_u32_e32 v136, 0x600, v249
	v_lshrrev_b32_e32 v137, 4, v136
	v_cmp_gt_u32_e32 vcc, s85, v136
	v_xor_b32_e32 v137, v137, v249
	v_bfe_u32 v175, v136, 4, 7
	v_cndmask_b32_e32 v138, v244, v245, vcc
	v_lshlrev_b32_e32 v137, 4, v137
	v_add_u32_e32 v138, 0, v138
	v_lshlrev_b32_e32 v139, 8, v175
	v_and_b32_e32 v137, 0xf0, v137
	v_add3_u32 v149, v138, v139, v137
	v_add_u32_e32 v138, 0x800, v249
	v_lshrrev_b32_e32 v139, 4, v138
	v_cmp_lt_u32_e32 vcc, s65, v249
	v_xor_b32_e32 v139, v139, v249
	v_bfe_u32 v177, v138, 4, 7
	v_cndmask_b32_e32 v140, v244, v245, vcc
	v_lshlrev_b32_e32 v139, 4, v139
	v_add_u32_e32 v140, 0, v140
	v_lshlrev_b32_e32 v141, 8, v177
	v_and_b32_e32 v139, 0xf0, v139
	v_add3_u32 v151, v140, v141, v139
	v_add_u32_e32 v140, 0xa00, v249
	v_lshrrev_b32_e32 v141, 4, v140
	v_cmp_gt_u32_e32 vcc, s85, v140
	v_xor_b32_e32 v141, v141, v249
	v_bfe_u32 v178, v140, 4, 7
	v_cndmask_b32_e32 v142, v244, v245, vcc
	v_lshlrev_b32_e32 v141, 4, v141
	v_add_u32_e32 v142, 0, v142
	v_lshlrev_b32_e32 v143, 8, v178
	v_and_b32_e32 v141, 0xf0, v141
	v_add3_u32 v152, v142, v143, v141
	v_add_u32_e32 v142, 0xc00, v249
	v_lshrrev_b32_e32 v143, 4, v142
	v_cmp_gt_u32_e32 vcc, s85, v142
	v_xor_b32_e32 v143, v143, v249
	v_bfe_u32 v179, v142, 4, 7
	v_cndmask_b32_e32 v144, v244, v245, vcc
	v_lshlrev_b32_e32 v143, 4, v143
	v_add_u32_e32 v144, 0, v144
	v_lshlrev_b32_e32 v145, 8, v179
	v_and_b32_e32 v143, 0xf0, v143
	v_add3_u32 v154, v144, v145, v143
	v_add_u32_e32 v144, 0xe00, v249
	v_lshrrev_b32_e32 v145, 4, v144
	v_cmp_gt_u32_e32 vcc, s85, v144
	v_xor_b32_e32 v145, v145, v249
	v_bfe_u32 v181, v144, 4, 7
	v_cndmask_b32_e32 v155, v244, v245, vcc
	v_lshlrev_b32_e32 v145, 4, v145
	v_add_u32_e32 v155, 0, v155
	v_lshlrev_b32_e32 v197, 8, v181
	v_and_b32_e32 v145, 0xf0, v145
	v_add3_u32 v155, v155, v197, v145
	v_lshl_add_u32 v197, v183, 8, 0
	v_cvt_f32_ubyte0_e32 v183, v182
	v_mul_f32_e32 v182, 0x3b808081, v183
	v_mul_f32_e32 v183, 0x3b808081, v198
	v_max_f32_e32 v182, 0x3b008081, v182
	v_max_f32_e32 v183, 0x3b008081, v183
	v_pk_mul_f32 v[126:127], v[126:127], v[182:183]
	v_mul_f32_e32 v182, 0x3b808081, v199
	v_mul_f32_e32 v183, 0x3b808081, v200
	v_max_f32_e32 v182, 0x3b008081, v182
	v_max_f32_e32 v183, 0x3b008081, v183
	v_pk_mul_f32 v[128:129], v[128:129], v[182:183]
	v_cvt_pk_bf16_f32 v182, v126, v127
	v_lshrrev_b32_e32 v126, 1, v249
	v_and_b32_e32 v126, 24, v126
	v_and_b32_e32 v127, 0xc0, v249
	v_cvt_pk_bf16_f32 v183, v128, v129
	v_or_b32_e32 v198, v126, v127
	v_bitop3_b32 v127, v126, v196, v127 bitop3:0x36
	s_waitcnt vmcnt(24)
; __device__ void mix_phase(const Params& p, int layer, bf16* shm, int wv) {
;     ...
;     _Pragma("unroll") for (int ai = 0; ai < 2; ++ai) {
;       unsigned (&w1)[4][2][2] = w1a[ai];
;       _Pragma("unroll") for (int m = 0; m < 4; ++m) _Pragma("unroll") for (int bj = 0; bj < 2; ++bj) _Pragma("unroll") for (int n = 0; n < 2; ++n) {
;         f32x4 g1 = gate_u8(w1[m][bj][n]); f32x4 v = acc[ai][bj][m][n];
;         for (int j = 0; j < 4; ++j) v[j] *= fmaxf(g1[j], 1.f / 510.f);
;         u32x2 o = {pk2(v[0], v[1]), pk2(v[2], v[3])};
;         *(u32x2*)stg_ptr(shm, bj, wr * 64 + m * 16 + fr, wc * 8 + n * 4 + fq) = o; }
	v_cvt_f32_ubyte0_e32 v128, v190
	v_cvt_f32_ubyte1_e32 v129, v190
	v_add_u32_e32 v126, v197, v127
	v_mul_f32_e32 v128, 0x3b808081, v128
	v_mul_f32_e32 v129, 0x3b808081, v129
	s_waitcnt vmcnt(0)
	ds_write_b64 v126, v[182:183] offset:32768
	v_cvt_f32_ubyte2_e32 v182, v190
	v_cvt_f32_ubyte3_e32 v183, v190
	v_max_f32_e32 v128, 0x3b008081, v128
	v_max_f32_e32 v129, 0x3b008081, v129
	v_pk_mul_f32 v[122:123], v[122:123], v[128:129]
	v_mul_f32_e32 v128, 0x3b808081, v182
	v_mul_f32_e32 v129, 0x3b808081, v183
	v_max_f32_e32 v128, 0x3b008081, v128
	v_max_f32_e32 v129, 0x3b008081, v129
	v_pk_mul_f32 v[124:125], v[124:125], v[128:129]
	v_cvt_f32_ubyte2_e32 v183, v184
	v_cvt_pk_bf16_f32 v129, v124, v125
	v_cvt_f32_ubyte0_e32 v124, v184
	v_cvt_f32_ubyte1_e32 v125, v184
	v_mul_f32_e32 v124, 0x3b808081, v124
	v_mul_f32_e32 v125, 0x3b808081, v125
	v_cvt_f32_ubyte3_e32 v184, v184
	v_max_f32_e32 v124, 0x3b008081, v124
	v_max_f32_e32 v125, 0x3b008081, v125
	v_pk_mul_f32 v[118:119], v[118:119], v[124:125]
	v_mul_f32_e32 v124, 0x3b808081, v183
	v_mul_f32_e32 v125, 0x3b808081, v184
	v_max_f32_e32 v124, 0x3b008081, v124
	v_max_f32_e32 v125, 0x3b008081, v125
	v_add_u32_e32 v182, 0x18000, v197
	v_pk_mul_f32 v[120:121], v[120:121], v[124:125]
	v_cvt_pk_bf16_f32 v118, v118, v119
	v_cvt_pk_bf16_f32 v119, v120, v121
	v_add_u32_e32 v120, v182, v127
	ds_write_b64 v120, v[118:119]
	v_cvt_f32_ubyte0_e32 v118, v185
	v_cvt_f32_ubyte1_e32 v119, v185
	v_mul_f32_e32 v118, 0x3b808081, v118
	v_mul_f32_e32 v119, 0x3b808081, v119
	v_cvt_f32_ubyte2_e32 v121, v185
	v_cvt_f32_ubyte3_e32 v124, v185
	v_max_f32_e32 v118, 0x3b008081, v118
	v_max_f32_e32 v119, 0x3b008081, v119
	v_pk_mul_f32 v[114:115], v[114:115], v[118:119]
	v_mul_f32_e32 v118, 0x3b808081, v121
	v_mul_f32_e32 v119, 0x3b808081, v124
	v_max_f32_e32 v118, 0x3b008081, v118
	v_max_f32_e32 v119, 0x3b008081, v119
	v_cvt_pk_bf16_f32 v128, v122, v123
	v_bitop3_b32 v123, v198, v196, 32 bitop3:0x36
	v_pk_mul_f32 v[116:117], v[116:117], v[118:119]
	v_cvt_pk_bf16_f32 v114, v114, v115
	v_cvt_pk_bf16_f32 v115, v116, v117
	v_add_u32_e32 v116, v182, v123
	ds_write_b64 v116, v[114:115]
	v_cvt_f32_ubyte0_e32 v114, v186
	v_cvt_f32_ubyte1_e32 v115, v186
	v_mul_f32_e32 v114, 0x3b808081, v114
	v_mul_f32_e32 v115, 0x3b808081, v115
	v_cvt_f32_ubyte2_e32 v117, v186
	v_cvt_f32_ubyte3_e32 v118, v186
	v_max_f32_e32 v114, 0x3b008081, v114
	v_max_f32_e32 v115, 0x3b008081, v115
	v_pk_mul_f32 v[110:111], v[110:111], v[114:115]
	v_mul_f32_e32 v114, 0x3b808081, v117
	v_mul_f32_e32 v115, 0x3b808081, v118
	v_max_f32_e32 v114, 0x3b008081, v114
	v_max_f32_e32 v115, 0x3b008081, v115
	v_pk_mul_f32 v[112:113], v[112:113], v[114:115]
	v_cvt_pk_bf16_f32 v110, v110, v111
	v_cvt_pk_bf16_f32 v111, v112, v113
	ds_write_b64 v126, v[110:111] offset:36864
	v_cvt_f32_ubyte0_e32 v110, v187
	v_cvt_f32_ubyte1_e32 v111, v187
	v_mul_f32_e32 v110, 0x3b808081, v110
	v_mul_f32_e32 v111, 0x3b808081, v111
	v_cvt_f32_ubyte2_e32 v112, v187
	v_cvt_f32_ubyte3_e32 v113, v187
	v_max_f32_e32 v110, 0x3b008081, v110
	v_max_f32_e32 v111, 0x3b008081, v111
	v_pk_mul_f32 v[106:107], v[106:107], v[110:111]
	v_mul_f32_e32 v110, 0x3b808081, v112
	v_mul_f32_e32 v111, 0x3b808081, v113
	v_max_f32_e32 v110, 0x3b008081, v110
	v_max_f32_e32 v111, 0x3b008081, v111
	v_pk_mul_f32 v[108:109], v[108:109], v[110:111]
	v_add_u32_e32 v122, v197, v123
	v_cvt_pk_bf16_f32 v106, v106, v107
	v_cvt_pk_bf16_f32 v107, v108, v109
	ds_write2st64_b64 v122, v[128:129], v[106:107] offset0:64 offset1:72
	v_cvt_f32_ubyte0_e32 v106, v188
	v_cvt_f32_ubyte1_e32 v107, v188
	v_mul_f32_e32 v106, 0x3b808081, v106
	v_mul_f32_e32 v107, 0x3b808081, v107
	v_cvt_f32_ubyte2_e32 v109, v188
	v_cvt_f32_ubyte3_e32 v110, v188
	v_max_f32_e32 v106, 0x3b008081, v106
	v_max_f32_e32 v107, 0x3b008081, v107
	v_pk_mul_f32 v[102:103], v[102:103], v[106:107]
	v_mul_f32_e32 v106, 0x3b808081, v109
	v_mul_f32_e32 v107, 0x3b808081, v110
	v_max_f32_e32 v106, 0x3b008081, v106
	v_max_f32_e32 v107, 0x3b008081, v107
	v_add_u32_e32 v108, 0x19000, v197
	v_pk_mul_f32 v[104:105], v[104:105], v[106:107]
	v_cvt_pk_bf16_f32 v102, v102, v103
	v_cvt_pk_bf16_f32 v103, v104, v105
	v_add_u32_e32 v106, v108, v127
	ds_write_b64 v106, v[102:103]
	v_cvt_f32_ubyte0_e32 v102, v189
	v_cvt_f32_ubyte1_e32 v103, v189
	v_mul_f32_e32 v102, 0x3b808081, v102
	v_mul_f32_e32 v103, 0x3b808081, v103
	v_cvt_f32_ubyte2_e32 v104, v189
	v_cvt_f32_ubyte3_e32 v105, v189
	v_max_f32_e32 v102, 0x3b008081, v102
	v_max_f32_e32 v103, 0x3b008081, v103
	v_pk_mul_f32 v[98:99], v[98:99], v[102:103]
	v_mul_f32_e32 v102, 0x3b808081, v104
	v_mul_f32_e32 v103, 0x3b808081, v105
	v_max_f32_e32 v102, 0x3b008081, v102
	v_max_f32_e32 v103, 0x3b008081, v103
	v_pk_mul_f32 v[100:101], v[100:101], v[102:103]
	v_cvt_pk_bf16_f32 v98, v98, v99
	v_cvt_pk_bf16_f32 v99, v100, v101
	v_add_u32_e32 v107, v108, v123
	ds_write_b64 v107, v[98:99]
	s_waitcnt vmcnt(23)
	v_cvt_f32_ubyte0_e32 v98, v191
	v_cvt_f32_ubyte1_e32 v99, v191
	v_mul_f32_e32 v98, 0x3b808081, v98
	v_mul_f32_e32 v99, 0x3b808081, v99
	v_cvt_f32_ubyte2_e32 v100, v191
	v_cvt_f32_ubyte3_e32 v101, v191
	v_max_f32_e32 v98, 0x3b008081, v98
	v_max_f32_e32 v99, 0x3b008081, v99
	v_pk_mul_f32 v[94:95], v[94:95], v[98:99]
	v_mul_f32_e32 v98, 0x3b808081, v100
	v_mul_f32_e32 v99, 0x3b808081, v101
	v_max_f32_e32 v98, 0x3b008081, v98
	v_max_f32_e32 v99, 0x3b008081, v99
	v_pk_mul_f32 v[96:97], v[96:97], v[98:99]
	v_cvt_pk_bf16_f32 v94, v94, v95
	v_cvt_pk_bf16_f32 v95, v96, v97
	ds_write_b64 v126, v[94:95] offset:40960
	s_waitcnt vmcnt(22)
; __device__ void mix_phase(const Params& p, int layer, bf16* shm, int wv) {
;     ...
;     _Pragma("unroll") for (int ai = 0; ai < 2; ++ai) {
;       unsigned (&w1)[4][2][2] = w1a[ai];
;       _Pragma("unroll") for (int m = 0; m < 4; ++m) _Pragma("unroll") for (int bj = 0; bj < 2; ++bj) _Pragma("unroll") for (int n = 0; n < 2; ++n) {
;         f32x4 g1 = gate_u8(w1[m][bj][n]); f32x4 v = acc[ai][bj][m][n];
;         for (int j = 0; j < 4; ++j) v[j] *= fmaxf(g1[j], 1.f / 510.f);
;         u32x2 o = {pk2(v[0], v[1]), pk2(v[2], v[3])};
;         *(u32x2*)stg_ptr(shm, bj, wr * 64 + m * 16 + fr, wc * 8 + n * 4 + fq) = o; }
;       stg_flush(shm, tid, MX + (size_t)(brow + ai * HALF) * DM + bcol, (size_t)DM, false, ai == 0);
	v_cvt_f32_ubyte0_e32 v94, v192
	v_cvt_f32_ubyte1_e32 v95, v192
	v_mul_f32_e32 v94, 0x3b808081, v94
	v_mul_f32_e32 v95, 0x3b808081, v95
	v_cvt_f32_ubyte2_e32 v96, v192
	v_cvt_f32_ubyte3_e32 v97, v192
	v_max_f32_e32 v94, 0x3b008081, v94
	v_max_f32_e32 v95, 0x3b008081, v95
	v_pk_mul_f32 v[90:91], v[90:91], v[94:95]
	v_mul_f32_e32 v94, 0x3b808081, v96
	v_mul_f32_e32 v95, 0x3b808081, v97
	v_max_f32_e32 v94, 0x3b008081, v94
	v_max_f32_e32 v95, 0x3b008081, v95
	v_pk_mul_f32 v[92:93], v[92:93], v[94:95]
	v_cvt_pk_bf16_f32 v90, v90, v91
	v_cvt_pk_bf16_f32 v91, v92, v93
	s_waitcnt vmcnt(21)
	v_cvt_f32_ubyte0_e32 v92, v193
	v_cvt_f32_ubyte1_e32 v93, v193
	v_mul_f32_e32 v92, 0x3b808081, v92
	v_mul_f32_e32 v93, 0x3b808081, v93
	v_cvt_f32_ubyte2_e32 v95, v193
	v_cvt_f32_ubyte3_e32 v96, v193
	v_max_f32_e32 v92, 0x3b008081, v92
	v_max_f32_e32 v93, 0x3b008081, v93
	v_pk_mul_f32 v[86:87], v[86:87], v[92:93]
	v_mul_f32_e32 v92, 0x3b808081, v95
	v_mul_f32_e32 v93, 0x3b808081, v96
	v_max_f32_e32 v92, 0x3b008081, v92
	v_max_f32_e32 v93, 0x3b008081, v93
	v_add_u32_e32 v94, 0x1a000, v197
	v_pk_mul_f32 v[88:89], v[88:89], v[92:93]
	v_cvt_pk_bf16_f32 v86, v86, v87
	v_cvt_pk_bf16_f32 v87, v88, v89
	v_add_u32_e32 v108, v94, v127
	ds_write_b64 v108, v[86:87]
	s_waitcnt vmcnt(20)
	v_cvt_f32_ubyte0_e32 v86, v180
	v_cvt_f32_ubyte1_e32 v87, v180
	v_mul_f32_e32 v86, 0x3b808081, v86
	v_mul_f32_e32 v87, 0x3b808081, v87
	v_cvt_f32_ubyte2_e32 v88, v180
	v_cvt_f32_ubyte3_e32 v89, v180
	v_max_f32_e32 v86, 0x3b008081, v86
	v_max_f32_e32 v87, 0x3b008081, v87
	v_pk_mul_f32 v[82:83], v[82:83], v[86:87]
	v_mul_f32_e32 v86, 0x3b808081, v88
	v_mul_f32_e32 v87, 0x3b808081, v89
	v_max_f32_e32 v86, 0x3b008081, v86
	v_max_f32_e32 v87, 0x3b008081, v87
	v_pk_mul_f32 v[84:85], v[84:85], v[86:87]
	v_cvt_pk_bf16_f32 v82, v82, v83
	v_cvt_pk_bf16_f32 v83, v84, v85
	v_add_u32_e32 v109, v94, v123
	ds_write_b64 v109, v[82:83]
	s_waitcnt vmcnt(19)
	v_cvt_f32_ubyte0_e32 v82, v176
	v_cvt_f32_ubyte1_e32 v83, v176
	v_mul_f32_e32 v82, 0x3b808081, v82
	v_mul_f32_e32 v83, 0x3b808081, v83
	v_cvt_f32_ubyte2_e32 v84, v176
	v_cvt_f32_ubyte3_e32 v85, v176
	v_max_f32_e32 v82, 0x3b008081, v82
	v_max_f32_e32 v83, 0x3b008081, v83
	v_pk_mul_f32 v[78:79], v[78:79], v[82:83]
	v_mul_f32_e32 v82, 0x3b808081, v84
	v_mul_f32_e32 v83, 0x3b808081, v85
	v_max_f32_e32 v82, 0x3b008081, v82
	v_max_f32_e32 v83, 0x3b008081, v83
	v_pk_mul_f32 v[80:81], v[80:81], v[82:83]
	v_cvt_pk_bf16_f32 v78, v78, v79
	v_cvt_pk_bf16_f32 v79, v80, v81
	ds_write_b64 v126, v[78:79] offset:45056
	s_waitcnt vmcnt(18)
	v_cvt_f32_ubyte0_e32 v78, v171
	v_cvt_f32_ubyte1_e32 v79, v171
	v_mul_f32_e32 v78, 0x3b808081, v78
	v_mul_f32_e32 v79, 0x3b808081, v79
	v_cvt_f32_ubyte2_e32 v80, v171
	v_cvt_f32_ubyte3_e32 v81, v171
	v_max_f32_e32 v78, 0x3b008081, v78
	v_max_f32_e32 v79, 0x3b008081, v79
	v_pk_mul_f32 v[74:75], v[74:75], v[78:79]
	v_mul_f32_e32 v78, 0x3b808081, v80
	v_mul_f32_e32 v79, 0x3b808081, v81
	v_max_f32_e32 v78, 0x3b008081, v78
	v_max_f32_e32 v79, 0x3b008081, v79
	v_pk_mul_f32 v[76:77], v[76:77], v[78:79]
	v_cvt_pk_bf16_f32 v74, v74, v75
	v_cvt_pk_bf16_f32 v75, v76, v77
	ds_write2st64_b64 v122, v[90:91], v[74:75] offset0:80 offset1:88
	s_waitcnt vmcnt(17)
	v_cvt_f32_ubyte0_e32 v74, v170
	v_cvt_f32_ubyte1_e32 v75, v170
	v_mul_f32_e32 v74, 0x3b808081, v74
	v_mul_f32_e32 v75, 0x3b808081, v75
	v_cvt_f32_ubyte2_e32 v77, v170
	v_cvt_f32_ubyte3_e32 v78, v170
	v_max_f32_e32 v74, 0x3b008081, v74
	v_max_f32_e32 v75, 0x3b008081, v75
	v_pk_mul_f32 v[70:71], v[70:71], v[74:75]
	v_mul_f32_e32 v74, 0x3b808081, v77
	v_mul_f32_e32 v75, 0x3b808081, v78
	v_max_f32_e32 v74, 0x3b008081, v74
	v_max_f32_e32 v75, 0x3b008081, v75
	v_add_u32_e32 v76, 0x1b000, v197
	v_pk_mul_f32 v[72:73], v[72:73], v[74:75]
	v_cvt_pk_bf16_f32 v70, v70, v71
	v_cvt_pk_bf16_f32 v71, v72, v73
	v_add_u32_e32 v110, v76, v127
	v_lshrrev_b32_e32 v130, 4, v249
	ds_write_b64 v110, v[70:71]
	s_waitcnt vmcnt(16)
	v_cvt_f32_ubyte0_e32 v70, v169
	v_cvt_f32_ubyte1_e32 v71, v169
	v_xor_b32_e32 v130, v130, v249
	v_mul_f32_e32 v70, 0x3b808081, v70
	v_mul_f32_e32 v71, 0x3b808081, v71
	v_lshlrev_b32_e32 v130, 4, v130
	v_cvt_f32_ubyte2_e32 v72, v169
	v_cvt_f32_ubyte3_e32 v73, v169
	v_max_f32_e32 v70, 0x3b008081, v70
	v_max_f32_e32 v71, 0x3b008081, v71
	v_add_u32_e32 v1, 0, v1
	v_lshlrev_b32_e32 v131, 8, v172
	v_and_b32_e32 v130, 0xf0, v130
	v_pk_mul_f32 v[66:67], v[66:67], v[70:71]
	v_mul_f32_e32 v70, 0x3b808081, v72
	v_mul_f32_e32 v71, 0x3b808081, v73
	s_addc_u32 s1, s35, s9
	v_add3_u32 v1, v1, v131, v130
	v_ashrrev_i32_e32 v130, 4, v249
	v_max_f32_e32 v70, 0x3b008081, v70
	v_max_f32_e32 v71, 0x3b008081, v71
	s_lshl_b64 s[8:9], s[6:7], 12
	v_and_b32_e32 v130, 0xffffff80, v130
	v_pk_mul_f32 v[68:69], v[68:69], v[70:71]
	s_add_u32 s8, s5, s8
	v_ashrrev_i32_e32 v131, 31, v130
	v_cvt_pk_bf16_f32 v66, v66, v67
	v_cvt_pk_bf16_f32 v67, v68, v69
	v_add_u32_e32 v111, v76, v123
	s_addc_u32 s9, s1, s9
	v_lshlrev_b32_e32 v68, 12, v172
	v_mov_b32_e32 v69, v0
	ds_write_b64 v111, v[66:67]
	v_lshl_add_u64 v[66:67], s[8:9], 0, v[68:69]
	v_lshlrev_b64 v[70:71], 1, v[130:131]
	v_ashrrev_i32_e32 v132, 4, v132
	s_waitcnt lgkmcnt(0)
	s_barrier
; #define LDS_BARRIER() do { asm volatile("s_waitcnt lgkmcnt(0)" ::: "memory"); __builtin_amdgcn_s_barrier(); asm volatile("" ::: "memory"); } while (0)
; __device__ __forceinline__ void st16_asm(void* ptr, u32x4 v) { asm volatile("global_store_dwordx4 %0, %1, off\n\ts_nop 7" :: "v"(ptr), "v"(v) : "memory"); }
; __device__ __forceinline__ void stg_flush(bf16* shm, int tid, bf16* dst, size_t pitch, bool first, bool tail_barrier = true) {
;   LDS_BARRIER();
;   if (first) asm volatile("s_waitcnt vmcnt(0)" ::: "memory");
;   _Pragma("unroll") for (int i = 0; i < 8; ++i) {
;     const int idx = tid + 512 * i, bjr = idx >> 11, row = (idx >> 4) & 127, c16 = idx & 15;
;     const u32x4 d = *(const u32x4*)stg_ptr(shm, bjr, row, 2 * c16);
;     st16_asm(dst + (size_t)row * pitch + bjr * HALF + c16 * 8, d); }
;   if (tail_barrier) LDS_BARRIER();
; __device__ void mix_phase(const Params& p, int layer, bf16* shm, int wv) {
;     ...
;     _Pragma("unroll") for (int ai = 0; ai < 2; ++ai) {
;       unsigned (&w1)[4][2][2] = w1a[ai];
;       _Pragma("unroll") for (int m = 0; m < 4; ++m) _Pragma("unroll") for (int bj = 0; bj < 2; ++bj) _Pragma("unroll") for (int n = 0; n < 2; ++n) {
;         f32x4 g1 = gate_u8(w1[m][bj][n]); f32x4 v = acc[ai][bj][m][n];
;         for (int j = 0; j < 4; ++j) v[j] *= fmaxf(g1[j], 1.f / 510.f);
;         u32x2 o = {pk2(v[0], v[1]), pk2(v[2], v[3])};
;         *(u32x2*)stg_ptr(shm, bj, wr * 64 + m * 16 + fr, wc * 8 + n * 4 + fq) = o; }
;       stg_flush(shm, tid, MX + (size_t)(brow + ai * HALF) * DM + bcol, (size_t)DM, false, ai == 0);
	v_lshl_add_u64 v[76:77], v[66:67], 0, v[70:71]
	v_lshlrev_b32_e32 v66, 4, v249
	v_and_b32_e32 v132, 0xffffff80, v132
	ds_read_b128 v[72:75], v1
	v_and_b32_e32 v66, 0xf0, v66
	v_mov_b32_e32 v67, v0
	v_ashrrev_i32_e32 v133, 31, v132
	v_lshl_add_u64 v[76:77], v[76:77], 0, v[66:67]
	s_waitcnt lgkmcnt(0)
	global_store_dwordx4 v[76:77], v[72:75], off sc1
	s_nop 7
	v_lshlrev_b32_e32 v72, 12, v173
	v_mov_b32_e32 v73, v0
	v_ashrrev_i32_e32 v134, 4, v134
	v_lshl_add_u64 v[80:81], s[8:9], 0, v[72:73]
	v_lshlrev_b64 v[74:75], 1, v[132:133]
	v_and_b32_e32 v134, 0xffffff80, v134
	ds_read_b128 v[76:79], v146
	v_lshl_add_u64 v[80:81], v[80:81], 0, v[74:75]
	v_ashrrev_i32_e32 v135, 31, v134
	v_lshl_add_u64 v[80:81], v[80:81], 0, v[66:67]
	s_waitcnt lgkmcnt(0)
	global_store_dwordx4 v[80:81], v[76:79], off sc1
	s_nop 7
	v_lshlrev_b32_e32 v76, 12, v174
	v_mov_b32_e32 v77, v0
	v_ashrrev_i32_e32 v136, 4, v136
	v_lshl_add_u64 v[84:85], s[8:9], 0, v[76:77]
	v_lshlrev_b64 v[78:79], 1, v[134:135]
	v_and_b32_e32 v136, 0xffffff80, v136
	ds_read_b128 v[80:83], v148
	v_lshl_add_u64 v[84:85], v[84:85], 0, v[78:79]
	v_ashrrev_i32_e32 v137, 31, v136
	v_lshl_add_u64 v[84:85], v[84:85], 0, v[66:67]
	s_waitcnt lgkmcnt(0)
	global_store_dwordx4 v[84:85], v[80:83], off sc1
	s_nop 7
	v_lshlrev_b32_e32 v80, 12, v175
	v_mov_b32_e32 v81, v0
	v_ashrrev_i32_e32 v138, 4, v138
	v_lshl_add_u64 v[88:89], s[8:9], 0, v[80:81]
	v_lshlrev_b64 v[82:83], 1, v[136:137]
	v_and_b32_e32 v138, 0xffffff80, v138
	ds_read_b128 v[84:87], v149
	v_lshl_add_u64 v[88:89], v[88:89], 0, v[82:83]
	v_ashrrev_i32_e32 v139, 31, v138
	v_lshl_add_u64 v[88:89], v[88:89], 0, v[66:67]
	s_waitcnt lgkmcnt(0)
	global_store_dwordx4 v[88:89], v[84:87], off sc1
	s_nop 7
	v_lshlrev_b32_e32 v84, 12, v177
	v_mov_b32_e32 v85, v0
	v_ashrrev_i32_e32 v140, 4, v140
	v_lshl_add_u64 v[92:93], s[8:9], 0, v[84:85]
	v_lshlrev_b64 v[86:87], 1, v[138:139]
	v_and_b32_e32 v140, 0xffffff80, v140
	ds_read_b128 v[88:91], v151
	v_lshl_add_u64 v[92:93], v[92:93], 0, v[86:87]
	v_ashrrev_i32_e32 v141, 31, v140
	v_lshl_add_u64 v[92:93], v[92:93], 0, v[66:67]
	s_waitcnt lgkmcnt(0)
	global_store_dwordx4 v[92:93], v[88:91], off sc1
	s_nop 7
	v_lshlrev_b32_e32 v88, 12, v178
	v_mov_b32_e32 v89, v0
	v_ashrrev_i32_e32 v142, 4, v142
	v_lshl_add_u64 v[96:97], s[8:9], 0, v[88:89]
	v_lshlrev_b64 v[90:91], 1, v[140:141]
	v_and_b32_e32 v142, 0xffffff80, v142
	ds_read_b128 v[92:95], v152
	v_lshl_add_u64 v[96:97], v[96:97], 0, v[90:91]
	v_ashrrev_i32_e32 v143, 31, v142
	v_lshl_add_u64 v[96:97], v[96:97], 0, v[66:67]
	s_waitcnt lgkmcnt(0)
	global_store_dwordx4 v[96:97], v[92:95], off sc1
	s_nop 7
	v_lshlrev_b32_e32 v92, 12, v179
	v_mov_b32_e32 v93, v0
	v_ashrrev_i32_e32 v144, 4, v144
	v_lshl_add_u64 v[100:101], s[8:9], 0, v[92:93]
	v_lshlrev_b64 v[94:95], 1, v[142:143]
	v_and_b32_e32 v144, 0xffffff80, v144
	ds_read_b128 v[96:99], v154
	v_lshl_add_u64 v[100:101], v[100:101], 0, v[94:95]
	v_ashrrev_i32_e32 v145, 31, v144
	v_lshl_add_u64 v[100:101], v[100:101], 0, v[66:67]
	s_waitcnt lgkmcnt(0)
	global_store_dwordx4 v[100:101], v[96:99], off sc1
	s_nop 7
	v_lshlrev_b32_e32 v96, 12, v181
	v_mov_b32_e32 v97, v0
	v_lshl_add_u64 v[104:105], s[8:9], 0, v[96:97]
	v_lshlrev_b64 v[98:99], 1, v[144:145]
	ds_read_b128 v[100:103], v155
	v_lshl_add_u64 v[104:105], v[104:105], 0, v[98:99]
	v_lshl_add_u64 v[104:105], v[104:105], 0, v[66:67]
	s_waitcnt lgkmcnt(0)
	global_store_dwordx4 v[104:105], v[100:103], off sc1
	s_nop 7
	s_waitcnt vmcnt(15)
	v_cvt_f32_ubyte0_e32 v100, v168
	v_cvt_f32_ubyte1_e32 v101, v168
	v_mul_f32_e32 v100, 0x3b808081, v100
	v_mul_f32_e32 v101, 0x3b808081, v101
	v_cvt_f32_ubyte2_e32 v102, v168
	v_cvt_f32_ubyte3_e32 v103, v168
	v_max_f32_e32 v100, 0x3b008081, v100
	v_max_f32_e32 v101, 0x3b008081, v101
	v_pk_mul_f32 v[62:63], v[62:63], v[100:101]
	v_mul_f32_e32 v100, 0x3b808081, v102
	v_mul_f32_e32 v101, 0x3b808081, v103
	v_max_f32_e32 v100, 0x3b008081, v100
	v_max_f32_e32 v101, 0x3b008081, v101
	v_pk_mul_f32 v[64:65], v[64:65], v[100:101]
	v_cvt_pk_bf16_f32 v62, v62, v63
	v_cvt_pk_bf16_f32 v63, v64, v65
	s_waitcnt lgkmcnt(0)
	s_barrier
	ds_write_b64 v126, v[62:63] offset:32768
	s_waitcnt vmcnt(14)
	v_cvt_f32_ubyte0_e32 v62, v167
	v_cvt_f32_ubyte1_e32 v63, v167
	v_mul_f32_e32 v62, 0x3b808081, v62
	v_mul_f32_e32 v63, 0x3b808081, v63
	v_cvt_f32_ubyte2_e32 v64, v167
	v_cvt_f32_ubyte3_e32 v65, v167
	v_max_f32_e32 v62, 0x3b008081, v62
	v_max_f32_e32 v63, 0x3b008081, v63
	v_pk_mul_f32 v[58:59], v[58:59], v[62:63]
	v_mul_f32_e32 v62, 0x3b808081, v64
	v_mul_f32_e32 v63, 0x3b808081, v65
	v_max_f32_e32 v62, 0x3b008081, v62
	v_max_f32_e32 v63, 0x3b008081, v63
	v_pk_mul_f32 v[60:61], v[60:61], v[62:63]
	v_cvt_pk_bf16_f32 v58, v58, v59
	v_cvt_pk_bf16_f32 v59, v60, v61
	s_waitcnt vmcnt(13)
	v_cvt_f32_ubyte0_e32 v60, v166
	v_cvt_f32_ubyte1_e32 v61, v166
	v_mul_f32_e32 v60, 0x3b808081, v60
	v_mul_f32_e32 v61, 0x3b808081, v61
	v_cvt_f32_ubyte2_e32 v62, v166
	v_cvt_f32_ubyte3_e32 v63, v166
	v_max_f32_e32 v60, 0x3b008081, v60
	v_max_f32_e32 v61, 0x3b008081, v61
	v_pk_mul_f32 v[54:55], v[54:55], v[60:61]
	v_mul_f32_e32 v60, 0x3b808081, v62
	v_mul_f32_e32 v61, 0x3b808081, v63
	v_max_f32_e32 v60, 0x3b008081, v60
	v_max_f32_e32 v61, 0x3b008081, v61
	v_pk_mul_f32 v[56:57], v[56:57], v[60:61]
	v_cvt_pk_bf16_f32 v54, v54, v55
	v_cvt_pk_bf16_f32 v55, v56, v57
	ds_write_b64 v120, v[54:55]
	s_waitcnt vmcnt(12)
; __device__ void mix_phase(const Params& p, int layer, bf16* shm, int wv) {
;     ...
;       _Pragma("unroll") for (int m = 0; m < 4; ++m) _Pragma("unroll") for (int bj = 0; bj < 2; ++bj) _Pragma("unroll") for (int n = 0; n < 2; ++n) {
;         f32x4 g1 = gate_u8(w1[m][bj][n]); f32x4 v = acc[ai][bj][m][n];
;         for (int j = 0; j < 4; ++j) v[j] *= fmaxf(g1[j], 1.f / 510.f);
;         u32x2 o = {pk2(v[0], v[1]), pk2(v[2], v[3])};
;         *(u32x2*)stg_ptr(shm, bj, wr * 64 + m * 16 + fr, wc * 8 + n * 4 + fq) = o; }
	v_cvt_f32_ubyte0_e32 v54, v165
	v_cvt_f32_ubyte1_e32 v55, v165
	v_mul_f32_e32 v54, 0x3b808081, v54
	v_mul_f32_e32 v55, 0x3b808081, v55
	v_cvt_f32_ubyte2_e32 v56, v165
	v_cvt_f32_ubyte3_e32 v57, v165
	v_max_f32_e32 v54, 0x3b008081, v54
	v_max_f32_e32 v55, 0x3b008081, v55
	v_pk_mul_f32 v[50:51], v[50:51], v[54:55]
	v_mul_f32_e32 v54, 0x3b808081, v56
	v_mul_f32_e32 v55, 0x3b808081, v57
	v_max_f32_e32 v54, 0x3b008081, v54
	v_max_f32_e32 v55, 0x3b008081, v55
	v_pk_mul_f32 v[52:53], v[52:53], v[54:55]
	v_cvt_pk_bf16_f32 v50, v50, v51
	v_cvt_pk_bf16_f32 v51, v52, v53
	ds_write_b64 v116, v[50:51]
	s_waitcnt vmcnt(11)
	v_cvt_f32_ubyte0_e32 v50, v164
	v_cvt_f32_ubyte1_e32 v51, v164
	v_mul_f32_e32 v50, 0x3b808081, v50
	v_mul_f32_e32 v51, 0x3b808081, v51
	v_cvt_f32_ubyte2_e32 v52, v164
	v_cvt_f32_ubyte3_e32 v53, v164
	v_max_f32_e32 v50, 0x3b008081, v50
	v_max_f32_e32 v51, 0x3b008081, v51
	v_pk_mul_f32 v[46:47], v[46:47], v[50:51]
	v_mul_f32_e32 v50, 0x3b808081, v52
	v_mul_f32_e32 v51, 0x3b808081, v53
	v_max_f32_e32 v50, 0x3b008081, v50
	v_max_f32_e32 v51, 0x3b008081, v51
	v_pk_mul_f32 v[48:49], v[48:49], v[50:51]
	v_cvt_pk_bf16_f32 v46, v46, v47
	v_cvt_pk_bf16_f32 v47, v48, v49
	ds_write_b64 v126, v[46:47] offset:36864
	s_waitcnt vmcnt(10)
	v_cvt_f32_ubyte0_e32 v46, v163
	v_cvt_f32_ubyte1_e32 v47, v163
	v_mul_f32_e32 v46, 0x3b808081, v46
	v_mul_f32_e32 v47, 0x3b808081, v47
	v_cvt_f32_ubyte2_e32 v48, v163
	v_cvt_f32_ubyte3_e32 v49, v163
	v_max_f32_e32 v46, 0x3b008081, v46
	v_max_f32_e32 v47, 0x3b008081, v47
	v_pk_mul_f32 v[42:43], v[42:43], v[46:47]
	v_mul_f32_e32 v46, 0x3b808081, v48
	v_mul_f32_e32 v47, 0x3b808081, v49
	v_max_f32_e32 v46, 0x3b008081, v46
	v_max_f32_e32 v47, 0x3b008081, v47
	v_pk_mul_f32 v[44:45], v[44:45], v[46:47]
	v_cvt_pk_bf16_f32 v42, v42, v43
	v_cvt_pk_bf16_f32 v43, v44, v45
	ds_write2st64_b64 v122, v[58:59], v[42:43] offset0:64 offset1:72
	s_waitcnt vmcnt(9)
	v_cvt_f32_ubyte0_e32 v42, v162
	v_cvt_f32_ubyte1_e32 v43, v162
	v_mul_f32_e32 v42, 0x3b808081, v42
	v_mul_f32_e32 v43, 0x3b808081, v43
	v_cvt_f32_ubyte2_e32 v44, v162
	v_cvt_f32_ubyte3_e32 v45, v162
	v_max_f32_e32 v42, 0x3b008081, v42
	v_max_f32_e32 v43, 0x3b008081, v43
	v_pk_mul_f32 v[38:39], v[38:39], v[42:43]
	v_mul_f32_e32 v42, 0x3b808081, v44
	v_mul_f32_e32 v43, 0x3b808081, v45
	v_max_f32_e32 v42, 0x3b008081, v42
	v_max_f32_e32 v43, 0x3b008081, v43
	v_pk_mul_f32 v[40:41], v[40:41], v[42:43]
	v_cvt_pk_bf16_f32 v38, v38, v39
	v_cvt_pk_bf16_f32 v39, v40, v41
	ds_write_b64 v106, v[38:39]
	s_waitcnt vmcnt(8)
	v_cvt_f32_ubyte0_e32 v38, v160
	v_cvt_f32_ubyte1_e32 v39, v160
	v_mul_f32_e32 v38, 0x3b808081, v38
	v_mul_f32_e32 v39, 0x3b808081, v39
	v_cvt_f32_ubyte2_e32 v40, v160
	v_cvt_f32_ubyte3_e32 v41, v160
	v_max_f32_e32 v38, 0x3b008081, v38
	v_max_f32_e32 v39, 0x3b008081, v39
	v_pk_mul_f32 v[34:35], v[34:35], v[38:39]
	v_mul_f32_e32 v38, 0x3b808081, v40
	v_mul_f32_e32 v39, 0x3b808081, v41
	v_max_f32_e32 v38, 0x3b008081, v38
	v_max_f32_e32 v39, 0x3b008081, v39
	v_pk_mul_f32 v[36:37], v[36:37], v[38:39]
	v_cvt_pk_bf16_f32 v34, v34, v35
	v_cvt_pk_bf16_f32 v35, v36, v37
	ds_write_b64 v107, v[34:35]
	s_waitcnt vmcnt(7)
	v_cvt_f32_ubyte0_e32 v34, v161
	v_cvt_f32_ubyte1_e32 v35, v161
	v_mul_f32_e32 v34, 0x3b808081, v34
	v_mul_f32_e32 v35, 0x3b808081, v35
	v_cvt_f32_ubyte2_e32 v36, v161
	v_cvt_f32_ubyte3_e32 v37, v161
	v_max_f32_e32 v34, 0x3b008081, v34
	v_max_f32_e32 v35, 0x3b008081, v35
	v_pk_mul_f32 v[30:31], v[30:31], v[34:35]
	v_mul_f32_e32 v34, 0x3b808081, v36
	v_mul_f32_e32 v35, 0x3b808081, v37
	v_max_f32_e32 v34, 0x3b008081, v34
	v_max_f32_e32 v35, 0x3b008081, v35
	v_pk_mul_f32 v[32:33], v[32:33], v[34:35]
	v_cvt_pk_bf16_f32 v30, v30, v31
	v_cvt_pk_bf16_f32 v31, v32, v33
	ds_write_b64 v126, v[30:31] offset:40960
	s_waitcnt vmcnt(6)
	v_cvt_f32_ubyte0_e32 v30, v159
	v_cvt_f32_ubyte1_e32 v31, v159
	v_mul_f32_e32 v30, 0x3b808081, v30
	v_mul_f32_e32 v31, 0x3b808081, v31
	v_cvt_f32_ubyte2_e32 v32, v159
	v_cvt_f32_ubyte3_e32 v33, v159
	v_max_f32_e32 v30, 0x3b008081, v30
	v_max_f32_e32 v31, 0x3b008081, v31
	v_pk_mul_f32 v[26:27], v[26:27], v[30:31]
	v_mul_f32_e32 v30, 0x3b808081, v32
	v_mul_f32_e32 v31, 0x3b808081, v33
	v_max_f32_e32 v30, 0x3b008081, v30
	v_max_f32_e32 v31, 0x3b008081, v31
	v_pk_mul_f32 v[28:29], v[28:29], v[30:31]
	v_cvt_pk_bf16_f32 v26, v26, v27
	v_cvt_pk_bf16_f32 v27, v28, v29
	s_waitcnt vmcnt(5)
	v_cvt_f32_ubyte0_e32 v28, v158
	v_cvt_f32_ubyte1_e32 v29, v158
	v_mul_f32_e32 v28, 0x3b808081, v28
	v_mul_f32_e32 v29, 0x3b808081, v29
	v_cvt_f32_ubyte2_e32 v30, v158
	v_cvt_f32_ubyte3_e32 v31, v158
	v_max_f32_e32 v28, 0x3b008081, v28
	v_max_f32_e32 v29, 0x3b008081, v29
	v_pk_mul_f32 v[22:23], v[22:23], v[28:29]
	v_mul_f32_e32 v28, 0x3b808081, v30
	v_mul_f32_e32 v29, 0x3b808081, v31
	v_max_f32_e32 v28, 0x3b008081, v28
	v_max_f32_e32 v29, 0x3b008081, v29
	v_pk_mul_f32 v[24:25], v[24:25], v[28:29]
	v_cvt_pk_bf16_f32 v22, v22, v23
	v_cvt_pk_bf16_f32 v23, v24, v25
	ds_write_b64 v108, v[22:23]
	s_waitcnt vmcnt(4)
; #define LDS_BARRIER() do { asm volatile("s_waitcnt lgkmcnt(0)" ::: "memory"); __builtin_amdgcn_s_barrier(); asm volatile("" ::: "memory"); } while (0)
; __device__ __forceinline__ void st16_asm(void* ptr, u32x4 v) { asm volatile("global_store_dwordx4 %0, %1, off\n\ts_nop 7" :: "v"(ptr), "v"(v) : "memory"); }
; __device__ __forceinline__ void stg_flush(bf16* shm, int tid, bf16* dst, size_t pitch, bool first, bool tail_barrier = true) {
;   LDS_BARRIER();
;   if (first) asm volatile("s_waitcnt vmcnt(0)" ::: "memory");
;   _Pragma("unroll") for (int i = 0; i < 8; ++i) {
;     const int idx = tid + 512 * i, bjr = idx >> 11, row = (idx >> 4) & 127, c16 = idx & 15;
;     const u32x4 d = *(const u32x4*)stg_ptr(shm, bjr, row, 2 * c16);
;     st16_asm(dst + (size_t)row * pitch + bjr * HALF + c16 * 8, d); }
;   if (tail_barrier) LDS_BARRIER();
; __device__ void mix_phase(const Params& p, int layer, bf16* shm, int wv) {
;     ...
;       _Pragma("unroll") for (int m = 0; m < 4; ++m) _Pragma("unroll") for (int bj = 0; bj < 2; ++bj) _Pragma("unroll") for (int n = 0; n < 2; ++n) {
;         f32x4 g1 = gate_u8(w1[m][bj][n]); f32x4 v = acc[ai][bj][m][n];
;         for (int j = 0; j < 4; ++j) v[j] *= fmaxf(g1[j], 1.f / 510.f);
;         u32x2 o = {pk2(v[0], v[1]), pk2(v[2], v[3])};
;         *(u32x2*)stg_ptr(shm, bj, wr * 64 + m * 16 + fr, wc * 8 + n * 4 + fq) = o; }
;       stg_flush(shm, tid, MX + (size_t)(brow + ai * HALF) * DM + bcol, (size_t)DM, false, ai == 0);
;     }
;     asm volatile("s_waitcnt vmcnt(0)" ::: "memory");
	v_cvt_f32_ubyte0_e32 v22, v157
	v_cvt_f32_ubyte1_e32 v23, v157
	v_mul_f32_e32 v22, 0x3b808081, v22
	v_mul_f32_e32 v23, 0x3b808081, v23
	v_cvt_f32_ubyte2_e32 v24, v157
	v_cvt_f32_ubyte3_e32 v25, v157
	v_max_f32_e32 v22, 0x3b008081, v22
	v_max_f32_e32 v23, 0x3b008081, v23
	v_pk_mul_f32 v[18:19], v[18:19], v[22:23]
	v_mul_f32_e32 v22, 0x3b808081, v24
	v_mul_f32_e32 v23, 0x3b808081, v25
	v_max_f32_e32 v22, 0x3b008081, v22
	v_max_f32_e32 v23, 0x3b008081, v23
	v_pk_mul_f32 v[20:21], v[20:21], v[22:23]
	v_cvt_pk_bf16_f32 v18, v18, v19
	v_cvt_pk_bf16_f32 v19, v20, v21
	ds_write_b64 v109, v[18:19]
	s_waitcnt vmcnt(3)
	v_cvt_f32_ubyte0_e32 v18, v156
	v_cvt_f32_ubyte1_e32 v19, v156
	v_mul_f32_e32 v18, 0x3b808081, v18
	v_mul_f32_e32 v19, 0x3b808081, v19
	v_cvt_f32_ubyte2_e32 v20, v156
	v_cvt_f32_ubyte3_e32 v21, v156
	v_max_f32_e32 v18, 0x3b008081, v18
	v_max_f32_e32 v19, 0x3b008081, v19
	v_pk_mul_f32 v[14:15], v[14:15], v[18:19]
	v_mul_f32_e32 v18, 0x3b808081, v20
	v_mul_f32_e32 v19, 0x3b808081, v21
	v_max_f32_e32 v18, 0x3b008081, v18
	v_max_f32_e32 v19, 0x3b008081, v19
	v_pk_mul_f32 v[16:17], v[16:17], v[18:19]
	v_cvt_pk_bf16_f32 v14, v14, v15
	v_cvt_pk_bf16_f32 v15, v16, v17
	ds_write_b64 v126, v[14:15] offset:45056
	s_waitcnt vmcnt(2)
	v_cvt_f32_ubyte0_e32 v14, v153
	v_cvt_f32_ubyte1_e32 v15, v153
	v_mul_f32_e32 v14, 0x3b808081, v14
	v_mul_f32_e32 v15, 0x3b808081, v15
	v_cvt_f32_ubyte2_e32 v16, v153
	v_cvt_f32_ubyte3_e32 v17, v153
	v_max_f32_e32 v14, 0x3b008081, v14
	v_max_f32_e32 v15, 0x3b008081, v15
	v_pk_mul_f32 v[10:11], v[10:11], v[14:15]
	v_mul_f32_e32 v14, 0x3b808081, v16
	v_mul_f32_e32 v15, 0x3b808081, v17
	v_max_f32_e32 v14, 0x3b008081, v14
	v_max_f32_e32 v15, 0x3b008081, v15
	v_pk_mul_f32 v[12:13], v[12:13], v[14:15]
	v_cvt_pk_bf16_f32 v10, v10, v11
	v_cvt_pk_bf16_f32 v11, v12, v13
	ds_write2st64_b64 v122, v[26:27], v[10:11] offset0:80 offset1:88
	s_waitcnt vmcnt(1)
	v_cvt_f32_ubyte0_e32 v10, v150
	v_cvt_f32_ubyte1_e32 v11, v150
	v_mul_f32_e32 v10, 0x3b808081, v10
	v_mul_f32_e32 v11, 0x3b808081, v11
	v_cvt_f32_ubyte2_e32 v12, v150
	v_cvt_f32_ubyte3_e32 v13, v150
	v_max_f32_e32 v10, 0x3b008081, v10
	v_max_f32_e32 v11, 0x3b008081, v11
	v_pk_mul_f32 v[6:7], v[6:7], v[10:11]
	v_mul_f32_e32 v10, 0x3b808081, v12
	v_mul_f32_e32 v11, 0x3b808081, v13
	v_max_f32_e32 v10, 0x3b008081, v10
	v_max_f32_e32 v11, 0x3b008081, v11
	v_pk_mul_f32 v[8:9], v[8:9], v[10:11]
	v_cvt_pk_bf16_f32 v6, v6, v7
	v_cvt_pk_bf16_f32 v7, v8, v9
	ds_write_b64 v110, v[6:7]
	s_waitcnt vmcnt(0)
	v_cvt_f32_ubyte0_e32 v6, v147
	v_cvt_f32_ubyte1_e32 v7, v147
	v_mul_f32_e32 v6, 0x3b808081, v6
	v_mul_f32_e32 v7, 0x3b808081, v7
	s_bitset1_b32 s6, 7
	v_cvt_f32_ubyte2_e32 v8, v147
	v_cvt_f32_ubyte3_e32 v9, v147
	v_max_f32_e32 v6, 0x3b008081, v6
	v_max_f32_e32 v7, 0x3b008081, v7
	s_ashr_i32 s7, s6, 31
	v_pk_mul_f32 v[2:3], v[2:3], v[6:7]
	v_mul_f32_e32 v6, 0x3b808081, v8
	v_mul_f32_e32 v7, 0x3b808081, v9
	s_lshl_b64 s[6:7], s[6:7], 12
	v_max_f32_e32 v6, 0x3b008081, v6
	v_max_f32_e32 v7, 0x3b008081, v7
	s_add_u32 s6, s5, s6
	v_pk_mul_f32 v[4:5], v[4:5], v[6:7]
	s_addc_u32 s7, s1, s7
	v_cvt_pk_bf16_f32 v2, v2, v3
	v_cvt_pk_bf16_f32 v3, v4, v5
	v_lshl_add_u64 v[6:7], s[6:7], 0, v[68:69]
	ds_write_b64 v111, v[2:3]
	v_lshl_add_u64 v[6:7], v[6:7], 0, v[70:71]
	s_waitcnt lgkmcnt(0)
	s_barrier
	v_lshl_add_u64 v[6:7], v[6:7], 0, v[66:67]
	ds_read_b128 v[2:5], v1
	s_waitcnt lgkmcnt(0)
	global_store_dwordx4 v[6:7], v[2:5], off sc1
	s_nop 7
	v_lshl_add_u64 v[6:7], s[6:7], 0, v[72:73]
	v_lshl_add_u64 v[6:7], v[6:7], 0, v[74:75]
	v_lshl_add_u64 v[6:7], v[6:7], 0, v[66:67]
	ds_read_b128 v[2:5], v146
	s_waitcnt lgkmcnt(0)
	global_store_dwordx4 v[6:7], v[2:5], off sc1
	s_nop 7
	v_lshl_add_u64 v[6:7], s[6:7], 0, v[76:77]
	v_lshl_add_u64 v[6:7], v[6:7], 0, v[78:79]
	v_lshl_add_u64 v[6:7], v[6:7], 0, v[66:67]
	ds_read_b128 v[2:5], v148
	s_waitcnt lgkmcnt(0)
	global_store_dwordx4 v[6:7], v[2:5], off sc1
	s_nop 7
	v_lshl_add_u64 v[6:7], s[6:7], 0, v[80:81]
	v_lshl_add_u64 v[6:7], v[6:7], 0, v[82:83]
	v_lshl_add_u64 v[6:7], v[6:7], 0, v[66:67]
	ds_read_b128 v[2:5], v149
	s_waitcnt lgkmcnt(0)
	global_store_dwordx4 v[6:7], v[2:5], off sc1
	s_nop 7
	v_lshl_add_u64 v[6:7], s[6:7], 0, v[84:85]
	v_lshl_add_u64 v[6:7], v[6:7], 0, v[86:87]
	v_lshl_add_u64 v[6:7], v[6:7], 0, v[66:67]
	ds_read_b128 v[2:5], v151
	s_waitcnt lgkmcnt(0)
	global_store_dwordx4 v[6:7], v[2:5], off sc1
	s_nop 7
	v_lshl_add_u64 v[6:7], s[6:7], 0, v[88:89]
	v_lshl_add_u64 v[6:7], v[6:7], 0, v[90:91]
	v_lshl_add_u64 v[6:7], v[6:7], 0, v[66:67]
	ds_read_b128 v[2:5], v152
	s_waitcnt lgkmcnt(0)
	global_store_dwordx4 v[6:7], v[2:5], off sc1
	s_nop 7
	v_lshl_add_u64 v[6:7], s[6:7], 0, v[92:93]
	v_lshl_add_u64 v[6:7], v[6:7], 0, v[94:95]
	v_lshl_add_u64 v[6:7], v[6:7], 0, v[66:67]
	ds_read_b128 v[2:5], v154
	s_waitcnt lgkmcnt(0)
	global_store_dwordx4 v[6:7], v[2:5], off sc1
	s_nop 7
	v_lshl_add_u64 v[6:7], s[6:7], 0, v[96:97]
	v_lshl_add_u64 v[6:7], v[6:7], 0, v[98:99]
	ds_read_b128 v[2:5], v155
	v_lshl_add_u64 v[6:7], v[6:7], 0, v[66:67]
	s_waitcnt lgkmcnt(0)
	global_store_dwordx4 v[6:7], v[2:5], off sc1
	s_nop 7
	s_waitcnt vmcnt(0)
	s_add_i32 s19, s19, 1
	s_mov_b64 s[6:7], 0

; #define LDS_BARRIER() do { asm volatile("s_waitcnt lgkmcnt(0)" ::: "memory"); __builtin_amdgcn_s_barrier(); asm volatile("" ::: "memory"); } while (0)
; __device__ __forceinline__ void st16_asm(void* ptr, u32x4 v) { asm volatile("global_store_dwordx4 %0, %1, off\n\ts_nop 7" :: "v"(ptr), "v"(v) : "memory"); }
; __device__ __forceinline__ void stg_flush(bf16* shm, int tid, bf16* dst, size_t pitch, bool first, bool tail_barrier = true) {
;   LDS_BARRIER();
;   if (first) asm volatile("s_waitcnt vmcnt(0)" ::: "memory");
;   _Pragma("unroll") for (int i = 0; i < 8; ++i) {
;     const int idx = tid + 512 * i, bjr = idx >> 11, row = (idx >> 4) & 127, c16 = idx & 15;
;     const u32x4 d = *(const u32x4*)stg_ptr(shm, bjr, row, 2 * c16);
;     st16_asm(dst + (size_t)row * pitch + bjr * HALF + c16 * 8, d); }
;   if (tail_barrier) LDS_BARRIER();
; template <int EPI>
; __device__ void gemm_phase(const bf16* A, int lda, const bf16* Bt, int K, int N, const Params& p, bool last, bf16* dstb, bf16* shm, unsigned long long* SSQ, int wv, const float* gbias = nullptr) {
;     ...
;         if (!last) stg_flush(shm, tid, Xb + (size_t)(brow + ai * HALF) * DM + bcol, (size_t)DM, false, ai == 0);
.LBB0_481:
	s_or_b64 exec, exec, s[4:5]
	s_or_b32 s4, s8, 0x80
	s_ashr_i32 s5, s4, 31
	s_lshl_b64 s[4:5], s[4:5], 12
	v_lshlrev_b32_e32 v6, 11, v115
	s_add_u32 s4, s14, s4
	s_addc_u32 s5, s15, s5
	v_lshlrev_b32_e32 v6, 1, v6
	v_mov_b32_e32 v7, v0
	v_lshl_add_u64 v[6:7], s[4:5], 0, v[6:7]
	v_lshl_add_u64 v[6:7], v[66:67], 1, v[6:7]
	v_mov_b32_e32 v83, v0
	v_lshlrev_b32_e32 v8, 11, v116
	s_waitcnt lgkmcnt(0)
	s_barrier
	v_lshl_add_u64 v[6:7], v[6:7], 0, v[82:83]
	ds_read_b128 v[2:5], v1
	s_waitcnt lgkmcnt(0)
	global_store_dwordx4 v[6:7], v[2:5], off sc1
	s_nop 7
	v_lshlrev_b32_e32 v6, 1, v8
	v_mov_b32_e32 v7, v0
	v_lshl_add_u64 v[6:7], s[4:5], 0, v[6:7]
	v_lshl_add_u64 v[6:7], v[68:69], 1, v[6:7]
	v_lshlrev_b32_e32 v9, 11, v117
	v_lshl_add_u64 v[6:7], v[6:7], 0, v[82:83]
	ds_read_b128 v[2:5], v125
	s_waitcnt lgkmcnt(0)
	global_store_dwordx4 v[6:7], v[2:5], off sc1
	s_nop 7
	v_lshlrev_b32_e32 v6, 1, v9
	v_mov_b32_e32 v7, v0
	v_lshl_add_u64 v[6:7], s[4:5], 0, v[6:7]
	v_lshl_add_u64 v[6:7], v[70:71], 1, v[6:7]
	v_lshlrev_b32_e32 v10, 11, v119
	v_lshl_add_u64 v[6:7], v[6:7], 0, v[82:83]
	ds_read_b128 v[2:5], v127
	s_waitcnt lgkmcnt(0)
	global_store_dwordx4 v[6:7], v[2:5], off sc1
	s_nop 7
	v_lshlrev_b32_e32 v6, 1, v10
	v_mov_b32_e32 v7, v0
	v_lshl_add_u64 v[6:7], s[4:5], 0, v[6:7]
	v_lshl_add_u64 v[6:7], v[72:73], 1, v[6:7]
	v_lshlrev_b32_e32 v11, 11, v120
	v_lshl_add_u64 v[6:7], v[6:7], 0, v[82:83]
	ds_read_b128 v[2:5], v128
	s_waitcnt lgkmcnt(0)
	global_store_dwordx4 v[6:7], v[2:5], off sc1
	s_nop 7
	v_lshlrev_b32_e32 v6, 1, v11
	v_mov_b32_e32 v7, v0
	v_lshl_add_u64 v[6:7], s[4:5], 0, v[6:7]
	v_lshl_add_u64 v[6:7], v[74:75], 1, v[6:7]
	v_lshlrev_b32_e32 v12, 11, v121
	v_lshl_add_u64 v[6:7], v[6:7], 0, v[82:83]
	ds_read_b128 v[2:5], v129
	s_waitcnt lgkmcnt(0)
	global_store_dwordx4 v[6:7], v[2:5], off sc1
	s_nop 7
	v_lshlrev_b32_e32 v6, 1, v12
	v_mov_b32_e32 v7, v0
	v_lshl_add_u64 v[6:7], s[4:5], 0, v[6:7]
	v_lshl_add_u64 v[6:7], v[76:77], 1, v[6:7]
	v_lshlrev_b32_e32 v13, 11, v123
	v_lshl_add_u64 v[6:7], v[6:7], 0, v[82:83]
	ds_read_b128 v[2:5], v133
	s_waitcnt lgkmcnt(0)
	global_store_dwordx4 v[6:7], v[2:5], off sc1
	s_nop 7
	v_lshlrev_b32_e32 v6, 1, v13
	v_mov_b32_e32 v7, v0
	v_lshl_add_u64 v[6:7], s[4:5], 0, v[6:7]
	v_lshl_add_u64 v[6:7], v[78:79], 1, v[6:7]
	v_lshlrev_b32_e32 v14, 11, v124
	v_lshl_add_u64 v[6:7], v[6:7], 0, v[82:83]
	ds_read_b128 v[2:5], v136
	s_waitcnt lgkmcnt(0)
	global_store_dwordx4 v[6:7], v[2:5], off sc1
	s_nop 7
	v_lshlrev_b32_e32 v6, 1, v14
	v_mov_b32_e32 v7, v0
	v_lshl_add_u64 v[6:7], s[4:5], 0, v[6:7]
	v_lshl_add_u64 v[6:7], v[80:81], 1, v[6:7]
	ds_read_b128 v[2:5], v137
	v_lshl_add_u64 v[6:7], v[6:7], 0, v[82:83]
	s_waitcnt lgkmcnt(0)
	global_store_dwordx4 v[6:7], v[2:5], off sc1
	s_nop 7
	s_andn2_b64 vcc, exec, s[12:13]
	s_cbranch_vccz .LBB0_514

;   #define LDA(dst,b,h) for(int m=0;m<4;++m)for(int k=0;k<2;++k) \
;     dst[m][k]=*reinterpret_cast<const bf16x8*>((char*)SA(b,h)+lds_byte(wr*64+m*16+fr,k*32+fq*8))
;   #define LDB(dst,b,h) for(int n=0;n<2;++n)for(int k=0;k<2;++k) \
;     dst[n][k]=*reinterpret_cast<const bf16x8*>((char*)SB(b,h)+lds_byte(wc*32+n*16+fr,k*32+fq*8))
;   #define MMA(ai,bj,At,Bt_) do{__builtin_amdgcn_s_setprio(1); \
;     for(int m=0;m<4;++m)for(int n=0;n<2;++n)for(int k=0;k<2;++k) \
;       acc[ai][bj][m][n]=__builtin_amdgcn_mfma_f32_16x16x32_bf16(Bt_[n][k],At[m][k],acc[ai][bj][m][n],0,0,0); \
;     __builtin_amdgcn_s_setprio(0);}while(0)
;   #define WAIT_V(n) asm volatile("s_waitcnt vmcnt(" #n ")":::"memory")
;   #define WAIT_L(n) asm volatile("s_waitcnt lgkmcnt(" #n ")":::"memory")
;   #define BAR __builtin_amdgcn_s_barrier()
;   #define SCHED __builtin_amdgcn_sched_barrier(0)
; template <bool TWO, class MID> ...
;     ...
;   for(int t=0;t<nt-2;t+=2){
;     if (TWO && t == nt1) mid();
;     LDB(B0,0,0); SCHED; LDA(At,0,0); STAGE_A(SA(1,1),1,t+1);
;     WAIT_L(8); BAR; WAIT_L(0); MMA(0,0,At,B0); BAR; SCHED;
;     LDB(B1,0,1); STAGE_B(SB(0,0),0,t+2);
;     BAR; WAIT_L(0); MMA(0,1,At,B1); BAR;
;     LDA(At,0,1); STAGE_A(SA(0,0),0,t+2);
;     BAR; WAIT_L(0); MMA(1,0,At,B0); BAR; SCHED;
;     STAGE_B(SB(0,1),1,t+2);
;     WAIT_V(6); BAR; MMA(1,1,At,B1); BAR;
.LBB0_489:
	ds_read_b128 v[166:169], v149
	ds_read_b128 v[170:173], v149 offset:1024
	ds_read_b128 v[174:177], v149 offset:2048
	ds_read_b128 v[178:181], v149 offset:3072
	ds_read_b128 v[182:185], v141
	ds_read_b128 v[186:189], v141 offset:1024
	ds_read_b128 v[190:193], v139
	ds_read_b128 v[196:199], v139 offset:1024
	ds_read_b128 v[200:203], v137
	ds_read_b128 v[204:207], v137 offset:1024
	ds_read_b128 v[208:211], v135
	ds_read_b128 v[212:215], v135 offset:1024
	s_add_u32 s19, s4, s10
	s_addc_u32 s24, s5, s11
	s_add_u32 s26, s19, 0x36080080
	s_addc_u32 s27, s24, 0
	v_lshl_add_u64 v[216:217], s[26:27], 0, v[132:133]
	v_readfirstlane_b32 s25, v148
	s_mov_b32 m0, s25
	global_load_lds_dwordx4 v[216:217], off
	v_lshl_add_u64 v[216:217], s[26:27], 0, v[130:131]
	v_readfirstlane_b32 s25, v150
	s_mov_b32 m0, s25
	global_load_lds_dwordx4 v[216:217], off
	s_waitcnt lgkmcnt(8)
	s_barrier
	s_waitcnt lgkmcnt(0)
	s_setprio 1
	s_waitcnt lgkmcnt(7)
	v_mfma_f32_16x16x32_bf16 v[126:129], v[166:169], v[182:185], v[126:129]
	v_mfma_f32_16x16x32_bf16 v[122:125], v[174:177], v[182:185], v[122:125]
	s_waitcnt lgkmcnt(5)
	v_mfma_f32_16x16x32_bf16 v[118:121], v[166:169], v[190:193], v[118:121]
	v_mfma_f32_16x16x32_bf16 v[114:117], v[174:177], v[190:193], v[114:117]
	s_waitcnt lgkmcnt(3)
	v_mfma_f32_16x16x32_bf16 v[110:113], v[166:169], v[200:203], v[110:113]
	v_mfma_f32_16x16x32_bf16 v[106:109], v[174:177], v[200:203], v[106:109]
	s_waitcnt lgkmcnt(1)
	v_mfma_f32_16x16x32_bf16 v[102:105], v[166:169], v[208:211], v[102:105]
	v_mfma_f32_16x16x32_bf16 v[98:101], v[174:177], v[208:211], v[98:101]
	v_mfma_f32_16x16x32_bf16 v[126:129], v[170:173], v[186:189], v[126:129]
	v_mfma_f32_16x16x32_bf16 v[122:125], v[178:181], v[186:189], v[122:125]
	v_mfma_f32_16x16x32_bf16 v[118:121], v[170:173], v[196:199], v[118:121]
	v_mfma_f32_16x16x32_bf16 v[114:117], v[178:181], v[196:199], v[114:117]
	v_mfma_f32_16x16x32_bf16 v[110:113], v[170:173], v[204:207], v[110:113]
	v_mfma_f32_16x16x32_bf16 v[106:109], v[178:181], v[204:207], v[106:109]
	s_waitcnt lgkmcnt(0)
	v_mfma_f32_16x16x32_bf16 v[102:105], v[170:173], v[212:215], v[102:105]
	v_mfma_f32_16x16x32_bf16 v[98:101], v[178:181], v[212:215], v[98:101]
	s_setprio 0
	s_barrier
	s_add_u32 s25, s4, s16
	ds_read_b128 v[216:219], v147
	ds_read_b128 v[220:223], v147 offset:1024
	ds_read_b128 v[224:227], v147 offset:2048
	ds_read_b128 v[228:231], v147 offset:3072
	s_addc_u32 s26, s5, s17
	s_add_u32 s28, s25, 0x3400100
	s_addc_u32 s29, s26, 0
	v_lshl_add_u64 v[232:233], s[28:29], 0, v[132:133]
	v_readfirstlane_b32 s27, v152
	s_mov_b32 m0, s27
	global_load_lds_dwordx4 v[232:233], off
	v_lshl_add_u64 v[232:233], s[28:29], 0, v[130:131]
	v_readfirstlane_b32 s27, v154
	s_mov_b32 m0, s27
	global_load_lds_dwordx4 v[232:233], off
	s_barrier
	s_waitcnt lgkmcnt(0)
	s_setprio 1
	s_waitcnt lgkmcnt(3)
	v_mfma_f32_16x16x32_bf16 v[94:97], v[216:219], v[182:185], v[94:97]
	s_waitcnt lgkmcnt(1)
	v_mfma_f32_16x16x32_bf16 v[90:93], v[224:227], v[182:185], v[90:93]
	v_mfma_f32_16x16x32_bf16 v[86:89], v[216:219], v[190:193], v[86:89]
	v_mfma_f32_16x16x32_bf16 v[82:85], v[224:227], v[190:193], v[82:85]
	v_mfma_f32_16x16x32_bf16 v[78:81], v[216:219], v[200:203], v[78:81]
	v_mfma_f32_16x16x32_bf16 v[74:77], v[224:227], v[200:203], v[74:77]
	v_mfma_f32_16x16x32_bf16 v[70:73], v[216:219], v[208:211], v[70:73]
	v_mfma_f32_16x16x32_bf16 v[66:69], v[224:227], v[208:211], v[66:69]
	v_mfma_f32_16x16x32_bf16 v[94:97], v[220:223], v[186:189], v[94:97]
	s_waitcnt lgkmcnt(0)
	v_mfma_f32_16x16x32_bf16 v[90:93], v[228:231], v[186:189], v[90:93]
	v_mfma_f32_16x16x32_bf16 v[86:89], v[220:223], v[196:199], v[86:89]
	v_mfma_f32_16x16x32_bf16 v[82:85], v[228:231], v[196:199], v[82:85]
	v_mfma_f32_16x16x32_bf16 v[78:81], v[220:223], v[204:207], v[78:81]
	v_mfma_f32_16x16x32_bf16 v[74:77], v[228:231], v[204:207], v[74:77]
	v_mfma_f32_16x16x32_bf16 v[70:73], v[220:223], v[212:215], v[70:73]
	v_mfma_f32_16x16x32_bf16 v[66:69], v[228:231], v[212:215], v[66:69]
	s_setprio 0
	s_barrier
	ds_read_b128 v[182:185], v141 offset:16384
	ds_read_b128 v[186:189], v141 offset:17408
	ds_read_b128 v[190:193], v139 offset:16384
	ds_read_b128 v[196:199], v139 offset:17408
	ds_read_b128 v[200:203], v137 offset:16384
	ds_read_b128 v[204:207], v137 offset:17408
	ds_read_b128 v[208:211], v135 offset:16384
	ds_read_b128 v[212:215], v135 offset:17408
	s_add_u32 s28, s19, 0x36000100
	s_addc_u32 s29, s24, 0
	v_lshl_add_u64 v[232:233], s[28:29], 0, v[132:133]
	v_readfirstlane_b32 s27, v138
	s_mov_b32 m0, s27
	global_load_lds_dwordx4 v[232:233], off
	v_lshl_add_u64 v[232:233], s[28:29], 0, v[130:131]
	v_readfirstlane_b32 s27, v156
	s_mov_b32 m0, s27
	global_load_lds_dwordx4 v[232:233], off
	s_barrier
	s_waitcnt lgkmcnt(0)
	s_setprio 1
	s_waitcnt lgkmcnt(7)
	v_mfma_f32_16x16x32_bf16 v[62:65], v[166:169], v[182:185], v[62:65]
	v_mfma_f32_16x16x32_bf16 v[58:61], v[174:177], v[182:185], v[58:61]
	s_waitcnt lgkmcnt(5)
	v_mfma_f32_16x16x32_bf16 v[54:57], v[166:169], v[190:193], v[54:57]
	v_mfma_f32_16x16x32_bf16 v[50:53], v[174:177], v[190:193], v[50:53]
	s_waitcnt lgkmcnt(3)
	v_mfma_f32_16x16x32_bf16 v[46:49], v[166:169], v[200:203], v[46:49]
	v_mfma_f32_16x16x32_bf16 v[42:45], v[174:177], v[200:203], v[42:45]
	s_waitcnt lgkmcnt(1)
	v_mfma_f32_16x16x32_bf16 v[38:41], v[166:169], v[208:211], v[38:41]
	v_mfma_f32_16x16x32_bf16 v[34:37], v[174:177], v[208:211], v[34:37]
	v_mfma_f32_16x16x32_bf16 v[62:65], v[170:173], v[186:189], v[62:65]
	v_mfma_f32_16x16x32_bf16 v[58:61], v[178:181], v[186:189], v[58:61]
	v_mfma_f32_16x16x32_bf16 v[54:57], v[170:173], v[196:199], v[54:57]
	v_mfma_f32_16x16x32_bf16 v[50:53], v[178:181], v[196:199], v[50:53]
	v_mfma_f32_16x16x32_bf16 v[46:49], v[170:173], v[204:207], v[46:49]
	v_mfma_f32_16x16x32_bf16 v[42:45], v[178:181], v[204:207], v[42:45]
	s_waitcnt lgkmcnt(0)
	v_mfma_f32_16x16x32_bf16 v[38:41], v[170:173], v[212:215], v[38:41]
	v_mfma_f32_16x16x32_bf16 v[34:37], v[178:181], v[212:215], v[34:37]
	s_setprio 0
	s_barrier
;   #define LDA(dst,b,h) for(int m=0;m<4;++m)for(int k=0;k<2;++k) \
;     dst[m][k]=*reinterpret_cast<const bf16x8*>((char*)SA(b,h)+lds_byte(wr*64+m*16+fr,k*32+fq*8))
;   #define LDB(dst,b,h) for(int n=0;n<2;++n)for(int k=0;k<2;++k) \
;     dst[n][k]=*reinterpret_cast<const bf16x8*>((char*)SB(b,h)+lds_byte(wc*32+n*16+fr,k*32+fq*8))
;   #define MMA(ai,bj,At,Bt_) do{__builtin_amdgcn_s_setprio(1); \
;     for(int m=0;m<4;++m)for(int n=0;n<2;++n)for(int k=0;k<2;++k) \
;       acc[ai][bj][m][n]=__builtin_amdgcn_mfma_f32_16x16x32_bf16(Bt_[n][k],At[m][k],acc[ai][bj][m][n],0,0,0); \
;     __builtin_amdgcn_s_setprio(0);}while(0)
;   #define WAIT_V(n) asm volatile("s_waitcnt vmcnt(" #n ")":::"memory")
;   #define WAIT_L(n) asm volatile("s_waitcnt lgkmcnt(" #n ")":::"memory")
;   #define BAR __builtin_amdgcn_s_barrier()
;   #define SCHED __builtin_amdgcn_sched_barrier(0)
; template <bool TWO, class MID> ...
;     ...
;     LDB(B0,0,0); SCHED; LDA(At,0,0); STAGE_A(SA(1,1),1,t+1);
;     WAIT_L(8); BAR; WAIT_L(0); MMA(0,0,At,B0); BAR; SCHED;
;     LDB(B1,0,1); STAGE_B(SB(0,0),0,t+2);
;     BAR; WAIT_L(0); MMA(0,1,At,B1); BAR;
;     LDA(At,0,1); STAGE_A(SA(0,0),0,t+2);
;     BAR; WAIT_L(0); MMA(1,0,At,B0); BAR; SCHED;
;     STAGE_B(SB(0,1),1,t+2);
;     WAIT_V(6); BAR; MMA(1,1,At,B1); BAR;
;     LDB(B0,1,0); SCHED; LDA(At,1,0); STAGE_A(SA(0,1),1,t+2);
;     WAIT_L(8); BAR; WAIT_L(0); MMA(0,0,At,B0); BAR; SCHED;
;     LDB(B1,1,1); STAGE_B(SB(1,0),0,t+3);
;     BAR; WAIT_L(0); MMA(0,1,At,B1); BAR;
;     LDA(At,1,1); STAGE_A(SA(1,0),0,t+3);
;     BAR; WAIT_L(0); MMA(1,0,At,B0); BAR; SCHED;
;     STAGE_B(SB(1,1),1,t+3);
;     WAIT_V(6); BAR; MMA(1,1,At,B1); BAR;
	s_add_u32 s28, s25, 0x3480100
	s_addc_u32 s29, s26, 0
	v_lshl_add_u64 v[166:167], s[28:29], 0, v[132:133]
	v_readfirstlane_b32 s27, v158
	s_mov_b32 m0, s27
	global_load_lds_dwordx4 v[166:167], off
	v_lshl_add_u64 v[166:167], s[28:29], 0, v[130:131]
	v_readfirstlane_b32 s27, v160
	s_mov_b32 m0, s27
	global_load_lds_dwordx4 v[166:167], off
	s_waitcnt vmcnt(6)
	s_barrier
	s_setprio 1
	v_mfma_f32_16x16x32_bf16 v[30:33], v[216:219], v[182:185], v[30:33]
	v_mfma_f32_16x16x32_bf16 v[26:29], v[224:227], v[182:185], v[26:29]
	v_mfma_f32_16x16x32_bf16 v[22:25], v[216:219], v[190:193], v[22:25]
	v_mfma_f32_16x16x32_bf16 v[18:21], v[224:227], v[190:193], v[18:21]
	v_mfma_f32_16x16x32_bf16 v[14:17], v[216:219], v[200:203], v[14:17]
	v_mfma_f32_16x16x32_bf16 v[10:13], v[224:227], v[200:203], v[10:13]
	v_mfma_f32_16x16x32_bf16 v[6:9], v[216:219], v[208:211], v[6:9]
	v_mfma_f32_16x16x32_bf16 v[2:5], v[224:227], v[208:211], v[2:5]
	v_mfma_f32_16x16x32_bf16 v[30:33], v[220:223], v[186:189], v[30:33]
	v_mfma_f32_16x16x32_bf16 v[26:29], v[228:231], v[186:189], v[26:29]
	v_mfma_f32_16x16x32_bf16 v[22:25], v[220:223], v[196:199], v[22:25]
	v_mfma_f32_16x16x32_bf16 v[18:21], v[228:231], v[196:199], v[18:21]
	v_mfma_f32_16x16x32_bf16 v[14:17], v[220:223], v[204:207], v[14:17]
	v_mfma_f32_16x16x32_bf16 v[10:13], v[228:231], v[204:207], v[10:13]
	v_mfma_f32_16x16x32_bf16 v[6:9], v[220:223], v[212:215], v[6:9]
	v_mfma_f32_16x16x32_bf16 v[2:5], v[228:231], v[212:215], v[2:5]
	s_setprio 0
	s_barrier
	ds_read_b128 v[166:169], v145
	ds_read_b128 v[170:173], v145 offset:1024
	ds_read_b128 v[174:177], v145 offset:2048
	ds_read_b128 v[178:181], v145 offset:3072
	ds_read_b128 v[182:185], v141 offset:32768
	ds_read_b128 v[186:189], v141 offset:33792
	ds_read_b128 v[190:193], v139 offset:32768
	ds_read_b128 v[196:199], v139 offset:33792
	ds_read_b128 v[200:203], v137 offset:32768
	ds_read_b128 v[204:207], v137 offset:33792
	ds_read_b128 v[208:211], v135 offset:32768
	ds_read_b128 v[212:215], v135 offset:33792
	s_add_u32 s28, s19, 0x36080100
	s_addc_u32 s29, s24, 0
	v_lshl_add_u64 v[216:217], s[28:29], 0, v[132:133]
	v_readfirstlane_b32 s27, v162
	s_mov_b32 m0, s27
	global_load_lds_dwordx4 v[216:217], off
	v_lshl_add_u64 v[216:217], s[28:29], 0, v[130:131]
	v_readfirstlane_b32 s27, v164
	s_mov_b32 m0, s27
	global_load_lds_dwordx4 v[216:217], off
	s_waitcnt lgkmcnt(8)
	s_barrier
	s_waitcnt lgkmcnt(0)
	s_setprio 1
	s_waitcnt lgkmcnt(7)
	v_mfma_f32_16x16x32_bf16 v[126:129], v[166:169], v[182:185], v[126:129]
	v_mfma_f32_16x16x32_bf16 v[122:125], v[174:177], v[182:185], v[122:125]
	s_waitcnt lgkmcnt(5)
	v_mfma_f32_16x16x32_bf16 v[118:121], v[166:169], v[190:193], v[118:121]
	v_mfma_f32_16x16x32_bf16 v[114:117], v[174:177], v[190:193], v[114:117]
	s_waitcnt lgkmcnt(3)
	v_mfma_f32_16x16x32_bf16 v[110:113], v[166:169], v[200:203], v[110:113]
	v_mfma_f32_16x16x32_bf16 v[106:109], v[174:177], v[200:203], v[106:109]
	s_waitcnt lgkmcnt(1)
	v_mfma_f32_16x16x32_bf16 v[102:105], v[166:169], v[208:211], v[102:105]
	v_mfma_f32_16x16x32_bf16 v[98:101], v[174:177], v[208:211], v[98:101]
	v_mfma_f32_16x16x32_bf16 v[126:129], v[170:173], v[186:189], v[126:129]
	v_mfma_f32_16x16x32_bf16 v[122:125], v[178:181], v[186:189], v[122:125]
	v_mfma_f32_16x16x32_bf16 v[118:121], v[170:173], v[196:199], v[118:121]
	v_mfma_f32_16x16x32_bf16 v[114:117], v[178:181], v[196:199], v[114:117]
	v_mfma_f32_16x16x32_bf16 v[110:113], v[170:173], v[204:207], v[110:113]
	v_mfma_f32_16x16x32_bf16 v[106:109], v[178:181], v[204:207], v[106:109]
	s_waitcnt lgkmcnt(0)
	v_mfma_f32_16x16x32_bf16 v[102:105], v[170:173], v[212:215], v[102:105]
	v_mfma_f32_16x16x32_bf16 v[98:101], v[178:181], v[212:215], v[98:101]
	s_setprio 0
	s_barrier
	ds_read_b128 v[216:219], v143
	ds_read_b128 v[220:223], v143 offset:1024
	ds_read_b128 v[224:227], v143 offset:2048
	ds_read_b128 v[228:231], v143 offset:3072
	s_add_u32 s28, s25, 0x3400180
	s_addc_u32 s29, s26, 0
	v_lshl_add_u64 v[232:233], s[28:29], 0, v[132:133]
	v_readfirstlane_b32 s27, v134
	s_mov_b32 m0, s27
	global_load_lds_dwordx4 v[232:233], off
	v_lshl_add_u64 v[232:233], s[28:29], 0, v[130:131]
	v_readfirstlane_b32 s27, v136
	s_mov_b32 m0, s27
	global_load_lds_dwordx4 v[232:233], off
	s_barrier
	s_waitcnt lgkmcnt(0)
	s_setprio 1
	s_waitcnt lgkmcnt(3)
	v_mfma_f32_16x16x32_bf16 v[94:97], v[216:219], v[182:185], v[94:97]
	s_waitcnt lgkmcnt(1)
	v_mfma_f32_16x16x32_bf16 v[90:93], v[224:227], v[182:185], v[90:93]
	v_mfma_f32_16x16x32_bf16 v[86:89], v[216:219], v[190:193], v[86:89]
	v_mfma_f32_16x16x32_bf16 v[82:85], v[224:227], v[190:193], v[82:85]
	v_mfma_f32_16x16x32_bf16 v[78:81], v[216:219], v[200:203], v[78:81]
	v_mfma_f32_16x16x32_bf16 v[74:77], v[224:227], v[200:203], v[74:77]
	v_mfma_f32_16x16x32_bf16 v[70:73], v[216:219], v[208:211], v[70:73]
	v_mfma_f32_16x16x32_bf16 v[66:69], v[224:227], v[208:211], v[66:69]
	v_mfma_f32_16x16x32_bf16 v[94:97], v[220:223], v[186:189], v[94:97]
	s_waitcnt lgkmcnt(0)
	v_mfma_f32_16x16x32_bf16 v[90:93], v[228:231], v[186:189], v[90:93]
	v_mfma_f32_16x16x32_bf16 v[86:89], v[220:223], v[196:199], v[86:89]
	v_mfma_f32_16x16x32_bf16 v[82:85], v[228:231], v[196:199], v[82:85]
	v_mfma_f32_16x16x32_bf16 v[78:81], v[220:223], v[204:207], v[78:81]
	v_mfma_f32_16x16x32_bf16 v[74:77], v[228:231], v[204:207], v[74:77]
	v_mfma_f32_16x16x32_bf16 v[70:73], v[220:223], v[212:215], v[70:73]
	v_mfma_f32_16x16x32_bf16 v[66:69], v[228:231], v[212:215], v[66:69]
	s_setprio 0
	s_barrier
;   #define LDA(dst,b,h) for(int m=0;m<4;++m)for(int k=0;k<2;++k) \
;     dst[m][k]=*reinterpret_cast<const bf16x8*>((char*)SA(b,h)+lds_byte(wr*64+m*16+fr,k*32+fq*8))
;   #define LDB(dst,b,h) for(int n=0;n<2;++n)for(int k=0;k<2;++k) \
;     dst[n][k]=*reinterpret_cast<const bf16x8*>((char*)SB(b,h)+lds_byte(wc*32+n*16+fr,k*32+fq*8))
;   #define MMA(ai,bj,At,Bt_) do{__builtin_amdgcn_s_setprio(1); \
;     for(int m=0;m<4;++m)for(int n=0;n<2;++n)for(int k=0;k<2;++k) \
;       acc[ai][bj][m][n]=__builtin_amdgcn_mfma_f32_16x16x32_bf16(Bt_[n][k],At[m][k],acc[ai][bj][m][n],0,0,0); \
;     __builtin_amdgcn_s_setprio(0);}while(0)
;   #define WAIT_V(n) asm volatile("s_waitcnt vmcnt(" #n ")":::"memory")
;   #define WAIT_L(n) asm volatile("s_waitcnt lgkmcnt(" #n ")":::"memory")
;   #define BAR __builtin_amdgcn_s_barrier()
;   #define SCHED __builtin_amdgcn_sched_barrier(0)
; template <bool TWO, class MID> ...
;     ...
;     LDB(B0,0,0); SCHED; LDA(At,0,0); STAGE_A(SA(1,1),1,t+1);
;     WAIT_L(8); BAR; WAIT_L(0); MMA(0,0,At,B0); BAR; SCHED;
;     LDB(B1,0,1); STAGE_B(SB(0,0),0,t+2);
;     BAR; WAIT_L(0); MMA(0,1,At,B1); BAR;
;     LDA(At,0,1); STAGE_A(SA(0,0),0,t+2);
;     BAR; WAIT_L(0); MMA(1,0,At,B0); BAR; SCHED;
;     STAGE_B(SB(0,1),1,t+2);
;     WAIT_V(6); BAR; MMA(1,1,At,B1); BAR;
;     LDB(B0,1,0); SCHED; LDA(At,1,0); STAGE_A(SA(0,1),1,t+2);
;     WAIT_L(8); BAR; WAIT_L(0); MMA(0,0,At,B0); BAR; SCHED;
;     LDB(B1,1,1); STAGE_B(SB(1,0),0,t+3);
;     BAR; WAIT_L(0); MMA(0,1,At,B1); BAR;
;     LDA(At,1,1); STAGE_A(SA(1,0),0,t+3);
;     BAR; WAIT_L(0); MMA(1,0,At,B0); BAR; SCHED;
;     STAGE_B(SB(1,1),1,t+3);
;     WAIT_V(6); BAR; MMA(1,1,At,B1); BAR;
;   }
;   { LDB(B0,0,0); LDA(At,0,0); STAGE_A(SA(1,1),1,nt-1);
;     BAR; WAIT_L(0); MMA(0,0,At,B0); BAR;
	ds_read_b128 v[182:185], v141 offset:49152
	ds_read_b128 v[186:189], v141 offset:50176
	ds_read_b128 v[190:193], v139 offset:49152
	ds_read_b128 v[196:199], v139 offset:50176
	ds_read_b128 v[200:203], v137 offset:49152
	ds_read_b128 v[204:207], v137 offset:50176
	ds_read_b128 v[208:211], v135 offset:49152
	ds_read_b128 v[212:215], v135 offset:50176
	s_add_u32 s28, s19, 0x36000180
	s_addc_u32 s29, s24, 0
	v_lshl_add_u64 v[232:233], s[28:29], 0, v[132:133]
	v_readfirstlane_b32 s19, v140
	s_mov_b32 m0, s19
	global_load_lds_dwordx4 v[232:233], off
	v_lshl_add_u64 v[232:233], s[28:29], 0, v[130:131]
	v_readfirstlane_b32 s19, v142
	s_mov_b32 m0, s19
	global_load_lds_dwordx4 v[232:233], off
	s_barrier
	s_waitcnt lgkmcnt(0)
	s_setprio 1
	s_waitcnt lgkmcnt(7)
	v_mfma_f32_16x16x32_bf16 v[62:65], v[166:169], v[182:185], v[62:65]
	v_mfma_f32_16x16x32_bf16 v[58:61], v[174:177], v[182:185], v[58:61]
	s_waitcnt lgkmcnt(5)
	v_mfma_f32_16x16x32_bf16 v[54:57], v[166:169], v[190:193], v[54:57]
	v_mfma_f32_16x16x32_bf16 v[50:53], v[174:177], v[190:193], v[50:53]
	s_waitcnt lgkmcnt(3)
	v_mfma_f32_16x16x32_bf16 v[46:49], v[166:169], v[200:203], v[46:49]
	v_mfma_f32_16x16x32_bf16 v[42:45], v[174:177], v[200:203], v[42:45]
	s_waitcnt lgkmcnt(1)
	v_mfma_f32_16x16x32_bf16 v[38:41], v[166:169], v[208:211], v[38:41]
	v_mfma_f32_16x16x32_bf16 v[34:37], v[174:177], v[208:211], v[34:37]
	v_mfma_f32_16x16x32_bf16 v[62:65], v[170:173], v[186:189], v[62:65]
	v_mfma_f32_16x16x32_bf16 v[58:61], v[178:181], v[186:189], v[58:61]
	v_mfma_f32_16x16x32_bf16 v[54:57], v[170:173], v[196:199], v[54:57]
	v_mfma_f32_16x16x32_bf16 v[50:53], v[178:181], v[196:199], v[50:53]
	v_mfma_f32_16x16x32_bf16 v[46:49], v[170:173], v[204:207], v[46:49]
	v_mfma_f32_16x16x32_bf16 v[42:45], v[178:181], v[204:207], v[42:45]
	s_waitcnt lgkmcnt(0)
	v_mfma_f32_16x16x32_bf16 v[38:41], v[170:173], v[212:215], v[38:41]
	v_mfma_f32_16x16x32_bf16 v[34:37], v[178:181], v[212:215], v[34:37]
	s_setprio 0
	s_barrier
	s_add_u32 s24, s25, 0x3480180
	s_addc_u32 s25, s26, 0
	v_lshl_add_u64 v[166:167], s[24:25], 0, v[132:133]
	v_readfirstlane_b32 s19, v144
	s_mov_b32 m0, s19
	global_load_lds_dwordx4 v[166:167], off
	v_lshl_add_u64 v[166:167], s[24:25], 0, v[130:131]
	v_readfirstlane_b32 s19, v146
	s_mov_b32 m0, s19
	global_load_lds_dwordx4 v[166:167], off
	s_waitcnt vmcnt(6)
	s_barrier
	s_setprio 1
	v_mfma_f32_16x16x32_bf16 v[30:33], v[216:219], v[182:185], v[30:33]
	v_mfma_f32_16x16x32_bf16 v[26:29], v[224:227], v[182:185], v[26:29]
	v_mfma_f32_16x16x32_bf16 v[22:25], v[216:219], v[190:193], v[22:25]
	v_mfma_f32_16x16x32_bf16 v[18:21], v[224:227], v[190:193], v[18:21]
	v_mfma_f32_16x16x32_bf16 v[14:17], v[216:219], v[200:203], v[14:17]
	v_mfma_f32_16x16x32_bf16 v[10:13], v[224:227], v[200:203], v[10:13]
	v_mfma_f32_16x16x32_bf16 v[6:9], v[216:219], v[208:211], v[6:9]
	v_mfma_f32_16x16x32_bf16 v[2:5], v[224:227], v[208:211], v[2:5]
	v_mfma_f32_16x16x32_bf16 v[30:33], v[220:223], v[186:189], v[30:33]
	v_mfma_f32_16x16x32_bf16 v[26:29], v[228:231], v[186:189], v[26:29]
	v_mfma_f32_16x16x32_bf16 v[22:25], v[220:223], v[196:199], v[22:25]
	v_mfma_f32_16x16x32_bf16 v[18:21], v[228:231], v[196:199], v[18:21]
	v_mfma_f32_16x16x32_bf16 v[14:17], v[220:223], v[204:207], v[14:17]
	v_mfma_f32_16x16x32_bf16 v[10:13], v[228:231], v[204:207], v[10:13]
	v_mfma_f32_16x16x32_bf16 v[6:9], v[220:223], v[212:215], v[6:9]
	v_mfma_f32_16x16x32_bf16 v[2:5], v[228:231], v[212:215], v[2:5]
	s_setprio 0
	s_add_i32 s18, s18, 2
	s_add_u32 s4, s4, 0x100
	s_addc_u32 s5, s5, 0
	s_cmp_lt_u32 s18, 28
	s_barrier
	s_cbranch_scc1 .LBB0_489
	ds_read_b128 v[152:155], v149
	ds_read_b128 v[156:159], v149 offset:1024
	ds_read_b128 v[160:163], v149 offset:2048
	ds_read_b128 v[164:167], v149 offset:3072
	ds_read_b128 v[168:171], v141
	ds_read_b128 v[172:175], v141 offset:1024
	ds_read_b128 v[176:179], v139
	ds_read_b128 v[180:183], v139 offset:1024
	ds_read_b128 v[184:187], v137
	ds_read_b128 v[188:191], v137 offset:1024
	ds_read_b128 v[196:199], v135
	ds_read_b128 v[200:203], v135 offset:1024
	s_add_u32 s4, s12, 0x80f80
	s_addc_u32 s5, s13, 0
	v_lshl_add_u64 v[132:133], s[4:5], 0, v[132:133]
	v_readfirstlane_b32 s12, v148
	s_mov_b32 m0, s12
	global_load_lds_dwordx4 v[132:133], off
	v_lshl_add_u64 v[130:131], s[4:5], 0, v[130:131]
	v_readfirstlane_b32 s4, v150
	s_mov_b32 m0, s4
	global_load_lds_dwordx4 v[130:131], off
	s_barrier
	s_waitcnt lgkmcnt(0)
	s_setprio 1
	s_waitcnt lgkmcnt(7)
	v_mfma_f32_16x16x32_bf16 v[126:129], v[152:155], v[168:171], v[126:129]
	v_mfma_f32_16x16x32_bf16 v[122:125], v[160:163], v[168:171], v[122:125]
	s_waitcnt lgkmcnt(5)
	v_mfma_f32_16x16x32_bf16 v[118:121], v[152:155], v[176:179], v[118:121]
	v_mfma_f32_16x16x32_bf16 v[114:117], v[160:163], v[176:179], v[114:117]
	s_waitcnt lgkmcnt(1)
	v_mfma_f32_16x16x32_bf16 v[102:105], v[152:155], v[196:199], v[102:105]
	v_mfma_f32_16x16x32_bf16 v[98:101], v[160:163], v[196:199], v[98:101]
	v_mfma_f32_16x16x32_bf16 v[126:129], v[156:159], v[172:175], v[126:129]
	v_mfma_f32_16x16x32_bf16 v[122:125], v[164:167], v[172:175], v[122:125]
	v_mfma_f32_16x16x32_bf16 v[118:121], v[156:159], v[180:183], v[118:121]
	v_mfma_f32_16x16x32_bf16 v[114:117], v[164:167], v[180:183], v[114:117]
	v_mfma_f32_16x16x32_bf16 v[110:113], v[152:155], v[184:187], v[110:113]
	v_mfma_f32_16x16x32_bf16 v[106:109], v[160:163], v[184:187], v[106:109]
	s_waitcnt lgkmcnt(0)
	v_mfma_f32_16x16x32_bf16 v[102:105], v[156:159], v[200:203], v[102:105]
	v_mfma_f32_16x16x32_bf16 v[98:101], v[164:167], v[200:203], v[98:101]
	v_mfma_f32_16x16x32_bf16 v[130:133], v[156:159], v[188:191], v[110:113]
	v_mfma_f32_16x16x32_bf16 v[148:151], v[164:167], v[188:191], v[106:109]
	s_setprio 0
	s_barrier
;   #define LDA(dst,b,h) for(int m=0;m<4;++m)for(int k=0;k<2;++k) \
;     dst[m][k]=*reinterpret_cast<const bf16x8*>((char*)SA(b,h)+lds_byte(wr*64+m*16+fr,k*32+fq*8))
;   #define LDB(dst,b,h) for(int n=0;n<2;++n)for(int k=0;k<2;++k) \
;     dst[n][k]=*reinterpret_cast<const bf16x8*>((char*)SB(b,h)+lds_byte(wc*32+n*16+fr,k*32+fq*8))
;   #define MMA(ai,bj,At,Bt_) do{__builtin_amdgcn_s_setprio(1); \
;     for(int m=0;m<4;++m)for(int n=0;n<2;++n)for(int k=0;k<2;++k) \
;       acc[ai][bj][m][n]=__builtin_amdgcn_mfma_f32_16x16x32_bf16(Bt_[n][k],At[m][k],acc[ai][bj][m][n],0,0,0); \
;     __builtin_amdgcn_s_setprio(0);}while(0)
;   #define WAIT_V(n) asm volatile("s_waitcnt vmcnt(" #n ")":::"memory")
;   #define WAIT_L(n) asm volatile("s_waitcnt lgkmcnt(" #n ")":::"memory")
;   #define BAR __builtin_amdgcn_s_barrier()
; template <bool TWO, class MID> ...
;     ...
;     BAR; WAIT_L(0); MMA(0,0,At,B0); BAR;
;     LDB(B1,0,1); BAR; WAIT_L(0); MMA(0,1,At,B1); BAR;
;     LDA(At,0,1); WAIT_V(4); BAR; WAIT_L(0); MMA(1,0,At,B0); MMA(1,1,At,B1); BAR; }
;   { LDB(B0,1,0); LDA(At,1,0); WAIT_V(2); BAR; WAIT_L(0); MMA(0,0,At,B0); BAR;
	s_nop 0
	ds_read_b128 v[106:109], v147
	ds_read_b128 v[110:113], v147 offset:1024
	ds_read_b128 v[204:207], v147 offset:2048
	ds_read_b128 v[208:211], v147 offset:3072
	s_barrier
	s_waitcnt lgkmcnt(0)
	s_setprio 1
	s_waitcnt lgkmcnt(3)
	v_mfma_f32_16x16x32_bf16 v[86:89], v[106:109], v[176:179], v[86:89]
	s_waitcnt lgkmcnt(1)
	v_mfma_f32_16x16x32_bf16 v[82:85], v[204:207], v[176:179], v[82:85]
	v_mfma_f32_16x16x32_bf16 v[70:73], v[106:109], v[196:199], v[70:73]
	v_mfma_f32_16x16x32_bf16 v[66:69], v[204:207], v[196:199], v[66:69]
	v_mfma_f32_16x16x32_bf16 v[94:97], v[106:109], v[168:171], v[94:97]
	v_mfma_f32_16x16x32_bf16 v[90:93], v[204:207], v[168:171], v[90:93]
	v_mfma_f32_16x16x32_bf16 v[86:89], v[110:113], v[180:183], v[86:89]
	s_waitcnt lgkmcnt(0)
	v_mfma_f32_16x16x32_bf16 v[82:85], v[208:211], v[180:183], v[82:85]
	v_mfma_f32_16x16x32_bf16 v[78:81], v[106:109], v[184:187], v[78:81]
	v_mfma_f32_16x16x32_bf16 v[74:77], v[204:207], v[184:187], v[74:77]
	v_mfma_f32_16x16x32_bf16 v[70:73], v[110:113], v[200:203], v[70:73]
	v_mfma_f32_16x16x32_bf16 v[66:69], v[208:211], v[200:203], v[66:69]
	v_mfma_f32_16x16x32_bf16 v[212:215], v[110:113], v[172:175], v[94:97]
	v_mfma_f32_16x16x32_bf16 v[168:171], v[208:211], v[172:175], v[90:93]
	v_mfma_f32_16x16x32_bf16 v[172:175], v[110:113], v[188:191], v[78:81]
	v_mfma_f32_16x16x32_bf16 v[176:179], v[208:211], v[188:191], v[74:77]
	s_setprio 0
	s_barrier
	s_nop 0
	ds_read_b128 v[74:77], v141 offset:16384
	ds_read_b128 v[78:81], v141 offset:17408
	ds_read_b128 v[90:93], v139 offset:16384
	ds_read_b128 v[94:97], v139 offset:17408
	ds_read_b128 v[180:183], v137 offset:16384
	ds_read_b128 v[184:187], v137 offset:17408
	ds_read_b128 v[188:191], v135 offset:16384
	ds_read_b128 v[196:199], v135 offset:17408
	s_waitcnt vmcnt(4)
	s_barrier
	s_waitcnt lgkmcnt(0)
	s_setprio 1
	s_waitcnt lgkmcnt(7)
	v_mfma_f32_16x16x32_bf16 v[62:65], v[152:155], v[74:77], v[62:65]
	v_mfma_f32_16x16x32_bf16 v[58:61], v[160:163], v[74:77], v[58:61]
	s_waitcnt lgkmcnt(5)
	v_mfma_f32_16x16x32_bf16 v[54:57], v[152:155], v[90:93], v[54:57]
	v_mfma_f32_16x16x32_bf16 v[50:53], v[160:163], v[90:93], v[50:53]
	s_waitcnt lgkmcnt(1)
	v_mfma_f32_16x16x32_bf16 v[38:41], v[152:155], v[188:191], v[38:41]
	v_mfma_f32_16x16x32_bf16 v[34:37], v[160:163], v[188:191], v[34:37]
	v_mfma_f32_16x16x32_bf16 v[62:65], v[156:159], v[78:81], v[62:65]
	v_mfma_f32_16x16x32_bf16 v[58:61], v[164:167], v[78:81], v[58:61]
	v_mfma_f32_16x16x32_bf16 v[54:57], v[156:159], v[94:97], v[54:57]
	v_mfma_f32_16x16x32_bf16 v[50:53], v[164:167], v[94:97], v[50:53]
	v_mfma_f32_16x16x32_bf16 v[46:49], v[152:155], v[180:183], v[46:49]
	v_mfma_f32_16x16x32_bf16 v[42:45], v[160:163], v[180:183], v[42:45]
	s_waitcnt lgkmcnt(0)
	v_mfma_f32_16x16x32_bf16 v[38:41], v[156:159], v[196:199], v[38:41]
	v_mfma_f32_16x16x32_bf16 v[34:37], v[164:167], v[196:199], v[34:37]
	v_mfma_f32_16x16x32_bf16 v[200:203], v[156:159], v[184:187], v[46:49]
	v_mfma_f32_16x16x32_bf16 v[216:219], v[164:167], v[184:187], v[42:45]
	s_setprio 0
	s_setprio 1
	v_mfma_f32_16x16x32_bf16 v[22:25], v[106:109], v[90:93], v[22:25]
	v_mfma_f32_16x16x32_bf16 v[18:21], v[204:207], v[90:93], v[18:21]
	v_mfma_f32_16x16x32_bf16 v[6:9], v[106:109], v[188:191], v[6:9]
	v_mfma_f32_16x16x32_bf16 v[2:5], v[204:207], v[188:191], v[2:5]
	v_mfma_f32_16x16x32_bf16 v[30:33], v[106:109], v[74:77], v[30:33]
	v_mfma_f32_16x16x32_bf16 v[26:29], v[204:207], v[74:77], v[26:29]
	v_mfma_f32_16x16x32_bf16 v[22:25], v[110:113], v[94:97], v[22:25]
	v_mfma_f32_16x16x32_bf16 v[18:21], v[208:211], v[94:97], v[18:21]
	v_mfma_f32_16x16x32_bf16 v[14:17], v[106:109], v[180:183], v[14:17]
	v_mfma_f32_16x16x32_bf16 v[10:13], v[204:207], v[180:183], v[10:13]
	v_mfma_f32_16x16x32_bf16 v[6:9], v[110:113], v[196:199], v[6:9]
	v_mfma_f32_16x16x32_bf16 v[2:5], v[208:211], v[196:199], v[2:5]
	v_mfma_f32_16x16x32_bf16 v[152:155], v[110:113], v[78:81], v[30:33]
	v_mfma_f32_16x16x32_bf16 v[156:159], v[208:211], v[78:81], v[26:29]
	v_mfma_f32_16x16x32_bf16 v[160:163], v[110:113], v[184:187], v[14:17]
	v_mfma_f32_16x16x32_bf16 v[164:167], v[208:211], v[184:187], v[10:13]
	s_setprio 0
	s_barrier
	s_nop 0
	ds_read_b128 v[10:13], v145
	ds_read_b128 v[14:17], v145 offset:1024
	ds_read_b128 v[180:183], v145 offset:2048
	ds_read_b128 v[144:147], v145 offset:3072
	ds_read_b128 v[26:29], v141 offset:32768
	ds_read_b128 v[30:33], v141 offset:33792
	ds_read_b128 v[42:45], v139 offset:32768
	ds_read_b128 v[46:49], v139 offset:33792
	ds_read_b128 v[184:187], v137 offset:32768
	ds_read_b128 v[188:191], v137 offset:33792
	ds_read_b128 v[196:199], v135 offset:32768
	ds_read_b128 v[204:207], v135 offset:33792
	s_waitcnt vmcnt(2)
	s_barrier
;   #define LDA(dst,b,h) for(int m=0;m<4;++m)for(int k=0;k<2;++k) \
;     dst[m][k]=*reinterpret_cast<const bf16x8*>((char*)SA(b,h)+lds_byte(wr*64+m*16+fr,k*32+fq*8))
;   #define LDB(dst,b,h) for(int n=0;n<2;++n)for(int k=0;k<2;++k) \
;     dst[n][k]=*reinterpret_cast<const bf16x8*>((char*)SB(b,h)+lds_byte(wc*32+n*16+fr,k*32+fq*8))
;   #define MMA(ai,bj,At,Bt_) do{__builtin_amdgcn_s_setprio(1); \
;     for(int m=0;m<4;++m)for(int n=0;n<2;++n)for(int k=0;k<2;++k) \
;       acc[ai][bj][m][n]=__builtin_amdgcn_mfma_f32_16x16x32_bf16(Bt_[n][k],At[m][k],acc[ai][bj][m][n],0,0,0); \
;     __builtin_amdgcn_s_setprio(0);}while(0)
;   #define WAIT_V(n) asm volatile("s_waitcnt vmcnt(" #n ")":::"memory")
;   #define WAIT_L(n) asm volatile("s_waitcnt lgkmcnt(" #n ")":::"memory")
;   #define BAR __builtin_amdgcn_s_barrier()
; template <bool TWO, class MID> ...
;     ...
;     LDB(B1,0,1); BAR; WAIT_L(0); MMA(0,1,At,B1); BAR;
;     LDA(At,0,1); WAIT_V(4); BAR; WAIT_L(0); MMA(1,0,At,B0); MMA(1,1,At,B1); BAR; }
;   { LDB(B0,1,0); LDA(At,1,0); WAIT_V(2); BAR; WAIT_L(0); MMA(0,0,At,B0); BAR;
;     LDB(B1,1,1); WAIT_V(0); BAR; WAIT_L(0); MMA(0,1,At,B1); BAR;
;     LDA(At,1,1); BAR; WAIT_L(0); MMA(1,0,At,B0); MMA(1,1,At,B1); BAR; }
;   if(wr==0)BAR;
	s_waitcnt lgkmcnt(0)
	s_setprio 1
	s_waitcnt lgkmcnt(7)
	v_mfma_f32_16x16x32_bf16 v[74:77], v[10:13], v[26:29], v[126:129]
	s_waitcnt lgkmcnt(6)
	v_mfma_f32_16x16x32_bf16 v[126:129], v[14:17], v[30:33], v[74:77]
	v_mfma_f32_16x16x32_bf16 v[74:77], v[180:183], v[26:29], v[122:125]
	v_mfma_f32_16x16x32_bf16 v[122:125], v[144:147], v[30:33], v[74:77]
	s_waitcnt lgkmcnt(5)
	v_mfma_f32_16x16x32_bf16 v[74:77], v[10:13], v[42:45], v[118:121]
	s_waitcnt lgkmcnt(4)
	v_mfma_f32_16x16x32_bf16 v[110:113], v[14:17], v[46:49], v[74:77]
	v_mfma_f32_16x16x32_bf16 v[74:77], v[180:183], v[42:45], v[114:117]
	v_mfma_f32_16x16x32_bf16 v[106:109], v[144:147], v[46:49], v[74:77]
	s_waitcnt lgkmcnt(3)
	v_mfma_f32_16x16x32_bf16 v[74:77], v[10:13], v[184:187], v[130:133]
	s_waitcnt lgkmcnt(2)
	v_mfma_f32_16x16x32_bf16 v[94:97], v[14:17], v[188:191], v[74:77]
	v_mfma_f32_16x16x32_bf16 v[74:77], v[180:183], v[184:187], v[148:151]
	v_mfma_f32_16x16x32_bf16 v[90:93], v[144:147], v[188:191], v[74:77]
	s_waitcnt lgkmcnt(1)
	v_mfma_f32_16x16x32_bf16 v[74:77], v[10:13], v[196:199], v[102:105]
	s_waitcnt lgkmcnt(0)
	v_mfma_f32_16x16x32_bf16 v[78:81], v[14:17], v[204:207], v[74:77]
	v_mfma_f32_16x16x32_bf16 v[74:77], v[180:183], v[196:199], v[98:101]
	v_mfma_f32_16x16x32_bf16 v[74:77], v[144:147], v[204:207], v[74:77]
	s_setprio 0
	s_barrier
	ds_read_b128 v[130:133], v143
	ds_read_b128 v[148:151], v143 offset:1024
	ds_read_b128 v[208:211], v143 offset:2048
	ds_read_b128 v[220:223], v143 offset:3072
	s_waitcnt vmcnt(0)
	s_barrier
	s_waitcnt lgkmcnt(0)
	s_setprio 1
	s_waitcnt lgkmcnt(3)
	v_mfma_f32_16x16x32_bf16 v[98:101], v[130:133], v[26:29], v[212:215]
	s_waitcnt lgkmcnt(1)
	v_mfma_f32_16x16x32_bf16 v[26:29], v[208:211], v[26:29], v[168:171]
	s_waitcnt lgkmcnt(0)
	v_mfma_f32_16x16x32_bf16 v[114:117], v[220:223], v[30:33], v[26:29]
	v_mfma_f32_16x16x32_bf16 v[26:29], v[130:133], v[42:45], v[86:89]
	v_mfma_f32_16x16x32_bf16 v[102:105], v[148:151], v[46:49], v[26:29]
	v_mfma_f32_16x16x32_bf16 v[26:29], v[208:211], v[42:45], v[82:85]
	v_mfma_f32_16x16x32_bf16 v[118:121], v[148:151], v[30:33], v[98:101]
	v_mfma_f32_16x16x32_bf16 v[98:101], v[220:223], v[46:49], v[26:29]
	v_mfma_f32_16x16x32_bf16 v[26:29], v[130:133], v[184:187], v[172:175]
	v_mfma_f32_16x16x32_bf16 v[86:89], v[148:151], v[188:191], v[26:29]
	v_mfma_f32_16x16x32_bf16 v[26:29], v[208:211], v[184:187], v[176:179]
	v_mfma_f32_16x16x32_bf16 v[82:85], v[220:223], v[188:191], v[26:29]
	v_mfma_f32_16x16x32_bf16 v[26:29], v[130:133], v[196:199], v[70:73]
	v_mfma_f32_16x16x32_bf16 v[70:73], v[148:151], v[204:207], v[26:29]
	v_mfma_f32_16x16x32_bf16 v[26:29], v[208:211], v[196:199], v[66:69]
	v_mfma_f32_16x16x32_bf16 v[66:69], v[220:223], v[204:207], v[26:29]
	s_setprio 0
	s_barrier
	ds_read_b128 v[168:171], v141 offset:49152
	ds_read_b128 v[140:143], v141 offset:50176
	ds_read_b128 v[172:175], v139 offset:49152
	ds_read_b128 v[176:179], v139 offset:50176
	ds_read_b128 v[184:187], v137 offset:49152
	ds_read_b128 v[136:139], v137 offset:50176
	ds_read_b128 v[188:191], v135 offset:49152
	ds_read_b128 v[196:199], v135 offset:50176
	s_barrier
	s_waitcnt lgkmcnt(0)
	s_setprio 1
	s_waitcnt lgkmcnt(7)
	v_mfma_f32_16x16x32_bf16 v[26:29], v[10:13], v[168:171], v[62:65]
	s_waitcnt lgkmcnt(6)
	v_mfma_f32_16x16x32_bf16 v[62:65], v[14:17], v[140:143], v[26:29]
	v_mfma_f32_16x16x32_bf16 v[26:29], v[180:183], v[168:171], v[58:61]
	v_mfma_f32_16x16x32_bf16 v[58:61], v[144:147], v[140:143], v[26:29]
	s_waitcnt lgkmcnt(5)
	v_mfma_f32_16x16x32_bf16 v[26:29], v[10:13], v[172:175], v[54:57]
	s_waitcnt lgkmcnt(4)
	v_mfma_f32_16x16x32_bf16 v[46:49], v[14:17], v[176:179], v[26:29]
	v_mfma_f32_16x16x32_bf16 v[26:29], v[180:183], v[172:175], v[50:53]
	v_mfma_f32_16x16x32_bf16 v[42:45], v[144:147], v[176:179], v[26:29]
	s_waitcnt lgkmcnt(3)
	v_mfma_f32_16x16x32_bf16 v[26:29], v[10:13], v[184:187], v[200:203]
	s_waitcnt lgkmcnt(1)
	v_mfma_f32_16x16x32_bf16 v[10:13], v[10:13], v[188:191], v[38:41]
	v_mfma_f32_16x16x32_bf16 v[30:33], v[14:17], v[136:139], v[26:29]
	v_mfma_f32_16x16x32_bf16 v[26:29], v[180:183], v[184:187], v[216:219]
	s_waitcnt lgkmcnt(0)
	v_mfma_f32_16x16x32_bf16 v[14:17], v[14:17], v[196:199], v[10:13]
	v_mfma_f32_16x16x32_bf16 v[10:13], v[180:183], v[188:191], v[34:37]
	v_mfma_f32_16x16x32_bf16 v[26:29], v[144:147], v[136:139], v[26:29]
	v_mfma_f32_16x16x32_bf16 v[10:13], v[144:147], v[196:199], v[10:13]
	s_setprio 0
	s_setprio 1
	v_mfma_f32_16x16x32_bf16 v[34:37], v[130:133], v[168:171], v[152:155]
	v_mfma_f32_16x16x32_bf16 v[54:57], v[148:151], v[140:143], v[34:37]
	v_mfma_f32_16x16x32_bf16 v[34:37], v[208:211], v[168:171], v[156:159]
	v_mfma_f32_16x16x32_bf16 v[18:21], v[208:211], v[172:175], v[18:21]
	v_mfma_f32_16x16x32_bf16 v[50:53], v[220:223], v[140:143], v[34:37]
	v_mfma_f32_16x16x32_bf16 v[22:25], v[130:133], v[172:175], v[22:25]
	v_mfma_f32_16x16x32_bf16 v[34:37], v[220:223], v[176:179], v[18:21]
	v_mfma_f32_16x16x32_bf16 v[18:21], v[130:133], v[184:187], v[160:163]
	v_mfma_f32_16x16x32_bf16 v[38:41], v[148:151], v[176:179], v[22:25]
	v_mfma_f32_16x16x32_bf16 v[22:25], v[148:151], v[136:139], v[18:21]
	v_mfma_f32_16x16x32_bf16 v[18:21], v[208:211], v[184:187], v[164:167]
	v_mfma_f32_16x16x32_bf16 v[6:9], v[130:133], v[188:191], v[6:9]
	v_mfma_f32_16x16x32_bf16 v[2:5], v[208:211], v[188:191], v[2:5]
	v_mfma_f32_16x16x32_bf16 v[18:21], v[220:223], v[136:139], v[18:21]
	v_mfma_f32_16x16x32_bf16 v[6:9], v[148:151], v[196:199], v[6:9]
	v_mfma_f32_16x16x32_bf16 v[2:5], v[220:223], v[196:199], v[2:5]
	s_setprio 0
	v_cmp_gt_u32_e32 vcc, s30, v1
	s_barrier
	s_and_saveexec_b64 s[4:5], vcc
	s_cbranch_execz .LBB0_492
	s_barrier

; #define LDS_BARRIER() do { asm volatile("s_waitcnt lgkmcnt(0)" ::: "memory"); __builtin_amdgcn_s_barrier(); asm volatile("" ::: "memory"); } while (0)
; __device__ __forceinline__ void st16_asm(void* ptr, u32x4 v) { asm volatile("global_store_dwordx4 %0, %1, off\n\ts_nop 7" :: "v"(ptr), "v"(v) : "memory"); }
; __device__ __forceinline__ void stg_flush(bf16* shm, int tid, bf16* dst, size_t pitch, bool first, bool tail_barrier = true) {
;   LDS_BARRIER();
;   if (first) asm volatile("s_waitcnt vmcnt(0)" ::: "memory");
;   _Pragma("unroll") for (int i = 0; i < 8; ++i) {
;     const int idx = tid + 512 * i, bjr = idx >> 11, row = (idx >> 4) & 127, c16 = idx & 15;
;     const u32x4 d = *(const u32x4*)stg_ptr(shm, bjr, row, 2 * c16);
;     st16_asm(dst + (size_t)row * pitch + bjr * HALF + c16 * 8, d); }
;   if (tail_barrier) LDS_BARRIER();
.LBB0_506:
	s_or_b64 exec, exec, s[4:5]
	v_lshrrev_b32_e32 v66, 4, v1
	v_lshlrev_b32_e32 v67, 3, v1
	v_and_b32_e32 v115, 0x7f, v66
	v_cmp_gt_u32_e64 s[4:5], s85, v1
	v_and_b32_e32 v90, 0x78, v67
	v_lshlrev_b32_e32 v68, 8, v115
	v_cndmask_b32_e64 v67, v244, v245, s[4:5]
	v_add3_u32 v82, 0, v67, v68
	v_add_u32_e32 v68, 0x200, v1
	v_bfe_u32 v116, v68, 4, 7
	v_cmp_gt_u32_e64 s[4:5], s85, v68
	v_lshlrev_b32_e32 v71, 8, v116
	v_xor_b32_e32 v66, v66, v1
	v_cndmask_b32_e64 v70, v244, v245, s[4:5]
	v_add3_u32 v91, 0, v70, v71
	v_add_u32_e32 v70, 0x400, v1
	v_bfe_u32 v117, v70, 4, 7
	v_cmp_gt_u32_e64 s[4:5], s85, v70
	v_lshlrev_b32_e32 v73, 8, v117
	v_lshlrev_b32_e32 v66, 4, v66
	v_cndmask_b32_e64 v72, v244, v245, s[4:5]
	v_add3_u32 v93, 0, v72, v73
	v_add_u32_e32 v72, 0x600, v1
	v_bfe_u32 v119, v72, 4, 7
	v_cmp_gt_u32_e64 s[4:5], s85, v72
	v_lshlrev_b32_e32 v75, 8, v119
	v_lshrrev_b32_e32 v69, 4, v68
	v_cndmask_b32_e64 v74, v244, v245, s[4:5]
	v_add3_u32 v95, 0, v74, v75
	v_add_u32_e32 v74, 0x800, v1
	v_bfe_u32 v120, v74, 4, 7
	v_cmp_lt_u32_e64 s[4:5], s65, v1
	v_lshlrev_b32_e32 v77, 8, v120
	v_lshrrev_b32_e32 v71, 4, v70
	v_cndmask_b32_e64 v76, v244, v245, s[4:5]
	v_add3_u32 v97, 0, v76, v77
	v_add_u32_e32 v76, 0xa00, v1
	v_bfe_u32 v121, v76, 4, 7
	v_cmp_gt_u32_e64 s[4:5], s85, v76
	v_lshlrev_b32_e32 v79, 8, v121
	v_lshrrev_b32_e32 v73, 4, v72
	v_cndmask_b32_e64 v78, v244, v245, s[4:5]
	v_add3_u32 v99, 0, v78, v79
	v_add_u32_e32 v78, 0xc00, v1
	v_bfe_u32 v123, v78, 4, 7
	v_cmp_gt_u32_e64 s[4:5], s85, v78
	v_lshlrev_b32_e32 v81, 8, v123
	v_lshrrev_b32_e32 v75, 4, v74
	v_cndmask_b32_e64 v80, v244, v245, s[4:5]
	v_add3_u32 v101, 0, v80, v81
	v_add_u32_e32 v80, 0xe00, v1
	v_lshrrev_b32_e32 v77, 4, v76
	v_lshrrev_b32_e32 v79, 4, v78
	v_lshrrev_b32_e32 v81, 4, v80
	v_and_b32_e32 v83, 0xf0, v66
	v_ashrrev_i32_e32 v66, 4, v1
	v_xor_b32_e32 v69, v69, v1
	v_xor_b32_e32 v71, v71, v1
	v_xor_b32_e32 v73, v73, v1
	v_xor_b32_e32 v75, v75, v1
	v_xor_b32_e32 v77, v77, v1
	v_xor_b32_e32 v79, v79, v1
	v_xor_b32_e32 v1, v81, v1
	v_cmp_gt_u32_e64 s[4:5], s85, v80
	v_lshlrev_b32_e32 v1, 4, v1
	v_and_b32_e32 v104, 0xf0, v1
	v_cndmask_b32_e64 v84, v244, v245, s[4:5]
	v_ashrrev_i32_e32 v1, 4, v80
	s_add_u32 s4, s14, s10
	v_and_b32_e32 v66, 0xffffff80, v66
	v_bfe_u32 v124, v80, 4, 7
	v_and_b32_e32 v80, 0xffffff80, v1
	s_addc_u32 s5, s15, s11
	v_add_u32_e32 v1, v82, v83
	v_lshlrev_b32_e32 v82, 12, v115
	v_mov_b32_e32 v83, v0
	v_ashrrev_i32_e32 v67, 31, v66
	v_lshl_add_u64 v[82:83], s[4:5], 0, v[82:83]
	v_lshl_add_u64 v[88:89], v[66:67], 1, v[82:83]
	v_lshlrev_b32_e32 v82, 1, v90
	v_mov_b32_e32 v83, v0
	v_ashrrev_i32_e32 v68, 4, v68
	v_lshlrev_b32_e32 v85, 8, v124
	s_waitcnt lgkmcnt(0)
	s_barrier
	v_lshl_add_u64 v[88:89], v[88:89], 0, v[82:83]
	v_lshlrev_b32_e32 v69, 4, v69
	v_and_b32_e32 v68, 0xffffff80, v68
	v_add3_u32 v103, 0, v84, v85
	ds_read_b128 v[84:87], v1
	s_waitcnt lgkmcnt(0)
	global_store_dwordx4 v[88:89], v[84:87], off sc1
	s_nop 7
	v_lshlrev_b32_e32 v88, 12, v116
	v_mov_b32_e32 v89, v0
	v_and_b32_e32 v92, 0xf0, v69
	v_ashrrev_i32_e32 v69, 31, v68
	v_lshl_add_u64 v[88:89], s[4:5], 0, v[88:89]
	v_lshl_add_u64 v[88:89], v[68:69], 1, v[88:89]
	v_ashrrev_i32_e32 v70, 4, v70
	v_add_u32_e32 v125, v91, v92
	v_lshl_add_u64 v[88:89], v[88:89], 0, v[82:83]
	v_lshlrev_b32_e32 v71, 4, v71
	v_and_b32_e32 v70, 0xffffff80, v70
	ds_read_b128 v[84:87], v125
	s_waitcnt lgkmcnt(0)
	global_store_dwordx4 v[88:89], v[84:87], off sc1
	s_nop 7
	v_lshlrev_b32_e32 v88, 12, v117
	v_mov_b32_e32 v89, v0
	v_and_b32_e32 v94, 0xf0, v71
	v_ashrrev_i32_e32 v71, 31, v70
	v_lshl_add_u64 v[88:89], s[4:5], 0, v[88:89]
	v_lshl_add_u64 v[88:89], v[70:71], 1, v[88:89]
	v_ashrrev_i32_e32 v72, 4, v72
	v_add_u32_e32 v127, v93, v94
	v_lshl_add_u64 v[88:89], v[88:89], 0, v[82:83]
	v_lshlrev_b32_e32 v73, 4, v73
	v_and_b32_e32 v72, 0xffffff80, v72
	ds_read_b128 v[84:87], v127
	s_waitcnt lgkmcnt(0)
	global_store_dwordx4 v[88:89], v[84:87], off sc1
	s_nop 7
	v_lshlrev_b32_e32 v88, 12, v119
	v_mov_b32_e32 v89, v0
	v_and_b32_e32 v96, 0xf0, v73
	v_ashrrev_i32_e32 v73, 31, v72
	v_lshl_add_u64 v[88:89], s[4:5], 0, v[88:89]
	v_lshl_add_u64 v[88:89], v[72:73], 1, v[88:89]
	v_ashrrev_i32_e32 v74, 4, v74
	v_add_u32_e32 v128, v95, v96
	v_lshl_add_u64 v[88:89], v[88:89], 0, v[82:83]
	v_lshlrev_b32_e32 v75, 4, v75
	v_and_b32_e32 v74, 0xffffff80, v74
	ds_read_b128 v[84:87], v128
	s_waitcnt lgkmcnt(0)
	global_store_dwordx4 v[88:89], v[84:87], off sc1
	s_nop 7
	v_lshlrev_b32_e32 v88, 12, v120
	v_mov_b32_e32 v89, v0
	v_and_b32_e32 v98, 0xf0, v75
	v_ashrrev_i32_e32 v75, 31, v74
	v_lshl_add_u64 v[88:89], s[4:5], 0, v[88:89]
	v_lshl_add_u64 v[88:89], v[74:75], 1, v[88:89]
	v_ashrrev_i32_e32 v76, 4, v76
	v_add_u32_e32 v129, v97, v98
	v_lshl_add_u64 v[88:89], v[88:89], 0, v[82:83]
	v_lshlrev_b32_e32 v77, 4, v77
	v_and_b32_e32 v76, 0xffffff80, v76
	ds_read_b128 v[84:87], v129
	s_waitcnt lgkmcnt(0)
	global_store_dwordx4 v[88:89], v[84:87], off sc1
	s_nop 7
	v_lshlrev_b32_e32 v88, 12, v121
	v_mov_b32_e32 v89, v0
	v_and_b32_e32 v100, 0xf0, v77
	v_ashrrev_i32_e32 v77, 31, v76
	v_lshl_add_u64 v[88:89], s[4:5], 0, v[88:89]
	v_lshl_add_u64 v[88:89], v[76:77], 1, v[88:89]
	v_ashrrev_i32_e32 v78, 4, v78
	v_add_u32_e32 v133, v99, v100
	v_lshl_add_u64 v[88:89], v[88:89], 0, v[82:83]
	v_lshlrev_b32_e32 v79, 4, v79
	v_and_b32_e32 v78, 0xffffff80, v78
	ds_read_b128 v[84:87], v133
	s_waitcnt lgkmcnt(0)
	global_store_dwordx4 v[88:89], v[84:87], off sc1
	s_nop 7
	v_lshlrev_b32_e32 v88, 12, v123
	v_mov_b32_e32 v89, v0
	v_and_b32_e32 v102, 0xf0, v79
	v_ashrrev_i32_e32 v79, 31, v78
	v_lshl_add_u64 v[88:89], s[4:5], 0, v[88:89]
	v_lshl_add_u64 v[88:89], v[78:79], 1, v[88:89]
	v_add_u32_e32 v136, v101, v102
	v_lshl_add_u64 v[88:89], v[88:89], 0, v[82:83]
	ds_read_b128 v[84:87], v136
	s_waitcnt lgkmcnt(0)
	global_store_dwordx4 v[88:89], v[84:87], off sc1
	s_nop 7
	v_lshlrev_b32_e32 v88, 12, v124
	v_mov_b32_e32 v89, v0
	v_ashrrev_i32_e32 v81, 31, v80
	v_add_u32_e32 v137, v103, v104
	v_lshl_add_u64 v[88:89], s[4:5], 0, v[88:89]
	ds_read_b128 v[84:87], v137
	v_lshl_add_u64 v[88:89], v[80:81], 1, v[88:89]
	v_lshl_add_u64 v[88:89], v[88:89], 0, v[82:83]
	s_waitcnt lgkmcnt(0)
	global_store_dwordx4 v[88:89], v[84:87], off sc1
	s_nop 7
	v_add_u32_e32 v84, 0x80, v132
	v_ashrrev_i32_e32 v85, 31, v84
	v_lshlrev_b64 v[84:85], 12, v[84:85]
	s_waitcnt lgkmcnt(0)
	s_barrier
; __device__ __forceinline__ float bflo(unsigned u) { return __uint_as_float(u << 16); }
; __device__ __forceinline__ float bfhi(unsigned u) { return __uint_as_float(u & 0xffff0000u); }
; #define shx(v, m) shxt<m>(v)
;     #define ISSUE_NEXT() do { if (more) { gemm_issue_part1(A, lda, Bt, K, pm * BM, pn * BM, shm, tid); fresh = false; \
;                                           asm volatile("s_waitcnt vmcnt(8)" ::: "memory"); }     \
;                               else asm volatile("s_waitcnt vmcnt(0)" ::: "memory"); } while (0)
; template <int EPI>
; __device__ void gemm_phase(const bf16* A, int lda, const bf16* Bt, int K, int N, const Params& p, bool last, bf16* dstb, bf16* shm, unsigned long long* SSQ, int wv, const float* gbias = nullptr) {
;     ...
;         _Pragma("unroll") for (int m = 0; m < 4; ++m) _Pragma("unroll") for (int bj = 0; bj < 2; ++bj) _Pragma("unroll") for (int n = 0; n < 2; ++n)
;           xo[m][bj][n] = *(const u32x2*)(Xb + (size_t)(brow + ai * HALF + wr * 64 + m * 16 + fr) * DM + bcol + wc * 32 + fq * 4 + bj * HALF + n * 16);
;         if (ai == 0) { ISSUE_NEXT(); asm volatile("s_waitcnt vmcnt(0)" ::: "memory"); } else asm volatile("s_waitcnt vmcnt(0)" ::: "memory");
;         _Pragma("unroll") for (int m = 0; m < 4; ++m) {
;           const int rl = ai * HALF + wr * 64 + m * 16 + fr;
;           const size_t ro = (size_t)(brow + rl) * DM + bcol + wc * 32 + fq * 4;
;           float ssq = 0.f;
;           _Pragma("unroll") for (int bj = 0; bj < 2; ++bj) _Pragma("unroll") for (int n = 0; n < 2; ++n) {
;             const u32x2 xv = xo[m][bj][n];
;             f32x4 v = acc[ai][bj][m][n];
;             v[0] += bflo(xv[0]); v[1] += bfhi(xv[0]); v[2] += bflo(xv[1]); v[3] += bfhi(xv[1]);
;             if (last) *(f32x4*)(p.out + ro + bj * HALF + n * 16) = v;
;             else {
;               u32x2 o = {pk2(v[0], v[1]), pk2(v[2], v[3])};
;               *(u32x2*)stg_ptr(shm, bj, wr * 64 + m * 16 + fr, wc * 8 + n * 4 + fq) = o;
;               float r0 = bflo(o[0]), r1 = bfhi(o[0]), r2 = bflo(o[1]), r3 = bfhi(o[1]);
;               ssq += (r0 * r0 + r1 * r1) + (r2 * r2 + r3 * r3); }
;           }
;           if (!last) { ssq += shx(ssq, 16); ssq += shx(ssq, 32); if (fq == 0) atomicAdd(SSQ + brow + rl, (unsigned long long)(ssq * SSQ_SCALE + 0.5f)); }
	v_lshl_add_u64 v[84:85], v[134:135], 0, v[84:85]
	global_load_dwordx2 v[138:139], v[84:85], off
	global_load_dwordx2 v[140:141], v[84:85], off offset:32
	global_load_dwordx2 v[142:143], v[84:85], off offset:256
	global_load_dwordx2 v[144:145], v[84:85], off offset:288
	v_add_u32_e32 v84, 0x90, v132
	v_ashrrev_i32_e32 v85, 31, v84
	v_lshlrev_b64 v[84:85], 12, v[84:85]
	v_lshl_add_u64 v[84:85], v[134:135], 0, v[84:85]
	global_load_dwordx2 v[106:107], v[84:85], off
	global_load_dwordx2 v[104:105], v[84:85], off offset:32
	global_load_dwordx2 v[102:103], v[84:85], off offset:256
	global_load_dwordx2 v[100:101], v[84:85], off offset:288
	v_add_u32_e32 v84, 0xa0, v132
	v_ashrrev_i32_e32 v85, 31, v84
	v_lshlrev_b64 v[84:85], 12, v[84:85]
	v_lshl_add_u64 v[84:85], v[134:135], 0, v[84:85]
	global_load_dwordx2 v[98:99], v[84:85], off
	global_load_dwordx2 v[96:97], v[84:85], off offset:32
	global_load_dwordx2 v[94:95], v[84:85], off offset:256
	global_load_dwordx2 v[92:93], v[84:85], off offset:288
	v_add_u32_e32 v84, 0xb0, v132
	v_ashrrev_i32_e32 v85, 31, v84
	v_lshlrev_b64 v[84:85], 12, v[84:85]
	v_lshl_add_u64 v[84:85], v[134:135], 0, v[84:85]
	global_load_dwordx2 v[90:91], v[84:85], off
	global_load_dwordx2 v[88:89], v[84:85], off offset:32
	global_load_dwordx2 v[86:87], v[84:85], off offset:256
	s_nop 0
	global_load_dwordx2 v[84:85], v[84:85], off offset:288
	s_waitcnt vmcnt(0)
	s_waitcnt vmcnt(15)
	v_lshlrev_b32_e32 v134, 16, v138
	v_and_b32_e32 v135, 0xffff0000, v138
	v_pk_add_f32 v[62:63], v[62:63], v[134:135]
	v_lshlrev_b32_e32 v134, 16, v139
	v_and_b32_e32 v135, 0xffff0000, v139
	v_pk_add_f32 v[64:65], v[64:65], v[134:135]
	v_cvt_pk_bf16_f32 v62, v62, v63
	v_cvt_pk_bf16_f32 v63, v64, v65
	ds_write_b64 v126, v[62:63] offset:32768
	v_lshlrev_b32_e32 v64, 16, v62
	v_and_b32_e32 v62, 0xffff0000, v62
	v_lshlrev_b32_e32 v65, 16, v63
	v_and_b32_e32 v63, 0xffff0000, v63
	v_mul_f32_e32 v62, v62, v62
	v_mul_f32_e32 v63, v63, v63
	v_fmac_f32_e32 v62, v64, v64
	v_fmac_f32_e32 v63, v65, v65
	v_add_f32_e32 v64, v62, v63
	s_waitcnt vmcnt(14)
	v_lshlrev_b32_e32 v62, 16, v140
	v_and_b32_e32 v63, 0xffff0000, v140
	v_pk_add_f32 v[58:59], v[58:59], v[62:63]
	v_lshlrev_b32_e32 v62, 16, v141
	v_and_b32_e32 v63, 0xffff0000, v141
	v_pk_add_f32 v[60:61], v[60:61], v[62:63]
	v_cvt_pk_bf16_f32 v58, v58, v59
	v_cvt_pk_bf16_f32 v59, v60, v61
	ds_write_b64 v122, v[58:59] offset:32768
	v_lshlrev_b32_e32 v60, 16, v58
	v_and_b32_e32 v58, 0xffff0000, v58
	v_lshlrev_b32_e32 v61, 16, v59
	v_and_b32_e32 v59, 0xffff0000, v59
	v_mul_f32_e32 v58, v58, v58
	v_mul_f32_e32 v59, v59, v59
	v_fmac_f32_e32 v58, v60, v60
	v_fmac_f32_e32 v59, v61, v61
	v_add_f32_e32 v58, v58, v59
	v_add_f32_e32 v60, v64, v58
	s_waitcnt vmcnt(13)
	v_lshlrev_b32_e32 v58, 16, v142
	v_and_b32_e32 v59, 0xffff0000, v142
	v_pk_add_f32 v[54:55], v[54:55], v[58:59]
	v_lshlrev_b32_e32 v58, 16, v143
	v_and_b32_e32 v59, 0xffff0000, v143
	v_pk_add_f32 v[56:57], v[56:57], v[58:59]
	v_cvt_pk_bf16_f32 v54, v54, v55
	v_cvt_pk_bf16_f32 v55, v56, v57
	ds_write_b64 v118, v[54:55]
	v_lshlrev_b32_e32 v56, 16, v54
	v_and_b32_e32 v54, 0xffff0000, v54
	v_lshlrev_b32_e32 v57, 16, v55
	v_and_b32_e32 v55, 0xffff0000, v55
	v_mul_f32_e32 v54, v54, v54
	v_mul_f32_e32 v55, v55, v55
	v_fmac_f32_e32 v54, v56, v56
	v_fmac_f32_e32 v55, v57, v57
	v_add_f32_e32 v54, v54, v55
	v_add_f32_e32 v56, v60, v54
	s_waitcnt vmcnt(12)
	v_lshlrev_b32_e32 v54, 16, v144
	v_and_b32_e32 v55, 0xffff0000, v144
	v_pk_add_f32 v[50:51], v[50:51], v[54:55]
	v_lshlrev_b32_e32 v54, 16, v145
	v_and_b32_e32 v55, 0xffff0000, v145
	v_pk_add_f32 v[52:53], v[52:53], v[54:55]
	v_cvt_pk_bf16_f32 v50, v50, v51
	v_cvt_pk_bf16_f32 v51, v52, v53
	ds_write_b64 v114, v[50:51]
	v_lshlrev_b32_e32 v52, 16, v50
	v_and_b32_e32 v50, 0xffff0000, v50
	v_lshlrev_b32_e32 v53, 16, v51
	v_and_b32_e32 v51, 0xffff0000, v51
	v_mul_f32_e32 v50, v50, v50
	v_mul_f32_e32 v51, v51, v51
	v_fmac_f32_e32 v50, v52, v52
	v_fmac_f32_e32 v51, v53, v53
	v_add_f32_e32 v50, v50, v51
	v_add_f32_e32 v50, v56, v50
	v_mov_b32_e32 v51, v50
	v_mov_b32_e32 v52, v50
	s_nop 1
	v_permlane16_swap_b32_e32 v51, v52
	v_xor_b32_e32 v51, v52, v51
	v_xor_b32_e32 v51, v51, v50
	v_add_f32_e32 v50, v50, v51
	v_mov_b32_e32 v51, v50
	v_mov_b32_e32 v52, v50
	s_nop 1
	v_permlane32_swap_b32_e32 v51, v52
	s_and_saveexec_b64 s[4:5], vcc
	s_cbranch_execz .LBB0_508
	v_xor_b32_e32 v51, v52, v51
	v_xor_b32_e32 v51, v51, v50
	v_add_f32_e32 v50, v50, v51
	v_fma_f32 v50, v50, s62, 0.5
	v_trunc_f32_e32 v50, v50
	v_mul_f32_e32 v51, 0x2f800000, v50
	v_floor_f32_e32 v51, v51
	v_fmac_f32_e32 v50, 0xcf800000, v51
	v_cvt_u32_f32_e32 v50, v50
	v_cvt_u32_f32_e32 v51, v51
	v_lshl_add_u64 v[52:53], v[130:131], 3, s[16:17]
	global_atomic_add_x2 v[52:53], v[50:51], off offset:1024

; #define LDS_BARRIER() do { asm volatile("s_waitcnt lgkmcnt(0)" ::: "memory"); __builtin_amdgcn_s_barrier(); asm volatile("" ::: "memory"); } while (0)
; __device__ __forceinline__ void st16_asm(void* ptr, u32x4 v) { asm volatile("global_store_dwordx4 %0, %1, off\n\ts_nop 7" :: "v"(ptr), "v"(v) : "memory"); }
; __device__ __forceinline__ char* stg_ptr(bf16* shm, int bj, int row, int chunk8) {
;   return (char*)shm + (bj ? 98304 : 32768) + row * 256 + ((chunk8 ^ ((row & 15) << 1)) << 3);
; }
; __device__ __forceinline__ void stg_flush(bf16* shm, int tid, bf16* dst, size_t pitch, bool first, bool tail_barrier = true) {
;   LDS_BARRIER();
;   if (first) asm volatile("s_waitcnt vmcnt(0)" ::: "memory");
;   _Pragma("unroll") for (int i = 0; i < 8; ++i) {
;     const int idx = tid + 512 * i, bjr = idx >> 11, row = (idx >> 4) & 127, c16 = idx & 15;
;     const u32x4 d = *(const u32x4*)stg_ptr(shm, bjr, row, 2 * c16);
;     st16_asm(dst + (size_t)row * pitch + bjr * HALF + c16 * 8, d); }
; template <int EPI>
; __device__ void gemm_phase(const bf16* A, int lda, const bf16* Bt, int K, int N, const Params& p, bool last, bf16* dstb, bf16* shm, unsigned long long* SSQ, int wv, const float* gbias = nullptr) {
;     ...
;         _Pragma("unroll") for (int m = 0; m < 4; ++m) {
;           const int rl = wr * 64 + m * 16 + fr; const float rs = rsv[ai][m];
;           _Pragma("unroll") for (int bj = 0; bj < 2; ++bj) _Pragma("unroll") for (int n = 0; n < 2; ++n) {
;             f32x4 v = acc[ai][bj][m][n] * rs;
;             for (int j = 0; j < 4; ++j) { float r = fmaxf(v[j], 0.f); v[j] = r * r; }
;             u32x2 o = {pk2(v[0], v[1]), pk2(v[2], v[3])};
;             *(u32x2*)stg_ptr(shm, bj, rl, wc * 8 + n * 4 + fq) = o; }
;         }
;         stg_flush(shm, tid, dstb + (size_t)(brow + ai * HALF) * N + bcol, (size_t)N, ai == 0, ai == 0);
.LBB0_554:
	v_lshrrev_b32_e32 v131, 4, v1
	v_cmp_gt_u32_e32 vcc, s85, v1
	v_xor_b32_e32 v131, v131, v1
	v_bfe_u32 v166, v1, 4, 7
	v_cndmask_b32_e32 v139, v244, v245, vcc
	v_lshlrev_b32_e32 v131, 4, v131
	v_add_u32_e32 v139, 0, v139
	v_lshlrev_b32_e32 v141, 8, v166
	v_and_b32_e32 v131, 0xf0, v131
	v_add3_u32 v131, v139, v141, v131
	v_ashrrev_i32_e32 v139, 4, v1
	v_add_u32_e32 v141, 0x200, v1
	v_and_b32_e32 v146, 0xffffff80, v139
	v_lshrrev_b32_e32 v139, 4, v141
	v_cmp_gt_u32_e32 vcc, s85, v141
	v_xor_b32_e32 v139, v139, v1
	v_bfe_u32 v167, v141, 4, 7
	v_cndmask_b32_e32 v143, v244, v245, vcc
	v_lshlrev_b32_e32 v139, 4, v139
	v_add_u32_e32 v143, 0, v143
	v_lshlrev_b32_e32 v145, 8, v167
	v_and_b32_e32 v139, 0xf0, v139
	v_add3_u32 v139, v143, v145, v139
	v_ashrrev_i32_e32 v141, 4, v141
	v_add_u32_e32 v143, 0x400, v1
	v_and_b32_e32 v148, 0xffffff80, v141
	v_lshrrev_b32_e32 v141, 4, v143
	v_cmp_gt_u32_e32 vcc, s85, v143
	v_xor_b32_e32 v141, v141, v1
	v_bfe_u32 v168, v143, 4, 7
	v_cndmask_b32_e32 v145, v244, v245, vcc
	v_lshlrev_b32_e32 v141, 4, v141
	v_add_u32_e32 v145, 0, v145
	v_lshlrev_b32_e32 v150, 8, v168
	v_and_b32_e32 v141, 0xf0, v141
	v_add3_u32 v141, v145, v150, v141
	v_ashrrev_i32_e32 v143, 4, v143
	v_add_u32_e32 v145, 0x600, v1
	v_and_b32_e32 v150, 0xffffff80, v143
	v_lshrrev_b32_e32 v143, 4, v145
	v_cmp_gt_u32_e32 vcc, s85, v145
	v_xor_b32_e32 v143, v143, v1
	v_bfe_u32 v169, v145, 4, 7
	v_cndmask_b32_e32 v152, v244, v245, vcc
	v_lshlrev_b32_e32 v143, 4, v143
	v_add_u32_e32 v152, 0, v152
	v_lshlrev_b32_e32 v153, 8, v169
	v_and_b32_e32 v143, 0xf0, v143
	v_ashrrev_i32_e32 v145, 4, v145
	v_add_u32_e32 v154, 0x800, v1
	v_add3_u32 v143, v152, v153, v143
	v_and_b32_e32 v152, 0xffffff80, v145
	v_lshrrev_b32_e32 v145, 4, v154
	v_cmp_lt_u32_e32 vcc, s65, v1
	v_xor_b32_e32 v145, v145, v1
	v_bfe_u32 v170, v154, 4, 7
	v_cndmask_b32_e32 v155, v244, v245, vcc
	v_lshlrev_b32_e32 v145, 4, v145
	v_add_u32_e32 v155, 0, v155
	v_lshlrev_b32_e32 v156, 8, v170
	v_and_b32_e32 v145, 0xf0, v145
	v_add3_u32 v145, v155, v156, v145
	v_add_u32_e32 v156, 0xa00, v1
	v_lshrrev_b32_e32 v157, 4, v156
	v_cmp_gt_u32_e32 vcc, s85, v156
	v_xor_b32_e32 v157, v157, v1
	v_bfe_u32 v171, v156, 4, 7
	v_cndmask_b32_e32 v158, v244, v245, vcc
	v_lshlrev_b32_e32 v157, 4, v157
	v_add_u32_e32 v158, 0, v158
	v_lshlrev_b32_e32 v159, 8, v171
	v_and_b32_e32 v157, 0xf0, v157
	v_add3_u32 v162, v158, v159, v157
	v_add_u32_e32 v158, 0xc00, v1
	v_lshrrev_b32_e32 v159, 4, v158
	v_cmp_gt_u32_e32 vcc, s85, v158
	v_xor_b32_e32 v159, v159, v1
	v_bfe_u32 v172, v158, 4, 7
	v_cndmask_b32_e32 v160, v244, v245, vcc
	v_lshlrev_b32_e32 v159, 4, v159
	v_pk_mul_f32 v[128:129], v[128:129], v[138:139] op_sel_hi:[1,0]
	v_pk_mul_f32 v[126:127], v[126:127], v[138:139] op_sel_hi:[1,0]
	v_add_u32_e32 v160, 0, v160
	v_lshlrev_b32_e32 v161, 8, v172
	v_and_b32_e32 v159, 0xf0, v159
	v_max_f32_e32 v126, 0, v126
	v_max_f32_e32 v127, 0, v127
	v_max_f32_e32 v128, 0, v128
	v_max_f32_e32 v129, 0, v129
	v_add3_u32 v163, v160, v161, v159
	v_add_u32_e32 v160, 0xe00, v1
	v_pk_mul_f32 v[126:127], v[126:127], v[126:127]
	v_pk_mul_f32 v[128:129], v[128:129], v[128:129]
	v_lshlrev_b32_e32 v165, 4, v137
	v_lshrrev_b32_e32 v161, 4, v160
	v_lshlrev_b32_e32 v133, 14, v133
	v_lshlrev_b32_e32 v137, 8, v137
	v_cvt_pk_bf16_f32 v126, v126, v127
	v_cvt_pk_bf16_f32 v127, v128, v129
	v_lshrrev_b32_e32 v128, 1, v1
	v_xor_b32_e32 v161, v161, v1
	v_add3_u32 v133, 0, v133, v137
	v_and_b32_e32 v128, 24, v128
	v_and_b32_e32 v1, 0xc0, v1
	v_pk_mul_f32 v[118:119], v[118:119], v[138:139] op_sel_hi:[1,0]
	v_or_b32_e32 v129, v128, v1
	v_bitop3_b32 v128, v128, v165, v1 bitop3:0x36
	v_pk_mul_f32 v[120:121], v[120:121], v[138:139] op_sel_hi:[1,0]
	v_max_f32_e32 v118, 0, v118
	v_max_f32_e32 v119, 0, v119
	v_pk_mul_f32 v[112:113], v[112:113], v[136:137] op_sel_hi:[1,0]
	v_pk_mul_f32 v[110:111], v[110:111], v[136:137] op_sel_hi:[1,0]
	v_pk_mul_f32 v[104:105], v[104:105], v[136:137] op_sel_hi:[1,0]
	v_pk_mul_f32 v[102:103], v[102:103], v[136:137] op_sel_hi:[1,0]
	v_pk_mul_f32 v[96:97], v[96:97], v[132:133] op_sel_hi:[1,0]
	v_pk_mul_f32 v[94:95], v[94:95], v[132:133] op_sel_hi:[1,0]
	v_pk_mul_f32 v[88:89], v[88:89], v[132:133] op_sel_hi:[1,0]
	v_pk_mul_f32 v[86:87], v[86:87], v[132:133] op_sel_hi:[1,0]
	v_pk_mul_f32 v[80:81], v[80:81], v[134:135] op_sel_hi:[1,0]
	v_pk_mul_f32 v[78:79], v[78:79], v[134:135] op_sel_hi:[1,0]
	v_pk_mul_f32 v[72:73], v[72:73], v[134:135] op_sel_hi:[1,0]
	v_pk_mul_f32 v[70:71], v[70:71], v[134:135] op_sel_hi:[1,0]
	v_add_u32_e32 v1, v133, v128
	v_pk_mul_f32 v[118:119], v[118:119], v[118:119]
	v_max_f32_e32 v120, 0, v120
	v_max_f32_e32 v121, 0, v121
	v_max_f32_e32 v110, 0, v110
	v_max_f32_e32 v111, 0, v111
	v_max_f32_e32 v112, 0, v112
	v_max_f32_e32 v113, 0, v113
	v_max_f32_e32 v102, 0, v102
	v_max_f32_e32 v103, 0, v103
	v_max_f32_e32 v104, 0, v104
	v_max_f32_e32 v105, 0, v105
	v_max_f32_e32 v94, 0, v94
	v_max_f32_e32 v95, 0, v95
	v_max_f32_e32 v96, 0, v96
	v_max_f32_e32 v97, 0, v97
	v_max_f32_e32 v86, 0, v86
	v_max_f32_e32 v87, 0, v87
	v_max_f32_e32 v88, 0, v88
	v_max_f32_e32 v89, 0, v89
	v_max_f32_e32 v78, 0, v78
	v_max_f32_e32 v79, 0, v79
	v_max_f32_e32 v80, 0, v80
	v_max_f32_e32 v81, 0, v81
	v_max_f32_e32 v70, 0, v70
	v_max_f32_e32 v71, 0, v71
	v_max_f32_e32 v72, 0, v72
	v_max_f32_e32 v73, 0, v73
	ds_write_b64 v1, v[126:127] offset:32768
	v_pk_mul_f32 v[120:121], v[120:121], v[120:121]
	v_cvt_pk_bf16_f32 v126, v118, v119
	v_bitop3_b32 v119, v129, v165, 32 bitop3:0x36
	v_pk_mul_f32 v[110:111], v[110:111], v[110:111]
	v_pk_mul_f32 v[112:113], v[112:113], v[112:113]
	v_pk_mul_f32 v[102:103], v[102:103], v[102:103]
; template <int EPI>
; __device__ void gemm_phase(const bf16* A, int lda, const bf16* Bt, int K, int N, const Params& p, bool last, bf16* dstb, bf16* shm, unsigned long long* SSQ, int wv, const float* gbias = nullptr) {
;     ...
;           const int rl = wr * 64 + m * 16 + fr; const float rs = rsv[ai][m];
;           _Pragma("unroll") for (int bj = 0; bj < 2; ++bj) _Pragma("unroll") for (int n = 0; n < 2; ++n) {
;             f32x4 v = acc[ai][bj][m][n] * rs;
;             for (int j = 0; j < 4; ++j) { float r = fmaxf(v[j], 0.f); v[j] = r * r; }
;             u32x2 o = {pk2(v[0], v[1]), pk2(v[2], v[3])};
;             *(u32x2*)stg_ptr(shm, bj, rl, wc * 8 + n * 4 + fq) = o; }
	v_pk_mul_f32 v[104:105], v[104:105], v[104:105]
	v_pk_mul_f32 v[94:95], v[94:95], v[94:95]
	v_pk_mul_f32 v[96:97], v[96:97], v[96:97]
	v_pk_mul_f32 v[86:87], v[86:87], v[86:87]
	v_pk_mul_f32 v[88:89], v[88:89], v[88:89]
	v_pk_mul_f32 v[78:79], v[78:79], v[78:79]
	v_pk_mul_f32 v[80:81], v[80:81], v[80:81]
	v_pk_mul_f32 v[70:71], v[70:71], v[70:71]
	v_pk_mul_f32 v[72:73], v[72:73], v[72:73]
	v_cvt_pk_bf16_f32 v127, v120, v121
	v_add_u32_e32 v118, v133, v119
	v_cvt_pk_bf16_f32 v110, v110, v111
	v_cvt_pk_bf16_f32 v111, v112, v113
	v_cvt_pk_bf16_f32 v102, v102, v103
	v_cvt_pk_bf16_f32 v103, v104, v105
	v_cvt_pk_bf16_f32 v94, v94, v95
	v_cvt_pk_bf16_f32 v95, v96, v97
	v_cvt_pk_bf16_f32 v86, v86, v87
	v_cvt_pk_bf16_f32 v87, v88, v89
	v_cvt_pk_bf16_f32 v78, v78, v79
	v_cvt_pk_bf16_f32 v79, v80, v81
	v_cvt_pk_bf16_f32 v70, v70, v71
	v_cvt_pk_bf16_f32 v71, v72, v73
	v_pk_mul_f32 v[120:121], v[124:125], v[138:139] op_sel_hi:[1,0]
	v_pk_mul_f32 v[122:123], v[122:123], v[138:139] op_sel_hi:[1,0]
	v_pk_mul_f32 v[116:117], v[116:117], v[138:139] op_sel_hi:[1,0]
	v_pk_mul_f32 v[114:115], v[114:115], v[138:139] op_sel_hi:[1,0]
	ds_write_b64 v1, v[110:111] offset:36864
	ds_write2st64_b64 v118, v[126:127], v[102:103] offset0:64 offset1:72
	v_pk_mul_f32 v[102:103], v[108:109], v[136:137] op_sel_hi:[1,0]
	v_pk_mul_f32 v[104:105], v[106:107], v[136:137] op_sel_hi:[1,0]
	v_pk_mul_f32 v[100:101], v[100:101], v[136:137] op_sel_hi:[1,0]
	v_pk_mul_f32 v[98:99], v[98:99], v[136:137] op_sel_hi:[1,0]
	ds_write_b64 v1, v[94:95] offset:40960
	v_pk_mul_f32 v[88:89], v[92:93], v[132:133] op_sel_hi:[1,0]
	v_pk_mul_f32 v[90:91], v[90:91], v[132:133] op_sel_hi:[1,0]
	v_pk_mul_f32 v[84:85], v[84:85], v[132:133] op_sel_hi:[1,0]
	v_pk_mul_f32 v[82:83], v[82:83], v[132:133] op_sel_hi:[1,0]
	ds_write_b64 v1, v[78:79] offset:45056
	ds_write2st64_b64 v118, v[86:87], v[70:71] offset0:80 offset1:88
	v_pk_mul_f32 v[70:71], v[76:77], v[134:135] op_sel_hi:[1,0]
	v_pk_mul_f32 v[72:73], v[74:75], v[134:135] op_sel_hi:[1,0]
	v_pk_mul_f32 v[68:69], v[68:69], v[134:135] op_sel_hi:[1,0]
	v_pk_mul_f32 v[66:67], v[66:67], v[134:135] op_sel_hi:[1,0]
	s_lshl_b64 s[12:13], s[10:11], 1
	v_max_f32_e32 v122, 0, v122
	v_max_f32_e32 v123, 0, v123
	v_max_f32_e32 v120, 0, v120
	v_max_f32_e32 v121, 0, v121
	v_max_f32_e32 v114, 0, v114
	v_max_f32_e32 v115, 0, v115
	v_max_f32_e32 v116, 0, v116
	v_max_f32_e32 v117, 0, v117
	v_max_f32_e32 v104, 0, v104
	v_max_f32_e32 v105, 0, v105
	v_max_f32_e32 v102, 0, v102
	v_max_f32_e32 v103, 0, v103
	v_max_f32_e32 v98, 0, v98
	v_max_f32_e32 v99, 0, v99
	v_max_f32_e32 v100, 0, v100
	v_max_f32_e32 v101, 0, v101
	v_max_f32_e32 v90, 0, v90
	v_max_f32_e32 v91, 0, v91
	v_max_f32_e32 v88, 0, v88
	v_max_f32_e32 v89, 0, v89
	v_max_f32_e32 v82, 0, v82
	v_max_f32_e32 v83, 0, v83
	v_max_f32_e32 v84, 0, v84
	v_max_f32_e32 v85, 0, v85
	v_max_f32_e32 v72, 0, v72
	v_max_f32_e32 v73, 0, v73
	v_max_f32_e32 v70, 0, v70
	v_max_f32_e32 v71, 0, v71
	v_max_f32_e32 v66, 0, v66
	v_max_f32_e32 v67, 0, v67
	v_max_f32_e32 v68, 0, v68
	v_max_f32_e32 v69, 0, v69
	s_add_u32 s11, s86, s12
	v_add_u32_e32 v129, 0x18000, v133
	v_pk_mul_f32 v[122:123], v[122:123], v[122:123]
	v_pk_mul_f32 v[120:121], v[120:121], v[120:121]
	v_pk_mul_f32 v[114:115], v[114:115], v[114:115]
	v_pk_mul_f32 v[116:117], v[116:117], v[116:117]
	v_add_u32_e32 v110, 0x19000, v133
	v_pk_mul_f32 v[104:105], v[104:105], v[104:105]
	v_pk_mul_f32 v[102:103], v[102:103], v[102:103]
	v_pk_mul_f32 v[98:99], v[98:99], v[98:99]
	v_pk_mul_f32 v[100:101], v[100:101], v[100:101]
	v_add_u32_e32 v94, 0x1a000, v133
	v_pk_mul_f32 v[90:91], v[90:91], v[90:91]
	v_pk_mul_f32 v[88:89], v[88:89], v[88:89]
	v_pk_mul_f32 v[82:83], v[82:83], v[82:83]
	v_pk_mul_f32 v[84:85], v[84:85], v[84:85]
	v_add_u32_e32 v78, 0x1b000, v133
	v_pk_mul_f32 v[72:73], v[72:73], v[72:73]
	v_pk_mul_f32 v[70:71], v[70:71], v[70:71]
	v_pk_mul_f32 v[66:67], v[66:67], v[66:67]
	v_pk_mul_f32 v[68:69], v[68:69], v[68:69]
	s_addc_u32 s10, s87, s13
	v_cvt_pk_bf16_f32 v122, v122, v123
	v_cvt_pk_bf16_f32 v123, v120, v121
	v_add_u32_e32 v120, v129, v128
	v_cvt_pk_bf16_f32 v114, v114, v115
	v_cvt_pk_bf16_f32 v115, v116, v117
	v_add_u32_e32 v116, v129, v119
	v_cvt_pk_bf16_f32 v104, v104, v105
	v_cvt_pk_bf16_f32 v105, v102, v103
	v_add_u32_e32 v106, v110, v128
	v_cvt_pk_bf16_f32 v98, v98, v99
	v_cvt_pk_bf16_f32 v99, v100, v101
	v_add_u32_e32 v107, v110, v119
	v_cvt_pk_bf16_f32 v90, v90, v91
	v_cvt_pk_bf16_f32 v91, v88, v89
	v_add_u32_e32 v108, v94, v128
	v_cvt_pk_bf16_f32 v82, v82, v83
	v_cvt_pk_bf16_f32 v83, v84, v85
	v_add_u32_e32 v109, v94, v119
	v_cvt_pk_bf16_f32 v72, v72, v73
	v_cvt_pk_bf16_f32 v73, v70, v71
	v_add_u32_e32 v110, v78, v128
	v_cvt_pk_bf16_f32 v66, v66, v67
	v_cvt_pk_bf16_f32 v67, v68, v69
	v_add_u32_e32 v111, v78, v119
	s_lshl_b64 s[12:13], s[6:7], 14
	ds_write_b64 v120, v[122:123]
	ds_write_b64 v116, v[114:115]
	ds_write_b64 v106, v[104:105]
	ds_write_b64 v107, v[98:99]
	ds_write_b64 v108, v[90:91]
	ds_write_b64 v109, v[82:83]
	ds_write_b64 v110, v[72:73]
	ds_write_b64 v111, v[66:67]
	s_add_u32 s12, s11, s12
	v_ashrrev_i32_e32 v147, 31, v146
	s_addc_u32 s13, s10, s13
	s_waitcnt lgkmcnt(0)
	s_barrier
; __device__ __forceinline__ void st16_asm(void* ptr, u32x4 v) { asm volatile("global_store_dwordx4 %0, %1, off\n\ts_nop 7" :: "v"(ptr), "v"(v) : "memory"); }
; __device__ __forceinline__ void stg_flush(bf16* shm, int tid, bf16* dst, size_t pitch, bool first, bool tail_barrier = true) {
;     ...
;   _Pragma("unroll") for (int i = 0; i < 8; ++i) {
;     const int idx = tid + 512 * i, bjr = idx >> 11, row = (idx >> 4) & 127, c16 = idx & 15;
;     const u32x4 d = *(const u32x4*)stg_ptr(shm, bjr, row, 2 * c16);
;     st16_asm(dst + (size_t)row * pitch + bjr * HALF + c16 * 8, d); }
; template <int EPI>
; __device__ void gemm_phase(const bf16* A, int lda, const bf16* Bt, int K, int N, const Params& p, bool last, bf16* dstb, bf16* shm, unsigned long long* SSQ, int wv, const float* gbias = nullptr) {
;     ...
;         _Pragma("unroll") for (int m = 0; m < 4; ++m) {
;           const int rl = wr * 64 + m * 16 + fr; const float rs = rsv[ai][m];
;           _Pragma("unroll") for (int bj = 0; bj < 2; ++bj) _Pragma("unroll") for (int n = 0; n < 2; ++n) {
;             f32x4 v = acc[ai][bj][m][n] * rs;
;             for (int j = 0; j < 4; ++j) { float r = fmaxf(v[j], 0.f); v[j] = r * r; }
;             u32x2 o = {pk2(v[0], v[1]), pk2(v[2], v[3])};
;             *(u32x2*)stg_ptr(shm, bj, rl, wc * 8 + n * 4 + fq) = o; }
	v_lshlrev_b32_e32 v68, 14, v166
	v_mov_b32_e32 v69, v0
	s_waitcnt vmcnt(0)
	v_lshl_add_u64 v[66:67], s[12:13], 0, v[68:69]
	v_lshlrev_b64 v[70:71], 1, v[146:147]
	ds_read_b128 v[72:75], v131
	v_lshl_add_u64 v[76:77], v[66:67], 0, v[70:71]
	v_and_b32_e32 v66, 0xf0, v135
	v_mov_b32_e32 v67, v0
	v_ashrrev_i32_e32 v149, 31, v148
	v_lshl_add_u64 v[76:77], v[76:77], 0, v[66:67]
	s_waitcnt lgkmcnt(0)
	global_store_dwordx4 v[76:77], v[72:75], off sc1
	s_nop 7
	v_lshlrev_b32_e32 v72, 14, v167
	v_mov_b32_e32 v73, v0
	v_lshl_add_u64 v[80:81], s[12:13], 0, v[72:73]
	v_lshlrev_b64 v[74:75], 1, v[148:149]
	ds_read_b128 v[76:79], v139
	v_lshl_add_u64 v[80:81], v[80:81], 0, v[74:75]
	v_ashrrev_i32_e32 v151, 31, v150
	v_lshl_add_u64 v[80:81], v[80:81], 0, v[66:67]
	s_waitcnt lgkmcnt(0)
	global_store_dwordx4 v[80:81], v[76:79], off sc1
	s_nop 7
	v_lshlrev_b32_e32 v76, 14, v168
	v_mov_b32_e32 v77, v0
	v_lshl_add_u64 v[84:85], s[12:13], 0, v[76:77]
	v_lshlrev_b64 v[78:79], 1, v[150:151]
	ds_read_b128 v[80:83], v141
	v_lshl_add_u64 v[84:85], v[84:85], 0, v[78:79]
	v_ashrrev_i32_e32 v153, 31, v152
	v_lshl_add_u64 v[84:85], v[84:85], 0, v[66:67]
	s_waitcnt lgkmcnt(0)
	global_store_dwordx4 v[84:85], v[80:83], off sc1
	s_nop 7
	v_lshlrev_b32_e32 v80, 14, v169
	v_mov_b32_e32 v81, v0
	v_ashrrev_i32_e32 v154, 4, v154
	v_lshl_add_u64 v[88:89], s[12:13], 0, v[80:81]
	v_lshlrev_b64 v[82:83], 1, v[152:153]
	v_and_b32_e32 v154, 0xffffff80, v154
	ds_read_b128 v[84:87], v143
	v_lshl_add_u64 v[88:89], v[88:89], 0, v[82:83]
	v_ashrrev_i32_e32 v155, 31, v154
	v_lshl_add_u64 v[88:89], v[88:89], 0, v[66:67]
	s_waitcnt lgkmcnt(0)
	global_store_dwordx4 v[88:89], v[84:87], off sc1
	s_nop 7
	v_lshlrev_b32_e32 v84, 14, v170
	v_mov_b32_e32 v85, v0
	v_ashrrev_i32_e32 v156, 4, v156
	v_lshl_add_u64 v[92:93], s[12:13], 0, v[84:85]
	v_lshlrev_b64 v[86:87], 1, v[154:155]
	v_and_b32_e32 v156, 0xffffff80, v156
	ds_read_b128 v[88:91], v145
	v_lshl_add_u64 v[92:93], v[92:93], 0, v[86:87]
	v_ashrrev_i32_e32 v157, 31, v156
	v_lshl_add_u64 v[92:93], v[92:93], 0, v[66:67]
	s_waitcnt lgkmcnt(0)
	global_store_dwordx4 v[92:93], v[88:91], off sc1
	s_nop 7
	v_lshlrev_b32_e32 v88, 14, v171
	v_mov_b32_e32 v89, v0
	v_ashrrev_i32_e32 v158, 4, v158
	v_lshl_add_u64 v[96:97], s[12:13], 0, v[88:89]
	v_lshlrev_b64 v[90:91], 1, v[156:157]
	v_and_b32_e32 v158, 0xffffff80, v158
	ds_read_b128 v[92:95], v162
	v_lshl_add_u64 v[96:97], v[96:97], 0, v[90:91]
	v_ashrrev_i32_e32 v159, 31, v158
	v_cmp_gt_u32_e32 vcc, s85, v160
	v_lshl_add_u64 v[96:97], v[96:97], 0, v[66:67]
	s_waitcnt lgkmcnt(0)
	global_store_dwordx4 v[96:97], v[92:95], off sc1
	s_nop 7
	v_lshlrev_b32_e32 v92, 14, v172
	v_mov_b32_e32 v93, v0
	v_bfe_u32 v173, v160, 4, 7
	v_cndmask_b32_e32 v164, v244, v245, vcc
	v_lshlrev_b32_e32 v161, 4, v161
	v_ashrrev_i32_e32 v160, 4, v160
	v_lshl_add_u64 v[100:101], s[12:13], 0, v[92:93]
	v_lshlrev_b64 v[94:95], 1, v[158:159]
	v_add_u32_e32 v164, 0, v164
	v_lshlrev_b32_e32 v174, 8, v173
	v_and_b32_e32 v161, 0xf0, v161
	v_and_b32_e32 v160, 0xffffff80, v160
	ds_read_b128 v[96:99], v163
	v_lshl_add_u64 v[100:101], v[100:101], 0, v[94:95]
	s_bitset1_b32 s6, 7
	v_add3_u32 v164, v164, v174, v161
	v_ashrrev_i32_e32 v161, 31, v160
	v_lshl_add_u64 v[100:101], v[100:101], 0, v[66:67]
	s_waitcnt lgkmcnt(0)
	global_store_dwordx4 v[100:101], v[96:99], off sc1
	s_nop 7
	v_lshlrev_b32_e32 v96, 14, v173
	v_mov_b32_e32 v97, v0
	v_pk_mul_f32 v[8:9], v[8:9], v[140:141] op_sel_hi:[1,0]
	v_pk_mul_f32 v[6:7], v[6:7], v[140:141] op_sel_hi:[1,0]
	s_ashr_i32 s7, s6, 31
	v_lshl_add_u64 v[104:105], s[12:13], 0, v[96:97]
	v_lshlrev_b64 v[98:99], 1, v[160:161]
	v_pk_mul_f32 v[64:65], v[64:65], v[130:131] op_sel_hi:[1,0]
	v_pk_mul_f32 v[62:63], v[62:63], v[130:131] op_sel_hi:[1,0]
	v_pk_mul_f32 v[60:61], v[60:61], v[130:131] op_sel_hi:[1,0]
	v_pk_mul_f32 v[58:59], v[58:59], v[130:131] op_sel_hi:[1,0]
	v_pk_mul_f32 v[56:57], v[56:57], v[130:131] op_sel_hi:[1,0]
	v_pk_mul_f32 v[54:55], v[54:55], v[130:131] op_sel_hi:[1,0]
	v_pk_mul_f32 v[52:53], v[52:53], v[130:131] op_sel_hi:[1,0]
	v_pk_mul_f32 v[50:51], v[50:51], v[130:131] op_sel_hi:[1,0]
	v_pk_mul_f32 v[48:49], v[48:49], v[144:145] op_sel_hi:[1,0]
	v_pk_mul_f32 v[46:47], v[46:47], v[144:145] op_sel_hi:[1,0]
	v_pk_mul_f32 v[44:45], v[44:45], v[144:145] op_sel_hi:[1,0]
	v_pk_mul_f32 v[42:43], v[42:43], v[144:145] op_sel_hi:[1,0]
	v_pk_mul_f32 v[40:41], v[40:41], v[144:145] op_sel_hi:[1,0]
	v_pk_mul_f32 v[38:39], v[38:39], v[144:145] op_sel_hi:[1,0]
	v_pk_mul_f32 v[36:37], v[36:37], v[144:145] op_sel_hi:[1,0]
	v_pk_mul_f32 v[34:35], v[34:35], v[144:145] op_sel_hi:[1,0]
	v_pk_mul_f32 v[32:33], v[32:33], v[142:143] op_sel_hi:[1,0]
	v_pk_mul_f32 v[30:31], v[30:31], v[142:143] op_sel_hi:[1,0]
	v_pk_mul_f32 v[28:29], v[28:29], v[142:143] op_sel_hi:[1,0]
	v_pk_mul_f32 v[26:27], v[26:27], v[142:143] op_sel_hi:[1,0]
	v_pk_mul_f32 v[24:25], v[24:25], v[142:143] op_sel_hi:[1,0]
	v_pk_mul_f32 v[22:23], v[22:23], v[142:143] op_sel_hi:[1,0]
	v_pk_mul_f32 v[20:21], v[20:21], v[142:143] op_sel_hi:[1,0]
	v_pk_mul_f32 v[18:19], v[18:19], v[142:143] op_sel_hi:[1,0]
	v_pk_mul_f32 v[16:17], v[16:17], v[140:141] op_sel_hi:[1,0]
	v_pk_mul_f32 v[14:15], v[14:15], v[140:141] op_sel_hi:[1,0]
	v_pk_mul_f32 v[12:13], v[12:13], v[140:141] op_sel_hi:[1,0]
	v_pk_mul_f32 v[10:11], v[10:11], v[140:141] op_sel_hi:[1,0]
	v_max_f32_e32 v6, 0, v6
	v_max_f32_e32 v7, 0, v7
	v_max_f32_e32 v8, 0, v8
	v_max_f32_e32 v9, 0, v9
	v_pk_mul_f32 v[4:5], v[4:5], v[140:141] op_sel_hi:[1,0]
	v_pk_mul_f32 v[2:3], v[2:3], v[140:141] op_sel_hi:[1,0]
	s_lshl_b64 s[6:7], s[6:7], 14
	v_lshl_add_u64 v[104:105], v[104:105], 0, v[98:99]
	v_max_f32_e32 v62, 0, v62
; __device__ __forceinline__ void st16_asm(void* ptr, u32x4 v) { asm volatile("global_store_dwordx4 %0, %1, off\n\ts_nop 7" :: "v"(ptr), "v"(v) : "memory"); }
; __device__ __forceinline__ void stg_flush(bf16* shm, int tid, bf16* dst, size_t pitch, bool first, bool tail_barrier = true) {
;     ...
;   _Pragma("unroll") for (int i = 0; i < 8; ++i) {
;     const int idx = tid + 512 * i, bjr = idx >> 11, row = (idx >> 4) & 127, c16 = idx & 15;
;     const u32x4 d = *(const u32x4*)stg_ptr(shm, bjr, row, 2 * c16);
;     st16_asm(dst + (size_t)row * pitch + bjr * HALF + c16 * 8, d); }
; template <int EPI>
; __device__ void gemm_phase(const bf16* A, int lda, const bf16* Bt, int K, int N, const Params& p, bool last, bf16* dstb, bf16* shm, unsigned long long* SSQ, int wv, const float* gbias = nullptr) {
;     ...
;         _Pragma("unroll") for (int m = 0; m < 4; ++m) {
;           const int rl = wr * 64 + m * 16 + fr; const float rs = rsv[ai][m];
;           _Pragma("unroll") for (int bj = 0; bj < 2; ++bj) _Pragma("unroll") for (int n = 0; n < 2; ++n) {
;             f32x4 v = acc[ai][bj][m][n] * rs;
;             for (int j = 0; j < 4; ++j) { float r = fmaxf(v[j], 0.f); v[j] = r * r; }
;             u32x2 o = {pk2(v[0], v[1]), pk2(v[2], v[3])};
;             *(u32x2*)stg_ptr(shm, bj, rl, wc * 8 + n * 4 + fq) = o; }
;         }
;         stg_flush(shm, tid, dstb + (size_t)(brow + ai * HALF) * N + bcol, (size_t)N, ai == 0, ai == 0);
	v_max_f32_e32 v63, 0, v63
	v_max_f32_e32 v64, 0, v64
	v_max_f32_e32 v65, 0, v65
	v_max_f32_e32 v58, 0, v58
	v_max_f32_e32 v59, 0, v59
	v_max_f32_e32 v60, 0, v60
	v_max_f32_e32 v61, 0, v61
	v_max_f32_e32 v54, 0, v54
	v_max_f32_e32 v55, 0, v55
	v_max_f32_e32 v56, 0, v56
	v_max_f32_e32 v57, 0, v57
	v_max_f32_e32 v50, 0, v50
	v_max_f32_e32 v51, 0, v51
	v_max_f32_e32 v52, 0, v52
	v_max_f32_e32 v53, 0, v53
	v_max_f32_e32 v46, 0, v46
	v_max_f32_e32 v47, 0, v47
	v_max_f32_e32 v48, 0, v48
	v_max_f32_e32 v49, 0, v49
	v_max_f32_e32 v42, 0, v42
	v_max_f32_e32 v43, 0, v43
	v_max_f32_e32 v44, 0, v44
	v_max_f32_e32 v45, 0, v45
	v_max_f32_e32 v38, 0, v38
	v_max_f32_e32 v39, 0, v39
	v_max_f32_e32 v40, 0, v40
	v_max_f32_e32 v41, 0, v41
	v_max_f32_e32 v34, 0, v34
	v_max_f32_e32 v35, 0, v35
	v_max_f32_e32 v36, 0, v36
	v_max_f32_e32 v37, 0, v37
	v_max_f32_e32 v30, 0, v30
	v_max_f32_e32 v31, 0, v31
	v_max_f32_e32 v32, 0, v32
	v_max_f32_e32 v33, 0, v33
	v_max_f32_e32 v26, 0, v26
	v_max_f32_e32 v27, 0, v27
	v_max_f32_e32 v28, 0, v28
	v_max_f32_e32 v29, 0, v29
	v_max_f32_e32 v22, 0, v22
	v_max_f32_e32 v23, 0, v23
	v_max_f32_e32 v24, 0, v24
	v_max_f32_e32 v25, 0, v25
	v_max_f32_e32 v18, 0, v18
	v_max_f32_e32 v19, 0, v19
	v_max_f32_e32 v20, 0, v20
	v_max_f32_e32 v21, 0, v21
	v_max_f32_e32 v14, 0, v14
	v_max_f32_e32 v15, 0, v15
	v_max_f32_e32 v16, 0, v16
	v_max_f32_e32 v17, 0, v17
	v_max_f32_e32 v10, 0, v10
	v_max_f32_e32 v11, 0, v11
	v_max_f32_e32 v12, 0, v12
	v_max_f32_e32 v13, 0, v13
	v_pk_mul_f32 v[6:7], v[6:7], v[6:7]
	v_pk_mul_f32 v[8:9], v[8:9], v[8:9]
	v_max_f32_e32 v2, 0, v2
	v_max_f32_e32 v3, 0, v3
	v_max_f32_e32 v4, 0, v4
	v_max_f32_e32 v5, 0, v5
	s_add_u32 s6, s11, s6
	ds_read_b128 v[100:103], v164
	v_lshl_add_u64 v[104:105], v[104:105], 0, v[66:67]
	s_waitcnt lgkmcnt(0)
	global_store_dwordx4 v[104:105], v[100:103], off sc1
	s_nop 7
	v_pk_mul_f32 v[62:63], v[62:63], v[62:63]
	v_pk_mul_f32 v[64:65], v[64:65], v[64:65]
	v_pk_mul_f32 v[58:59], v[58:59], v[58:59]
	v_pk_mul_f32 v[60:61], v[60:61], v[60:61]
	v_pk_mul_f32 v[54:55], v[54:55], v[54:55]
	v_pk_mul_f32 v[56:57], v[56:57], v[56:57]
	v_pk_mul_f32 v[50:51], v[50:51], v[50:51]
	v_pk_mul_f32 v[52:53], v[52:53], v[52:53]
	v_pk_mul_f32 v[46:47], v[46:47], v[46:47]
	v_pk_mul_f32 v[48:49], v[48:49], v[48:49]
	v_pk_mul_f32 v[42:43], v[42:43], v[42:43]
	v_pk_mul_f32 v[44:45], v[44:45], v[44:45]
	v_pk_mul_f32 v[38:39], v[38:39], v[38:39]
	v_pk_mul_f32 v[40:41], v[40:41], v[40:41]
	v_pk_mul_f32 v[34:35], v[34:35], v[34:35]
	v_pk_mul_f32 v[36:37], v[36:37], v[36:37]
	v_pk_mul_f32 v[30:31], v[30:31], v[30:31]
	v_pk_mul_f32 v[32:33], v[32:33], v[32:33]
	v_pk_mul_f32 v[26:27], v[26:27], v[26:27]
	v_pk_mul_f32 v[28:29], v[28:29], v[28:29]
	v_pk_mul_f32 v[22:23], v[22:23], v[22:23]
	v_pk_mul_f32 v[24:25], v[24:25], v[24:25]
	v_pk_mul_f32 v[18:19], v[18:19], v[18:19]
	v_pk_mul_f32 v[20:21], v[20:21], v[20:21]
	v_pk_mul_f32 v[14:15], v[14:15], v[14:15]
	v_pk_mul_f32 v[16:17], v[16:17], v[16:17]
	v_pk_mul_f32 v[10:11], v[10:11], v[10:11]
	v_pk_mul_f32 v[12:13], v[12:13], v[12:13]
	v_cvt_pk_bf16_f32 v6, v6, v7
	v_cvt_pk_bf16_f32 v7, v8, v9
	v_pk_mul_f32 v[2:3], v[2:3], v[2:3]
	v_pk_mul_f32 v[4:5], v[4:5], v[4:5]
	s_addc_u32 s7, s10, s7
	s_waitcnt lgkmcnt(0)
	s_barrier
	v_cvt_pk_bf16_f32 v62, v62, v63
	v_cvt_pk_bf16_f32 v63, v64, v65
	v_cvt_pk_bf16_f32 v58, v58, v59
	v_cvt_pk_bf16_f32 v59, v60, v61
	v_cvt_pk_bf16_f32 v54, v54, v55
	v_cvt_pk_bf16_f32 v55, v56, v57
	v_cvt_pk_bf16_f32 v50, v50, v51
	v_cvt_pk_bf16_f32 v51, v52, v53
	v_cvt_pk_bf16_f32 v46, v46, v47
	v_cvt_pk_bf16_f32 v47, v48, v49
	v_cvt_pk_bf16_f32 v42, v42, v43
	v_cvt_pk_bf16_f32 v43, v44, v45
	v_cvt_pk_bf16_f32 v38, v38, v39
	v_cvt_pk_bf16_f32 v39, v40, v41
	v_cvt_pk_bf16_f32 v34, v34, v35
	v_cvt_pk_bf16_f32 v35, v36, v37
	v_cvt_pk_bf16_f32 v30, v30, v31
	v_cvt_pk_bf16_f32 v31, v32, v33
	v_cvt_pk_bf16_f32 v26, v26, v27
	v_cvt_pk_bf16_f32 v27, v28, v29
	v_cvt_pk_bf16_f32 v22, v22, v23
	v_cvt_pk_bf16_f32 v23, v24, v25
	v_cvt_pk_bf16_f32 v18, v18, v19
	v_cvt_pk_bf16_f32 v19, v20, v21
	v_cvt_pk_bf16_f32 v14, v14, v15
	v_cvt_pk_bf16_f32 v15, v16, v17
	v_cvt_pk_bf16_f32 v10, v10, v11
	v_cvt_pk_bf16_f32 v11, v12, v13
	ds_write_b64 v110, v[6:7]
	v_cvt_pk_bf16_f32 v2, v2, v3
	v_cvt_pk_bf16_f32 v3, v4, v5
	v_lshl_add_u64 v[6:7], s[6:7], 0, v[68:69]
	ds_write_b64 v1, v[62:63] offset:32768
	ds_write_b64 v120, v[54:55]
	ds_write_b64 v116, v[50:51]
	ds_write_b64 v1, v[46:47] offset:36864
	ds_write2st64_b64 v118, v[58:59], v[42:43] offset0:64 offset1:72
	ds_write_b64 v106, v[38:39]
	ds_write_b64 v107, v[34:35]
	ds_write_b64 v1, v[30:31] offset:40960
	ds_write_b64 v108, v[22:23]
	ds_write_b64 v109, v[18:19]
	ds_write_b64 v1, v[14:15] offset:45056
	ds_write2st64_b64 v118, v[26:27], v[10:11] offset0:80 offset1:88
	ds_write_b64 v111, v[2:3]
	v_lshl_add_u64 v[6:7], v[6:7], 0, v[70:71]
	s_waitcnt lgkmcnt(0)
	s_barrier
	v_lshl_add_u64 v[6:7], v[6:7], 0, v[66:67]
	ds_read_b128 v[2:5], v131
	s_waitcnt lgkmcnt(0)
	global_store_dwordx4 v[6:7], v[2:5], off sc1
	s_nop 7
	v_lshl_add_u64 v[6:7], s[6:7], 0, v[72:73]
	v_lshl_add_u64 v[6:7], v[6:7], 0, v[74:75]
	v_lshl_add_u64 v[6:7], v[6:7], 0, v[66:67]
	ds_read_b128 v[2:5], v139
	s_waitcnt lgkmcnt(0)
	global_store_dwordx4 v[6:7], v[2:5], off sc1
	s_nop 7
	v_lshl_add_u64 v[6:7], s[6:7], 0, v[76:77]
	v_lshl_add_u64 v[6:7], v[6:7], 0, v[78:79]
	v_lshl_add_u64 v[6:7], v[6:7], 0, v[66:67]
	ds_read_b128 v[2:5], v141
	s_waitcnt lgkmcnt(0)
	global_store_dwordx4 v[6:7], v[2:5], off sc1
	s_nop 7
	v_lshl_add_u64 v[6:7], s[6:7], 0, v[80:81]
	v_lshl_add_u64 v[6:7], v[6:7], 0, v[82:83]
	v_lshl_add_u64 v[6:7], v[6:7], 0, v[66:67]
	ds_read_b128 v[2:5], v143
	s_waitcnt lgkmcnt(0)
	global_store_dwordx4 v[6:7], v[2:5], off sc1
	s_nop 7
	v_lshl_add_u64 v[6:7], s[6:7], 0, v[84:85]
	v_lshl_add_u64 v[6:7], v[6:7], 0, v[86:87]
	v_lshl_add_u64 v[6:7], v[6:7], 0, v[66:67]
	ds_read_b128 v[2:5], v145
	s_waitcnt lgkmcnt(0)
	global_store_dwordx4 v[6:7], v[2:5], off sc1
	s_nop 7
	v_lshl_add_u64 v[6:7], s[6:7], 0, v[88:89]
	v_lshl_add_u64 v[6:7], v[6:7], 0, v[90:91]
	v_lshl_add_u64 v[6:7], v[6:7], 0, v[66:67]
	ds_read_b128 v[2:5], v162
	s_waitcnt lgkmcnt(0)
	global_store_dwordx4 v[6:7], v[2:5], off sc1
	s_nop 7
	v_lshl_add_u64 v[6:7], s[6:7], 0, v[92:93]
	v_lshl_add_u64 v[6:7], v[6:7], 0, v[94:95]
	v_lshl_add_u64 v[6:7], v[6:7], 0, v[66:67]
	ds_read_b128 v[2:5], v163
	s_waitcnt lgkmcnt(0)
	global_store_dwordx4 v[6:7], v[2:5], off sc1
	s_nop 7
	v_lshl_add_u64 v[6:7], s[6:7], 0, v[96:97]
	v_lshl_add_u64 v[6:7], v[6:7], 0, v[98:99]
	ds_read_b128 v[2:5], v164
	v_lshl_add_u64 v[6:7], v[6:7], 0, v[66:67]
	s_waitcnt lgkmcnt(0)
	global_store_dwordx4 v[6:7], v[2:5], off sc1
	s_nop 7
	s_andn2_b64 vcc, exec, s[4:5]
	s_cbranch_vccz .LBB0_571

;   #define LDA(dst,b,h) for(int m=0;m<4;++m)for(int k=0;k<2;++k) \
;     dst[m][k]=*reinterpret_cast<const bf16x8*>((char*)SA(b,h)+lds_byte(wr*64+m*16+fr,k*32+fq*8))
;   #define LDB(dst,b,h) for(int n=0;n<2;++n)for(int k=0;k<2;++k) \
;     dst[n][k]=*reinterpret_cast<const bf16x8*>((char*)SB(b,h)+lds_byte(wc*32+n*16+fr,k*32+fq*8))
;   #define MMA(ai,bj,At,Bt_) do{__builtin_amdgcn_s_setprio(1); \
;     for(int m=0;m<4;++m)for(int n=0;n<2;++n)for(int k=0;k<2;++k) \
;       acc[ai][bj][m][n]=__builtin_amdgcn_mfma_f32_16x16x32_bf16(Bt_[n][k],At[m][k],acc[ai][bj][m][n],0,0,0); \
;     __builtin_amdgcn_s_setprio(0);}while(0)
;   #define WAIT_V(n) asm volatile("s_waitcnt vmcnt(" #n ")":::"memory")
;   #define WAIT_L(n) asm volatile("s_waitcnt lgkmcnt(" #n ")":::"memory")
;   #define BAR __builtin_amdgcn_s_barrier()
;   #define SCHED __builtin_amdgcn_sched_barrier(0)
; template <bool TWO, class MID> ...
;     ...
;     LDB(B0,0,0); SCHED; LDA(At,0,0); STAGE_A(SA(1,1),1,t+1);
;     WAIT_L(8); BAR; WAIT_L(0); MMA(0,0,At,B0); BAR; SCHED;
;     LDB(B1,0,1); STAGE_B(SB(0,0),0,t+2);
;     BAR; WAIT_L(0); MMA(0,1,At,B1); BAR;
;     LDA(At,0,1); STAGE_A(SA(0,0),0,t+2);
;     BAR; WAIT_L(0); MMA(1,0,At,B0); BAR; SCHED;
;     STAGE_B(SB(0,1),1,t+2);
;     WAIT_V(6); BAR; MMA(1,1,At,B1); BAR;
;     LDB(B0,1,0); SCHED; LDA(At,1,0); STAGE_A(SA(0,1),1,t+2);
;     WAIT_L(8); BAR; WAIT_L(0); MMA(0,0,At,B0); BAR; SCHED;
;     LDB(B1,1,1); STAGE_B(SB(1,0),0,t+3);
;     BAR; WAIT_L(0); MMA(0,1,At,B1); BAR;
;     LDA(At,1,1); STAGE_A(SA(1,0),0,t+3);
;     BAR; WAIT_L(0); MMA(1,0,At,B0); BAR; SCHED;
;     STAGE_B(SB(1,1),1,t+3);
;     WAIT_V(6); BAR; MMA(1,1,At,B1); BAR;
.LBB0_562:
	ds_read_b128 v[166:169], v149
	ds_read_b128 v[170:173], v149 offset:1024
	ds_read_b128 v[174:177], v149 offset:2048
	ds_read_b128 v[178:181], v149 offset:3072
	ds_read_b128 v[182:185], v141
	ds_read_b128 v[186:189], v141 offset:1024
	ds_read_b128 v[190:193], v139
	ds_read_b128 v[196:199], v139 offset:1024
	ds_read_b128 v[200:203], v137
	ds_read_b128 v[204:207], v137 offset:1024
	ds_read_b128 v[208:211], v135
	ds_read_b128 v[212:215], v135 offset:1024
	s_add_u32 s23, s4, s12
	s_addc_u32 s24, s5, s13
	s_add_u32 s26, s23, 0x8080080
	s_addc_u32 s27, s24, 0
	v_lshl_add_u64 v[216:217], s[26:27], 0, v[132:133]
	v_readfirstlane_b32 s25, v148
	s_mov_b32 m0, s25
	global_load_lds_dwordx4 v[216:217], off
	v_lshl_add_u64 v[216:217], s[26:27], 0, v[130:131]
	v_readfirstlane_b32 s25, v150
	s_mov_b32 m0, s25
	global_load_lds_dwordx4 v[216:217], off
	s_waitcnt lgkmcnt(8)
	s_barrier
	s_waitcnt lgkmcnt(0)
	s_setprio 1
	s_waitcnt lgkmcnt(7)
	v_mfma_f32_16x16x32_bf16 v[126:129], v[166:169], v[182:185], v[126:129]
	v_mfma_f32_16x16x32_bf16 v[122:125], v[174:177], v[182:185], v[122:125]
	s_waitcnt lgkmcnt(5)
	v_mfma_f32_16x16x32_bf16 v[118:121], v[166:169], v[190:193], v[118:121]
	v_mfma_f32_16x16x32_bf16 v[114:117], v[174:177], v[190:193], v[114:117]
	s_waitcnt lgkmcnt(3)
	v_mfma_f32_16x16x32_bf16 v[110:113], v[166:169], v[200:203], v[110:113]
	v_mfma_f32_16x16x32_bf16 v[106:109], v[174:177], v[200:203], v[106:109]
	s_waitcnt lgkmcnt(1)
	v_mfma_f32_16x16x32_bf16 v[102:105], v[166:169], v[208:211], v[102:105]
	v_mfma_f32_16x16x32_bf16 v[98:101], v[174:177], v[208:211], v[98:101]
	v_mfma_f32_16x16x32_bf16 v[126:129], v[170:173], v[186:189], v[126:129]
	v_mfma_f32_16x16x32_bf16 v[122:125], v[178:181], v[186:189], v[122:125]
	v_mfma_f32_16x16x32_bf16 v[118:121], v[170:173], v[196:199], v[118:121]
	v_mfma_f32_16x16x32_bf16 v[114:117], v[178:181], v[196:199], v[114:117]
	v_mfma_f32_16x16x32_bf16 v[110:113], v[170:173], v[204:207], v[110:113]
	v_mfma_f32_16x16x32_bf16 v[106:109], v[178:181], v[204:207], v[106:109]
	s_waitcnt lgkmcnt(0)
	v_mfma_f32_16x16x32_bf16 v[102:105], v[170:173], v[212:215], v[102:105]
	v_mfma_f32_16x16x32_bf16 v[98:101], v[178:181], v[212:215], v[98:101]
	s_setprio 0
	s_barrier
	s_add_u32 s25, s4, s14
	ds_read_b128 v[216:219], v147
	ds_read_b128 v[220:223], v147 offset:1024
	ds_read_b128 v[224:227], v147 offset:2048
	ds_read_b128 v[228:231], v147 offset:3072
	s_addc_u32 s26, s5, s15
	s_add_u32 s28, s25, 0x3c00100
	s_addc_u32 s29, s26, 0
	v_lshl_add_u64 v[232:233], s[28:29], 0, v[132:133]
	v_readfirstlane_b32 s27, v152
	s_mov_b32 m0, s27
	global_load_lds_dwordx4 v[232:233], off
	v_lshl_add_u64 v[232:233], s[28:29], 0, v[130:131]
	v_readfirstlane_b32 s27, v154
	s_mov_b32 m0, s27
	global_load_lds_dwordx4 v[232:233], off
	s_barrier
	s_waitcnt lgkmcnt(0)
	s_setprio 1
	s_waitcnt lgkmcnt(3)
	v_mfma_f32_16x16x32_bf16 v[94:97], v[216:219], v[182:185], v[94:97]
	s_waitcnt lgkmcnt(1)
	v_mfma_f32_16x16x32_bf16 v[90:93], v[224:227], v[182:185], v[90:93]
	v_mfma_f32_16x16x32_bf16 v[86:89], v[216:219], v[190:193], v[86:89]
	v_mfma_f32_16x16x32_bf16 v[82:85], v[224:227], v[190:193], v[82:85]
	v_mfma_f32_16x16x32_bf16 v[78:81], v[216:219], v[200:203], v[78:81]
	v_mfma_f32_16x16x32_bf16 v[74:77], v[224:227], v[200:203], v[74:77]
	v_mfma_f32_16x16x32_bf16 v[70:73], v[216:219], v[208:211], v[70:73]
	v_mfma_f32_16x16x32_bf16 v[66:69], v[224:227], v[208:211], v[66:69]
	v_mfma_f32_16x16x32_bf16 v[94:97], v[220:223], v[186:189], v[94:97]
	s_waitcnt lgkmcnt(0)
	v_mfma_f32_16x16x32_bf16 v[90:93], v[228:231], v[186:189], v[90:93]
	v_mfma_f32_16x16x32_bf16 v[86:89], v[220:223], v[196:199], v[86:89]
	v_mfma_f32_16x16x32_bf16 v[82:85], v[228:231], v[196:199], v[82:85]
	v_mfma_f32_16x16x32_bf16 v[78:81], v[220:223], v[204:207], v[78:81]
	v_mfma_f32_16x16x32_bf16 v[74:77], v[228:231], v[204:207], v[74:77]
	v_mfma_f32_16x16x32_bf16 v[70:73], v[220:223], v[212:215], v[70:73]
	v_mfma_f32_16x16x32_bf16 v[66:69], v[228:231], v[212:215], v[66:69]
	s_setprio 0
	s_barrier
	ds_read_b128 v[182:185], v141 offset:16384
	ds_read_b128 v[186:189], v141 offset:17408
	ds_read_b128 v[190:193], v139 offset:16384
	ds_read_b128 v[196:199], v139 offset:17408
	ds_read_b128 v[200:203], v137 offset:16384
	ds_read_b128 v[204:207], v137 offset:17408
	ds_read_b128 v[208:211], v135 offset:16384
	ds_read_b128 v[212:215], v135 offset:17408
	s_add_u32 s28, s23, 0x8000100
	s_addc_u32 s29, s24, 0
	v_lshl_add_u64 v[232:233], s[28:29], 0, v[132:133]
	v_readfirstlane_b32 s27, v138
	s_mov_b32 m0, s27
	global_load_lds_dwordx4 v[232:233], off
	v_lshl_add_u64 v[232:233], s[28:29], 0, v[130:131]
	v_readfirstlane_b32 s27, v156
	s_mov_b32 m0, s27
	global_load_lds_dwordx4 v[232:233], off
	s_barrier
	s_waitcnt lgkmcnt(0)
	s_setprio 1
	s_waitcnt lgkmcnt(7)
	v_mfma_f32_16x16x32_bf16 v[62:65], v[166:169], v[182:185], v[62:65]
	v_mfma_f32_16x16x32_bf16 v[58:61], v[174:177], v[182:185], v[58:61]
	s_waitcnt lgkmcnt(5)
	v_mfma_f32_16x16x32_bf16 v[54:57], v[166:169], v[190:193], v[54:57]
	v_mfma_f32_16x16x32_bf16 v[50:53], v[174:177], v[190:193], v[50:53]
	s_waitcnt lgkmcnt(3)
	v_mfma_f32_16x16x32_bf16 v[46:49], v[166:169], v[200:203], v[46:49]
	v_mfma_f32_16x16x32_bf16 v[42:45], v[174:177], v[200:203], v[42:45]
	s_waitcnt lgkmcnt(1)
	v_mfma_f32_16x16x32_bf16 v[38:41], v[166:169], v[208:211], v[38:41]
	v_mfma_f32_16x16x32_bf16 v[34:37], v[174:177], v[208:211], v[34:37]
	v_mfma_f32_16x16x32_bf16 v[62:65], v[170:173], v[186:189], v[62:65]
	v_mfma_f32_16x16x32_bf16 v[58:61], v[178:181], v[186:189], v[58:61]
	v_mfma_f32_16x16x32_bf16 v[54:57], v[170:173], v[196:199], v[54:57]
	v_mfma_f32_16x16x32_bf16 v[50:53], v[178:181], v[196:199], v[50:53]
	v_mfma_f32_16x16x32_bf16 v[46:49], v[170:173], v[204:207], v[46:49]
	v_mfma_f32_16x16x32_bf16 v[42:45], v[178:181], v[204:207], v[42:45]
	s_waitcnt lgkmcnt(0)
	v_mfma_f32_16x16x32_bf16 v[38:41], v[170:173], v[212:215], v[38:41]
	v_mfma_f32_16x16x32_bf16 v[34:37], v[178:181], v[212:215], v[34:37]
	s_setprio 0
	s_barrier
;   #define LDA(dst,b,h) for(int m=0;m<4;++m)for(int k=0;k<2;++k) \
;     dst[m][k]=*reinterpret_cast<const bf16x8*>((char*)SA(b,h)+lds_byte(wr*64+m*16+fr,k*32+fq*8))
;   #define LDB(dst,b,h) for(int n=0;n<2;++n)for(int k=0;k<2;++k) \
;     dst[n][k]=*reinterpret_cast<const bf16x8*>((char*)SB(b,h)+lds_byte(wc*32+n*16+fr,k*32+fq*8))
;   #define MMA(ai,bj,At,Bt_) do{__builtin_amdgcn_s_setprio(1); \
;     for(int m=0;m<4;++m)for(int n=0;n<2;++n)for(int k=0;k<2;++k) \
;       acc[ai][bj][m][n]=__builtin_amdgcn_mfma_f32_16x16x32_bf16(Bt_[n][k],At[m][k],acc[ai][bj][m][n],0,0,0); \
;     __builtin_amdgcn_s_setprio(0);}while(0)
;   #define WAIT_V(n) asm volatile("s_waitcnt vmcnt(" #n ")":::"memory")
;   #define WAIT_L(n) asm volatile("s_waitcnt lgkmcnt(" #n ")":::"memory")
;   #define BAR __builtin_amdgcn_s_barrier()
;   #define SCHED __builtin_amdgcn_sched_barrier(0)
; template <bool TWO, class MID> ...
;     ...
;     LDB(B0,0,0); SCHED; LDA(At,0,0); STAGE_A(SA(1,1),1,t+1);
;     WAIT_L(8); BAR; WAIT_L(0); MMA(0,0,At,B0); BAR; SCHED;
;     LDB(B1,0,1); STAGE_B(SB(0,0),0,t+2);
;     BAR; WAIT_L(0); MMA(0,1,At,B1); BAR;
;     LDA(At,0,1); STAGE_A(SA(0,0),0,t+2);
;     BAR; WAIT_L(0); MMA(1,0,At,B0); BAR; SCHED;
;     STAGE_B(SB(0,1),1,t+2);
;     WAIT_V(6); BAR; MMA(1,1,At,B1); BAR;
;     LDB(B0,1,0); SCHED; LDA(At,1,0); STAGE_A(SA(0,1),1,t+2);
;     WAIT_L(8); BAR; WAIT_L(0); MMA(0,0,At,B0); BAR; SCHED;
;     LDB(B1,1,1); STAGE_B(SB(1,0),0,t+3);
;     BAR; WAIT_L(0); MMA(0,1,At,B1); BAR;
;     LDA(At,1,1); STAGE_A(SA(1,0),0,t+3);
;     BAR; WAIT_L(0); MMA(1,0,At,B0); BAR; SCHED;
;     STAGE_B(SB(1,1),1,t+3);
;     WAIT_V(6); BAR; MMA(1,1,At,B1); BAR;
	s_add_u32 s28, s25, 0x3c80100
	s_addc_u32 s29, s26, 0
	v_lshl_add_u64 v[166:167], s[28:29], 0, v[132:133]
	v_readfirstlane_b32 s27, v158
	s_mov_b32 m0, s27
	global_load_lds_dwordx4 v[166:167], off
	v_lshl_add_u64 v[166:167], s[28:29], 0, v[130:131]
	v_readfirstlane_b32 s27, v160
	s_mov_b32 m0, s27
	global_load_lds_dwordx4 v[166:167], off
	s_waitcnt vmcnt(6)
	s_barrier
	s_setprio 1
	v_mfma_f32_16x16x32_bf16 v[30:33], v[216:219], v[182:185], v[30:33]
	v_mfma_f32_16x16x32_bf16 v[26:29], v[224:227], v[182:185], v[26:29]
	v_mfma_f32_16x16x32_bf16 v[22:25], v[216:219], v[190:193], v[22:25]
	v_mfma_f32_16x16x32_bf16 v[18:21], v[224:227], v[190:193], v[18:21]
	v_mfma_f32_16x16x32_bf16 v[14:17], v[216:219], v[200:203], v[14:17]
	v_mfma_f32_16x16x32_bf16 v[10:13], v[224:227], v[200:203], v[10:13]
	v_mfma_f32_16x16x32_bf16 v[6:9], v[216:219], v[208:211], v[6:9]
	v_mfma_f32_16x16x32_bf16 v[2:5], v[224:227], v[208:211], v[2:5]
	v_mfma_f32_16x16x32_bf16 v[30:33], v[220:223], v[186:189], v[30:33]
	v_mfma_f32_16x16x32_bf16 v[26:29], v[228:231], v[186:189], v[26:29]
	v_mfma_f32_16x16x32_bf16 v[22:25], v[220:223], v[196:199], v[22:25]
	v_mfma_f32_16x16x32_bf16 v[18:21], v[228:231], v[196:199], v[18:21]
	v_mfma_f32_16x16x32_bf16 v[14:17], v[220:223], v[204:207], v[14:17]
	v_mfma_f32_16x16x32_bf16 v[10:13], v[228:231], v[204:207], v[10:13]
	v_mfma_f32_16x16x32_bf16 v[6:9], v[220:223], v[212:215], v[6:9]
	v_mfma_f32_16x16x32_bf16 v[2:5], v[228:231], v[212:215], v[2:5]
	s_setprio 0
	s_barrier
	ds_read_b128 v[166:169], v145
	ds_read_b128 v[170:173], v145 offset:1024
	ds_read_b128 v[174:177], v145 offset:2048
	ds_read_b128 v[178:181], v145 offset:3072
	ds_read_b128 v[182:185], v141 offset:32768
	ds_read_b128 v[186:189], v141 offset:33792
	ds_read_b128 v[190:193], v139 offset:32768
	ds_read_b128 v[196:199], v139 offset:33792
	ds_read_b128 v[200:203], v137 offset:32768
	ds_read_b128 v[204:207], v137 offset:33792
	ds_read_b128 v[208:211], v135 offset:32768
	ds_read_b128 v[212:215], v135 offset:33792
	s_add_u32 s28, s23, 0x8080100
	s_addc_u32 s29, s24, 0
	v_lshl_add_u64 v[216:217], s[28:29], 0, v[132:133]
	v_readfirstlane_b32 s27, v162
	s_mov_b32 m0, s27
	global_load_lds_dwordx4 v[216:217], off
	v_lshl_add_u64 v[216:217], s[28:29], 0, v[130:131]
	v_readfirstlane_b32 s27, v164
	s_mov_b32 m0, s27
	global_load_lds_dwordx4 v[216:217], off
	s_waitcnt lgkmcnt(8)
	s_barrier
	s_waitcnt lgkmcnt(0)
	s_setprio 1
	s_waitcnt lgkmcnt(7)
	v_mfma_f32_16x16x32_bf16 v[126:129], v[166:169], v[182:185], v[126:129]
	v_mfma_f32_16x16x32_bf16 v[122:125], v[174:177], v[182:185], v[122:125]
	s_waitcnt lgkmcnt(5)
	v_mfma_f32_16x16x32_bf16 v[118:121], v[166:169], v[190:193], v[118:121]
	v_mfma_f32_16x16x32_bf16 v[114:117], v[174:177], v[190:193], v[114:117]
	s_waitcnt lgkmcnt(3)
	v_mfma_f32_16x16x32_bf16 v[110:113], v[166:169], v[200:203], v[110:113]
	v_mfma_f32_16x16x32_bf16 v[106:109], v[174:177], v[200:203], v[106:109]
	s_waitcnt lgkmcnt(1)
	v_mfma_f32_16x16x32_bf16 v[102:105], v[166:169], v[208:211], v[102:105]
	v_mfma_f32_16x16x32_bf16 v[98:101], v[174:177], v[208:211], v[98:101]
	v_mfma_f32_16x16x32_bf16 v[126:129], v[170:173], v[186:189], v[126:129]
	v_mfma_f32_16x16x32_bf16 v[122:125], v[178:181], v[186:189], v[122:125]
	v_mfma_f32_16x16x32_bf16 v[118:121], v[170:173], v[196:199], v[118:121]
	v_mfma_f32_16x16x32_bf16 v[114:117], v[178:181], v[196:199], v[114:117]
	v_mfma_f32_16x16x32_bf16 v[110:113], v[170:173], v[204:207], v[110:113]
	v_mfma_f32_16x16x32_bf16 v[106:109], v[178:181], v[204:207], v[106:109]
	s_waitcnt lgkmcnt(0)
	v_mfma_f32_16x16x32_bf16 v[102:105], v[170:173], v[212:215], v[102:105]
	v_mfma_f32_16x16x32_bf16 v[98:101], v[178:181], v[212:215], v[98:101]
	s_setprio 0
	s_barrier
	ds_read_b128 v[216:219], v143
	ds_read_b128 v[220:223], v143 offset:1024
	ds_read_b128 v[224:227], v143 offset:2048
	ds_read_b128 v[228:231], v143 offset:3072
	s_add_u32 s28, s25, 0x3c00180
	s_addc_u32 s29, s26, 0
	v_lshl_add_u64 v[232:233], s[28:29], 0, v[132:133]
	v_readfirstlane_b32 s27, v134
	s_mov_b32 m0, s27
	global_load_lds_dwordx4 v[232:233], off
	v_lshl_add_u64 v[232:233], s[28:29], 0, v[130:131]
	v_readfirstlane_b32 s27, v136
	s_mov_b32 m0, s27
	global_load_lds_dwordx4 v[232:233], off
	s_barrier
	s_waitcnt lgkmcnt(0)
	s_setprio 1
	s_waitcnt lgkmcnt(3)
	v_mfma_f32_16x16x32_bf16 v[94:97], v[216:219], v[182:185], v[94:97]
	s_waitcnt lgkmcnt(1)
	v_mfma_f32_16x16x32_bf16 v[90:93], v[224:227], v[182:185], v[90:93]
	v_mfma_f32_16x16x32_bf16 v[86:89], v[216:219], v[190:193], v[86:89]
	v_mfma_f32_16x16x32_bf16 v[82:85], v[224:227], v[190:193], v[82:85]
	v_mfma_f32_16x16x32_bf16 v[78:81], v[216:219], v[200:203], v[78:81]
	v_mfma_f32_16x16x32_bf16 v[74:77], v[224:227], v[200:203], v[74:77]
	v_mfma_f32_16x16x32_bf16 v[70:73], v[216:219], v[208:211], v[70:73]
	v_mfma_f32_16x16x32_bf16 v[66:69], v[224:227], v[208:211], v[66:69]
	v_mfma_f32_16x16x32_bf16 v[94:97], v[220:223], v[186:189], v[94:97]
	s_waitcnt lgkmcnt(0)
	v_mfma_f32_16x16x32_bf16 v[90:93], v[228:231], v[186:189], v[90:93]
	v_mfma_f32_16x16x32_bf16 v[86:89], v[220:223], v[196:199], v[86:89]
	v_mfma_f32_16x16x32_bf16 v[82:85], v[228:231], v[196:199], v[82:85]
	v_mfma_f32_16x16x32_bf16 v[78:81], v[220:223], v[204:207], v[78:81]
	v_mfma_f32_16x16x32_bf16 v[74:77], v[228:231], v[204:207], v[74:77]
	v_mfma_f32_16x16x32_bf16 v[70:73], v[220:223], v[212:215], v[70:73]
	v_mfma_f32_16x16x32_bf16 v[66:69], v[228:231], v[212:215], v[66:69]
	s_setprio 0
	s_barrier
;   #define LDA(dst,b,h) for(int m=0;m<4;++m)for(int k=0;k<2;++k) \
;     dst[m][k]=*reinterpret_cast<const bf16x8*>((char*)SA(b,h)+lds_byte(wr*64+m*16+fr,k*32+fq*8))
;   #define LDB(dst,b,h) for(int n=0;n<2;++n)for(int k=0;k<2;++k) \
;     dst[n][k]=*reinterpret_cast<const bf16x8*>((char*)SB(b,h)+lds_byte(wc*32+n*16+fr,k*32+fq*8))
;   #define MMA(ai,bj,At,Bt_) do{__builtin_amdgcn_s_setprio(1); \
;     for(int m=0;m<4;++m)for(int n=0;n<2;++n)for(int k=0;k<2;++k) \
;       acc[ai][bj][m][n]=__builtin_amdgcn_mfma_f32_16x16x32_bf16(Bt_[n][k],At[m][k],acc[ai][bj][m][n],0,0,0); \
;     __builtin_amdgcn_s_setprio(0);}while(0)
;   #define WAIT_V(n) asm volatile("s_waitcnt vmcnt(" #n ")":::"memory")
;   #define WAIT_L(n) asm volatile("s_waitcnt lgkmcnt(" #n ")":::"memory")
;   #define BAR __builtin_amdgcn_s_barrier()
;   #define SCHED __builtin_amdgcn_sched_barrier(0)
; template <bool TWO, class MID> ...
;     ...
;     LDB(B0,0,0); SCHED; LDA(At,0,0); STAGE_A(SA(1,1),1,t+1);
;     WAIT_L(8); BAR; WAIT_L(0); MMA(0,0,At,B0); BAR; SCHED;
;     LDB(B1,0,1); STAGE_B(SB(0,0),0,t+2);
;     BAR; WAIT_L(0); MMA(0,1,At,B1); BAR;
;     LDA(At,0,1); STAGE_A(SA(0,0),0,t+2);
;     BAR; WAIT_L(0); MMA(1,0,At,B0); BAR; SCHED;
;     STAGE_B(SB(0,1),1,t+2);
;     WAIT_V(6); BAR; MMA(1,1,At,B1); BAR;
;     LDB(B0,1,0); SCHED; LDA(At,1,0); STAGE_A(SA(0,1),1,t+2);
;     WAIT_L(8); BAR; WAIT_L(0); MMA(0,0,At,B0); BAR; SCHED;
;     LDB(B1,1,1); STAGE_B(SB(1,0),0,t+3);
;     BAR; WAIT_L(0); MMA(0,1,At,B1); BAR;
;     LDA(At,1,1); STAGE_A(SA(1,0),0,t+3);
;     BAR; WAIT_L(0); MMA(1,0,At,B0); BAR; SCHED;
;     STAGE_B(SB(1,1),1,t+3);
;     WAIT_V(6); BAR; MMA(1,1,At,B1); BAR;
;   }
;   { LDB(B0,0,0); LDA(At,0,0); STAGE_A(SA(1,1),1,nt-1);
;     BAR; WAIT_L(0); MMA(0,0,At,B0); BAR;
	ds_read_b128 v[182:185], v141 offset:49152
	ds_read_b128 v[186:189], v141 offset:50176
	ds_read_b128 v[190:193], v139 offset:49152
	ds_read_b128 v[196:199], v139 offset:50176
	ds_read_b128 v[200:203], v137 offset:49152
	ds_read_b128 v[204:207], v137 offset:50176
	ds_read_b128 v[208:211], v135 offset:49152
	ds_read_b128 v[212:215], v135 offset:50176
	s_add_u32 s28, s23, 0x8000180
	s_addc_u32 s29, s24, 0
	v_lshl_add_u64 v[232:233], s[28:29], 0, v[132:133]
	v_readfirstlane_b32 s23, v140
	s_mov_b32 m0, s23
	global_load_lds_dwordx4 v[232:233], off
	v_lshl_add_u64 v[232:233], s[28:29], 0, v[130:131]
	v_readfirstlane_b32 s23, v142
	s_mov_b32 m0, s23
	global_load_lds_dwordx4 v[232:233], off
	s_barrier
	s_waitcnt lgkmcnt(0)
	s_setprio 1
	s_waitcnt lgkmcnt(7)
	v_mfma_f32_16x16x32_bf16 v[62:65], v[166:169], v[182:185], v[62:65]
	v_mfma_f32_16x16x32_bf16 v[58:61], v[174:177], v[182:185], v[58:61]
	s_waitcnt lgkmcnt(5)
	v_mfma_f32_16x16x32_bf16 v[54:57], v[166:169], v[190:193], v[54:57]
	v_mfma_f32_16x16x32_bf16 v[50:53], v[174:177], v[190:193], v[50:53]
	s_waitcnt lgkmcnt(3)
	v_mfma_f32_16x16x32_bf16 v[46:49], v[166:169], v[200:203], v[46:49]
	v_mfma_f32_16x16x32_bf16 v[42:45], v[174:177], v[200:203], v[42:45]
	s_waitcnt lgkmcnt(1)
	v_mfma_f32_16x16x32_bf16 v[38:41], v[166:169], v[208:211], v[38:41]
	v_mfma_f32_16x16x32_bf16 v[34:37], v[174:177], v[208:211], v[34:37]
	v_mfma_f32_16x16x32_bf16 v[62:65], v[170:173], v[186:189], v[62:65]
	v_mfma_f32_16x16x32_bf16 v[58:61], v[178:181], v[186:189], v[58:61]
	v_mfma_f32_16x16x32_bf16 v[54:57], v[170:173], v[196:199], v[54:57]
	v_mfma_f32_16x16x32_bf16 v[50:53], v[178:181], v[196:199], v[50:53]
	v_mfma_f32_16x16x32_bf16 v[46:49], v[170:173], v[204:207], v[46:49]
	v_mfma_f32_16x16x32_bf16 v[42:45], v[178:181], v[204:207], v[42:45]
	s_waitcnt lgkmcnt(0)
	v_mfma_f32_16x16x32_bf16 v[38:41], v[170:173], v[212:215], v[38:41]
	v_mfma_f32_16x16x32_bf16 v[34:37], v[178:181], v[212:215], v[34:37]
	s_setprio 0
	s_barrier
	s_add_u32 s24, s25, 0x3c80180
	s_addc_u32 s25, s26, 0
	v_lshl_add_u64 v[166:167], s[24:25], 0, v[132:133]
	v_readfirstlane_b32 s23, v144
	s_mov_b32 m0, s23
	global_load_lds_dwordx4 v[166:167], off
	v_lshl_add_u64 v[166:167], s[24:25], 0, v[130:131]
	v_readfirstlane_b32 s23, v146
	s_mov_b32 m0, s23
	global_load_lds_dwordx4 v[166:167], off
	s_waitcnt vmcnt(6)
	s_barrier
	s_setprio 1
	v_mfma_f32_16x16x32_bf16 v[30:33], v[216:219], v[182:185], v[30:33]
	v_mfma_f32_16x16x32_bf16 v[26:29], v[224:227], v[182:185], v[26:29]
	v_mfma_f32_16x16x32_bf16 v[22:25], v[216:219], v[190:193], v[22:25]
	v_mfma_f32_16x16x32_bf16 v[18:21], v[224:227], v[190:193], v[18:21]
	v_mfma_f32_16x16x32_bf16 v[14:17], v[216:219], v[200:203], v[14:17]
	v_mfma_f32_16x16x32_bf16 v[10:13], v[224:227], v[200:203], v[10:13]
	v_mfma_f32_16x16x32_bf16 v[6:9], v[216:219], v[208:211], v[6:9]
	v_mfma_f32_16x16x32_bf16 v[2:5], v[224:227], v[208:211], v[2:5]
	v_mfma_f32_16x16x32_bf16 v[30:33], v[220:223], v[186:189], v[30:33]
	v_mfma_f32_16x16x32_bf16 v[26:29], v[228:231], v[186:189], v[26:29]
	v_mfma_f32_16x16x32_bf16 v[22:25], v[220:223], v[196:199], v[22:25]
	v_mfma_f32_16x16x32_bf16 v[18:21], v[228:231], v[196:199], v[18:21]
	v_mfma_f32_16x16x32_bf16 v[14:17], v[220:223], v[204:207], v[14:17]
	v_mfma_f32_16x16x32_bf16 v[10:13], v[228:231], v[204:207], v[10:13]
	v_mfma_f32_16x16x32_bf16 v[6:9], v[220:223], v[212:215], v[6:9]
	v_mfma_f32_16x16x32_bf16 v[2:5], v[228:231], v[212:215], v[2:5]
	s_setprio 0
	s_add_i32 s22, s22, 2
	s_add_u32 s4, s4, 0x100
	s_addc_u32 s5, s5, 0
	s_cmp_lt_u32 s22, 28
	s_barrier
	s_cbranch_scc1 .LBB0_562
	ds_read_b128 v[152:155], v149
	ds_read_b128 v[156:159], v149 offset:1024
	ds_read_b128 v[160:163], v149 offset:2048
	ds_read_b128 v[164:167], v149 offset:3072
	ds_read_b128 v[168:171], v141
	ds_read_b128 v[172:175], v141 offset:1024
	ds_read_b128 v[176:179], v139
	ds_read_b128 v[180:183], v139 offset:1024
	ds_read_b128 v[184:187], v137
	ds_read_b128 v[188:191], v137 offset:1024
	ds_read_b128 v[196:199], v135
	ds_read_b128 v[200:203], v135 offset:1024
	s_add_u32 s4, s19, 0x80f80
	s_addc_u32 s5, s21, 0
	v_lshl_add_u64 v[132:133], s[4:5], 0, v[132:133]
	v_readfirstlane_b32 s12, v148
	s_mov_b32 m0, s12
	global_load_lds_dwordx4 v[132:133], off
	v_lshl_add_u64 v[130:131], s[4:5], 0, v[130:131]
	v_readfirstlane_b32 s4, v150
	s_mov_b32 m0, s4
	global_load_lds_dwordx4 v[130:131], off
	s_barrier
	s_waitcnt lgkmcnt(0)
	s_setprio 1
	s_waitcnt lgkmcnt(7)
	v_mfma_f32_16x16x32_bf16 v[126:129], v[152:155], v[168:171], v[126:129]
	v_mfma_f32_16x16x32_bf16 v[122:125], v[160:163], v[168:171], v[122:125]
	s_waitcnt lgkmcnt(5)
	v_mfma_f32_16x16x32_bf16 v[114:117], v[160:163], v[176:179], v[114:117]
	s_waitcnt lgkmcnt(3)
	v_mfma_f32_16x16x32_bf16 v[106:109], v[160:163], v[184:187], v[106:109]
	s_waitcnt lgkmcnt(1)
	v_mfma_f32_16x16x32_bf16 v[98:101], v[160:163], v[196:199], v[98:101]
	v_mfma_f32_16x16x32_bf16 v[126:129], v[156:159], v[172:175], v[126:129]
	v_mfma_f32_16x16x32_bf16 v[122:125], v[164:167], v[172:175], v[122:125]
	v_mfma_f32_16x16x32_bf16 v[118:121], v[152:155], v[176:179], v[118:121]
	v_mfma_f32_16x16x32_bf16 v[114:117], v[164:167], v[180:183], v[114:117]
	v_mfma_f32_16x16x32_bf16 v[110:113], v[152:155], v[184:187], v[110:113]
	v_mfma_f32_16x16x32_bf16 v[106:109], v[164:167], v[188:191], v[106:109]
	v_mfma_f32_16x16x32_bf16 v[102:105], v[152:155], v[196:199], v[102:105]
	s_waitcnt lgkmcnt(0)
	v_mfma_f32_16x16x32_bf16 v[98:101], v[164:167], v[200:203], v[98:101]
	v_mfma_f32_16x16x32_bf16 v[130:133], v[156:159], v[180:183], v[118:121]
	v_mfma_f32_16x16x32_bf16 v[148:151], v[156:159], v[188:191], v[110:113]
	v_mfma_f32_16x16x32_bf16 v[204:207], v[156:159], v[200:203], v[102:105]
	s_setprio 0
	s_barrier
;   #define LDA(dst,b,h) for(int m=0;m<4;++m)for(int k=0;k<2;++k) \
;     dst[m][k]=*reinterpret_cast<const bf16x8*>((char*)SA(b,h)+lds_byte(wr*64+m*16+fr,k*32+fq*8))
;   #define LDB(dst,b,h) for(int n=0;n<2;++n)for(int k=0;k<2;++k) \
;     dst[n][k]=*reinterpret_cast<const bf16x8*>((char*)SB(b,h)+lds_byte(wc*32+n*16+fr,k*32+fq*8))
;   #define MMA(ai,bj,At,Bt_) do{__builtin_amdgcn_s_setprio(1); \
;     for(int m=0;m<4;++m)for(int n=0;n<2;++n)for(int k=0;k<2;++k) \
;       acc[ai][bj][m][n]=__builtin_amdgcn_mfma_f32_16x16x32_bf16(Bt_[n][k],At[m][k],acc[ai][bj][m][n],0,0,0); \
;     __builtin_amdgcn_s_setprio(0);}while(0)
;   #define WAIT_V(n) asm volatile("s_waitcnt vmcnt(" #n ")":::"memory")
;   #define WAIT_L(n) asm volatile("s_waitcnt lgkmcnt(" #n ")":::"memory")
;   #define BAR __builtin_amdgcn_s_barrier()
; template <bool TWO, class MID> ...
;     ...
;     BAR; WAIT_L(0); MMA(0,0,At,B0); BAR;
;     LDB(B1,0,1); BAR; WAIT_L(0); MMA(0,1,At,B1); BAR;
;     LDA(At,0,1); WAIT_V(4); BAR; WAIT_L(0); MMA(1,0,At,B0); MMA(1,1,At,B1); BAR; }
;   { LDB(B0,1,0); LDA(At,1,0); WAIT_V(2); BAR; WAIT_L(0); MMA(0,0,At,B0); BAR;
	s_nop 0
	ds_read_b128 v[102:105], v147
	ds_read_b128 v[110:113], v147 offset:1024
	ds_read_b128 v[118:121], v147 offset:2048
	ds_read_b128 v[208:211], v147 offset:3072
	s_barrier
	s_waitcnt lgkmcnt(0)
	s_setprio 1
	s_waitcnt lgkmcnt(1)
	v_mfma_f32_16x16x32_bf16 v[90:93], v[118:121], v[168:171], v[90:93]
	v_mfma_f32_16x16x32_bf16 v[82:85], v[118:121], v[176:179], v[82:85]
	v_mfma_f32_16x16x32_bf16 v[74:77], v[118:121], v[184:187], v[74:77]
	v_mfma_f32_16x16x32_bf16 v[66:69], v[118:121], v[196:199], v[66:69]
	v_mfma_f32_16x16x32_bf16 v[94:97], v[102:105], v[168:171], v[94:97]
	s_waitcnt lgkmcnt(0)
	v_mfma_f32_16x16x32_bf16 v[90:93], v[208:211], v[172:175], v[90:93]
	v_mfma_f32_16x16x32_bf16 v[86:89], v[102:105], v[176:179], v[86:89]
	v_mfma_f32_16x16x32_bf16 v[82:85], v[208:211], v[180:183], v[82:85]
	v_mfma_f32_16x16x32_bf16 v[78:81], v[102:105], v[184:187], v[78:81]
	v_mfma_f32_16x16x32_bf16 v[74:77], v[208:211], v[188:191], v[74:77]
	v_mfma_f32_16x16x32_bf16 v[70:73], v[102:105], v[196:199], v[70:73]
	v_mfma_f32_16x16x32_bf16 v[66:69], v[208:211], v[200:203], v[66:69]
	v_mfma_f32_16x16x32_bf16 v[212:215], v[110:113], v[172:175], v[94:97]
	v_mfma_f32_16x16x32_bf16 v[168:171], v[110:113], v[180:183], v[86:89]
	v_mfma_f32_16x16x32_bf16 v[172:175], v[110:113], v[188:191], v[78:81]
	v_mfma_f32_16x16x32_bf16 v[176:179], v[110:113], v[200:203], v[70:73]
	s_setprio 0
	s_barrier
	s_nop 0
	ds_read_b128 v[70:73], v141 offset:16384
	ds_read_b128 v[78:81], v141 offset:17408
	ds_read_b128 v[86:89], v139 offset:16384
	ds_read_b128 v[94:97], v139 offset:17408
	ds_read_b128 v[180:183], v137 offset:16384
	ds_read_b128 v[184:187], v137 offset:17408
	ds_read_b128 v[188:191], v135 offset:16384
	ds_read_b128 v[196:199], v135 offset:17408
	s_waitcnt vmcnt(4)
	s_barrier
	s_waitcnt lgkmcnt(0)
	s_setprio 1
	s_waitcnt lgkmcnt(7)
	v_mfma_f32_16x16x32_bf16 v[62:65], v[152:155], v[70:73], v[62:65]
	v_mfma_f32_16x16x32_bf16 v[58:61], v[160:163], v[70:73], v[58:61]
	s_waitcnt lgkmcnt(5)
	v_mfma_f32_16x16x32_bf16 v[54:57], v[152:155], v[86:89], v[54:57]
	v_mfma_f32_16x16x32_bf16 v[50:53], v[160:163], v[86:89], v[50:53]
	s_waitcnt lgkmcnt(1)
	v_mfma_f32_16x16x32_bf16 v[38:41], v[152:155], v[188:191], v[38:41]
	v_mfma_f32_16x16x32_bf16 v[34:37], v[160:163], v[188:191], v[34:37]
	v_mfma_f32_16x16x32_bf16 v[62:65], v[156:159], v[78:81], v[62:65]
	v_mfma_f32_16x16x32_bf16 v[58:61], v[164:167], v[78:81], v[58:61]
	v_mfma_f32_16x16x32_bf16 v[54:57], v[156:159], v[94:97], v[54:57]
	v_mfma_f32_16x16x32_bf16 v[50:53], v[164:167], v[94:97], v[50:53]
	v_mfma_f32_16x16x32_bf16 v[46:49], v[152:155], v[180:183], v[46:49]
	v_mfma_f32_16x16x32_bf16 v[42:45], v[160:163], v[180:183], v[42:45]
	s_waitcnt lgkmcnt(0)
	v_mfma_f32_16x16x32_bf16 v[38:41], v[156:159], v[196:199], v[38:41]
	v_mfma_f32_16x16x32_bf16 v[34:37], v[164:167], v[196:199], v[34:37]
	v_mfma_f32_16x16x32_bf16 v[200:203], v[156:159], v[184:187], v[46:49]
	v_mfma_f32_16x16x32_bf16 v[216:219], v[164:167], v[184:187], v[42:45]
	s_setprio 0
	s_setprio 1
	v_mfma_f32_16x16x32_bf16 v[22:25], v[102:105], v[86:89], v[22:25]
	v_mfma_f32_16x16x32_bf16 v[18:21], v[118:121], v[86:89], v[18:21]
	v_mfma_f32_16x16x32_bf16 v[6:9], v[102:105], v[188:191], v[6:9]
	v_mfma_f32_16x16x32_bf16 v[2:5], v[118:121], v[188:191], v[2:5]
	v_mfma_f32_16x16x32_bf16 v[30:33], v[102:105], v[70:73], v[30:33]
	v_mfma_f32_16x16x32_bf16 v[26:29], v[118:121], v[70:73], v[26:29]
	v_mfma_f32_16x16x32_bf16 v[22:25], v[110:113], v[94:97], v[22:25]
	v_mfma_f32_16x16x32_bf16 v[18:21], v[208:211], v[94:97], v[18:21]
	v_mfma_f32_16x16x32_bf16 v[14:17], v[102:105], v[180:183], v[14:17]
	v_mfma_f32_16x16x32_bf16 v[10:13], v[118:121], v[180:183], v[10:13]
	v_mfma_f32_16x16x32_bf16 v[6:9], v[110:113], v[196:199], v[6:9]
	v_mfma_f32_16x16x32_bf16 v[2:5], v[208:211], v[196:199], v[2:5]
	v_mfma_f32_16x16x32_bf16 v[152:155], v[110:113], v[78:81], v[30:33]
	v_mfma_f32_16x16x32_bf16 v[156:159], v[208:211], v[78:81], v[26:29]
	v_mfma_f32_16x16x32_bf16 v[160:163], v[110:113], v[184:187], v[14:17]
	v_mfma_f32_16x16x32_bf16 v[164:167], v[208:211], v[184:187], v[10:13]
	s_setprio 0
	s_barrier
	s_nop 0
	ds_read_b128 v[10:13], v145
	ds_read_b128 v[14:17], v145 offset:1024
	ds_read_b128 v[180:183], v145 offset:2048
	ds_read_b128 v[144:147], v145 offset:3072
	ds_read_b128 v[26:29], v141 offset:32768
	ds_read_b128 v[30:33], v141 offset:33792
	ds_read_b128 v[42:45], v139 offset:32768
	ds_read_b128 v[46:49], v139 offset:33792
	ds_read_b128 v[184:187], v137 offset:32768
	ds_read_b128 v[188:191], v137 offset:33792
	ds_read_b128 v[196:199], v135 offset:32768
	ds_read_b128 v[208:211], v135 offset:33792
	s_waitcnt vmcnt(2)
	s_barrier
;   #define LDA(dst,b,h) for(int m=0;m<4;++m)for(int k=0;k<2;++k) \
;     dst[m][k]=*reinterpret_cast<const bf16x8*>((char*)SA(b,h)+lds_byte(wr*64+m*16+fr,k*32+fq*8))
;   #define LDB(dst,b,h) for(int n=0;n<2;++n)for(int k=0;k<2;++k) \
;     dst[n][k]=*reinterpret_cast<const bf16x8*>((char*)SB(b,h)+lds_byte(wc*32+n*16+fr,k*32+fq*8))
;   #define MMA(ai,bj,At,Bt_) do{__builtin_amdgcn_s_setprio(1); \
;     for(int m=0;m<4;++m)for(int n=0;n<2;++n)for(int k=0;k<2;++k) \
;       acc[ai][bj][m][n]=__builtin_amdgcn_mfma_f32_16x16x32_bf16(Bt_[n][k],At[m][k],acc[ai][bj][m][n],0,0,0); \
;     __builtin_amdgcn_s_setprio(0);}while(0)
;   #define WAIT_V(n) asm volatile("s_waitcnt vmcnt(" #n ")":::"memory")
;   #define WAIT_L(n) asm volatile("s_waitcnt lgkmcnt(" #n ")":::"memory")
;   #define BAR __builtin_amdgcn_s_barrier()
; template <bool TWO, class MID> ...
;     ...
;     LDB(B1,0,1); BAR; WAIT_L(0); MMA(0,1,At,B1); BAR;
;     LDA(At,0,1); WAIT_V(4); BAR; WAIT_L(0); MMA(1,0,At,B0); MMA(1,1,At,B1); BAR; }
;   { LDB(B0,1,0); LDA(At,1,0); WAIT_V(2); BAR; WAIT_L(0); MMA(0,0,At,B0); BAR;
;     LDB(B1,1,1); WAIT_V(0); BAR; WAIT_L(0); MMA(0,1,At,B1); BAR;
;     LDA(At,1,1); BAR; WAIT_L(0); MMA(1,0,At,B0); MMA(1,1,At,B1); BAR; }
;   if(wr==0)BAR;
	s_waitcnt lgkmcnt(0)
	s_setprio 1
	s_waitcnt lgkmcnt(7)
	v_mfma_f32_16x16x32_bf16 v[70:73], v[10:13], v[26:29], v[126:129]
	s_waitcnt lgkmcnt(6)
	v_mfma_f32_16x16x32_bf16 v[126:129], v[14:17], v[30:33], v[70:73]
	v_mfma_f32_16x16x32_bf16 v[70:73], v[180:183], v[26:29], v[122:125]
	v_mfma_f32_16x16x32_bf16 v[118:121], v[144:147], v[30:33], v[70:73]
	s_waitcnt lgkmcnt(5)
	v_mfma_f32_16x16x32_bf16 v[70:73], v[10:13], v[42:45], v[130:133]
	s_waitcnt lgkmcnt(4)
	v_mfma_f32_16x16x32_bf16 v[110:113], v[14:17], v[46:49], v[70:73]
	v_mfma_f32_16x16x32_bf16 v[70:73], v[180:183], v[42:45], v[114:117]
	v_mfma_f32_16x16x32_bf16 v[102:105], v[144:147], v[46:49], v[70:73]
	s_waitcnt lgkmcnt(3)
	v_mfma_f32_16x16x32_bf16 v[70:73], v[10:13], v[184:187], v[148:151]
	s_waitcnt lgkmcnt(2)
	v_mfma_f32_16x16x32_bf16 v[94:97], v[14:17], v[188:191], v[70:73]
	v_mfma_f32_16x16x32_bf16 v[70:73], v[180:183], v[184:187], v[106:109]
	v_mfma_f32_16x16x32_bf16 v[86:89], v[144:147], v[188:191], v[70:73]
	s_waitcnt lgkmcnt(1)
	v_mfma_f32_16x16x32_bf16 v[70:73], v[10:13], v[196:199], v[204:207]
	s_waitcnt lgkmcnt(0)
	v_mfma_f32_16x16x32_bf16 v[78:81], v[14:17], v[208:211], v[70:73]
	v_mfma_f32_16x16x32_bf16 v[70:73], v[180:183], v[196:199], v[98:101]
	v_mfma_f32_16x16x32_bf16 v[70:73], v[144:147], v[208:211], v[70:73]
	s_setprio 0
	s_barrier
	ds_read_b128 v[130:133], v143
	ds_read_b128 v[148:151], v143 offset:1024
	ds_read_b128 v[204:207], v143 offset:2048
	ds_read_b128 v[220:223], v143 offset:3072
	s_waitcnt vmcnt(0)
	s_barrier
	s_waitcnt lgkmcnt(0)
	s_setprio 1
	s_waitcnt lgkmcnt(3)
	v_mfma_f32_16x16x32_bf16 v[98:101], v[130:133], v[26:29], v[212:215]
	s_waitcnt lgkmcnt(1)
	v_mfma_f32_16x16x32_bf16 v[26:29], v[204:207], v[26:29], v[90:93]
	s_waitcnt lgkmcnt(0)
	v_mfma_f32_16x16x32_bf16 v[114:117], v[220:223], v[30:33], v[26:29]
	v_mfma_f32_16x16x32_bf16 v[26:29], v[130:133], v[42:45], v[168:171]
	v_mfma_f32_16x16x32_bf16 v[106:109], v[148:151], v[46:49], v[26:29]
	v_mfma_f32_16x16x32_bf16 v[26:29], v[204:207], v[42:45], v[82:85]
	v_mfma_f32_16x16x32_bf16 v[122:125], v[148:151], v[30:33], v[98:101]
	v_mfma_f32_16x16x32_bf16 v[98:101], v[220:223], v[46:49], v[26:29]
	v_mfma_f32_16x16x32_bf16 v[26:29], v[130:133], v[184:187], v[172:175]
	v_mfma_f32_16x16x32_bf16 v[90:93], v[148:151], v[188:191], v[26:29]
	v_mfma_f32_16x16x32_bf16 v[26:29], v[204:207], v[184:187], v[74:77]
	v_mfma_f32_16x16x32_bf16 v[82:85], v[220:223], v[188:191], v[26:29]
	v_mfma_f32_16x16x32_bf16 v[26:29], v[130:133], v[196:199], v[176:179]
	v_mfma_f32_16x16x32_bf16 v[74:77], v[148:151], v[208:211], v[26:29]
	v_mfma_f32_16x16x32_bf16 v[26:29], v[204:207], v[196:199], v[66:69]
	v_mfma_f32_16x16x32_bf16 v[66:69], v[220:223], v[208:211], v[26:29]
	s_setprio 0
	s_barrier
	ds_read_b128 v[168:171], v141 offset:49152
	ds_read_b128 v[140:143], v141 offset:50176
	ds_read_b128 v[172:175], v139 offset:49152
	ds_read_b128 v[176:179], v139 offset:50176
	ds_read_b128 v[184:187], v137 offset:49152
	ds_read_b128 v[136:139], v137 offset:50176
	ds_read_b128 v[188:191], v135 offset:49152
	ds_read_b128 v[196:199], v135 offset:50176
	s_barrier
	s_waitcnt lgkmcnt(0)
	s_setprio 1
	s_waitcnt lgkmcnt(7)
	v_mfma_f32_16x16x32_bf16 v[26:29], v[10:13], v[168:171], v[62:65]
	s_waitcnt lgkmcnt(6)
	v_mfma_f32_16x16x32_bf16 v[62:65], v[14:17], v[140:143], v[26:29]
	v_mfma_f32_16x16x32_bf16 v[26:29], v[180:183], v[168:171], v[58:61]
	v_mfma_f32_16x16x32_bf16 v[58:61], v[144:147], v[140:143], v[26:29]
	s_waitcnt lgkmcnt(5)
	v_mfma_f32_16x16x32_bf16 v[26:29], v[10:13], v[172:175], v[54:57]
	s_waitcnt lgkmcnt(4)
	v_mfma_f32_16x16x32_bf16 v[46:49], v[14:17], v[176:179], v[26:29]
	v_mfma_f32_16x16x32_bf16 v[26:29], v[180:183], v[172:175], v[50:53]
	v_mfma_f32_16x16x32_bf16 v[42:45], v[144:147], v[176:179], v[26:29]
	s_waitcnt lgkmcnt(3)
	v_mfma_f32_16x16x32_bf16 v[26:29], v[10:13], v[184:187], v[200:203]
	s_waitcnt lgkmcnt(1)
	v_mfma_f32_16x16x32_bf16 v[10:13], v[10:13], v[188:191], v[38:41]
	v_mfma_f32_16x16x32_bf16 v[30:33], v[14:17], v[136:139], v[26:29]
	v_mfma_f32_16x16x32_bf16 v[26:29], v[180:183], v[184:187], v[216:219]
	s_waitcnt lgkmcnt(0)
	v_mfma_f32_16x16x32_bf16 v[14:17], v[14:17], v[196:199], v[10:13]
	v_mfma_f32_16x16x32_bf16 v[10:13], v[180:183], v[188:191], v[34:37]
	v_mfma_f32_16x16x32_bf16 v[26:29], v[144:147], v[136:139], v[26:29]
	v_mfma_f32_16x16x32_bf16 v[10:13], v[144:147], v[196:199], v[10:13]
	s_setprio 0
	s_setprio 1
	v_mfma_f32_16x16x32_bf16 v[34:37], v[130:133], v[168:171], v[152:155]
	v_mfma_f32_16x16x32_bf16 v[54:57], v[148:151], v[140:143], v[34:37]
	v_mfma_f32_16x16x32_bf16 v[34:37], v[204:207], v[168:171], v[156:159]
	v_mfma_f32_16x16x32_bf16 v[18:21], v[204:207], v[172:175], v[18:21]
	v_mfma_f32_16x16x32_bf16 v[50:53], v[220:223], v[140:143], v[34:37]
	v_mfma_f32_16x16x32_bf16 v[22:25], v[130:133], v[172:175], v[22:25]
	v_mfma_f32_16x16x32_bf16 v[34:37], v[220:223], v[176:179], v[18:21]
	v_mfma_f32_16x16x32_bf16 v[18:21], v[130:133], v[184:187], v[160:163]
	v_mfma_f32_16x16x32_bf16 v[38:41], v[148:151], v[176:179], v[22:25]
	v_mfma_f32_16x16x32_bf16 v[22:25], v[148:151], v[136:139], v[18:21]
	v_mfma_f32_16x16x32_bf16 v[18:21], v[204:207], v[184:187], v[164:167]
	v_mfma_f32_16x16x32_bf16 v[6:9], v[130:133], v[188:191], v[6:9]
	v_mfma_f32_16x16x32_bf16 v[2:5], v[204:207], v[188:191], v[2:5]
	v_mfma_f32_16x16x32_bf16 v[18:21], v[220:223], v[136:139], v[18:21]
	v_mfma_f32_16x16x32_bf16 v[6:9], v[148:151], v[196:199], v[6:9]
	v_mfma_f32_16x16x32_bf16 v[2:5], v[220:223], v[196:199], v[2:5]
	s_setprio 0
	v_cmp_gt_u32_e32 vcc, s30, v1
	s_barrier
	s_and_saveexec_b64 s[4:5], vcc
	s_cbranch_execz .LBB0_565
	s_barrier

; #define LDS_BARRIER() do { asm volatile("s_waitcnt lgkmcnt(0)" ::: "memory"); __builtin_amdgcn_s_barrier(); asm volatile("" ::: "memory"); } while (0)
; __device__ __forceinline__ void st16_asm(void* ptr, u32x4 v) { asm volatile("global_store_dwordx4 %0, %1, off\n\ts_nop 7" :: "v"(ptr), "v"(v) : "memory"); }
; __device__ __forceinline__ void stg_flush(bf16* shm, int tid, bf16* dst, size_t pitch, bool first, bool tail_barrier = true) {
;   LDS_BARRIER();
;   if (first) asm volatile("s_waitcnt vmcnt(0)" ::: "memory");
;   _Pragma("unroll") for (int i = 0; i < 8; ++i) {
;     const int idx = tid + 512 * i, bjr = idx >> 11, row = (idx >> 4) & 127, c16 = idx & 15;
;     const u32x4 d = *(const u32x4*)stg_ptr(shm, bjr, row, 2 * c16);
;     st16_asm(dst + (size_t)row * pitch + bjr * HALF + c16 * 8, d); }
;   if (tail_barrier) LDS_BARRIER();
.LBB0_611:
	s_or_b64 exec, exec, s[4:5]
	s_or_b32 s0, s8, 0x80
	s_ashr_i32 s1, s0, 31
	s_lshl_b64 s[0:1], s[0:1], 12
	s_add_u32 s0, s14, s0
	s_addc_u32 s1, s15, s1
	v_lshlrev_b32_e32 v6, 1, v119
	v_mov_b32_e32 v7, v0
	v_lshl_add_u64 v[6:7], s[0:1], 0, v[6:7]
	v_lshl_add_u64 v[6:7], v[66:67], 1, v[6:7]
	v_lshlrev_b32_e32 v8, 1, v117
	v_mov_b32_e32 v9, v0
	s_waitcnt lgkmcnt(0)
	s_barrier
	v_add_u32_e32 v2, v118, v120
	v_lshl_add_u64 v[6:7], v[6:7], 0, v[8:9]
	ds_read_b128 v[2:5], v2
	s_waitcnt lgkmcnt(0)
	global_store_dwordx4 v[6:7], v[2:5], off sc1
	s_nop 7
	v_lshlrev_b32_e32 v6, 1, v123
	v_mov_b32_e32 v7, v0
	v_lshl_add_u64 v[6:7], s[0:1], 0, v[6:7]
	v_lshl_add_u64 v[6:7], v[68:69], 1, v[6:7]
	v_add_u32_e32 v2, v121, v124
	v_lshl_add_u64 v[6:7], v[6:7], 0, v[8:9]
	ds_read_b128 v[2:5], v2
	s_waitcnt lgkmcnt(0)
	global_store_dwordx4 v[6:7], v[2:5], off sc1
	s_nop 7
	v_lshlrev_b32_e32 v6, 1, v127
	v_mov_b32_e32 v7, v0
	v_lshl_add_u64 v[6:7], s[0:1], 0, v[6:7]
	v_lshl_add_u64 v[6:7], v[70:71], 1, v[6:7]
	v_add_u32_e32 v2, v125, v128
	v_lshl_add_u64 v[6:7], v[6:7], 0, v[8:9]
	ds_read_b128 v[2:5], v2
	s_waitcnt lgkmcnt(0)
	global_store_dwordx4 v[6:7], v[2:5], off sc1
	s_nop 7
	v_lshlrev_b32_e32 v6, 1, v142
	v_mov_b32_e32 v7, v0
	v_lshl_add_u64 v[6:7], s[0:1], 0, v[6:7]
	v_lshl_add_u64 v[6:7], v[72:73], 1, v[6:7]
	v_add_u32_e32 v2, v129, v143
	v_lshl_add_u64 v[6:7], v[6:7], 0, v[8:9]
	ds_read_b128 v[2:5], v2
	s_waitcnt lgkmcnt(0)
	global_store_dwordx4 v[6:7], v[2:5], off sc1
	s_nop 7
	v_lshlrev_b32_e32 v6, 1, v145
	v_mov_b32_e32 v7, v0
	v_lshl_add_u64 v[6:7], s[0:1], 0, v[6:7]
	v_lshl_add_u64 v[6:7], v[74:75], 1, v[6:7]
	v_add_u32_e32 v2, v144, v146
	v_lshl_add_u64 v[6:7], v[6:7], 0, v[8:9]
	ds_read_b128 v[2:5], v2
	s_waitcnt lgkmcnt(0)
	global_store_dwordx4 v[6:7], v[2:5], off sc1
	s_nop 7
	v_lshlrev_b32_e32 v6, 1, v148
	v_mov_b32_e32 v7, v0
	v_lshl_add_u64 v[6:7], s[0:1], 0, v[6:7]
	v_lshl_add_u64 v[6:7], v[76:77], 1, v[6:7]
	v_add_u32_e32 v2, v147, v149
	v_lshl_add_u64 v[6:7], v[6:7], 0, v[8:9]
	ds_read_b128 v[2:5], v2
	s_waitcnt lgkmcnt(0)
	global_store_dwordx4 v[6:7], v[2:5], off sc1
	s_nop 7
	v_lshlrev_b32_e32 v6, 1, v151
	v_mov_b32_e32 v7, v0
	v_lshl_add_u64 v[6:7], s[0:1], 0, v[6:7]
	v_lshl_add_u64 v[6:7], v[78:79], 1, v[6:7]
	v_add_u32_e32 v2, v150, v152
	v_lshl_add_u64 v[6:7], v[6:7], 0, v[8:9]
	ds_read_b128 v[2:5], v2
	s_waitcnt lgkmcnt(0)
	global_store_dwordx4 v[6:7], v[2:5], off sc1
	s_nop 7
	v_lshlrev_b32_e32 v6, 1, v1
	v_mov_b32_e32 v7, v0
	v_lshl_add_u64 v[6:7], s[0:1], 0, v[6:7]
	v_add_u32_e32 v2, v153, v154
	v_lshl_add_u64 v[6:7], v[80:81], 1, v[6:7]
	ds_read_b128 v[2:5], v2
	v_lshl_add_u64 v[6:7], v[6:7], 0, v[8:9]
	s_waitcnt lgkmcnt(0)
	global_store_dwordx4 v[6:7], v[2:5], off sc1
	s_nop 7

;   #define LDA(dst,b,h) for(int m=0;m<4;++m)for(int k=0;k<2;++k) \
;     dst[m][k]=*reinterpret_cast<const bf16x8*>((char*)SA(b,h)+lds_byte(wr*64+m*16+fr,k*32+fq*8))
;   #define LDB(dst,b,h) for(int n=0;n<2;++n)for(int k=0;k<2;++k) \
;     dst[n][k]=*reinterpret_cast<const bf16x8*>((char*)SB(b,h)+lds_byte(wc*32+n*16+fr,k*32+fq*8))
;   #define MMA(ai,bj,At,Bt_) do{__builtin_amdgcn_s_setprio(1); \
;     for(int m=0;m<4;++m)for(int n=0;n<2;++n)for(int k=0;k<2;++k) \
;       acc[ai][bj][m][n]=__builtin_amdgcn_mfma_f32_16x16x32_bf16(Bt_[n][k],At[m][k],acc[ai][bj][m][n],0,0,0); \
;     __builtin_amdgcn_s_setprio(0);}while(0)
;   #define WAIT_V(n) asm volatile("s_waitcnt vmcnt(" #n ")":::"memory")
;   #define WAIT_L(n) asm volatile("s_waitcnt lgkmcnt(" #n ")":::"memory")
;   #define BAR __builtin_amdgcn_s_barrier()
;   #define SCHED __builtin_amdgcn_sched_barrier(0)
; template <bool TWO, class MID> ...
;     ...
;     LDB(B0,0,0); SCHED; LDA(At,0,0); STAGE_A(SA(1,1),1,t+1);
;     WAIT_L(8); BAR; WAIT_L(0); MMA(0,0,At,B0); BAR; SCHED;
;     LDB(B1,0,1); STAGE_B(SB(0,0),0,t+2);
;     BAR; WAIT_L(0); MMA(0,1,At,B1); BAR;
;     LDA(At,0,1); STAGE_A(SA(0,0),0,t+2);
;     BAR; WAIT_L(0); MMA(1,0,At,B0); BAR; SCHED;
;     STAGE_B(SB(0,1),1,t+2);
;     WAIT_V(6); BAR; MMA(1,1,At,B1); BAR;
;     LDB(B0,1,0); SCHED; LDA(At,1,0); STAGE_A(SA(0,1),1,t+2);
;     WAIT_L(8); BAR; WAIT_L(0); MMA(0,0,At,B0); BAR; SCHED;
;     LDB(B1,1,1); STAGE_B(SB(1,0),0,t+3);
;     BAR; WAIT_L(0); MMA(0,1,At,B1); BAR;
;     LDA(At,1,1); STAGE_A(SA(1,0),0,t+3);
;     BAR; WAIT_L(0); MMA(1,0,At,B0); BAR; SCHED;
;     STAGE_B(SB(1,1),1,t+3);
;     WAIT_V(6); BAR; MMA(1,1,At,B1); BAR;
.LBB0_620:
	ds_read_b128 v[166:169], v149
	ds_read_b128 v[170:173], v149 offset:1024
	ds_read_b128 v[174:177], v149 offset:2048
	ds_read_b128 v[178:181], v149 offset:3072
	ds_read_b128 v[182:185], v141
	ds_read_b128 v[186:189], v141 offset:1024
	ds_read_b128 v[190:193], v139
	ds_read_b128 v[196:199], v139 offset:1024
	ds_read_b128 v[200:203], v137
	ds_read_b128 v[204:207], v137 offset:1024
	ds_read_b128 v[208:211], v135
	ds_read_b128 v[212:215], v135 offset:1024
	s_add_u32 s15, s0, s16
	s_addc_u32 s18, s1, s17
	s_add_u32 s24, s15, 0x10200080
	s_addc_u32 s25, s18, 0
	v_lshl_add_u64 v[216:217], s[24:25], 0, v[132:133]
	v_readfirstlane_b32 s19, v148
	s_mov_b32 m0, s19
	global_load_lds_dwordx4 v[216:217], off
	v_lshl_add_u64 v[216:217], s[24:25], 0, v[130:131]
	v_readfirstlane_b32 s19, v150
	s_mov_b32 m0, s19
	global_load_lds_dwordx4 v[216:217], off
	s_waitcnt lgkmcnt(8)
	s_barrier
	s_waitcnt lgkmcnt(0)
	s_setprio 1
	s_waitcnt lgkmcnt(7)
	v_mfma_f32_16x16x32_bf16 v[126:129], v[166:169], v[182:185], v[126:129]
	v_mfma_f32_16x16x32_bf16 v[122:125], v[174:177], v[182:185], v[122:125]
	s_waitcnt lgkmcnt(5)
	v_mfma_f32_16x16x32_bf16 v[118:121], v[166:169], v[190:193], v[118:121]
	v_mfma_f32_16x16x32_bf16 v[114:117], v[174:177], v[190:193], v[114:117]
	s_waitcnt lgkmcnt(3)
	v_mfma_f32_16x16x32_bf16 v[110:113], v[166:169], v[200:203], v[110:113]
	v_mfma_f32_16x16x32_bf16 v[106:109], v[174:177], v[200:203], v[106:109]
	s_waitcnt lgkmcnt(1)
	v_mfma_f32_16x16x32_bf16 v[102:105], v[166:169], v[208:211], v[102:105]
	v_mfma_f32_16x16x32_bf16 v[98:101], v[174:177], v[208:211], v[98:101]
	v_mfma_f32_16x16x32_bf16 v[126:129], v[170:173], v[186:189], v[126:129]
	v_mfma_f32_16x16x32_bf16 v[122:125], v[178:181], v[186:189], v[122:125]
	v_mfma_f32_16x16x32_bf16 v[118:121], v[170:173], v[196:199], v[118:121]
	v_mfma_f32_16x16x32_bf16 v[114:117], v[178:181], v[196:199], v[114:117]
	v_mfma_f32_16x16x32_bf16 v[110:113], v[170:173], v[204:207], v[110:113]
	v_mfma_f32_16x16x32_bf16 v[106:109], v[178:181], v[204:207], v[106:109]
	s_waitcnt lgkmcnt(0)
	v_mfma_f32_16x16x32_bf16 v[102:105], v[170:173], v[212:215], v[102:105]
	v_mfma_f32_16x16x32_bf16 v[98:101], v[178:181], v[212:215], v[98:101]
	s_setprio 0
	s_barrier
	s_add_u32 s19, s0, s4
	ds_read_b128 v[216:219], v147
	ds_read_b128 v[220:223], v147 offset:1024
	ds_read_b128 v[224:227], v147 offset:2048
	ds_read_b128 v[228:231], v147 offset:3072
	s_addc_u32 s24, s1, s5
	s_add_u32 s26, s19, 0x5c00100
	s_addc_u32 s27, s24, 0
	v_lshl_add_u64 v[232:233], s[26:27], 0, v[132:133]
	v_readfirstlane_b32 s25, v152
	s_mov_b32 m0, s25
	global_load_lds_dwordx4 v[232:233], off
	v_lshl_add_u64 v[232:233], s[26:27], 0, v[130:131]
	v_readfirstlane_b32 s25, v154
	s_mov_b32 m0, s25
	global_load_lds_dwordx4 v[232:233], off
	s_barrier
	s_waitcnt lgkmcnt(0)
	s_setprio 1
	s_waitcnt lgkmcnt(3)
	v_mfma_f32_16x16x32_bf16 v[94:97], v[216:219], v[182:185], v[94:97]
	s_waitcnt lgkmcnt(1)
	v_mfma_f32_16x16x32_bf16 v[90:93], v[224:227], v[182:185], v[90:93]
	v_mfma_f32_16x16x32_bf16 v[86:89], v[216:219], v[190:193], v[86:89]
	v_mfma_f32_16x16x32_bf16 v[82:85], v[224:227], v[190:193], v[82:85]
	v_mfma_f32_16x16x32_bf16 v[78:81], v[216:219], v[200:203], v[78:81]
	v_mfma_f32_16x16x32_bf16 v[74:77], v[224:227], v[200:203], v[74:77]
	v_mfma_f32_16x16x32_bf16 v[70:73], v[216:219], v[208:211], v[70:73]
	v_mfma_f32_16x16x32_bf16 v[66:69], v[224:227], v[208:211], v[66:69]
	v_mfma_f32_16x16x32_bf16 v[94:97], v[220:223], v[186:189], v[94:97]
	s_waitcnt lgkmcnt(0)
	v_mfma_f32_16x16x32_bf16 v[90:93], v[228:231], v[186:189], v[90:93]
	v_mfma_f32_16x16x32_bf16 v[86:89], v[220:223], v[196:199], v[86:89]
	v_mfma_f32_16x16x32_bf16 v[82:85], v[228:231], v[196:199], v[82:85]
	v_mfma_f32_16x16x32_bf16 v[78:81], v[220:223], v[204:207], v[78:81]
	v_mfma_f32_16x16x32_bf16 v[74:77], v[228:231], v[204:207], v[74:77]
	v_mfma_f32_16x16x32_bf16 v[70:73], v[220:223], v[212:215], v[70:73]
	v_mfma_f32_16x16x32_bf16 v[66:69], v[228:231], v[212:215], v[66:69]
	s_setprio 0
	s_barrier
	ds_read_b128 v[182:185], v141 offset:16384
	ds_read_b128 v[186:189], v141 offset:17408
	ds_read_b128 v[190:193], v139 offset:16384
	ds_read_b128 v[196:199], v139 offset:17408
	ds_read_b128 v[200:203], v137 offset:16384
	ds_read_b128 v[204:207], v137 offset:17408
	ds_read_b128 v[208:211], v135 offset:16384
	ds_read_b128 v[212:215], v135 offset:17408
	s_add_u32 s26, s15, 0x10000100
	s_addc_u32 s27, s18, 0
	v_lshl_add_u64 v[232:233], s[26:27], 0, v[132:133]
	v_readfirstlane_b32 s25, v138
	s_mov_b32 m0, s25
	global_load_lds_dwordx4 v[232:233], off
	v_lshl_add_u64 v[232:233], s[26:27], 0, v[130:131]
	v_readfirstlane_b32 s25, v156
	s_mov_b32 m0, s25
	global_load_lds_dwordx4 v[232:233], off
	s_barrier
	s_waitcnt lgkmcnt(0)
	s_setprio 1
	s_waitcnt lgkmcnt(7)
	v_mfma_f32_16x16x32_bf16 v[62:65], v[166:169], v[182:185], v[62:65]
	v_mfma_f32_16x16x32_bf16 v[58:61], v[174:177], v[182:185], v[58:61]
	s_waitcnt lgkmcnt(5)
	v_mfma_f32_16x16x32_bf16 v[54:57], v[166:169], v[190:193], v[54:57]
	v_mfma_f32_16x16x32_bf16 v[50:53], v[174:177], v[190:193], v[50:53]
	s_waitcnt lgkmcnt(3)
	v_mfma_f32_16x16x32_bf16 v[46:49], v[166:169], v[200:203], v[46:49]
	v_mfma_f32_16x16x32_bf16 v[42:45], v[174:177], v[200:203], v[42:45]
	s_waitcnt lgkmcnt(1)
	v_mfma_f32_16x16x32_bf16 v[38:41], v[166:169], v[208:211], v[38:41]
	v_mfma_f32_16x16x32_bf16 v[34:37], v[174:177], v[208:211], v[34:37]
	v_mfma_f32_16x16x32_bf16 v[62:65], v[170:173], v[186:189], v[62:65]
	v_mfma_f32_16x16x32_bf16 v[58:61], v[178:181], v[186:189], v[58:61]
	v_mfma_f32_16x16x32_bf16 v[54:57], v[170:173], v[196:199], v[54:57]
	v_mfma_f32_16x16x32_bf16 v[50:53], v[178:181], v[196:199], v[50:53]
	v_mfma_f32_16x16x32_bf16 v[46:49], v[170:173], v[204:207], v[46:49]
	v_mfma_f32_16x16x32_bf16 v[42:45], v[178:181], v[204:207], v[42:45]
	s_waitcnt lgkmcnt(0)
	v_mfma_f32_16x16x32_bf16 v[38:41], v[170:173], v[212:215], v[38:41]
	v_mfma_f32_16x16x32_bf16 v[34:37], v[178:181], v[212:215], v[34:37]
	s_setprio 0
	s_barrier
;   #define LDA(dst,b,h) for(int m=0;m<4;++m)for(int k=0;k<2;++k) \
;     dst[m][k]=*reinterpret_cast<const bf16x8*>((char*)SA(b,h)+lds_byte(wr*64+m*16+fr,k*32+fq*8))
;   #define LDB(dst,b,h) for(int n=0;n<2;++n)for(int k=0;k<2;++k) \
;     dst[n][k]=*reinterpret_cast<const bf16x8*>((char*)SB(b,h)+lds_byte(wc*32+n*16+fr,k*32+fq*8))
;   #define MMA(ai,bj,At,Bt_) do{__builtin_amdgcn_s_setprio(1); \
;     for(int m=0;m<4;++m)for(int n=0;n<2;++n)for(int k=0;k<2;++k) \
;       acc[ai][bj][m][n]=__builtin_amdgcn_mfma_f32_16x16x32_bf16(Bt_[n][k],At[m][k],acc[ai][bj][m][n],0,0,0); \
;     __builtin_amdgcn_s_setprio(0);}while(0)
;   #define WAIT_V(n) asm volatile("s_waitcnt vmcnt(" #n ")":::"memory")
;   #define WAIT_L(n) asm volatile("s_waitcnt lgkmcnt(" #n ")":::"memory")
;   #define BAR __builtin_amdgcn_s_barrier()
;   #define SCHED __builtin_amdgcn_sched_barrier(0)
; template <bool TWO, class MID> ...
;     ...
;     LDB(B0,0,0); SCHED; LDA(At,0,0); STAGE_A(SA(1,1),1,t+1);
;     WAIT_L(8); BAR; WAIT_L(0); MMA(0,0,At,B0); BAR; SCHED;
;     LDB(B1,0,1); STAGE_B(SB(0,0),0,t+2);
;     BAR; WAIT_L(0); MMA(0,1,At,B1); BAR;
;     LDA(At,0,1); STAGE_A(SA(0,0),0,t+2);
;     BAR; WAIT_L(0); MMA(1,0,At,B0); BAR; SCHED;
;     STAGE_B(SB(0,1),1,t+2);
;     WAIT_V(6); BAR; MMA(1,1,At,B1); BAR;
;     LDB(B0,1,0); SCHED; LDA(At,1,0); STAGE_A(SA(0,1),1,t+2);
;     WAIT_L(8); BAR; WAIT_L(0); MMA(0,0,At,B0); BAR; SCHED;
;     LDB(B1,1,1); STAGE_B(SB(1,0),0,t+3);
;     BAR; WAIT_L(0); MMA(0,1,At,B1); BAR;
;     LDA(At,1,1); STAGE_A(SA(1,0),0,t+3);
;     BAR; WAIT_L(0); MMA(1,0,At,B0); BAR; SCHED;
;     STAGE_B(SB(1,1),1,t+3);
;     WAIT_V(6); BAR; MMA(1,1,At,B1); BAR;
	s_add_u32 s26, s19, 0x5e00100
	s_addc_u32 s27, s24, 0
	v_lshl_add_u64 v[166:167], s[26:27], 0, v[132:133]
	v_readfirstlane_b32 s25, v158
	s_mov_b32 m0, s25
	global_load_lds_dwordx4 v[166:167], off
	v_lshl_add_u64 v[166:167], s[26:27], 0, v[130:131]
	v_readfirstlane_b32 s25, v160
	s_mov_b32 m0, s25
	global_load_lds_dwordx4 v[166:167], off
	s_waitcnt vmcnt(6)
	s_barrier
	s_setprio 1
	v_mfma_f32_16x16x32_bf16 v[30:33], v[216:219], v[182:185], v[30:33]
	v_mfma_f32_16x16x32_bf16 v[26:29], v[224:227], v[182:185], v[26:29]
	v_mfma_f32_16x16x32_bf16 v[22:25], v[216:219], v[190:193], v[22:25]
	v_mfma_f32_16x16x32_bf16 v[18:21], v[224:227], v[190:193], v[18:21]
	v_mfma_f32_16x16x32_bf16 v[14:17], v[216:219], v[200:203], v[14:17]
	v_mfma_f32_16x16x32_bf16 v[10:13], v[224:227], v[200:203], v[10:13]
	v_mfma_f32_16x16x32_bf16 v[6:9], v[216:219], v[208:211], v[6:9]
	v_mfma_f32_16x16x32_bf16 v[2:5], v[224:227], v[208:211], v[2:5]
	v_mfma_f32_16x16x32_bf16 v[30:33], v[220:223], v[186:189], v[30:33]
	v_mfma_f32_16x16x32_bf16 v[26:29], v[228:231], v[186:189], v[26:29]
	v_mfma_f32_16x16x32_bf16 v[22:25], v[220:223], v[196:199], v[22:25]
	v_mfma_f32_16x16x32_bf16 v[18:21], v[228:231], v[196:199], v[18:21]
	v_mfma_f32_16x16x32_bf16 v[14:17], v[220:223], v[204:207], v[14:17]
	v_mfma_f32_16x16x32_bf16 v[10:13], v[228:231], v[204:207], v[10:13]
	v_mfma_f32_16x16x32_bf16 v[6:9], v[220:223], v[212:215], v[6:9]
	v_mfma_f32_16x16x32_bf16 v[2:5], v[228:231], v[212:215], v[2:5]
	s_setprio 0
	s_barrier
	ds_read_b128 v[166:169], v145
	ds_read_b128 v[170:173], v145 offset:1024
	ds_read_b128 v[174:177], v145 offset:2048
	ds_read_b128 v[178:181], v145 offset:3072
	ds_read_b128 v[182:185], v141 offset:32768
	ds_read_b128 v[186:189], v141 offset:33792
	ds_read_b128 v[190:193], v139 offset:32768
	ds_read_b128 v[196:199], v139 offset:33792
	ds_read_b128 v[200:203], v137 offset:32768
	ds_read_b128 v[204:207], v137 offset:33792
	ds_read_b128 v[208:211], v135 offset:32768
	ds_read_b128 v[212:215], v135 offset:33792
	s_add_u32 s26, s15, 0x10200100
	s_addc_u32 s27, s18, 0
	v_lshl_add_u64 v[216:217], s[26:27], 0, v[132:133]
	v_readfirstlane_b32 s25, v162
	s_mov_b32 m0, s25
	global_load_lds_dwordx4 v[216:217], off
	v_lshl_add_u64 v[216:217], s[26:27], 0, v[130:131]
	v_readfirstlane_b32 s25, v164
	s_mov_b32 m0, s25
	global_load_lds_dwordx4 v[216:217], off
	s_waitcnt lgkmcnt(8)
	s_barrier
	s_waitcnt lgkmcnt(0)
	s_setprio 1
	s_waitcnt lgkmcnt(7)
	v_mfma_f32_16x16x32_bf16 v[126:129], v[166:169], v[182:185], v[126:129]
	v_mfma_f32_16x16x32_bf16 v[122:125], v[174:177], v[182:185], v[122:125]
	s_waitcnt lgkmcnt(5)
	v_mfma_f32_16x16x32_bf16 v[118:121], v[166:169], v[190:193], v[118:121]
	v_mfma_f32_16x16x32_bf16 v[114:117], v[174:177], v[190:193], v[114:117]
	s_waitcnt lgkmcnt(3)
	v_mfma_f32_16x16x32_bf16 v[110:113], v[166:169], v[200:203], v[110:113]
	v_mfma_f32_16x16x32_bf16 v[106:109], v[174:177], v[200:203], v[106:109]
	s_waitcnt lgkmcnt(1)
	v_mfma_f32_16x16x32_bf16 v[102:105], v[166:169], v[208:211], v[102:105]
	v_mfma_f32_16x16x32_bf16 v[98:101], v[174:177], v[208:211], v[98:101]
	v_mfma_f32_16x16x32_bf16 v[126:129], v[170:173], v[186:189], v[126:129]
	v_mfma_f32_16x16x32_bf16 v[122:125], v[178:181], v[186:189], v[122:125]
	v_mfma_f32_16x16x32_bf16 v[118:121], v[170:173], v[196:199], v[118:121]
	v_mfma_f32_16x16x32_bf16 v[114:117], v[178:181], v[196:199], v[114:117]
	v_mfma_f32_16x16x32_bf16 v[110:113], v[170:173], v[204:207], v[110:113]
	v_mfma_f32_16x16x32_bf16 v[106:109], v[178:181], v[204:207], v[106:109]
	s_waitcnt lgkmcnt(0)
	v_mfma_f32_16x16x32_bf16 v[102:105], v[170:173], v[212:215], v[102:105]
	v_mfma_f32_16x16x32_bf16 v[98:101], v[178:181], v[212:215], v[98:101]
	s_setprio 0
	s_barrier
	ds_read_b128 v[216:219], v143
	ds_read_b128 v[220:223], v143 offset:1024
	ds_read_b128 v[224:227], v143 offset:2048
	ds_read_b128 v[228:231], v143 offset:3072
	s_add_u32 s26, s19, 0x5c00180
	s_addc_u32 s27, s24, 0
	v_lshl_add_u64 v[232:233], s[26:27], 0, v[132:133]
	v_readfirstlane_b32 s25, v134
	s_mov_b32 m0, s25
	global_load_lds_dwordx4 v[232:233], off
	v_lshl_add_u64 v[232:233], s[26:27], 0, v[130:131]
	v_readfirstlane_b32 s25, v136
	s_mov_b32 m0, s25
	global_load_lds_dwordx4 v[232:233], off
	s_barrier
	s_waitcnt lgkmcnt(0)
	s_setprio 1
	s_waitcnt lgkmcnt(3)
	v_mfma_f32_16x16x32_bf16 v[94:97], v[216:219], v[182:185], v[94:97]
	s_waitcnt lgkmcnt(1)
	v_mfma_f32_16x16x32_bf16 v[90:93], v[224:227], v[182:185], v[90:93]
	v_mfma_f32_16x16x32_bf16 v[86:89], v[216:219], v[190:193], v[86:89]
	v_mfma_f32_16x16x32_bf16 v[82:85], v[224:227], v[190:193], v[82:85]
	v_mfma_f32_16x16x32_bf16 v[78:81], v[216:219], v[200:203], v[78:81]
	v_mfma_f32_16x16x32_bf16 v[74:77], v[224:227], v[200:203], v[74:77]
	v_mfma_f32_16x16x32_bf16 v[70:73], v[216:219], v[208:211], v[70:73]
	v_mfma_f32_16x16x32_bf16 v[66:69], v[224:227], v[208:211], v[66:69]
	v_mfma_f32_16x16x32_bf16 v[94:97], v[220:223], v[186:189], v[94:97]
	s_waitcnt lgkmcnt(0)
	v_mfma_f32_16x16x32_bf16 v[90:93], v[228:231], v[186:189], v[90:93]
	v_mfma_f32_16x16x32_bf16 v[86:89], v[220:223], v[196:199], v[86:89]
	v_mfma_f32_16x16x32_bf16 v[82:85], v[228:231], v[196:199], v[82:85]
	v_mfma_f32_16x16x32_bf16 v[78:81], v[220:223], v[204:207], v[78:81]
	v_mfma_f32_16x16x32_bf16 v[74:77], v[228:231], v[204:207], v[74:77]
	v_mfma_f32_16x16x32_bf16 v[70:73], v[220:223], v[212:215], v[70:73]
	v_mfma_f32_16x16x32_bf16 v[66:69], v[228:231], v[212:215], v[66:69]
	s_setprio 0
	s_barrier
;   #define LDA(dst,b,h) for(int m=0;m<4;++m)for(int k=0;k<2;++k) \
;     dst[m][k]=*reinterpret_cast<const bf16x8*>((char*)SA(b,h)+lds_byte(wr*64+m*16+fr,k*32+fq*8))
;   #define LDB(dst,b,h) for(int n=0;n<2;++n)for(int k=0;k<2;++k) \
;     dst[n][k]=*reinterpret_cast<const bf16x8*>((char*)SB(b,h)+lds_byte(wc*32+n*16+fr,k*32+fq*8))
;   #define MMA(ai,bj,At,Bt_) do{__builtin_amdgcn_s_setprio(1); \
;     for(int m=0;m<4;++m)for(int n=0;n<2;++n)for(int k=0;k<2;++k) \
;       acc[ai][bj][m][n]=__builtin_amdgcn_mfma_f32_16x16x32_bf16(Bt_[n][k],At[m][k],acc[ai][bj][m][n],0,0,0); \
;     __builtin_amdgcn_s_setprio(0);}while(0)
;   #define WAIT_V(n) asm volatile("s_waitcnt vmcnt(" #n ")":::"memory")
;   #define WAIT_L(n) asm volatile("s_waitcnt lgkmcnt(" #n ")":::"memory")
;   #define BAR __builtin_amdgcn_s_barrier()
;   #define SCHED __builtin_amdgcn_sched_barrier(0)
; template <bool TWO, class MID> ...
;     ...
;     LDB(B0,0,0); SCHED; LDA(At,0,0); STAGE_A(SA(1,1),1,t+1);
;     WAIT_L(8); BAR; WAIT_L(0); MMA(0,0,At,B0); BAR; SCHED;
;     LDB(B1,0,1); STAGE_B(SB(0,0),0,t+2);
;     BAR; WAIT_L(0); MMA(0,1,At,B1); BAR;
;     LDA(At,0,1); STAGE_A(SA(0,0),0,t+2);
;     BAR; WAIT_L(0); MMA(1,0,At,B0); BAR; SCHED;
;     STAGE_B(SB(0,1),1,t+2);
;     WAIT_V(6); BAR; MMA(1,1,At,B1); BAR;
;     LDB(B0,1,0); SCHED; LDA(At,1,0); STAGE_A(SA(0,1),1,t+2);
;     WAIT_L(8); BAR; WAIT_L(0); MMA(0,0,At,B0); BAR; SCHED;
;     LDB(B1,1,1); STAGE_B(SB(1,0),0,t+3);
;     BAR; WAIT_L(0); MMA(0,1,At,B1); BAR;
;     LDA(At,1,1); STAGE_A(SA(1,0),0,t+3);
;     BAR; WAIT_L(0); MMA(1,0,At,B0); BAR; SCHED;
;     STAGE_B(SB(1,1),1,t+3);
;     WAIT_V(6); BAR; MMA(1,1,At,B1); BAR;
;   }
;   { LDB(B0,0,0); LDA(At,0,0); STAGE_A(SA(1,1),1,nt-1);
;     BAR; WAIT_L(0); MMA(0,0,At,B0); BAR;
	ds_read_b128 v[182:185], v141 offset:49152
	ds_read_b128 v[186:189], v141 offset:50176
	ds_read_b128 v[190:193], v139 offset:49152
	ds_read_b128 v[196:199], v139 offset:50176
	ds_read_b128 v[200:203], v137 offset:49152
	ds_read_b128 v[204:207], v137 offset:50176
	ds_read_b128 v[208:211], v135 offset:49152
	ds_read_b128 v[212:215], v135 offset:50176
	s_add_u32 s26, s15, 0x10000180
	s_addc_u32 s27, s18, 0
	v_lshl_add_u64 v[232:233], s[26:27], 0, v[132:133]
	v_readfirstlane_b32 s15, v140
	s_mov_b32 m0, s15
	global_load_lds_dwordx4 v[232:233], off
	v_lshl_add_u64 v[232:233], s[26:27], 0, v[130:131]
	v_readfirstlane_b32 s15, v142
	s_mov_b32 m0, s15
	global_load_lds_dwordx4 v[232:233], off
	s_barrier
	s_waitcnt lgkmcnt(0)
	s_setprio 1
	s_waitcnt lgkmcnt(7)
	v_mfma_f32_16x16x32_bf16 v[62:65], v[166:169], v[182:185], v[62:65]
	v_mfma_f32_16x16x32_bf16 v[58:61], v[174:177], v[182:185], v[58:61]
	s_waitcnt lgkmcnt(5)
	v_mfma_f32_16x16x32_bf16 v[54:57], v[166:169], v[190:193], v[54:57]
	v_mfma_f32_16x16x32_bf16 v[50:53], v[174:177], v[190:193], v[50:53]
	s_waitcnt lgkmcnt(3)
	v_mfma_f32_16x16x32_bf16 v[46:49], v[166:169], v[200:203], v[46:49]
	v_mfma_f32_16x16x32_bf16 v[42:45], v[174:177], v[200:203], v[42:45]
	s_waitcnt lgkmcnt(1)
	v_mfma_f32_16x16x32_bf16 v[38:41], v[166:169], v[208:211], v[38:41]
	v_mfma_f32_16x16x32_bf16 v[34:37], v[174:177], v[208:211], v[34:37]
	v_mfma_f32_16x16x32_bf16 v[62:65], v[170:173], v[186:189], v[62:65]
	v_mfma_f32_16x16x32_bf16 v[58:61], v[178:181], v[186:189], v[58:61]
	v_mfma_f32_16x16x32_bf16 v[54:57], v[170:173], v[196:199], v[54:57]
	v_mfma_f32_16x16x32_bf16 v[50:53], v[178:181], v[196:199], v[50:53]
	v_mfma_f32_16x16x32_bf16 v[46:49], v[170:173], v[204:207], v[46:49]
	v_mfma_f32_16x16x32_bf16 v[42:45], v[178:181], v[204:207], v[42:45]
	s_waitcnt lgkmcnt(0)
	v_mfma_f32_16x16x32_bf16 v[38:41], v[170:173], v[212:215], v[38:41]
	v_mfma_f32_16x16x32_bf16 v[34:37], v[178:181], v[212:215], v[34:37]
	s_setprio 0
	s_barrier
	s_add_u32 s18, s19, 0x5e00180
	s_addc_u32 s19, s24, 0
	v_lshl_add_u64 v[166:167], s[18:19], 0, v[132:133]
	v_readfirstlane_b32 s15, v144
	s_mov_b32 m0, s15
	global_load_lds_dwordx4 v[166:167], off
	v_lshl_add_u64 v[166:167], s[18:19], 0, v[130:131]
	v_readfirstlane_b32 s15, v146
	s_mov_b32 m0, s15
	global_load_lds_dwordx4 v[166:167], off
	s_waitcnt vmcnt(6)
	s_barrier
	s_setprio 1
	v_mfma_f32_16x16x32_bf16 v[30:33], v[216:219], v[182:185], v[30:33]
	v_mfma_f32_16x16x32_bf16 v[26:29], v[224:227], v[182:185], v[26:29]
	v_mfma_f32_16x16x32_bf16 v[22:25], v[216:219], v[190:193], v[22:25]
	v_mfma_f32_16x16x32_bf16 v[18:21], v[224:227], v[190:193], v[18:21]
	v_mfma_f32_16x16x32_bf16 v[14:17], v[216:219], v[200:203], v[14:17]
	v_mfma_f32_16x16x32_bf16 v[10:13], v[224:227], v[200:203], v[10:13]
	v_mfma_f32_16x16x32_bf16 v[6:9], v[216:219], v[208:211], v[6:9]
	v_mfma_f32_16x16x32_bf16 v[2:5], v[224:227], v[208:211], v[2:5]
	v_mfma_f32_16x16x32_bf16 v[30:33], v[220:223], v[186:189], v[30:33]
	v_mfma_f32_16x16x32_bf16 v[26:29], v[228:231], v[186:189], v[26:29]
	v_mfma_f32_16x16x32_bf16 v[22:25], v[220:223], v[196:199], v[22:25]
	v_mfma_f32_16x16x32_bf16 v[18:21], v[228:231], v[196:199], v[18:21]
	v_mfma_f32_16x16x32_bf16 v[14:17], v[220:223], v[204:207], v[14:17]
	v_mfma_f32_16x16x32_bf16 v[10:13], v[228:231], v[204:207], v[10:13]
	v_mfma_f32_16x16x32_bf16 v[6:9], v[220:223], v[212:215], v[6:9]
	v_mfma_f32_16x16x32_bf16 v[2:5], v[228:231], v[212:215], v[2:5]
	s_setprio 0
	s_add_i32 s14, s14, 2
	s_add_u32 s0, s0, 0x100
	s_addc_u32 s1, s1, 0
	s_cmpk_lt_u32 s14, 0x7c
	s_barrier
	s_cbranch_scc1 .LBB0_620
	ds_read_b128 v[152:155], v149
	ds_read_b128 v[156:159], v149 offset:1024
	ds_read_b128 v[160:163], v149 offset:2048
	ds_read_b128 v[164:167], v149 offset:3072
	ds_read_b128 v[168:171], v141
	ds_read_b128 v[172:175], v141 offset:1024
	ds_read_b128 v[176:179], v139
	ds_read_b128 v[180:183], v139 offset:1024
	ds_read_b128 v[184:187], v137
	ds_read_b128 v[188:191], v137 offset:1024
	ds_read_b128 v[196:199], v135
	ds_read_b128 v[200:203], v135 offset:1024
	s_add_u32 s0, s12, 0x203f80
	s_addc_u32 s1, s13, 0
	v_lshl_add_u64 v[132:133], s[0:1], 0, v[132:133]
	v_readfirstlane_b32 s12, v148
	s_mov_b32 m0, s12
	global_load_lds_dwordx4 v[132:133], off
	v_lshl_add_u64 v[130:131], s[0:1], 0, v[130:131]
	v_readfirstlane_b32 s0, v150
	s_mov_b32 m0, s0
	global_load_lds_dwordx4 v[130:131], off
	s_barrier
	s_waitcnt lgkmcnt(0)
	s_setprio 1
	s_waitcnt lgkmcnt(7)
	v_mfma_f32_16x16x32_bf16 v[126:129], v[152:155], v[168:171], v[126:129]
	v_mfma_f32_16x16x32_bf16 v[122:125], v[160:163], v[168:171], v[122:125]
	s_waitcnt lgkmcnt(5)
	v_mfma_f32_16x16x32_bf16 v[118:121], v[152:155], v[176:179], v[118:121]
	v_mfma_f32_16x16x32_bf16 v[114:117], v[160:163], v[176:179], v[114:117]
	s_waitcnt lgkmcnt(1)
	v_mfma_f32_16x16x32_bf16 v[102:105], v[152:155], v[196:199], v[102:105]
	v_mfma_f32_16x16x32_bf16 v[98:101], v[160:163], v[196:199], v[98:101]
	v_mfma_f32_16x16x32_bf16 v[126:129], v[156:159], v[172:175], v[126:129]
	v_mfma_f32_16x16x32_bf16 v[122:125], v[164:167], v[172:175], v[122:125]
	v_mfma_f32_16x16x32_bf16 v[118:121], v[156:159], v[180:183], v[118:121]
	v_mfma_f32_16x16x32_bf16 v[114:117], v[164:167], v[180:183], v[114:117]
	v_mfma_f32_16x16x32_bf16 v[110:113], v[152:155], v[184:187], v[110:113]
	v_mfma_f32_16x16x32_bf16 v[106:109], v[160:163], v[184:187], v[106:109]
	s_waitcnt lgkmcnt(0)
	v_mfma_f32_16x16x32_bf16 v[102:105], v[156:159], v[200:203], v[102:105]
	v_mfma_f32_16x16x32_bf16 v[98:101], v[164:167], v[200:203], v[98:101]
	v_mfma_f32_16x16x32_bf16 v[130:133], v[156:159], v[188:191], v[110:113]
	v_mfma_f32_16x16x32_bf16 v[148:151], v[164:167], v[188:191], v[106:109]
	s_setprio 0
	s_barrier
;   #define LDA(dst,b,h) for(int m=0;m<4;++m)for(int k=0;k<2;++k) \
;     dst[m][k]=*reinterpret_cast<const bf16x8*>((char*)SA(b,h)+lds_byte(wr*64+m*16+fr,k*32+fq*8))
;   #define LDB(dst,b,h) for(int n=0;n<2;++n)for(int k=0;k<2;++k) \
;     dst[n][k]=*reinterpret_cast<const bf16x8*>((char*)SB(b,h)+lds_byte(wc*32+n*16+fr,k*32+fq*8))
;   #define MMA(ai,bj,At,Bt_) do{__builtin_amdgcn_s_setprio(1); \
;     for(int m=0;m<4;++m)for(int n=0;n<2;++n)for(int k=0;k<2;++k) \
;       acc[ai][bj][m][n]=__builtin_amdgcn_mfma_f32_16x16x32_bf16(Bt_[n][k],At[m][k],acc[ai][bj][m][n],0,0,0); \
;     __builtin_amdgcn_s_setprio(0);}while(0)
;   #define WAIT_V(n) asm volatile("s_waitcnt vmcnt(" #n ")":::"memory")
;   #define WAIT_L(n) asm volatile("s_waitcnt lgkmcnt(" #n ")":::"memory")
;   #define BAR __builtin_amdgcn_s_barrier()
; template <bool TWO, class MID> ...
;     ...
;     BAR; WAIT_L(0); MMA(0,0,At,B0); BAR;
;     LDB(B1,0,1); BAR; WAIT_L(0); MMA(0,1,At,B1); BAR;
;     LDA(At,0,1); WAIT_V(4); BAR; WAIT_L(0); MMA(1,0,At,B0); MMA(1,1,At,B1); BAR; }
;   { LDB(B0,1,0); LDA(At,1,0); WAIT_V(2); BAR; WAIT_L(0); MMA(0,0,At,B0); BAR;
	s_nop 0
	ds_read_b128 v[106:109], v147
	ds_read_b128 v[110:113], v147 offset:1024
	ds_read_b128 v[204:207], v147 offset:2048
	ds_read_b128 v[208:211], v147 offset:3072
	s_barrier
	s_waitcnt lgkmcnt(0)
	s_setprio 1
	s_waitcnt lgkmcnt(3)
	v_mfma_f32_16x16x32_bf16 v[86:89], v[106:109], v[176:179], v[86:89]
	s_waitcnt lgkmcnt(1)
	v_mfma_f32_16x16x32_bf16 v[82:85], v[204:207], v[176:179], v[82:85]
	v_mfma_f32_16x16x32_bf16 v[70:73], v[106:109], v[196:199], v[70:73]
	v_mfma_f32_16x16x32_bf16 v[66:69], v[204:207], v[196:199], v[66:69]
	v_mfma_f32_16x16x32_bf16 v[94:97], v[106:109], v[168:171], v[94:97]
	v_mfma_f32_16x16x32_bf16 v[90:93], v[204:207], v[168:171], v[90:93]
	v_mfma_f32_16x16x32_bf16 v[86:89], v[110:113], v[180:183], v[86:89]
	s_waitcnt lgkmcnt(0)
	v_mfma_f32_16x16x32_bf16 v[82:85], v[208:211], v[180:183], v[82:85]
	v_mfma_f32_16x16x32_bf16 v[78:81], v[106:109], v[184:187], v[78:81]
	v_mfma_f32_16x16x32_bf16 v[74:77], v[204:207], v[184:187], v[74:77]
	v_mfma_f32_16x16x32_bf16 v[70:73], v[110:113], v[200:203], v[70:73]
	v_mfma_f32_16x16x32_bf16 v[66:69], v[208:211], v[200:203], v[66:69]
	v_mfma_f32_16x16x32_bf16 v[212:215], v[110:113], v[172:175], v[94:97]
	v_mfma_f32_16x16x32_bf16 v[168:171], v[208:211], v[172:175], v[90:93]
	v_mfma_f32_16x16x32_bf16 v[172:175], v[110:113], v[188:191], v[78:81]
	v_mfma_f32_16x16x32_bf16 v[176:179], v[208:211], v[188:191], v[74:77]
	s_setprio 0
	s_barrier
	s_nop 0
	ds_read_b128 v[74:77], v141 offset:16384
	ds_read_b128 v[78:81], v141 offset:17408
	ds_read_b128 v[90:93], v139 offset:16384
	ds_read_b128 v[94:97], v139 offset:17408
	ds_read_b128 v[180:183], v137 offset:16384
	ds_read_b128 v[184:187], v137 offset:17408
	ds_read_b128 v[188:191], v135 offset:16384
	ds_read_b128 v[196:199], v135 offset:17408
	s_waitcnt vmcnt(4)
	s_barrier
	s_waitcnt lgkmcnt(0)
	s_setprio 1
	s_waitcnt lgkmcnt(7)
	v_mfma_f32_16x16x32_bf16 v[62:65], v[152:155], v[74:77], v[62:65]
	v_mfma_f32_16x16x32_bf16 v[58:61], v[160:163], v[74:77], v[58:61]
	s_waitcnt lgkmcnt(5)
	v_mfma_f32_16x16x32_bf16 v[54:57], v[152:155], v[90:93], v[54:57]
	v_mfma_f32_16x16x32_bf16 v[50:53], v[160:163], v[90:93], v[50:53]
	s_waitcnt lgkmcnt(1)
	v_mfma_f32_16x16x32_bf16 v[38:41], v[152:155], v[188:191], v[38:41]
	v_mfma_f32_16x16x32_bf16 v[34:37], v[160:163], v[188:191], v[34:37]
	v_mfma_f32_16x16x32_bf16 v[62:65], v[156:159], v[78:81], v[62:65]
	v_mfma_f32_16x16x32_bf16 v[58:61], v[164:167], v[78:81], v[58:61]
	v_mfma_f32_16x16x32_bf16 v[54:57], v[156:159], v[94:97], v[54:57]
	v_mfma_f32_16x16x32_bf16 v[50:53], v[164:167], v[94:97], v[50:53]
	v_mfma_f32_16x16x32_bf16 v[46:49], v[152:155], v[180:183], v[46:49]
	v_mfma_f32_16x16x32_bf16 v[42:45], v[160:163], v[180:183], v[42:45]
	s_waitcnt lgkmcnt(0)
	v_mfma_f32_16x16x32_bf16 v[38:41], v[156:159], v[196:199], v[38:41]
	v_mfma_f32_16x16x32_bf16 v[34:37], v[164:167], v[196:199], v[34:37]
	v_mfma_f32_16x16x32_bf16 v[200:203], v[156:159], v[184:187], v[46:49]
	v_mfma_f32_16x16x32_bf16 v[216:219], v[164:167], v[184:187], v[42:45]
	s_setprio 0
	s_setprio 1
	v_mfma_f32_16x16x32_bf16 v[22:25], v[106:109], v[90:93], v[22:25]
	v_mfma_f32_16x16x32_bf16 v[18:21], v[204:207], v[90:93], v[18:21]
	v_mfma_f32_16x16x32_bf16 v[6:9], v[106:109], v[188:191], v[6:9]
	v_mfma_f32_16x16x32_bf16 v[2:5], v[204:207], v[188:191], v[2:5]
	v_mfma_f32_16x16x32_bf16 v[30:33], v[106:109], v[74:77], v[30:33]
	v_mfma_f32_16x16x32_bf16 v[26:29], v[204:207], v[74:77], v[26:29]
	v_mfma_f32_16x16x32_bf16 v[22:25], v[110:113], v[94:97], v[22:25]
	v_mfma_f32_16x16x32_bf16 v[18:21], v[208:211], v[94:97], v[18:21]
	v_mfma_f32_16x16x32_bf16 v[14:17], v[106:109], v[180:183], v[14:17]
	v_mfma_f32_16x16x32_bf16 v[10:13], v[204:207], v[180:183], v[10:13]
	v_mfma_f32_16x16x32_bf16 v[6:9], v[110:113], v[196:199], v[6:9]
	v_mfma_f32_16x16x32_bf16 v[2:5], v[208:211], v[196:199], v[2:5]
	v_mfma_f32_16x16x32_bf16 v[152:155], v[110:113], v[78:81], v[30:33]
	v_mfma_f32_16x16x32_bf16 v[156:159], v[208:211], v[78:81], v[26:29]
	v_mfma_f32_16x16x32_bf16 v[160:163], v[110:113], v[184:187], v[14:17]
	v_mfma_f32_16x16x32_bf16 v[164:167], v[208:211], v[184:187], v[10:13]
	s_setprio 0
	s_barrier
	s_nop 0
	ds_read_b128 v[10:13], v145
	ds_read_b128 v[14:17], v145 offset:1024
	ds_read_b128 v[180:183], v145 offset:2048
	ds_read_b128 v[144:147], v145 offset:3072
	ds_read_b128 v[26:29], v141 offset:32768
	ds_read_b128 v[30:33], v141 offset:33792
	ds_read_b128 v[42:45], v139 offset:32768
	ds_read_b128 v[46:49], v139 offset:33792
	ds_read_b128 v[184:187], v137 offset:32768
	ds_read_b128 v[188:191], v137 offset:33792
	ds_read_b128 v[196:199], v135 offset:32768
	ds_read_b128 v[204:207], v135 offset:33792
	s_waitcnt vmcnt(2)
	s_barrier
;   #define LDA(dst,b,h) for(int m=0;m<4;++m)for(int k=0;k<2;++k) \
;     dst[m][k]=*reinterpret_cast<const bf16x8*>((char*)SA(b,h)+lds_byte(wr*64+m*16+fr,k*32+fq*8))
;   #define LDB(dst,b,h) for(int n=0;n<2;++n)for(int k=0;k<2;++k) \
;     dst[n][k]=*reinterpret_cast<const bf16x8*>((char*)SB(b,h)+lds_byte(wc*32+n*16+fr,k*32+fq*8))
;   #define MMA(ai,bj,At,Bt_) do{__builtin_amdgcn_s_setprio(1); \
;     for(int m=0;m<4;++m)for(int n=0;n<2;++n)for(int k=0;k<2;++k) \
;       acc[ai][bj][m][n]=__builtin_amdgcn_mfma_f32_16x16x32_bf16(Bt_[n][k],At[m][k],acc[ai][bj][m][n],0,0,0); \
;     __builtin_amdgcn_s_setprio(0);}while(0)
;   #define WAIT_V(n) asm volatile("s_waitcnt vmcnt(" #n ")":::"memory")
;   #define WAIT_L(n) asm volatile("s_waitcnt lgkmcnt(" #n ")":::"memory")
;   #define BAR __builtin_amdgcn_s_barrier()
; template <bool TWO, class MID> ...
;     ...
;     LDB(B1,0,1); BAR; WAIT_L(0); MMA(0,1,At,B1); BAR;
;     LDA(At,0,1); WAIT_V(4); BAR; WAIT_L(0); MMA(1,0,At,B0); MMA(1,1,At,B1); BAR; }
;   { LDB(B0,1,0); LDA(At,1,0); WAIT_V(2); BAR; WAIT_L(0); MMA(0,0,At,B0); BAR;
;     LDB(B1,1,1); WAIT_V(0); BAR; WAIT_L(0); MMA(0,1,At,B1); BAR;
;     LDA(At,1,1); BAR; WAIT_L(0); MMA(1,0,At,B0); MMA(1,1,At,B1); BAR; }
;   if(wr==0)BAR;
	s_waitcnt lgkmcnt(0)
	s_setprio 1
	s_waitcnt lgkmcnt(7)
	v_mfma_f32_16x16x32_bf16 v[74:77], v[10:13], v[26:29], v[126:129]
	s_waitcnt lgkmcnt(6)
	v_mfma_f32_16x16x32_bf16 v[126:129], v[14:17], v[30:33], v[74:77]
	v_mfma_f32_16x16x32_bf16 v[74:77], v[180:183], v[26:29], v[122:125]
	v_mfma_f32_16x16x32_bf16 v[122:125], v[144:147], v[30:33], v[74:77]
	s_waitcnt lgkmcnt(5)
	v_mfma_f32_16x16x32_bf16 v[74:77], v[10:13], v[42:45], v[118:121]
	s_waitcnt lgkmcnt(4)
	v_mfma_f32_16x16x32_bf16 v[110:113], v[14:17], v[46:49], v[74:77]
	v_mfma_f32_16x16x32_bf16 v[74:77], v[180:183], v[42:45], v[114:117]
	v_mfma_f32_16x16x32_bf16 v[106:109], v[144:147], v[46:49], v[74:77]
	s_waitcnt lgkmcnt(3)
	v_mfma_f32_16x16x32_bf16 v[74:77], v[10:13], v[184:187], v[130:133]
	s_waitcnt lgkmcnt(2)
	v_mfma_f32_16x16x32_bf16 v[94:97], v[14:17], v[188:191], v[74:77]
	v_mfma_f32_16x16x32_bf16 v[74:77], v[180:183], v[184:187], v[148:151]
	v_mfma_f32_16x16x32_bf16 v[90:93], v[144:147], v[188:191], v[74:77]
	s_waitcnt lgkmcnt(1)
	v_mfma_f32_16x16x32_bf16 v[74:77], v[10:13], v[196:199], v[102:105]
	s_waitcnt lgkmcnt(0)
	v_mfma_f32_16x16x32_bf16 v[78:81], v[14:17], v[204:207], v[74:77]
	v_mfma_f32_16x16x32_bf16 v[74:77], v[180:183], v[196:199], v[98:101]
	v_mfma_f32_16x16x32_bf16 v[74:77], v[144:147], v[204:207], v[74:77]
	s_setprio 0
	s_barrier
	ds_read_b128 v[130:133], v143
	ds_read_b128 v[148:151], v143 offset:1024
	ds_read_b128 v[208:211], v143 offset:2048
	ds_read_b128 v[220:223], v143 offset:3072
	s_waitcnt vmcnt(0)
	s_barrier
	s_waitcnt lgkmcnt(0)
	s_setprio 1
	s_waitcnt lgkmcnt(3)
	v_mfma_f32_16x16x32_bf16 v[98:101], v[130:133], v[26:29], v[212:215]
	s_waitcnt lgkmcnt(1)
	v_mfma_f32_16x16x32_bf16 v[26:29], v[208:211], v[26:29], v[168:171]
	s_waitcnt lgkmcnt(0)
	v_mfma_f32_16x16x32_bf16 v[114:117], v[220:223], v[30:33], v[26:29]
	v_mfma_f32_16x16x32_bf16 v[26:29], v[130:133], v[42:45], v[86:89]
	v_mfma_f32_16x16x32_bf16 v[102:105], v[148:151], v[46:49], v[26:29]
	v_mfma_f32_16x16x32_bf16 v[26:29], v[208:211], v[42:45], v[82:85]
	v_mfma_f32_16x16x32_bf16 v[118:121], v[148:151], v[30:33], v[98:101]
	v_mfma_f32_16x16x32_bf16 v[98:101], v[220:223], v[46:49], v[26:29]
	v_mfma_f32_16x16x32_bf16 v[26:29], v[130:133], v[184:187], v[172:175]
	v_mfma_f32_16x16x32_bf16 v[86:89], v[148:151], v[188:191], v[26:29]
	v_mfma_f32_16x16x32_bf16 v[26:29], v[208:211], v[184:187], v[176:179]
	v_mfma_f32_16x16x32_bf16 v[82:85], v[220:223], v[188:191], v[26:29]
	v_mfma_f32_16x16x32_bf16 v[26:29], v[130:133], v[196:199], v[70:73]
	v_mfma_f32_16x16x32_bf16 v[70:73], v[148:151], v[204:207], v[26:29]
	v_mfma_f32_16x16x32_bf16 v[26:29], v[208:211], v[196:199], v[66:69]
	v_mfma_f32_16x16x32_bf16 v[66:69], v[220:223], v[204:207], v[26:29]
	s_setprio 0
	s_barrier
	ds_read_b128 v[168:171], v141 offset:49152
	ds_read_b128 v[140:143], v141 offset:50176
	ds_read_b128 v[172:175], v139 offset:49152
	ds_read_b128 v[176:179], v139 offset:50176
	ds_read_b128 v[184:187], v137 offset:49152
	ds_read_b128 v[136:139], v137 offset:50176
	ds_read_b128 v[188:191], v135 offset:49152
	ds_read_b128 v[196:199], v135 offset:50176
	s_barrier
	s_waitcnt lgkmcnt(0)
	s_setprio 1
	s_waitcnt lgkmcnt(7)
	v_mfma_f32_16x16x32_bf16 v[26:29], v[10:13], v[168:171], v[62:65]
	s_waitcnt lgkmcnt(6)
	v_mfma_f32_16x16x32_bf16 v[62:65], v[14:17], v[140:143], v[26:29]
	v_mfma_f32_16x16x32_bf16 v[26:29], v[180:183], v[168:171], v[58:61]
	v_mfma_f32_16x16x32_bf16 v[58:61], v[144:147], v[140:143], v[26:29]
	s_waitcnt lgkmcnt(5)
	v_mfma_f32_16x16x32_bf16 v[26:29], v[10:13], v[172:175], v[54:57]
	s_waitcnt lgkmcnt(4)
	v_mfma_f32_16x16x32_bf16 v[46:49], v[14:17], v[176:179], v[26:29]
	v_mfma_f32_16x16x32_bf16 v[26:29], v[180:183], v[172:175], v[50:53]
	v_mfma_f32_16x16x32_bf16 v[42:45], v[144:147], v[176:179], v[26:29]
	s_waitcnt lgkmcnt(3)
	v_mfma_f32_16x16x32_bf16 v[26:29], v[10:13], v[184:187], v[200:203]
	s_waitcnt lgkmcnt(1)
	v_mfma_f32_16x16x32_bf16 v[10:13], v[10:13], v[188:191], v[38:41]
	v_mfma_f32_16x16x32_bf16 v[30:33], v[14:17], v[136:139], v[26:29]
	v_mfma_f32_16x16x32_bf16 v[26:29], v[180:183], v[184:187], v[216:219]
	s_waitcnt lgkmcnt(0)
	v_mfma_f32_16x16x32_bf16 v[14:17], v[14:17], v[196:199], v[10:13]
	v_mfma_f32_16x16x32_bf16 v[10:13], v[180:183], v[188:191], v[34:37]
	v_mfma_f32_16x16x32_bf16 v[26:29], v[144:147], v[136:139], v[26:29]
	v_mfma_f32_16x16x32_bf16 v[10:13], v[144:147], v[196:199], v[10:13]
	s_setprio 0
	s_setprio 1
	v_mfma_f32_16x16x32_bf16 v[34:37], v[130:133], v[168:171], v[152:155]
	v_mfma_f32_16x16x32_bf16 v[54:57], v[148:151], v[140:143], v[34:37]
	v_mfma_f32_16x16x32_bf16 v[34:37], v[208:211], v[168:171], v[156:159]
	v_mfma_f32_16x16x32_bf16 v[18:21], v[208:211], v[172:175], v[18:21]
	v_mfma_f32_16x16x32_bf16 v[50:53], v[220:223], v[140:143], v[34:37]
	v_mfma_f32_16x16x32_bf16 v[22:25], v[130:133], v[172:175], v[22:25]
	v_mfma_f32_16x16x32_bf16 v[34:37], v[220:223], v[176:179], v[18:21]
	v_mfma_f32_16x16x32_bf16 v[18:21], v[130:133], v[184:187], v[160:163]
	v_mfma_f32_16x16x32_bf16 v[38:41], v[148:151], v[176:179], v[22:25]
	v_mfma_f32_16x16x32_bf16 v[22:25], v[148:151], v[136:139], v[18:21]
	v_mfma_f32_16x16x32_bf16 v[18:21], v[208:211], v[184:187], v[164:167]
	v_mfma_f32_16x16x32_bf16 v[6:9], v[130:133], v[188:191], v[6:9]
	v_mfma_f32_16x16x32_bf16 v[2:5], v[208:211], v[188:191], v[2:5]
	v_mfma_f32_16x16x32_bf16 v[18:21], v[220:223], v[136:139], v[18:21]
	v_mfma_f32_16x16x32_bf16 v[6:9], v[148:151], v[196:199], v[6:9]
	v_mfma_f32_16x16x32_bf16 v[2:5], v[220:223], v[196:199], v[2:5]
	s_setprio 0
	v_cmp_gt_u32_e32 vcc, s30, v1
	s_barrier
	s_and_saveexec_b64 s[0:1], vcc
	s_cbranch_execz .LBB0_623
	s_barrier

; #define LDS_BARRIER() do { asm volatile("s_waitcnt lgkmcnt(0)" ::: "memory"); __builtin_amdgcn_s_barrier(); asm volatile("" ::: "memory"); } while (0)
; __device__ __forceinline__ void st16_asm(void* ptr, u32x4 v) { asm volatile("global_store_dwordx4 %0, %1, off\n\ts_nop 7" :: "v"(ptr), "v"(v) : "memory"); }
; __device__ __forceinline__ void stg_flush(bf16* shm, int tid, bf16* dst, size_t pitch, bool first, bool tail_barrier = true) {
;   LDS_BARRIER();
;   if (first) asm volatile("s_waitcnt vmcnt(0)" ::: "memory");
;   _Pragma("unroll") for (int i = 0; i < 8; ++i) {
;     const int idx = tid + 512 * i, bjr = idx >> 11, row = (idx >> 4) & 127, c16 = idx & 15;
;     const u32x4 d = *(const u32x4*)stg_ptr(shm, bjr, row, 2 * c16);
;     st16_asm(dst + (size_t)row * pitch + bjr * HALF + c16 * 8, d); }
;   if (tail_barrier) LDS_BARRIER();
.LBB0_708:
	s_or_b64 exec, exec, s[18:19]
	s_lshl_b64 s[18:19], s[8:9], 12
	s_add_u32 s18, s14, s18
	s_addc_u32 s19, s15, s19
	v_lshlrev_b32_e32 v86, 1, v119
	v_mov_b32_e32 v87, v0
	v_lshl_add_u64 v[86:87], s[18:19], 0, v[86:87]
	v_lshl_add_u64 v[86:87], v[66:67], 1, v[86:87]
	v_lshlrev_b32_e32 v88, 1, v117
	v_mov_b32_e32 v89, v0
	s_waitcnt lgkmcnt(0)
	s_barrier
	v_add_u32_e32 v82, v118, v120
	v_lshl_add_u64 v[86:87], v[86:87], 0, v[88:89]
	ds_read_b128 v[82:85], v82
	s_waitcnt lgkmcnt(0)
	global_store_dwordx4 v[86:87], v[82:85], off sc1
	s_nop 7
	v_lshlrev_b32_e32 v86, 1, v123
	v_mov_b32_e32 v87, v0
	v_lshl_add_u64 v[86:87], s[18:19], 0, v[86:87]
	v_lshl_add_u64 v[86:87], v[68:69], 1, v[86:87]
	v_add_u32_e32 v82, v121, v124
	v_lshl_add_u64 v[86:87], v[86:87], 0, v[88:89]
	ds_read_b128 v[82:85], v82
	s_waitcnt lgkmcnt(0)
	global_store_dwordx4 v[86:87], v[82:85], off sc1
	s_nop 7
	v_lshlrev_b32_e32 v86, 1, v127
	v_mov_b32_e32 v87, v0
	v_lshl_add_u64 v[86:87], s[18:19], 0, v[86:87]
	v_lshl_add_u64 v[86:87], v[70:71], 1, v[86:87]
	v_add_u32_e32 v82, v125, v128
	v_lshl_add_u64 v[86:87], v[86:87], 0, v[88:89]
	ds_read_b128 v[82:85], v82
	s_waitcnt lgkmcnt(0)
	global_store_dwordx4 v[86:87], v[82:85], off sc1
	s_nop 7
	v_lshlrev_b32_e32 v86, 1, v142
	v_mov_b32_e32 v87, v0
	v_lshl_add_u64 v[86:87], s[18:19], 0, v[86:87]
	v_lshl_add_u64 v[86:87], v[72:73], 1, v[86:87]
	v_add_u32_e32 v82, v129, v143
	v_lshl_add_u64 v[86:87], v[86:87], 0, v[88:89]
	ds_read_b128 v[82:85], v82
	s_waitcnt lgkmcnt(0)
	global_store_dwordx4 v[86:87], v[82:85], off sc1
	s_nop 7
	v_lshlrev_b32_e32 v86, 1, v145
	v_mov_b32_e32 v87, v0
	v_lshl_add_u64 v[86:87], s[18:19], 0, v[86:87]
	v_lshl_add_u64 v[86:87], v[74:75], 1, v[86:87]
	v_add_u32_e32 v82, v144, v146
	v_lshl_add_u64 v[86:87], v[86:87], 0, v[88:89]
	ds_read_b128 v[82:85], v82
	s_waitcnt lgkmcnt(0)
	global_store_dwordx4 v[86:87], v[82:85], off sc1
	s_nop 7
	v_lshlrev_b32_e32 v86, 1, v148
	v_mov_b32_e32 v87, v0
	v_lshl_add_u64 v[86:87], s[18:19], 0, v[86:87]
	v_lshl_add_u64 v[86:87], v[76:77], 1, v[86:87]
	v_add_u32_e32 v82, v147, v149
	v_lshl_add_u64 v[86:87], v[86:87], 0, v[88:89]
	ds_read_b128 v[82:85], v82
	s_waitcnt lgkmcnt(0)
	global_store_dwordx4 v[86:87], v[82:85], off sc1
	s_nop 7
	v_lshlrev_b32_e32 v86, 1, v151
	v_mov_b32_e32 v87, v0
	v_lshl_add_u64 v[86:87], s[18:19], 0, v[86:87]
	v_lshl_add_u64 v[86:87], v[78:79], 1, v[86:87]
	v_add_u32_e32 v82, v150, v152
	v_lshl_add_u64 v[86:87], v[86:87], 0, v[88:89]
	ds_read_b128 v[82:85], v82
	s_waitcnt lgkmcnt(0)
	global_store_dwordx4 v[86:87], v[82:85], off sc1
	s_nop 7
	v_lshlrev_b32_e32 v86, 1, v1
	v_mov_b32_e32 v87, v0
	v_lshl_add_u64 v[86:87], s[18:19], 0, v[86:87]
	v_add_u32_e32 v82, v153, v154
	v_lshl_add_u64 v[86:87], v[80:81], 1, v[86:87]
	ds_read_b128 v[82:85], v82
	v_lshl_add_u64 v[86:87], v[86:87], 0, v[88:89]
	s_waitcnt lgkmcnt(0)
	global_store_dwordx4 v[86:87], v[82:85], off sc1
	s_nop 7
	s_waitcnt lgkmcnt(0)
	s_barrier
